# GEMM K-loops: pre-MFMA s_barrier moved below the first 4 MFMAs of each block, all 18 K-loops
# speedup vs baseline: 1.0430x; 1.0430x over previous
.LBB0_408:
	ds_read_b128 v[34:37], v196
	ds_read_b128 v[38:41], v196 offset:1024
	ds_read_b128 v[42:45], v196 offset:2048
	ds_read_b128 v[46:49], v196 offset:3072
	ds_read_b128 v[146:149], v197
	ds_read_b128 v[150:153], v197 offset:1024
	ds_read_b128 v[184:187], v197 offset:2048
	ds_read_b128 v[188:191], v197 offset:3072
	s_add_i32 s11, s6, 2
	s_add_u32 s12, s4, 0x80
	s_addc_u32 s7, s5, 0
	s_cmp_eq_u32 s27, s6
	s_cselect_b32 s6, s54, s12
	s_cselect_b32 s7, s55, s7
	s_cselect_b32 s13, s61, s9
	s_cselect_b32 s12, s60, s8
	v_lshl_add_u64 v[192:193], s[4:5], 0, v[174:175]
	s_add_i32 m0, s88, 0xc000
	ds_read_b128 v[200:203], v198
	ds_read_b128 v[204:207], v198 offset:1024
	ds_read_b128 v[208:211], v198 offset:2048
	ds_read_b128 v[212:215], v198 offset:3072
	ds_read_b128 v[216:219], v198 offset:4096
	ds_read_b128 v[220:223], v198 offset:5120
	ds_read_b128 v[224:227], v198 offset:6144
	ds_read_b128 v[228:231], v198 offset:7168
	global_load_lds_dwordx4 v[192:193], off
	v_lshl_add_u64 v[192:193], s[4:5], 0, v[176:177]
	s_add_i32 m0, s88, 0xe000
	s_nop 0
	global_load_lds_dwordx4 v[192:193], off
	s_waitcnt vmcnt(8)
	s_waitcnt lgkmcnt(0)
	s_setprio 1
	s_waitcnt lgkmcnt(0)
	v_mfma_f32_16x16x32_bf16 v[142:145], v[34:37], v[200:203], v[142:145]
	v_mfma_f32_16x16x32_bf16 v[138:141], v[42:45], v[200:203], v[138:141]
	v_mfma_f32_16x16x32_bf16 v[126:129], v[34:37], v[208:211], v[126:129]
	v_mfma_f32_16x16x32_bf16 v[122:125], v[42:45], v[208:211], v[122:125]
	s_barrier
	v_mfma_f32_16x16x32_bf16 v[110:113], v[34:37], v[216:219], v[110:113]
	v_mfma_f32_16x16x32_bf16 v[106:109], v[42:45], v[216:219], v[106:109]
	v_mfma_f32_16x16x32_bf16 v[94:97], v[34:37], v[224:227], v[94:97]
	v_mfma_f32_16x16x32_bf16 v[90:93], v[42:45], v[224:227], v[90:93]
	v_mfma_f32_16x16x32_bf16 v[142:145], v[38:41], v[204:207], v[142:145]
	v_mfma_f32_16x16x32_bf16 v[138:141], v[46:49], v[204:207], v[138:141]
	v_mfma_f32_16x16x32_bf16 v[126:129], v[38:41], v[212:215], v[126:129]
	v_mfma_f32_16x16x32_bf16 v[122:125], v[46:49], v[212:215], v[122:125]
	v_mfma_f32_16x16x32_bf16 v[110:113], v[38:41], v[220:223], v[110:113]
	v_mfma_f32_16x16x32_bf16 v[106:109], v[46:49], v[220:223], v[106:109]
	v_mfma_f32_16x16x32_bf16 v[94:97], v[38:41], v[228:231], v[94:97]
	v_mfma_f32_16x16x32_bf16 v[90:93], v[46:49], v[228:231], v[90:93]
	s_setprio 0
	s_setprio 1
	v_mfma_f32_16x16x32_bf16 v[134:137], v[146:149], v[200:203], v[134:137]
	v_mfma_f32_16x16x32_bf16 v[130:133], v[184:187], v[200:203], v[130:133]
	v_mfma_f32_16x16x32_bf16 v[118:121], v[146:149], v[208:211], v[118:121]
	v_mfma_f32_16x16x32_bf16 v[114:117], v[184:187], v[208:211], v[114:117]
	v_mfma_f32_16x16x32_bf16 v[102:105], v[146:149], v[216:219], v[102:105]
	v_mfma_f32_16x16x32_bf16 v[98:101], v[184:187], v[216:219], v[98:101]
	v_mfma_f32_16x16x32_bf16 v[86:89], v[146:149], v[224:227], v[86:89]
	v_mfma_f32_16x16x32_bf16 v[82:85], v[184:187], v[224:227], v[82:85]
	v_mfma_f32_16x16x32_bf16 v[134:137], v[150:153], v[204:207], v[134:137]
	v_mfma_f32_16x16x32_bf16 v[130:133], v[188:191], v[204:207], v[130:133]
	v_mfma_f32_16x16x32_bf16 v[118:121], v[150:153], v[212:215], v[118:121]
	v_mfma_f32_16x16x32_bf16 v[114:117], v[188:191], v[212:215], v[114:117]
	v_mfma_f32_16x16x32_bf16 v[102:105], v[150:153], v[220:223], v[102:105]
	v_mfma_f32_16x16x32_bf16 v[98:101], v[188:191], v[220:223], v[98:101]
	v_mfma_f32_16x16x32_bf16 v[86:89], v[150:153], v[228:231], v[86:89]
	v_mfma_f32_16x16x32_bf16 v[82:85], v[188:191], v[228:231], v[82:85]
	s_setprio 0
	s_barrier
	s_add_i32 s24, s84, s81
	v_lshl_add_u64 v[192:193], s[12:13], 0, v[156:157]
	s_mov_b32 m0, s24
	ds_read_b128 v[200:203], v198 offset:16384
	ds_read_b128 v[204:207], v198 offset:17408
	ds_read_b128 v[208:211], v198 offset:18432
	ds_read_b128 v[212:215], v198 offset:19456
	ds_read_b128 v[216:219], v198 offset:20480
	ds_read_b128 v[220:223], v198 offset:21504
	ds_read_b128 v[224:227], v198 offset:22528
	ds_read_b128 v[228:231], v198 offset:23552
	global_load_lds_dwordx4 v[192:193], off
	s_add_i32 m0, s24, 0x2000
	v_lshl_add_u64 v[232:233], s[12:13], 0, v[160:161]
	s_add_u32 s12, s12, s20
	s_addc_u32 s13, s13, s21
	s_add_i32 s24, s85, s81
	global_load_lds_dwordx4 v[232:233], off
	v_lshl_add_u64 v[234:235], s[12:13], 0, v[156:157]
	s_mov_b32 m0, s24
	v_lshl_add_u64 v[236:237], s[12:13], 0, v[160:161]
	global_load_lds_dwordx4 v[234:235], off
	s_add_i32 m0, s24, 0x2000
	v_lshl_add_u64 v[238:239], s[6:7], 0, v[154:155]
	global_load_lds_dwordx4 v[236:237], off
	s_mov_b32 m0, s88
	v_lshl_add_u64 v[240:241], s[6:7], 0, v[158:159]
	global_load_lds_dwordx4 v[238:239], off
	s_mov_b32 m0, s90
	s_nop 0
	global_load_lds_dwordx4 v[240:241], off
	s_waitcnt vmcnt(8)
	s_waitcnt lgkmcnt(0)
	s_setprio 1
	s_waitcnt lgkmcnt(0)
	v_mfma_f32_16x16x32_bf16 v[78:81], v[34:37], v[200:203], v[78:81]
	v_mfma_f32_16x16x32_bf16 v[74:77], v[42:45], v[200:203], v[74:77]
	v_mfma_f32_16x16x32_bf16 v[62:65], v[34:37], v[208:211], v[62:65]
	v_mfma_f32_16x16x32_bf16 v[58:61], v[42:45], v[208:211], v[58:61]
	s_barrier
	v_mfma_f32_16x16x32_bf16 v[30:33], v[34:37], v[216:219], v[30:33]
	v_mfma_f32_16x16x32_bf16 v[26:29], v[42:45], v[216:219], v[26:29]
	v_mfma_f32_16x16x32_bf16 v[14:17], v[34:37], v[224:227], v[14:17]
	v_mfma_f32_16x16x32_bf16 v[10:13], v[42:45], v[224:227], v[10:13]
	v_mfma_f32_16x16x32_bf16 v[78:81], v[38:41], v[204:207], v[78:81]
	v_mfma_f32_16x16x32_bf16 v[74:77], v[46:49], v[204:207], v[74:77]
	v_mfma_f32_16x16x32_bf16 v[62:65], v[38:41], v[212:215], v[62:65]
	v_mfma_f32_16x16x32_bf16 v[58:61], v[46:49], v[212:215], v[58:61]
	v_mfma_f32_16x16x32_bf16 v[30:33], v[38:41], v[220:223], v[30:33]
	v_mfma_f32_16x16x32_bf16 v[26:29], v[46:49], v[220:223], v[26:29]
	v_mfma_f32_16x16x32_bf16 v[14:17], v[38:41], v[228:231], v[14:17]
	v_mfma_f32_16x16x32_bf16 v[10:13], v[46:49], v[228:231], v[10:13]
	s_setprio 0
	s_setprio 1
	v_mfma_f32_16x16x32_bf16 v[22:25], v[146:149], v[216:219], v[22:25]
	v_mfma_f32_16x16x32_bf16 v[18:21], v[184:187], v[216:219], v[18:21]
	v_mfma_f32_16x16x32_bf16 v[6:9], v[146:149], v[224:227], v[6:9]
	v_mfma_f32_16x16x32_bf16 v[2:5], v[184:187], v[224:227], v[2:5]
	v_mfma_f32_16x16x32_bf16 v[34:37], v[146:149], v[200:203], v[70:73]
	v_mfma_f32_16x16x32_bf16 v[38:41], v[184:187], v[200:203], v[66:69]
	v_mfma_f32_16x16x32_bf16 v[42:45], v[146:149], v[208:211], v[54:57]
	v_mfma_f32_16x16x32_bf16 v[46:49], v[184:187], v[208:211], v[50:53]
	v_mfma_f32_16x16x32_bf16 v[22:25], v[150:153], v[220:223], v[22:25]
	v_mfma_f32_16x16x32_bf16 v[18:21], v[188:191], v[220:223], v[18:21]
	v_mfma_f32_16x16x32_bf16 v[6:9], v[150:153], v[228:231], v[6:9]
	v_mfma_f32_16x16x32_bf16 v[2:5], v[188:191], v[228:231], v[2:5]
	v_mfma_f32_16x16x32_bf16 v[34:37], v[150:153], v[204:207], v[34:37]
	v_mfma_f32_16x16x32_bf16 v[38:41], v[188:191], v[204:207], v[38:41]
	v_mfma_f32_16x16x32_bf16 v[42:45], v[150:153], v[212:215], v[42:45]
	v_mfma_f32_16x16x32_bf16 v[46:49], v[188:191], v[212:215], v[46:49]
	s_setprio 0
	s_barrier
	s_add_i32 s12, 0, 0x18000
	s_add_i32 s13, 0, 0x1c000
	v_add_u32_e32 v70, s12, v194
	v_add_u32_e32 v162, s13, v194
	ds_read_b128 v[50:53], v70
	ds_read_b128 v[54:57], v70 offset:1024
	ds_read_b128 v[66:69], v70 offset:2048
	ds_read_b128 v[70:73], v70 offset:3072
	ds_read_b128 v[146:149], v162
	ds_read_b128 v[150:153], v162 offset:1024
	ds_read_b128 v[184:187], v162 offset:2048
	ds_read_b128 v[188:191], v162 offset:3072
	s_add_u32 s6, s6, s20
	s_addc_u32 s7, s7, s21
	s_mov_b32 m0, s91
	v_lshl_add_u64 v[242:243], s[6:7], 0, v[154:155]
	ds_read_b128 v[200:203], v198 offset:32768
	ds_read_b128 v[204:207], v198 offset:33792
	ds_read_b128 v[208:211], v198 offset:34816
	ds_read_b128 v[212:215], v198 offset:35840
	ds_read_b128 v[216:219], v198 offset:36864
	ds_read_b128 v[220:223], v198 offset:37888
	ds_read_b128 v[224:227], v198 offset:38912
	ds_read_b128 v[228:231], v198 offset:39936
	global_load_lds_dwordx4 v[242:243], off
	v_lshl_add_u64 v[242:243], s[6:7], 0, v[158:159]
	s_mov_b32 m0, s95
	s_nop 0
	global_load_lds_dwordx4 v[242:243], off
	s_waitcnt vmcnt(8)
	s_waitcnt lgkmcnt(0)
	s_setprio 1
	s_waitcnt lgkmcnt(0)
	v_mfma_f32_16x16x32_bf16 v[142:145], v[50:53], v[200:203], v[142:145]
	v_mfma_f32_16x16x32_bf16 v[138:141], v[66:69], v[200:203], v[138:141]
	v_mfma_f32_16x16x32_bf16 v[126:129], v[50:53], v[208:211], v[126:129]
	v_mfma_f32_16x16x32_bf16 v[122:125], v[66:69], v[208:211], v[122:125]
	s_barrier
	v_mfma_f32_16x16x32_bf16 v[110:113], v[50:53], v[216:219], v[110:113]
	v_mfma_f32_16x16x32_bf16 v[106:109], v[66:69], v[216:219], v[106:109]
	v_mfma_f32_16x16x32_bf16 v[94:97], v[50:53], v[224:227], v[94:97]
	v_mfma_f32_16x16x32_bf16 v[90:93], v[66:69], v[224:227], v[90:93]
	v_mfma_f32_16x16x32_bf16 v[142:145], v[54:57], v[204:207], v[142:145]
	v_mfma_f32_16x16x32_bf16 v[138:141], v[70:73], v[204:207], v[138:141]
	v_mfma_f32_16x16x32_bf16 v[126:129], v[54:57], v[212:215], v[126:129]
	v_mfma_f32_16x16x32_bf16 v[122:125], v[70:73], v[212:215], v[122:125]
	v_mfma_f32_16x16x32_bf16 v[110:113], v[54:57], v[220:223], v[110:113]
	v_mfma_f32_16x16x32_bf16 v[106:109], v[70:73], v[220:223], v[106:109]
	v_mfma_f32_16x16x32_bf16 v[94:97], v[54:57], v[228:231], v[94:97]
	v_mfma_f32_16x16x32_bf16 v[90:93], v[70:73], v[228:231], v[90:93]
	s_setprio 0
	s_setprio 1
	v_mfma_f32_16x16x32_bf16 v[134:137], v[146:149], v[200:203], v[134:137]
	v_mfma_f32_16x16x32_bf16 v[130:133], v[184:187], v[200:203], v[130:133]
	v_mfma_f32_16x16x32_bf16 v[118:121], v[146:149], v[208:211], v[118:121]
	v_mfma_f32_16x16x32_bf16 v[114:117], v[184:187], v[208:211], v[114:117]
	v_mfma_f32_16x16x32_bf16 v[102:105], v[146:149], v[216:219], v[102:105]
	v_mfma_f32_16x16x32_bf16 v[98:101], v[184:187], v[216:219], v[98:101]
	v_mfma_f32_16x16x32_bf16 v[86:89], v[146:149], v[224:227], v[86:89]
	v_mfma_f32_16x16x32_bf16 v[82:85], v[184:187], v[224:227], v[82:85]
	v_mfma_f32_16x16x32_bf16 v[134:137], v[150:153], v[204:207], v[134:137]
	v_mfma_f32_16x16x32_bf16 v[130:133], v[188:191], v[204:207], v[130:133]
	v_mfma_f32_16x16x32_bf16 v[118:121], v[150:153], v[212:215], v[118:121]
	v_mfma_f32_16x16x32_bf16 v[114:117], v[188:191], v[212:215], v[114:117]
	v_mfma_f32_16x16x32_bf16 v[102:105], v[150:153], v[220:223], v[102:105]
	v_mfma_f32_16x16x32_bf16 v[98:101], v[188:191], v[220:223], v[98:101]
	v_mfma_f32_16x16x32_bf16 v[86:89], v[150:153], v[228:231], v[86:89]
	v_mfma_f32_16x16x32_bf16 v[82:85], v[188:191], v[228:231], v[82:85]
	s_setprio 0
	s_barrier
	s_add_i32 s6, s12, s81
	v_lshl_add_u64 v[192:193], v[192:193], 0, s[44:45]
	s_mov_b32 m0, s6
	ds_read_b128 v[200:203], v198 offset:49152
	ds_read_b128 v[204:207], v198 offset:50176
	ds_read_b128 v[208:211], v198 offset:51200
	ds_read_b128 v[212:215], v198 offset:52224
	ds_read_b128 v[216:219], v198 offset:53248
	ds_read_b128 v[220:223], v198 offset:54272
	ds_read_b128 v[224:227], v198 offset:55296
	ds_read_b128 v[228:231], v198 offset:56320
	global_load_lds_dwordx4 v[192:193], off
	v_lshl_add_u64 v[192:193], v[232:233], 0, s[44:45]
	s_add_i32 m0, s6, 0x2000
	s_add_i32 s6, s13, s81
	global_load_lds_dwordx4 v[192:193], off
	v_lshl_add_u64 v[192:193], v[234:235], 0, s[44:45]
	s_mov_b32 m0, s6
	s_nop 0
	global_load_lds_dwordx4 v[192:193], off
	v_lshl_add_u64 v[192:193], v[236:237], 0, s[44:45]
	s_add_i32 m0, s6, 0x2000
	s_nop 0
	global_load_lds_dwordx4 v[192:193], off
	v_lshl_add_u64 v[192:193], v[238:239], 0, s[44:45]
	s_mov_b32 m0, s17
	s_nop 0
	global_load_lds_dwordx4 v[192:193], off
	v_lshl_add_u64 v[192:193], v[240:241], 0, s[44:45]
	s_mov_b32 m0, s94
	s_nop 0
	global_load_lds_dwordx4 v[192:193], off
	s_waitcnt vmcnt(8)
	s_waitcnt lgkmcnt(0)
	s_setprio 1
	s_waitcnt lgkmcnt(0)
	v_mfma_f32_16x16x32_bf16 v[78:81], v[50:53], v[200:203], v[78:81]
	v_mfma_f32_16x16x32_bf16 v[74:77], v[66:69], v[200:203], v[74:77]
	v_mfma_f32_16x16x32_bf16 v[62:65], v[50:53], v[208:211], v[62:65]
	v_mfma_f32_16x16x32_bf16 v[58:61], v[66:69], v[208:211], v[58:61]
	s_barrier
	v_mfma_f32_16x16x32_bf16 v[30:33], v[50:53], v[216:219], v[30:33]
	v_mfma_f32_16x16x32_bf16 v[26:29], v[66:69], v[216:219], v[26:29]
	v_mfma_f32_16x16x32_bf16 v[14:17], v[50:53], v[224:227], v[14:17]
	v_mfma_f32_16x16x32_bf16 v[10:13], v[66:69], v[224:227], v[10:13]
	v_mfma_f32_16x16x32_bf16 v[78:81], v[54:57], v[204:207], v[78:81]
	v_mfma_f32_16x16x32_bf16 v[74:77], v[70:73], v[204:207], v[74:77]
	v_mfma_f32_16x16x32_bf16 v[62:65], v[54:57], v[212:215], v[62:65]
	v_mfma_f32_16x16x32_bf16 v[58:61], v[70:73], v[212:215], v[58:61]
	v_mfma_f32_16x16x32_bf16 v[30:33], v[54:57], v[220:223], v[30:33]
	v_mfma_f32_16x16x32_bf16 v[26:29], v[70:73], v[220:223], v[26:29]
	v_mfma_f32_16x16x32_bf16 v[14:17], v[54:57], v[228:231], v[14:17]
	v_mfma_f32_16x16x32_bf16 v[10:13], v[70:73], v[228:231], v[10:13]
	s_setprio 0
	s_setprio 1
	v_mfma_f32_16x16x32_bf16 v[34:37], v[146:149], v[200:203], v[34:37]
	v_mfma_f32_16x16x32_bf16 v[70:73], v[150:153], v[204:207], v[34:37]
	v_mfma_f32_16x16x32_bf16 v[34:37], v[184:187], v[200:203], v[38:41]
	v_mfma_f32_16x16x32_bf16 v[66:69], v[188:191], v[204:207], v[34:37]
	v_mfma_f32_16x16x32_bf16 v[34:37], v[146:149], v[208:211], v[42:45]
	v_mfma_f32_16x16x32_bf16 v[54:57], v[150:153], v[212:215], v[34:37]
	v_mfma_f32_16x16x32_bf16 v[34:37], v[184:187], v[208:211], v[46:49]
	v_mfma_f32_16x16x32_bf16 v[22:25], v[146:149], v[216:219], v[22:25]
	v_mfma_f32_16x16x32_bf16 v[18:21], v[184:187], v[216:219], v[18:21]
	v_mfma_f32_16x16x32_bf16 v[6:9], v[146:149], v[224:227], v[6:9]
	v_mfma_f32_16x16x32_bf16 v[2:5], v[184:187], v[224:227], v[2:5]
	v_mfma_f32_16x16x32_bf16 v[50:53], v[188:191], v[212:215], v[34:37]
	v_mfma_f32_16x16x32_bf16 v[22:25], v[150:153], v[220:223], v[22:25]
	v_mfma_f32_16x16x32_bf16 v[18:21], v[188:191], v[220:223], v[18:21]
	v_mfma_f32_16x16x32_bf16 v[6:9], v[150:153], v[228:231], v[6:9]
	v_mfma_f32_16x16x32_bf16 v[2:5], v[188:191], v[228:231], v[2:5]
	s_setprio 0
	s_barrier
	s_add_u32 s4, s4, 0x100
	s_addc_u32 s5, s5, 0
	s_add_u32 s8, s8, 0x100
	s_addc_u32 s9, s9, 0
	s_cmp_ge_i32 s11, s26
	s_mov_b32 s6, s11
	s_cbranch_scc0 .LBB0_408

.LBB0_895:
	v_add_u32_e32 v158, s84, v227
	v_add_u32_e32 v174, s85, v227
	ds_read_b128 v[146:149], v158
	ds_read_b128 v[150:153], v158 offset:1024
	ds_read_b128 v[154:157], v158 offset:2048
	ds_read_b128 v[158:161], v158 offset:3072
	ds_read_b128 v[162:165], v174
	ds_read_b128 v[166:169], v174 offset:1024
	ds_read_b128 v[170:173], v174 offset:2048
	ds_read_b128 v[174:177], v174 offset:3072
	s_add_i32 s16, s50, 2
	s_add_u32 s17, s46, 0x80
	s_addc_u32 s51, s47, 0
	s_cmp_eq_u32 s81, s50
	s_cselect_b32 s50, s4, s17
	s_cselect_b32 s51, s5, s51
	s_cselect_b32 s55, s45, vcc_hi
	s_cselect_b32 s54, s44, vcc_lo
	v_lshl_add_u64 v[210:211], s[46:47], 0, v[138:139]
	s_add_i32 m0, s63, 0xc000
	ds_read_b128 v[178:181], v229
	ds_read_b128 v[182:185], v229 offset:1024
	ds_read_b128 v[186:189], v229 offset:2048
	ds_read_b128 v[190:193], v229 offset:3072
	ds_read_b128 v[194:197], v229 offset:4096
	ds_read_b128 v[198:201], v229 offset:5120
	ds_read_b128 v[202:205], v229 offset:6144
	ds_read_b128 v[206:209], v229 offset:7168
	global_load_lds_dwordx4 v[210:211], off
	v_lshl_add_u64 v[210:211], s[46:47], 0, v[140:141]
	s_add_i32 m0, s63, 0xe000
	s_nop 0
	global_load_lds_dwordx4 v[210:211], off
	s_waitcnt vmcnt(8)
	s_waitcnt lgkmcnt(0)
	s_setprio 1
	s_waitcnt lgkmcnt(0)
	v_mfma_i32_16x16x64_i8 v[126:129], v[146:149], v[178:181], v[126:129]
	v_mfma_i32_16x16x64_i8 v[122:125], v[154:157], v[178:181], v[122:125]
	v_mfma_i32_16x16x64_i8 v[118:121], v[146:149], v[186:189], v[118:121]
	v_mfma_i32_16x16x64_i8 v[114:117], v[154:157], v[186:189], v[114:117]
	s_barrier
	v_mfma_i32_16x16x64_i8 v[106:109], v[146:149], v[194:197], v[106:109]
	v_mfma_i32_16x16x64_i8 v[98:101], v[154:157], v[194:197], v[98:101]
	v_mfma_i32_16x16x64_i8 v[90:93], v[146:149], v[202:205], v[90:93]
	v_mfma_i32_16x16x64_i8 v[82:85], v[154:157], v[202:205], v[82:85]
	v_mfma_i32_16x16x64_i8 v[126:129], v[150:153], v[182:185], v[126:129]
	v_mfma_i32_16x16x64_i8 v[122:125], v[158:161], v[182:185], v[122:125]
	v_mfma_i32_16x16x64_i8 v[118:121], v[150:153], v[190:193], v[118:121]
	v_mfma_i32_16x16x64_i8 v[114:117], v[158:161], v[190:193], v[114:117]
	v_mfma_i32_16x16x64_i8 v[106:109], v[150:153], v[198:201], v[106:109]
	v_mfma_i32_16x16x64_i8 v[98:101], v[158:161], v[198:201], v[98:101]
	v_mfma_i32_16x16x64_i8 v[90:93], v[150:153], v[206:209], v[90:93]
	v_mfma_i32_16x16x64_i8 v[82:85], v[158:161], v[206:209], v[82:85]
	s_setprio 0
	s_setprio 1
	v_mfma_i32_16x16x64_i8 v[110:113], v[162:165], v[178:181], v[110:113]
	v_mfma_i32_16x16x64_i8 v[102:105], v[170:173], v[178:181], v[102:105]
	v_mfma_i32_16x16x64_i8 v[94:97], v[162:165], v[186:189], v[94:97]
	v_mfma_i32_16x16x64_i8 v[86:89], v[170:173], v[186:189], v[86:89]
	v_mfma_i32_16x16x64_i8 v[78:81], v[162:165], v[194:197], v[78:81]
	v_mfma_i32_16x16x64_i8 v[74:77], v[170:173], v[194:197], v[74:77]
	v_mfma_i32_16x16x64_i8 v[70:73], v[162:165], v[202:205], v[70:73]
	v_mfma_i32_16x16x64_i8 v[66:69], v[170:173], v[202:205], v[66:69]
	v_mfma_i32_16x16x64_i8 v[110:113], v[166:169], v[182:185], v[110:113]
	v_mfma_i32_16x16x64_i8 v[102:105], v[174:177], v[182:185], v[102:105]
	v_mfma_i32_16x16x64_i8 v[94:97], v[166:169], v[190:193], v[94:97]
	v_mfma_i32_16x16x64_i8 v[86:89], v[174:177], v[190:193], v[86:89]
	v_mfma_i32_16x16x64_i8 v[78:81], v[166:169], v[198:201], v[78:81]
	v_mfma_i32_16x16x64_i8 v[74:77], v[174:177], v[198:201], v[74:77]
	v_mfma_i32_16x16x64_i8 v[70:73], v[166:169], v[206:209], v[70:73]
	v_mfma_i32_16x16x64_i8 v[66:69], v[174:177], v[206:209], v[66:69]
	s_setprio 0
	s_barrier
	s_add_i32 s17, s84, s62
	v_lshl_add_u64 v[210:211], s[54:55], 0, v[132:133]
	s_mov_b32 m0, s17
	ds_read_b128 v[178:181], v229 offset:16384
	ds_read_b128 v[182:185], v229 offset:17408
	ds_read_b128 v[186:189], v229 offset:18432
	ds_read_b128 v[190:193], v229 offset:19456
	ds_read_b128 v[194:197], v229 offset:20480
	ds_read_b128 v[198:201], v229 offset:21504
	ds_read_b128 v[202:205], v229 offset:22528
	ds_read_b128 v[206:209], v229 offset:23552
	global_load_lds_dwordx4 v[210:211], off
	s_add_i32 m0, s17, 0x2000
	v_lshl_add_u64 v[212:213], s[54:55], 0, v[136:137]
	s_add_u32 s54, s54, s8
	s_addc_u32 s55, s55, s9
	s_add_i32 s17, s85, s62
	global_load_lds_dwordx4 v[212:213], off
	v_lshl_add_u64 v[214:215], s[54:55], 0, v[132:133]
	s_mov_b32 m0, s17
	v_lshl_add_u64 v[216:217], s[54:55], 0, v[136:137]
	global_load_lds_dwordx4 v[214:215], off
	s_add_i32 m0, s17, 0x2000
	v_lshl_add_u64 v[218:219], s[50:51], 0, v[130:131]
	global_load_lds_dwordx4 v[216:217], off
	s_mov_b32 m0, s63
	v_lshl_add_u64 v[220:221], s[50:51], 0, v[134:135]
	global_load_lds_dwordx4 v[218:219], off
	s_mov_b32 m0, s64
	s_nop 0
	global_load_lds_dwordx4 v[220:221], off
	s_waitcnt vmcnt(8)
	s_waitcnt lgkmcnt(0)
	s_setprio 1
	s_waitcnt lgkmcnt(0)
	v_mfma_i32_16x16x64_i8 v[62:65], v[146:149], v[178:181], v[62:65]
	v_mfma_i32_16x16x64_i8 v[58:61], v[154:157], v[178:181], v[58:61]
	v_mfma_i32_16x16x64_i8 v[54:57], v[146:149], v[186:189], v[54:57]
	v_mfma_i32_16x16x64_i8 v[50:53], v[154:157], v[186:189], v[50:53]
	s_barrier
	v_mfma_i32_16x16x64_i8 v[42:45], v[146:149], v[194:197], v[42:45]
	v_mfma_i32_16x16x64_i8 v[34:37], v[154:157], v[194:197], v[34:37]
	v_mfma_i32_16x16x64_i8 v[26:29], v[146:149], v[202:205], v[26:29]
	v_mfma_i32_16x16x64_i8 v[18:21], v[154:157], v[202:205], v[18:21]
	v_mfma_i32_16x16x64_i8 v[62:65], v[150:153], v[182:185], v[62:65]
	v_mfma_i32_16x16x64_i8 v[58:61], v[158:161], v[182:185], v[58:61]
	v_mfma_i32_16x16x64_i8 v[54:57], v[150:153], v[190:193], v[54:57]
	v_mfma_i32_16x16x64_i8 v[50:53], v[158:161], v[190:193], v[50:53]
	v_mfma_i32_16x16x64_i8 v[42:45], v[150:153], v[198:201], v[42:45]
	v_mfma_i32_16x16x64_i8 v[34:37], v[158:161], v[198:201], v[34:37]
	v_mfma_i32_16x16x64_i8 v[26:29], v[150:153], v[206:209], v[26:29]
	v_mfma_i32_16x16x64_i8 v[18:21], v[158:161], v[206:209], v[18:21]
	s_setprio 0
	s_setprio 1
	v_mfma_i32_16x16x64_i8 v[46:49], v[162:165], v[178:181], v[46:49]
	v_mfma_i32_16x16x64_i8 v[38:41], v[170:173], v[178:181], v[38:41]
	v_mfma_i32_16x16x64_i8 v[30:33], v[162:165], v[186:189], v[30:33]
	v_mfma_i32_16x16x64_i8 v[22:25], v[170:173], v[186:189], v[22:25]
	v_mfma_i32_16x16x64_i8 v[14:17], v[162:165], v[194:197], v[14:17]
	v_mfma_i32_16x16x64_i8 v[10:13], v[170:173], v[194:197], v[10:13]
	v_mfma_i32_16x16x64_i8 v[6:9], v[162:165], v[202:205], v[6:9]
	v_mfma_i32_16x16x64_i8 v[2:5], v[170:173], v[202:205], v[2:5]
	v_mfma_i32_16x16x64_i8 v[46:49], v[166:169], v[182:185], v[46:49]
	v_mfma_i32_16x16x64_i8 v[38:41], v[174:177], v[182:185], v[38:41]
	v_mfma_i32_16x16x64_i8 v[30:33], v[166:169], v[190:193], v[30:33]
	v_mfma_i32_16x16x64_i8 v[22:25], v[174:177], v[190:193], v[22:25]
	v_mfma_i32_16x16x64_i8 v[14:17], v[166:169], v[198:201], v[14:17]
	v_mfma_i32_16x16x64_i8 v[10:13], v[174:177], v[198:201], v[10:13]
	v_mfma_i32_16x16x64_i8 v[6:9], v[166:169], v[206:209], v[6:9]
	v_mfma_i32_16x16x64_i8 v[2:5], v[174:177], v[206:209], v[2:5]
	s_setprio 0
	s_barrier
	s_add_i32 s17, 0, 0x18000
	s_add_i32 s54, 0, 0x1c000
	v_add_u32_e32 v158, s17, v227
	v_add_u32_e32 v174, s54, v227
	ds_read_b128 v[146:149], v158
	ds_read_b128 v[150:153], v158 offset:1024
	ds_read_b128 v[154:157], v158 offset:2048
	ds_read_b128 v[158:161], v158 offset:3072
	ds_read_b128 v[162:165], v174
	ds_read_b128 v[166:169], v174 offset:1024
	ds_read_b128 v[170:173], v174 offset:2048
	ds_read_b128 v[174:177], v174 offset:3072
	s_add_u32 s50, s50, s8
	s_addc_u32 s51, s51, s9
	s_mov_b32 m0, s65
	v_lshl_add_u64 v[222:223], s[50:51], 0, v[130:131]
	ds_read_b128 v[178:181], v229 offset:32768
	ds_read_b128 v[182:185], v229 offset:33792
	ds_read_b128 v[186:189], v229 offset:34816
	ds_read_b128 v[190:193], v229 offset:35840
	ds_read_b128 v[194:197], v229 offset:36864
	ds_read_b128 v[198:201], v229 offset:37888
	ds_read_b128 v[202:205], v229 offset:38912
	ds_read_b128 v[206:209], v229 offset:39936
	global_load_lds_dwordx4 v[222:223], off
	v_lshl_add_u64 v[222:223], s[50:51], 0, v[134:135]
	s_mov_b32 m0, s86
	s_nop 0
	global_load_lds_dwordx4 v[222:223], off
	s_waitcnt vmcnt(8)
	s_waitcnt lgkmcnt(0)
	s_setprio 1
	s_waitcnt lgkmcnt(0)
	v_mfma_i32_16x16x64_i8 v[126:129], v[146:149], v[178:181], v[126:129]
	v_mfma_i32_16x16x64_i8 v[122:125], v[154:157], v[178:181], v[122:125]
	v_mfma_i32_16x16x64_i8 v[118:121], v[146:149], v[186:189], v[118:121]
	v_mfma_i32_16x16x64_i8 v[114:117], v[154:157], v[186:189], v[114:117]
	s_barrier
	v_mfma_i32_16x16x64_i8 v[106:109], v[146:149], v[194:197], v[106:109]
	v_mfma_i32_16x16x64_i8 v[98:101], v[154:157], v[194:197], v[98:101]
	v_mfma_i32_16x16x64_i8 v[90:93], v[146:149], v[202:205], v[90:93]
	v_mfma_i32_16x16x64_i8 v[82:85], v[154:157], v[202:205], v[82:85]
	v_mfma_i32_16x16x64_i8 v[126:129], v[150:153], v[182:185], v[126:129]
	v_mfma_i32_16x16x64_i8 v[122:125], v[158:161], v[182:185], v[122:125]
	v_mfma_i32_16x16x64_i8 v[118:121], v[150:153], v[190:193], v[118:121]
	v_mfma_i32_16x16x64_i8 v[114:117], v[158:161], v[190:193], v[114:117]
	v_mfma_i32_16x16x64_i8 v[106:109], v[150:153], v[198:201], v[106:109]
	v_mfma_i32_16x16x64_i8 v[98:101], v[158:161], v[198:201], v[98:101]
	v_mfma_i32_16x16x64_i8 v[90:93], v[150:153], v[206:209], v[90:93]
	v_mfma_i32_16x16x64_i8 v[82:85], v[158:161], v[206:209], v[82:85]
	s_setprio 0
	s_setprio 1
	v_mfma_i32_16x16x64_i8 v[110:113], v[162:165], v[178:181], v[110:113]
	v_mfma_i32_16x16x64_i8 v[102:105], v[170:173], v[178:181], v[102:105]
	v_mfma_i32_16x16x64_i8 v[94:97], v[162:165], v[186:189], v[94:97]
	v_mfma_i32_16x16x64_i8 v[86:89], v[170:173], v[186:189], v[86:89]
	v_mfma_i32_16x16x64_i8 v[78:81], v[162:165], v[194:197], v[78:81]
	v_mfma_i32_16x16x64_i8 v[74:77], v[170:173], v[194:197], v[74:77]
	v_mfma_i32_16x16x64_i8 v[70:73], v[162:165], v[202:205], v[70:73]
	v_mfma_i32_16x16x64_i8 v[66:69], v[170:173], v[202:205], v[66:69]
	v_mfma_i32_16x16x64_i8 v[110:113], v[166:169], v[182:185], v[110:113]
	v_mfma_i32_16x16x64_i8 v[102:105], v[174:177], v[182:185], v[102:105]
	v_mfma_i32_16x16x64_i8 v[94:97], v[166:169], v[190:193], v[94:97]
	v_mfma_i32_16x16x64_i8 v[86:89], v[174:177], v[190:193], v[86:89]
	v_mfma_i32_16x16x64_i8 v[78:81], v[166:169], v[198:201], v[78:81]
	v_mfma_i32_16x16x64_i8 v[74:77], v[174:177], v[198:201], v[74:77]
	v_mfma_i32_16x16x64_i8 v[70:73], v[166:169], v[206:209], v[70:73]
	v_mfma_i32_16x16x64_i8 v[66:69], v[174:177], v[206:209], v[66:69]
	s_setprio 0
	s_barrier
	s_add_i32 s17, s17, s62
	v_lshl_add_u64 v[210:211], v[210:211], 0, s[36:37]
	s_mov_b32 m0, s17
	ds_read_b128 v[178:181], v229 offset:49152
	ds_read_b128 v[182:185], v229 offset:50176
	ds_read_b128 v[186:189], v229 offset:51200
	ds_read_b128 v[190:193], v229 offset:52224
	ds_read_b128 v[194:197], v229 offset:53248
	ds_read_b128 v[198:201], v229 offset:54272
	ds_read_b128 v[202:205], v229 offset:55296
	ds_read_b128 v[206:209], v229 offset:56320
	global_load_lds_dwordx4 v[210:211], off
	v_lshl_add_u64 v[210:211], v[212:213], 0, s[36:37]
	s_add_i32 m0, s17, 0x2000
	s_add_i32 s17, s54, s62
	global_load_lds_dwordx4 v[210:211], off
	v_lshl_add_u64 v[210:211], v[214:215], 0, s[36:37]
	s_mov_b32 m0, s17
	s_nop 0
	global_load_lds_dwordx4 v[210:211], off
	v_lshl_add_u64 v[210:211], v[216:217], 0, s[36:37]
	s_add_i32 m0, s17, 0x2000
	s_nop 0
	global_load_lds_dwordx4 v[210:211], off
	v_lshl_add_u64 v[210:211], v[218:219], 0, s[36:37]
	s_mov_b32 m0, s95
	s_nop 0
	global_load_lds_dwordx4 v[210:211], off
	v_lshl_add_u64 v[210:211], v[220:221], 0, s[36:37]
	s_mov_b32 m0, s80
	s_nop 0
	global_load_lds_dwordx4 v[210:211], off
	s_waitcnt vmcnt(8)
	s_waitcnt lgkmcnt(0)
	s_setprio 1
	s_waitcnt lgkmcnt(0)
	v_mfma_i32_16x16x64_i8 v[62:65], v[146:149], v[178:181], v[62:65]
	v_mfma_i32_16x16x64_i8 v[58:61], v[154:157], v[178:181], v[58:61]
	v_mfma_i32_16x16x64_i8 v[54:57], v[146:149], v[186:189], v[54:57]
	v_mfma_i32_16x16x64_i8 v[50:53], v[154:157], v[186:189], v[50:53]
	s_barrier
	v_mfma_i32_16x16x64_i8 v[42:45], v[146:149], v[194:197], v[42:45]
	v_mfma_i32_16x16x64_i8 v[34:37], v[154:157], v[194:197], v[34:37]
	v_mfma_i32_16x16x64_i8 v[26:29], v[146:149], v[202:205], v[26:29]
	v_mfma_i32_16x16x64_i8 v[18:21], v[154:157], v[202:205], v[18:21]
	v_mfma_i32_16x16x64_i8 v[62:65], v[150:153], v[182:185], v[62:65]
	v_mfma_i32_16x16x64_i8 v[58:61], v[158:161], v[182:185], v[58:61]
	v_mfma_i32_16x16x64_i8 v[54:57], v[150:153], v[190:193], v[54:57]
	v_mfma_i32_16x16x64_i8 v[50:53], v[158:161], v[190:193], v[50:53]
	v_mfma_i32_16x16x64_i8 v[42:45], v[150:153], v[198:201], v[42:45]
	v_mfma_i32_16x16x64_i8 v[34:37], v[158:161], v[198:201], v[34:37]
	v_mfma_i32_16x16x64_i8 v[26:29], v[150:153], v[206:209], v[26:29]
	v_mfma_i32_16x16x64_i8 v[18:21], v[158:161], v[206:209], v[18:21]
	s_setprio 0
	s_setprio 1
	v_mfma_i32_16x16x64_i8 v[46:49], v[162:165], v[178:181], v[46:49]
	v_mfma_i32_16x16x64_i8 v[38:41], v[170:173], v[178:181], v[38:41]
	v_mfma_i32_16x16x64_i8 v[30:33], v[162:165], v[186:189], v[30:33]
	v_mfma_i32_16x16x64_i8 v[22:25], v[170:173], v[186:189], v[22:25]
	v_mfma_i32_16x16x64_i8 v[14:17], v[162:165], v[194:197], v[14:17]
	v_mfma_i32_16x16x64_i8 v[10:13], v[170:173], v[194:197], v[10:13]
	v_mfma_i32_16x16x64_i8 v[6:9], v[162:165], v[202:205], v[6:9]
	v_mfma_i32_16x16x64_i8 v[2:5], v[170:173], v[202:205], v[2:5]
	v_mfma_i32_16x16x64_i8 v[46:49], v[166:169], v[182:185], v[46:49]
	v_mfma_i32_16x16x64_i8 v[38:41], v[174:177], v[182:185], v[38:41]
	v_mfma_i32_16x16x64_i8 v[30:33], v[166:169], v[190:193], v[30:33]
	v_mfma_i32_16x16x64_i8 v[22:25], v[174:177], v[190:193], v[22:25]
	v_mfma_i32_16x16x64_i8 v[14:17], v[166:169], v[198:201], v[14:17]
	v_mfma_i32_16x16x64_i8 v[10:13], v[174:177], v[198:201], v[10:13]
	v_mfma_i32_16x16x64_i8 v[6:9], v[166:169], v[206:209], v[6:9]
	v_mfma_i32_16x16x64_i8 v[2:5], v[174:177], v[206:209], v[2:5]
	s_setprio 0
	s_barrier
	s_add_u32 s46, s46, 0x100
	s_addc_u32 s47, s47, 0
	s_add_u32 vcc_lo, vcc_lo, 0x100
	s_addc_u32 vcc_hi, vcc_hi, 0
	s_cmp_ge_i32 s16, s90
	s_mov_b32 s50, s16
	s_cbranch_scc0 .LBB0_895
	v_cvt_f32_i32_e32 v220, v126
	v_cvt_f32_i32_e32 v221, v127
	v_cvt_f32_i32_e32 v218, v128
	v_cvt_f32_i32_e32 v219, v129
	v_cvt_f32_i32_e32 v224, v122
	v_cvt_f32_i32_e32 v225, v123
	v_cvt_f32_i32_e32 v222, v124
	v_cvt_f32_i32_e32 v223, v125
	v_cvt_f32_i32_e32 v212, v110
	v_cvt_f32_i32_e32 v213, v111
	v_cvt_f32_i32_e32 v210, v112
	v_cvt_f32_i32_e32 v211, v113
	v_cvt_f32_i32_e32 v216, v102
	v_cvt_f32_i32_e32 v217, v103
	v_cvt_f32_i32_e32 v214, v104
	v_cvt_f32_i32_e32 v215, v105
	v_cvt_f32_i32_e32 v204, v118
	v_cvt_f32_i32_e32 v205, v119
	v_cvt_f32_i32_e32 v202, v120
	v_cvt_f32_i32_e32 v203, v121
	v_cvt_f32_i32_e32 v208, v114
	v_cvt_f32_i32_e32 v209, v115
	v_cvt_f32_i32_e32 v206, v116
	v_cvt_f32_i32_e32 v207, v117
	v_cvt_f32_i32_e32 v198, v94
	v_cvt_f32_i32_e32 v199, v95
	v_cvt_f32_i32_e32 v194, v96
	v_cvt_f32_i32_e32 v195, v97
	v_cvt_f32_i32_e32 v200, v86
	v_cvt_f32_i32_e32 v201, v87
	v_cvt_f32_i32_e32 v196, v88
	v_cvt_f32_i32_e32 v197, v89
	v_cvt_f32_i32_e32 v188, v106
	v_cvt_f32_i32_e32 v189, v107
	v_cvt_f32_i32_e32 v186, v108
	v_cvt_f32_i32_e32 v187, v109
	v_cvt_f32_i32_e32 v192, v98
	v_cvt_f32_i32_e32 v193, v99
	v_cvt_f32_i32_e32 v190, v100
	v_cvt_f32_i32_e32 v191, v101
	v_cvt_f32_i32_e32 v182, v78
	v_cvt_f32_i32_e32 v183, v79
	v_cvt_f32_i32_e32 v178, v80
	v_cvt_f32_i32_e32 v179, v81
	v_cvt_f32_i32_e32 v184, v74
	v_cvt_f32_i32_e32 v185, v75
	v_cvt_f32_i32_e32 v180, v76
	v_cvt_f32_i32_e32 v181, v77
	v_cvt_f32_i32_e32 v170, v90
	v_cvt_f32_i32_e32 v171, v91
	v_cvt_f32_i32_e32 v168, v92
	v_cvt_f32_i32_e32 v169, v93
	v_cvt_f32_i32_e32 v174, v82
	v_cvt_f32_i32_e32 v175, v83
	v_cvt_f32_i32_e32 v172, v84
	v_cvt_f32_i32_e32 v173, v85
	v_cvt_f32_i32_e32 v164, v70
	v_cvt_f32_i32_e32 v165, v71
	v_cvt_f32_i32_e32 v160, v72
	v_cvt_f32_i32_e32 v161, v73
	v_cvt_f32_i32_e32 v166, v66
	v_cvt_f32_i32_e32 v167, v67
	v_cvt_f32_i32_e32 v162, v68
	v_cvt_f32_i32_e32 v163, v69
	v_cvt_f32_i32_e32 v154, v62
	v_cvt_f32_i32_e32 v155, v63
	v_cvt_f32_i32_e32 v152, v64
	v_cvt_f32_i32_e32 v153, v65
	v_cvt_f32_i32_e32 v158, v58
	v_cvt_f32_i32_e32 v159, v59
	v_cvt_f32_i32_e32 v156, v60
	v_cvt_f32_i32_e32 v157, v61
	v_cvt_f32_i32_e32 v148, v46
	v_cvt_f32_i32_e32 v149, v47
	v_cvt_f32_i32_e32 v128, v48
	v_cvt_f32_i32_e32 v129, v49
	v_cvt_f32_i32_e32 v150, v38
	v_cvt_f32_i32_e32 v151, v39
	v_cvt_f32_i32_e32 v146, v40
	v_cvt_f32_i32_e32 v147, v41
	v_cvt_f32_i32_e32 v122, v54
	v_cvt_f32_i32_e32 v123, v55
	v_cvt_f32_i32_e32 v120, v56
	v_cvt_f32_i32_e32 v121, v57
	v_cvt_f32_i32_e32 v126, v50
	v_cvt_f32_i32_e32 v127, v51
	v_cvt_f32_i32_e32 v124, v52
	v_cvt_f32_i32_e32 v125, v53
	v_cvt_f32_i32_e32 v114, v30
	v_cvt_f32_i32_e32 v115, v31
	v_cvt_f32_i32_e32 v110, v32
	v_cvt_f32_i32_e32 v111, v33
	v_cvt_f32_i32_e32 v116, v22
	v_cvt_f32_i32_e32 v117, v23
	v_cvt_f32_i32_e32 v112, v24
	v_cvt_f32_i32_e32 v113, v25
	v_cvt_f32_i32_e32 v102, v42
	v_cvt_f32_i32_e32 v103, v43
	v_cvt_f32_i32_e32 v100, v44
	v_cvt_f32_i32_e32 v101, v45
	v_cvt_f32_i32_e32 v106, v34
	v_cvt_f32_i32_e32 v107, v35
	v_cvt_f32_i32_e32 v104, v36
	v_cvt_f32_i32_e32 v105, v37
	v_cvt_f32_i32_e32 v96, v14
	v_cvt_f32_i32_e32 v97, v15
	v_cvt_f32_i32_e32 v92, v16
	v_cvt_f32_i32_e32 v93, v17
	v_cvt_f32_i32_e32 v98, v10
	v_cvt_f32_i32_e32 v99, v11
	v_cvt_f32_i32_e32 v94, v12
	v_cvt_f32_i32_e32 v95, v13
	v_cvt_f32_i32_e32 v52, v26
	v_cvt_f32_i32_e32 v53, v27
	v_cvt_f32_i32_e32 v50, v28
	v_cvt_f32_i32_e32 v51, v29
	v_cvt_f32_i32_e32 v56, v18
	v_cvt_f32_i32_e32 v57, v19
	v_cvt_f32_i32_e32 v54, v20
	v_cvt_f32_i32_e32 v55, v21
	v_cvt_f32_i32_e32 v46, v6
	v_cvt_f32_i32_e32 v47, v7
	v_cvt_f32_i32_e32 v42, v8
	v_cvt_f32_i32_e32 v43, v9
	v_cvt_f32_i32_e32 v48, v2
	v_cvt_f32_i32_e32 v49, v3
	v_cvt_f32_i32_e32 v44, v4
	v_cvt_f32_i32_e32 v45, v5

.LBB0_1087:
	v_add_u32_e32 v138, s80, v188
	ds_read_b128 v[148:151], v138
	ds_read_b128 v[152:155], v138 offset:1024
	ds_read_b128 v[156:159], v138 offset:2048
	ds_read_b128 v[160:163], v138 offset:3072
	v_add_u32_e32 v138, s81, v188
	ds_read_b128 v[164:167], v138
	ds_read_b128 v[168:171], v138 offset:1024
	ds_read_b128 v[172:175], v138 offset:2048
	ds_read_b128 v[176:179], v138 offset:3072
	s_add_i32 s84, s34, 2
	s_add_u32 s85, s30, 0x80
	s_addc_u32 s35, s31, 0
	s_cmp_eq_u32 s64, s34
	s_cselect_b32 s34, s2, s85
	s_cselect_b32 s35, s3, s35
	s_cselect_b32 s87, s29, s39
	s_cselect_b32 s86, s28, s38
	v_lshl_add_u64 v[184:185], s[30:31], 0, v[140:141]
	s_add_i32 m0, s50, 0xc000
	ds_read_b128 v[180:183], v189
	ds_read_b128 v[190:193], v189 offset:1024
	ds_read_b128 v[194:197], v189 offset:2048
	ds_read_b128 v[198:201], v189 offset:3072
	ds_read_b128 v[202:205], v189 offset:4096
	ds_read_b128 v[206:209], v189 offset:5120
	ds_read_b128 v[210:213], v189 offset:6144
	ds_read_b128 v[214:217], v189 offset:7168
	global_load_lds_dwordx4 v[184:185], off
	v_lshl_add_u64 v[184:185], s[30:31], 0, v[142:143]
	s_add_i32 m0, s50, 0xe000
	s_nop 0
	global_load_lds_dwordx4 v[184:185], off
	s_waitcnt vmcnt(8)
	s_waitcnt lgkmcnt(0)
	s_setprio 1
	s_waitcnt lgkmcnt(0)
	v_mfma_i32_16x16x64_i8 v[126:129], v[148:151], v[180:183], v[126:129]
	v_mfma_i32_16x16x64_i8 v[122:125], v[156:159], v[180:183], v[122:125]
	v_mfma_i32_16x16x64_i8 v[118:121], v[148:151], v[194:197], v[118:121]
	v_mfma_i32_16x16x64_i8 v[114:117], v[156:159], v[194:197], v[114:117]
	s_barrier
	v_mfma_i32_16x16x64_i8 v[106:109], v[148:151], v[202:205], v[106:109]
	v_mfma_i32_16x16x64_i8 v[98:101], v[156:159], v[202:205], v[98:101]
	v_mfma_i32_16x16x64_i8 v[90:93], v[148:151], v[210:213], v[90:93]
	v_mfma_i32_16x16x64_i8 v[82:85], v[156:159], v[210:213], v[82:85]
	v_mfma_i32_16x16x64_i8 v[126:129], v[152:155], v[190:193], v[126:129]
	v_mfma_i32_16x16x64_i8 v[122:125], v[160:163], v[190:193], v[122:125]
	v_mfma_i32_16x16x64_i8 v[118:121], v[152:155], v[198:201], v[118:121]
	v_mfma_i32_16x16x64_i8 v[114:117], v[160:163], v[198:201], v[114:117]
	v_mfma_i32_16x16x64_i8 v[106:109], v[152:155], v[206:209], v[106:109]
	v_mfma_i32_16x16x64_i8 v[98:101], v[160:163], v[206:209], v[98:101]
	v_mfma_i32_16x16x64_i8 v[90:93], v[152:155], v[214:217], v[90:93]
	v_mfma_i32_16x16x64_i8 v[82:85], v[160:163], v[214:217], v[82:85]
	s_setprio 0
	s_setprio 1
	v_mfma_i32_16x16x64_i8 v[110:113], v[164:167], v[180:183], v[110:113]
	v_mfma_i32_16x16x64_i8 v[102:105], v[172:175], v[180:183], v[102:105]
	v_mfma_i32_16x16x64_i8 v[94:97], v[164:167], v[194:197], v[94:97]
	v_mfma_i32_16x16x64_i8 v[86:89], v[172:175], v[194:197], v[86:89]
	v_mfma_i32_16x16x64_i8 v[78:81], v[164:167], v[202:205], v[78:81]
	v_mfma_i32_16x16x64_i8 v[74:77], v[172:175], v[202:205], v[74:77]
	v_mfma_i32_16x16x64_i8 v[70:73], v[164:167], v[210:213], v[70:73]
	v_mfma_i32_16x16x64_i8 v[66:69], v[172:175], v[210:213], v[66:69]
	v_mfma_i32_16x16x64_i8 v[110:113], v[168:171], v[190:193], v[110:113]
	v_mfma_i32_16x16x64_i8 v[102:105], v[176:179], v[190:193], v[102:105]
	v_mfma_i32_16x16x64_i8 v[94:97], v[168:171], v[198:201], v[94:97]
	v_mfma_i32_16x16x64_i8 v[86:89], v[176:179], v[198:201], v[86:89]
	v_mfma_i32_16x16x64_i8 v[78:81], v[168:171], v[206:209], v[78:81]
	v_mfma_i32_16x16x64_i8 v[74:77], v[176:179], v[206:209], v[74:77]
	v_mfma_i32_16x16x64_i8 v[70:73], v[168:171], v[214:217], v[70:73]
	v_mfma_i32_16x16x64_i8 v[66:69], v[176:179], v[214:217], v[66:69]
	s_setprio 0
	s_barrier
	s_add_i32 s85, s80, s47
	v_lshl_add_u64 v[184:185], s[86:87], 0, v[132:133]
	s_mov_b32 m0, s85
	ds_read_b128 v[180:183], v189 offset:16384
	ds_read_b128 v[190:193], v189 offset:17408
	ds_read_b128 v[194:197], v189 offset:18432
	ds_read_b128 v[198:201], v189 offset:19456
	ds_read_b128 v[202:205], v189 offset:20480
	ds_read_b128 v[206:209], v189 offset:21504
	ds_read_b128 v[210:213], v189 offset:22528
	ds_read_b128 v[214:217], v189 offset:23552
	global_load_lds_dwordx4 v[184:185], off
	s_add_i32 m0, s85, 0x2000
	v_lshl_add_u64 v[218:219], s[86:87], 0, v[136:137]
	s_add_u32 s86, s86, s6
	s_addc_u32 s87, s87, s7
	s_add_i32 s85, s81, s47
	global_load_lds_dwordx4 v[218:219], off
	v_lshl_add_u64 v[220:221], s[86:87], 0, v[132:133]
	s_mov_b32 m0, s85
	v_lshl_add_u64 v[222:223], s[86:87], 0, v[136:137]
	global_load_lds_dwordx4 v[220:221], off
	s_add_i32 m0, s85, 0x2000
	v_lshl_add_u64 v[224:225], s[34:35], 0, v[130:131]
	global_load_lds_dwordx4 v[222:223], off
	s_mov_b32 m0, s50
	v_lshl_add_u64 v[226:227], s[34:35], 0, v[134:135]
	global_load_lds_dwordx4 v[224:225], off
	s_mov_b32 m0, s51
	s_nop 0
	global_load_lds_dwordx4 v[226:227], off
	s_waitcnt vmcnt(8)
	s_waitcnt lgkmcnt(0)
	s_setprio 1
	s_waitcnt lgkmcnt(0)
	v_mfma_i32_16x16x64_i8 v[62:65], v[148:151], v[180:183], v[62:65]
	v_mfma_i32_16x16x64_i8 v[58:61], v[156:159], v[180:183], v[58:61]
	v_mfma_i32_16x16x64_i8 v[54:57], v[148:151], v[194:197], v[54:57]
	v_mfma_i32_16x16x64_i8 v[50:53], v[156:159], v[194:197], v[50:53]
	s_barrier
	v_mfma_i32_16x16x64_i8 v[42:45], v[148:151], v[202:205], v[42:45]
	v_mfma_i32_16x16x64_i8 v[34:37], v[156:159], v[202:205], v[34:37]
	v_mfma_i32_16x16x64_i8 v[26:29], v[148:151], v[210:213], v[26:29]
	v_mfma_i32_16x16x64_i8 v[18:21], v[156:159], v[210:213], v[18:21]
	v_mfma_i32_16x16x64_i8 v[62:65], v[152:155], v[190:193], v[62:65]
	v_mfma_i32_16x16x64_i8 v[58:61], v[160:163], v[190:193], v[58:61]
	v_mfma_i32_16x16x64_i8 v[54:57], v[152:155], v[198:201], v[54:57]
	v_mfma_i32_16x16x64_i8 v[50:53], v[160:163], v[198:201], v[50:53]
	v_mfma_i32_16x16x64_i8 v[42:45], v[152:155], v[206:209], v[42:45]
	v_mfma_i32_16x16x64_i8 v[34:37], v[160:163], v[206:209], v[34:37]
	v_mfma_i32_16x16x64_i8 v[26:29], v[152:155], v[214:217], v[26:29]
	v_mfma_i32_16x16x64_i8 v[18:21], v[160:163], v[214:217], v[18:21]
	s_setprio 0
	s_setprio 1
	v_mfma_i32_16x16x64_i8 v[46:49], v[164:167], v[180:183], v[46:49]
	v_mfma_i32_16x16x64_i8 v[38:41], v[172:175], v[180:183], v[38:41]
	v_mfma_i32_16x16x64_i8 v[30:33], v[164:167], v[194:197], v[30:33]
	v_mfma_i32_16x16x64_i8 v[22:25], v[172:175], v[194:197], v[22:25]
	v_mfma_i32_16x16x64_i8 v[14:17], v[164:167], v[202:205], v[14:17]
	v_mfma_i32_16x16x64_i8 v[10:13], v[172:175], v[202:205], v[10:13]
	v_mfma_i32_16x16x64_i8 v[6:9], v[164:167], v[210:213], v[6:9]
	v_mfma_i32_16x16x64_i8 v[2:5], v[172:175], v[210:213], v[2:5]
	v_mfma_i32_16x16x64_i8 v[46:49], v[168:171], v[190:193], v[46:49]
	v_mfma_i32_16x16x64_i8 v[38:41], v[176:179], v[190:193], v[38:41]
	v_mfma_i32_16x16x64_i8 v[30:33], v[168:171], v[198:201], v[30:33]
	v_mfma_i32_16x16x64_i8 v[22:25], v[176:179], v[198:201], v[22:25]
	v_mfma_i32_16x16x64_i8 v[14:17], v[168:171], v[206:209], v[14:17]
	v_mfma_i32_16x16x64_i8 v[10:13], v[176:179], v[206:209], v[10:13]
	v_mfma_i32_16x16x64_i8 v[6:9], v[168:171], v[214:217], v[6:9]
	v_mfma_i32_16x16x64_i8 v[2:5], v[176:179], v[214:217], v[2:5]
	s_setprio 0
	s_barrier
	s_add_i32 s85, 0, 0x18000
	v_add_u32_e32 v138, s85, v188
	s_add_i32 s86, 0, 0x1c000
	ds_read_b128 v[148:151], v138
	ds_read_b128 v[152:155], v138 offset:1024
	ds_read_b128 v[156:159], v138 offset:2048
	ds_read_b128 v[160:163], v138 offset:3072
	v_add_u32_e32 v138, s86, v188
	ds_read_b128 v[164:167], v138
	ds_read_b128 v[168:171], v138 offset:1024
	ds_read_b128 v[172:175], v138 offset:2048
	ds_read_b128 v[176:179], v138 offset:3072
	s_add_u32 s34, s34, s6
	s_addc_u32 s35, s35, s7
	s_mov_b32 m0, s54
	v_lshl_add_u64 v[228:229], s[34:35], 0, v[130:131]
	ds_read_b128 v[180:183], v189 offset:32768
	ds_read_b128 v[190:193], v189 offset:33792
	ds_read_b128 v[194:197], v189 offset:34816
	ds_read_b128 v[198:201], v189 offset:35840
	ds_read_b128 v[202:205], v189 offset:36864
	ds_read_b128 v[206:209], v189 offset:37888
	ds_read_b128 v[210:213], v189 offset:38912
	ds_read_b128 v[214:217], v189 offset:39936
	global_load_lds_dwordx4 v[228:229], off
	v_lshl_add_u64 v[228:229], s[34:35], 0, v[134:135]
	s_mov_b32 m0, s55
	s_nop 0
	global_load_lds_dwordx4 v[228:229], off
	s_waitcnt vmcnt(8)
	s_waitcnt lgkmcnt(0)
	s_setprio 1
	s_waitcnt lgkmcnt(0)
	v_mfma_i32_16x16x64_i8 v[126:129], v[148:151], v[180:183], v[126:129]
	v_mfma_i32_16x16x64_i8 v[122:125], v[156:159], v[180:183], v[122:125]
	v_mfma_i32_16x16x64_i8 v[118:121], v[148:151], v[194:197], v[118:121]
	v_mfma_i32_16x16x64_i8 v[114:117], v[156:159], v[194:197], v[114:117]
	s_barrier
	v_mfma_i32_16x16x64_i8 v[106:109], v[148:151], v[202:205], v[106:109]
	v_mfma_i32_16x16x64_i8 v[98:101], v[156:159], v[202:205], v[98:101]
	v_mfma_i32_16x16x64_i8 v[90:93], v[148:151], v[210:213], v[90:93]
	v_mfma_i32_16x16x64_i8 v[82:85], v[156:159], v[210:213], v[82:85]
	v_mfma_i32_16x16x64_i8 v[126:129], v[152:155], v[190:193], v[126:129]
	v_mfma_i32_16x16x64_i8 v[122:125], v[160:163], v[190:193], v[122:125]
	v_mfma_i32_16x16x64_i8 v[118:121], v[152:155], v[198:201], v[118:121]
	v_mfma_i32_16x16x64_i8 v[114:117], v[160:163], v[198:201], v[114:117]
	v_mfma_i32_16x16x64_i8 v[106:109], v[152:155], v[206:209], v[106:109]
	v_mfma_i32_16x16x64_i8 v[98:101], v[160:163], v[206:209], v[98:101]
	v_mfma_i32_16x16x64_i8 v[90:93], v[152:155], v[214:217], v[90:93]
	v_mfma_i32_16x16x64_i8 v[82:85], v[160:163], v[214:217], v[82:85]
	s_setprio 0
	s_setprio 1
	v_mfma_i32_16x16x64_i8 v[110:113], v[164:167], v[180:183], v[110:113]
	v_mfma_i32_16x16x64_i8 v[102:105], v[172:175], v[180:183], v[102:105]
	v_mfma_i32_16x16x64_i8 v[94:97], v[164:167], v[194:197], v[94:97]
	v_mfma_i32_16x16x64_i8 v[86:89], v[172:175], v[194:197], v[86:89]
	v_mfma_i32_16x16x64_i8 v[78:81], v[164:167], v[202:205], v[78:81]
	v_mfma_i32_16x16x64_i8 v[74:77], v[172:175], v[202:205], v[74:77]
	v_mfma_i32_16x16x64_i8 v[70:73], v[164:167], v[210:213], v[70:73]
	v_mfma_i32_16x16x64_i8 v[66:69], v[172:175], v[210:213], v[66:69]
	v_mfma_i32_16x16x64_i8 v[110:113], v[168:171], v[190:193], v[110:113]
	v_mfma_i32_16x16x64_i8 v[102:105], v[176:179], v[190:193], v[102:105]
	v_mfma_i32_16x16x64_i8 v[94:97], v[168:171], v[198:201], v[94:97]
	v_mfma_i32_16x16x64_i8 v[86:89], v[176:179], v[198:201], v[86:89]
	v_mfma_i32_16x16x64_i8 v[78:81], v[168:171], v[206:209], v[78:81]
	v_mfma_i32_16x16x64_i8 v[74:77], v[176:179], v[206:209], v[74:77]
	v_mfma_i32_16x16x64_i8 v[70:73], v[168:171], v[214:217], v[70:73]
	v_mfma_i32_16x16x64_i8 v[66:69], v[176:179], v[214:217], v[66:69]
	s_setprio 0
	s_barrier
	s_add_i32 s34, s85, s47
	v_lshl_add_u64 v[184:185], v[184:185], 0, s[22:23]
	s_mov_b32 m0, s34
	ds_read_b128 v[180:183], v189 offset:49152
	ds_read_b128 v[190:193], v189 offset:50176
	ds_read_b128 v[194:197], v189 offset:51200
	ds_read_b128 v[198:201], v189 offset:52224
	ds_read_b128 v[202:205], v189 offset:53248
	ds_read_b128 v[206:209], v189 offset:54272
	ds_read_b128 v[210:213], v189 offset:55296
	ds_read_b128 v[214:217], v189 offset:56320
	global_load_lds_dwordx4 v[184:185], off
	v_lshl_add_u64 v[184:185], v[218:219], 0, s[22:23]
	s_add_i32 m0, s34, 0x2000
	s_add_i32 s34, s86, s47
	global_load_lds_dwordx4 v[184:185], off
	v_lshl_add_u64 v[184:185], v[220:221], 0, s[22:23]
	s_mov_b32 m0, s34
	s_nop 0
	global_load_lds_dwordx4 v[184:185], off
	v_lshl_add_u64 v[184:185], v[222:223], 0, s[22:23]
	s_add_i32 m0, s34, 0x2000
	s_nop 0
	global_load_lds_dwordx4 v[184:185], off
	v_lshl_add_u64 v[184:185], v[224:225], 0, s[22:23]
	s_mov_b32 m0, s59
	s_nop 0
	global_load_lds_dwordx4 v[184:185], off
	v_lshl_add_u64 v[184:185], v[226:227], 0, s[22:23]
	s_mov_b32 m0, s60
	s_nop 0
	global_load_lds_dwordx4 v[184:185], off
	s_waitcnt vmcnt(8)
	s_waitcnt lgkmcnt(0)
	s_setprio 1
	s_waitcnt lgkmcnt(0)
	v_mfma_i32_16x16x64_i8 v[62:65], v[148:151], v[180:183], v[62:65]
	v_mfma_i32_16x16x64_i8 v[58:61], v[156:159], v[180:183], v[58:61]
	v_mfma_i32_16x16x64_i8 v[54:57], v[148:151], v[194:197], v[54:57]
	v_mfma_i32_16x16x64_i8 v[50:53], v[156:159], v[194:197], v[50:53]
	s_barrier
	v_mfma_i32_16x16x64_i8 v[42:45], v[148:151], v[202:205], v[42:45]
	v_mfma_i32_16x16x64_i8 v[34:37], v[156:159], v[202:205], v[34:37]
	v_mfma_i32_16x16x64_i8 v[26:29], v[148:151], v[210:213], v[26:29]
	v_mfma_i32_16x16x64_i8 v[18:21], v[156:159], v[210:213], v[18:21]
	v_mfma_i32_16x16x64_i8 v[62:65], v[152:155], v[190:193], v[62:65]
	v_mfma_i32_16x16x64_i8 v[58:61], v[160:163], v[190:193], v[58:61]
	v_mfma_i32_16x16x64_i8 v[54:57], v[152:155], v[198:201], v[54:57]
	v_mfma_i32_16x16x64_i8 v[50:53], v[160:163], v[198:201], v[50:53]
	v_mfma_i32_16x16x64_i8 v[42:45], v[152:155], v[206:209], v[42:45]
	v_mfma_i32_16x16x64_i8 v[34:37], v[160:163], v[206:209], v[34:37]
	v_mfma_i32_16x16x64_i8 v[26:29], v[152:155], v[214:217], v[26:29]
	v_mfma_i32_16x16x64_i8 v[18:21], v[160:163], v[214:217], v[18:21]
	s_setprio 0
	s_setprio 1
	v_mfma_i32_16x16x64_i8 v[46:49], v[164:167], v[180:183], v[46:49]
	v_mfma_i32_16x16x64_i8 v[38:41], v[172:175], v[180:183], v[38:41]
	v_mfma_i32_16x16x64_i8 v[30:33], v[164:167], v[194:197], v[30:33]
	v_mfma_i32_16x16x64_i8 v[22:25], v[172:175], v[194:197], v[22:25]
	v_mfma_i32_16x16x64_i8 v[14:17], v[164:167], v[202:205], v[14:17]
	v_mfma_i32_16x16x64_i8 v[10:13], v[172:175], v[202:205], v[10:13]
	v_mfma_i32_16x16x64_i8 v[6:9], v[164:167], v[210:213], v[6:9]
	v_mfma_i32_16x16x64_i8 v[2:5], v[172:175], v[210:213], v[2:5]
	v_mfma_i32_16x16x64_i8 v[46:49], v[168:171], v[190:193], v[46:49]
	v_mfma_i32_16x16x64_i8 v[38:41], v[176:179], v[190:193], v[38:41]
	v_mfma_i32_16x16x64_i8 v[30:33], v[168:171], v[198:201], v[30:33]
	v_mfma_i32_16x16x64_i8 v[22:25], v[176:179], v[198:201], v[22:25]
	v_mfma_i32_16x16x64_i8 v[14:17], v[168:171], v[206:209], v[14:17]
	v_mfma_i32_16x16x64_i8 v[10:13], v[176:179], v[206:209], v[10:13]
	v_mfma_i32_16x16x64_i8 v[6:9], v[168:171], v[214:217], v[6:9]
	v_mfma_i32_16x16x64_i8 v[2:5], v[176:179], v[214:217], v[2:5]
	s_setprio 0
	s_barrier
	s_add_u32 s30, s30, 0x100
	s_addc_u32 s31, s31, 0
	s_add_u32 s38, s38, 0x100
	s_addc_u32 s39, s39, 0
	s_cmp_ge_i32 s84, s61
	s_mov_b32 s34, s84
	s_cbranch_scc0 .LBB0_1087
	v_cvt_f32_i32_e32 v172, v126
	v_cvt_f32_i32_e32 v173, v127
	v_cvt_f32_i32_e32 v170, v128
	v_cvt_f32_i32_e32 v171, v129
	v_cvt_f32_i32_e32 v174, v122
	v_cvt_f32_i32_e32 v175, v123
	v_cvt_f32_i32_e32 v176, v124
	v_cvt_f32_i32_e32 v177, v125
	v_cvt_f32_i32_e32 v180, v110
	v_cvt_f32_i32_e32 v181, v111
	v_cvt_f32_i32_e32 v182, v112
	v_cvt_f32_i32_e32 v183, v113
	v_cvt_f32_i32_e32 v178, v102
	v_cvt_f32_i32_e32 v179, v103
	v_cvt_f32_i32_e32 v184, v104
	v_cvt_f32_i32_e32 v185, v105
	v_cvt_f32_i32_e32 v152, v118
	v_cvt_f32_i32_e32 v153, v119
	v_cvt_f32_i32_e32 v154, v120
	v_cvt_f32_i32_e32 v155, v121
	v_cvt_f32_i32_e32 v156, v114
	v_cvt_f32_i32_e32 v157, v115
	v_cvt_f32_i32_e32 v158, v116
	v_cvt_f32_i32_e32 v159, v117
	v_cvt_f32_i32_e32 v160, v94
	v_cvt_f32_i32_e32 v161, v95
	v_cvt_f32_i32_e32 v162, v96
	v_cvt_f32_i32_e32 v163, v97
	v_cvt_f32_i32_e32 v164, v86
	v_cvt_f32_i32_e32 v165, v87
	v_cvt_f32_i32_e32 v166, v88
	v_cvt_f32_i32_e32 v167, v89
	v_cvt_f32_i32_e32 v118, v106
	v_cvt_f32_i32_e32 v119, v107
	v_cvt_f32_i32_e32 v120, v108
	v_cvt_f32_i32_e32 v121, v109
	v_cvt_f32_i32_e32 v122, v98
	v_cvt_f32_i32_e32 v123, v99
	v_cvt_f32_i32_e32 v124, v100
	v_cvt_f32_i32_e32 v125, v101
	v_cvt_f32_i32_e32 v126, v78
	v_cvt_f32_i32_e32 v127, v79
	v_cvt_f32_i32_e32 v128, v80
	v_cvt_f32_i32_e32 v129, v81
	v_cvt_f32_i32_e32 v148, v74
	v_cvt_f32_i32_e32 v149, v75
	v_cvt_f32_i32_e32 v150, v76
	v_cvt_f32_i32_e32 v151, v77
	v_cvt_f32_i32_e32 v102, v90
	v_cvt_f32_i32_e32 v103, v91
	v_cvt_f32_i32_e32 v104, v92
	v_cvt_f32_i32_e32 v105, v93
	v_cvt_f32_i32_e32 v106, v82
	v_cvt_f32_i32_e32 v107, v83
	v_cvt_f32_i32_e32 v108, v84
	v_cvt_f32_i32_e32 v109, v85
	v_cvt_f32_i32_e32 v110, v70
	v_cvt_f32_i32_e32 v111, v71
	v_cvt_f32_i32_e32 v112, v72
	v_cvt_f32_i32_e32 v113, v73
	v_cvt_f32_i32_e32 v114, v66
	v_cvt_f32_i32_e32 v115, v67
	v_cvt_f32_i32_e32 v116, v68
	v_cvt_f32_i32_e32 v117, v69
	v_cvt_f32_i32_e32 v82, v62
	v_cvt_f32_i32_e32 v83, v63
	v_cvt_f32_i32_e32 v84, v64
	v_cvt_f32_i32_e32 v85, v65
	v_cvt_f32_i32_e32 v86, v58
	v_cvt_f32_i32_e32 v87, v59
	v_cvt_f32_i32_e32 v88, v60
	v_cvt_f32_i32_e32 v89, v61
	v_cvt_f32_i32_e32 v92, v46
	v_cvt_f32_i32_e32 v93, v47
	v_cvt_f32_i32_e32 v94, v48
	v_cvt_f32_i32_e32 v95, v49
	v_cvt_f32_i32_e32 v96, v38
	v_cvt_f32_i32_e32 v97, v39
	v_cvt_f32_i32_e32 v98, v40
	v_cvt_f32_i32_e32 v99, v41
	v_cvt_f32_i32_e32 v66, v54
	v_cvt_f32_i32_e32 v67, v55
	v_cvt_f32_i32_e32 v68, v56
	v_cvt_f32_i32_e32 v69, v57
	v_cvt_f32_i32_e32 v70, v50
	v_cvt_f32_i32_e32 v71, v51
	v_cvt_f32_i32_e32 v72, v52
	v_cvt_f32_i32_e32 v73, v53
	v_cvt_f32_i32_e32 v74, v30
	v_cvt_f32_i32_e32 v75, v31
	v_cvt_f32_i32_e32 v76, v32
	v_cvt_f32_i32_e32 v77, v33
	v_cvt_f32_i32_e32 v78, v22
	v_cvt_f32_i32_e32 v79, v23
	v_cvt_f32_i32_e32 v80, v24
	v_cvt_f32_i32_e32 v81, v25
	v_cvt_f32_i32_e32 v50, v42
	v_cvt_f32_i32_e32 v51, v43
	v_cvt_f32_i32_e32 v52, v44
	v_cvt_f32_i32_e32 v53, v45
	v_cvt_f32_i32_e32 v54, v34
	v_cvt_f32_i32_e32 v55, v35
	v_cvt_f32_i32_e32 v56, v36
	v_cvt_f32_i32_e32 v57, v37
	v_cvt_f32_i32_e32 v58, v14
	v_cvt_f32_i32_e32 v59, v15
	v_cvt_f32_i32_e32 v60, v16
	v_cvt_f32_i32_e32 v61, v17
	v_cvt_f32_i32_e32 v62, v10
	v_cvt_f32_i32_e32 v63, v11
	v_cvt_f32_i32_e32 v64, v12
	v_cvt_f32_i32_e32 v65, v13
	v_cvt_f32_i32_e32 v34, v26
	v_cvt_f32_i32_e32 v35, v27
	v_cvt_f32_i32_e32 v36, v28
	v_cvt_f32_i32_e32 v37, v29
	v_cvt_f32_i32_e32 v38, v18
	v_cvt_f32_i32_e32 v39, v19
	v_cvt_f32_i32_e32 v40, v20
	v_cvt_f32_i32_e32 v41, v21
	v_cvt_f32_i32_e32 v42, v6
	v_cvt_f32_i32_e32 v43, v7
	v_cvt_f32_i32_e32 v44, v8
	v_cvt_f32_i32_e32 v45, v9
	v_cvt_f32_i32_e32 v46, v2
	v_cvt_f32_i32_e32 v47, v3
	v_cvt_f32_i32_e32 v48, v4
	v_cvt_f32_i32_e32 v49, v5

.LBB0_1170:
	s_waitcnt lgkmcnt(0)
	ds_read_b128 v[114:117], v209
	ds_read_b128 v[118:121], v209 offset:1024
	ds_read_b128 v[122:125], v209 offset:2048
	ds_read_b128 v[126:129], v209 offset:3072
	ds_read_b128 v[146:149], v210
	ds_read_b128 v[150:153], v210 offset:1024
	ds_read_b128 v[154:157], v210 offset:2048
	ds_read_b128 v[158:161], v210 offset:3072
	s_add_i32 s92, s42, 2
	s_add_u32 s43, s38, 0x4000
	s_addc_u32 s44, s39, 0
	s_cmp_eq_u32 s81, s42
	s_cselect_b32 s45, s5, s44
	s_cselect_b32 s44, s4, s43
	s_cselect_b32 s94, s36, s90
	s_cselect_b32 s95, s37, s91
	s_add_u32 s42, s44, 0x8000
	s_addc_u32 s43, s45, 0
	v_lshl_add_u64 v[218:219], s[38:39], 0, v[170:171]
	s_add_i32 m0, s55, 0xc000
	ds_read_b128 v[178:181], v211
	ds_read_b128 v[182:185], v211 offset:1024
	ds_read_b128 v[186:189], v211 offset:2048
	ds_read_b128 v[190:193], v211 offset:3072
	ds_read_b128 v[194:197], v211 offset:4096
	ds_read_b128 v[198:201], v211 offset:5120
	ds_read_b128 v[202:205], v211 offset:6144
	ds_read_b128 v[214:217], v211 offset:7168
	global_load_lds_dwordx4 v[218:219], off
	v_lshl_add_u64 v[218:219], s[38:39], 0, v[172:173]
	s_add_i32 m0, s55, 0xe000
	s_nop 0
	global_load_lds_dwordx4 v[218:219], off
	s_waitcnt vmcnt(8)
	s_waitcnt lgkmcnt(0)
	s_setprio 1
	s_waitcnt lgkmcnt(0)
	v_mfma_f32_16x16x32_bf16 v[142:145], v[114:117], v[178:181], v[142:145]
	v_mfma_f32_16x16x32_bf16 v[138:141], v[122:125], v[178:181], v[138:141]
	v_mfma_f32_16x16x32_bf16 v[110:113], v[114:117], v[186:189], v[110:113]
	v_mfma_f32_16x16x32_bf16 v[106:109], v[122:125], v[186:189], v[106:109]
	s_barrier
	v_mfma_f32_16x16x32_bf16 v[94:97], v[114:117], v[194:197], v[94:97]
	v_mfma_f32_16x16x32_bf16 v[90:93], v[122:125], v[194:197], v[90:93]
	v_mfma_f32_16x16x32_bf16 v[78:81], v[114:117], v[202:205], v[78:81]
	v_mfma_f32_16x16x32_bf16 v[74:77], v[122:125], v[202:205], v[74:77]
	v_mfma_f32_16x16x32_bf16 v[142:145], v[118:121], v[182:185], v[142:145]
	v_mfma_f32_16x16x32_bf16 v[138:141], v[126:129], v[182:185], v[138:141]
	v_mfma_f32_16x16x32_bf16 v[110:113], v[118:121], v[190:193], v[110:113]
	v_mfma_f32_16x16x32_bf16 v[106:109], v[126:129], v[190:193], v[106:109]
	v_mfma_f32_16x16x32_bf16 v[94:97], v[118:121], v[198:201], v[94:97]
	v_mfma_f32_16x16x32_bf16 v[90:93], v[126:129], v[198:201], v[90:93]
	v_mfma_f32_16x16x32_bf16 v[78:81], v[118:121], v[214:217], v[78:81]
	v_mfma_f32_16x16x32_bf16 v[74:77], v[126:129], v[214:217], v[74:77]
	s_setprio 0
	s_setprio 1
	v_mfma_f32_16x16x32_bf16 v[134:137], v[146:149], v[178:181], v[134:137]
	v_mfma_f32_16x16x32_bf16 v[130:133], v[154:157], v[178:181], v[130:133]
	v_mfma_f32_16x16x32_bf16 v[102:105], v[146:149], v[186:189], v[102:105]
	v_mfma_f32_16x16x32_bf16 v[98:101], v[154:157], v[186:189], v[98:101]
	v_mfma_f32_16x16x32_bf16 v[86:89], v[146:149], v[194:197], v[86:89]
	v_mfma_f32_16x16x32_bf16 v[82:85], v[154:157], v[194:197], v[82:85]
	v_mfma_f32_16x16x32_bf16 v[70:73], v[146:149], v[202:205], v[70:73]
	v_mfma_f32_16x16x32_bf16 v[66:69], v[154:157], v[202:205], v[66:69]
	v_mfma_f32_16x16x32_bf16 v[134:137], v[150:153], v[182:185], v[134:137]
	v_mfma_f32_16x16x32_bf16 v[130:133], v[158:161], v[182:185], v[130:133]
	v_mfma_f32_16x16x32_bf16 v[102:105], v[150:153], v[190:193], v[102:105]
	v_mfma_f32_16x16x32_bf16 v[98:101], v[158:161], v[190:193], v[98:101]
	v_mfma_f32_16x16x32_bf16 v[86:89], v[150:153], v[198:201], v[86:89]
	v_mfma_f32_16x16x32_bf16 v[82:85], v[158:161], v[198:201], v[82:85]
	v_mfma_f32_16x16x32_bf16 v[70:73], v[150:153], v[214:217], v[70:73]
	v_mfma_f32_16x16x32_bf16 v[66:69], v[158:161], v[214:217], v[66:69]
	s_setprio 0
	s_barrier
	s_add_i32 s93, s84, s54
	v_lshl_add_u64 v[218:219], s[94:95], 0, v[164:165]
	s_mov_b32 m0, s93
	ds_read_b128 v[178:181], v211 offset:16384
	ds_read_b128 v[182:185], v211 offset:17408
	ds_read_b128 v[186:189], v211 offset:18432
	ds_read_b128 v[190:193], v211 offset:19456
	ds_read_b128 v[194:197], v211 offset:20480
	ds_read_b128 v[198:201], v211 offset:21504
	ds_read_b128 v[202:205], v211 offset:22528
	ds_read_b128 v[214:217], v211 offset:23552
	global_load_lds_dwordx4 v[218:219], off
	s_add_i32 m0, s93, 0x2000
	v_lshl_add_u64 v[220:221], s[94:95], 0, v[168:169]
	s_add_u32 s94, s94, s8
	s_addc_u32 s95, s95, s9
	s_add_i32 s93, s85, s54
	global_load_lds_dwordx4 v[220:221], off
	v_lshl_add_u64 v[222:223], s[94:95], 0, v[164:165]
	s_mov_b32 m0, s93
	v_lshl_add_u64 v[224:225], s[94:95], 0, v[168:169]
	global_load_lds_dwordx4 v[222:223], off
	s_add_i32 m0, s93, 0x2000
	v_lshl_add_u64 v[226:227], s[44:45], 0, v[162:163]
	global_load_lds_dwordx4 v[224:225], off
	s_mov_b32 m0, s55
	s_nop 0
	global_load_lds_dwordx4 v[226:227], off
	v_lshl_add_u64 v[226:227], s[44:45], 0, v[166:167]
	s_mov_b32 m0, s56
	s_nop 0
	global_load_lds_dwordx4 v[226:227], off
	s_waitcnt vmcnt(8)
	s_waitcnt lgkmcnt(0)
	s_setprio 1
	s_waitcnt lgkmcnt(0)
	v_mfma_f32_16x16x32_bf16 v[62:65], v[114:117], v[178:181], v[62:65]
	v_mfma_f32_16x16x32_bf16 v[58:61], v[122:125], v[178:181], v[58:61]
	v_mfma_f32_16x16x32_bf16 v[46:49], v[114:117], v[186:189], v[46:49]
	v_mfma_f32_16x16x32_bf16 v[42:45], v[122:125], v[186:189], v[42:45]
	s_barrier
	v_mfma_f32_16x16x32_bf16 v[30:33], v[114:117], v[194:197], v[30:33]
	v_mfma_f32_16x16x32_bf16 v[26:29], v[122:125], v[194:197], v[26:29]
	v_mfma_f32_16x16x32_bf16 v[14:17], v[114:117], v[202:205], v[14:17]
	v_mfma_f32_16x16x32_bf16 v[10:13], v[122:125], v[202:205], v[10:13]
	v_mfma_f32_16x16x32_bf16 v[62:65], v[118:121], v[182:185], v[62:65]
	v_mfma_f32_16x16x32_bf16 v[58:61], v[126:129], v[182:185], v[58:61]
	v_mfma_f32_16x16x32_bf16 v[46:49], v[118:121], v[190:193], v[46:49]
	v_mfma_f32_16x16x32_bf16 v[42:45], v[126:129], v[190:193], v[42:45]
	v_mfma_f32_16x16x32_bf16 v[30:33], v[118:121], v[198:201], v[30:33]
	v_mfma_f32_16x16x32_bf16 v[26:29], v[126:129], v[198:201], v[26:29]
	v_mfma_f32_16x16x32_bf16 v[14:17], v[118:121], v[214:217], v[14:17]
	v_mfma_f32_16x16x32_bf16 v[10:13], v[126:129], v[214:217], v[10:13]
	s_setprio 0
	s_setprio 1
	v_mfma_f32_16x16x32_bf16 v[54:57], v[146:149], v[178:181], v[54:57]
	v_mfma_f32_16x16x32_bf16 v[50:53], v[154:157], v[178:181], v[50:53]
	v_mfma_f32_16x16x32_bf16 v[38:41], v[146:149], v[186:189], v[38:41]
	v_mfma_f32_16x16x32_bf16 v[34:37], v[154:157], v[186:189], v[34:37]
	v_mfma_f32_16x16x32_bf16 v[22:25], v[146:149], v[194:197], v[22:25]
	v_mfma_f32_16x16x32_bf16 v[18:21], v[154:157], v[194:197], v[18:21]
	v_mfma_f32_16x16x32_bf16 v[6:9], v[146:149], v[202:205], v[6:9]
	v_mfma_f32_16x16x32_bf16 v[2:5], v[154:157], v[202:205], v[2:5]
	v_mfma_f32_16x16x32_bf16 v[54:57], v[150:153], v[182:185], v[54:57]
	v_mfma_f32_16x16x32_bf16 v[50:53], v[158:161], v[182:185], v[50:53]
	v_mfma_f32_16x16x32_bf16 v[38:41], v[150:153], v[190:193], v[38:41]
	v_mfma_f32_16x16x32_bf16 v[34:37], v[158:161], v[190:193], v[34:37]
	v_mfma_f32_16x16x32_bf16 v[22:25], v[150:153], v[198:201], v[22:25]
	v_mfma_f32_16x16x32_bf16 v[18:21], v[158:161], v[198:201], v[18:21]
	v_mfma_f32_16x16x32_bf16 v[6:9], v[150:153], v[214:217], v[6:9]
	v_mfma_f32_16x16x32_bf16 v[2:5], v[158:161], v[214:217], v[2:5]
	s_setprio 0
	s_barrier
	s_add_i32 s93, 0, 0x18000
	s_add_i32 s94, 0, 0x1c000
	v_add_u32_e32 v126, s93, v207
	v_add_u32_e32 v158, s94, v207
	ds_read_b128 v[114:117], v126
	ds_read_b128 v[118:121], v126 offset:1024
	ds_read_b128 v[122:125], v126 offset:2048
	ds_read_b128 v[126:129], v126 offset:3072
	ds_read_b128 v[146:149], v158
	ds_read_b128 v[150:153], v158 offset:1024
	ds_read_b128 v[154:157], v158 offset:2048
	ds_read_b128 v[158:161], v158 offset:3072
	s_add_u32 s44, s44, 0x4000
	s_addc_u32 s45, s45, 0
	s_mov_b32 m0, s57
	v_lshl_add_u64 v[226:227], s[44:45], 0, v[162:163]
	ds_read_b128 v[178:181], v211 offset:32768
	ds_read_b128 v[182:185], v211 offset:33792
	ds_read_b128 v[186:189], v211 offset:34816
	ds_read_b128 v[190:193], v211 offset:35840
	ds_read_b128 v[194:197], v211 offset:36864
	ds_read_b128 v[198:201], v211 offset:37888
	ds_read_b128 v[202:205], v211 offset:38912
	ds_read_b128 v[214:217], v211 offset:39936
	global_load_lds_dwordx4 v[226:227], off
	v_lshl_add_u64 v[226:227], s[44:45], 0, v[166:167]
	s_mov_b32 m0, s58
	s_nop 0
	global_load_lds_dwordx4 v[226:227], off
	s_waitcnt vmcnt(8)
	s_waitcnt lgkmcnt(0)
	s_setprio 1
	s_waitcnt lgkmcnt(0)
	v_mfma_f32_16x16x32_bf16 v[142:145], v[114:117], v[178:181], v[142:145]
	v_mfma_f32_16x16x32_bf16 v[138:141], v[122:125], v[178:181], v[138:141]
	v_mfma_f32_16x16x32_bf16 v[110:113], v[114:117], v[186:189], v[110:113]
	v_mfma_f32_16x16x32_bf16 v[106:109], v[122:125], v[186:189], v[106:109]
	s_barrier
	v_mfma_f32_16x16x32_bf16 v[94:97], v[114:117], v[194:197], v[94:97]
	v_mfma_f32_16x16x32_bf16 v[90:93], v[122:125], v[194:197], v[90:93]
	v_mfma_f32_16x16x32_bf16 v[78:81], v[114:117], v[202:205], v[78:81]
	v_mfma_f32_16x16x32_bf16 v[74:77], v[122:125], v[202:205], v[74:77]
	v_mfma_f32_16x16x32_bf16 v[142:145], v[118:121], v[182:185], v[142:145]
	v_mfma_f32_16x16x32_bf16 v[138:141], v[126:129], v[182:185], v[138:141]
	v_mfma_f32_16x16x32_bf16 v[110:113], v[118:121], v[190:193], v[110:113]
	v_mfma_f32_16x16x32_bf16 v[106:109], v[126:129], v[190:193], v[106:109]
	v_mfma_f32_16x16x32_bf16 v[94:97], v[118:121], v[198:201], v[94:97]
	v_mfma_f32_16x16x32_bf16 v[90:93], v[126:129], v[198:201], v[90:93]
	v_mfma_f32_16x16x32_bf16 v[78:81], v[118:121], v[214:217], v[78:81]
	v_mfma_f32_16x16x32_bf16 v[74:77], v[126:129], v[214:217], v[74:77]
	s_setprio 0
	s_setprio 1
	v_mfma_f32_16x16x32_bf16 v[134:137], v[146:149], v[178:181], v[134:137]
	v_mfma_f32_16x16x32_bf16 v[130:133], v[154:157], v[178:181], v[130:133]
	v_mfma_f32_16x16x32_bf16 v[102:105], v[146:149], v[186:189], v[102:105]
	v_mfma_f32_16x16x32_bf16 v[98:101], v[154:157], v[186:189], v[98:101]
	v_mfma_f32_16x16x32_bf16 v[86:89], v[146:149], v[194:197], v[86:89]
	v_mfma_f32_16x16x32_bf16 v[82:85], v[154:157], v[194:197], v[82:85]
	v_mfma_f32_16x16x32_bf16 v[70:73], v[146:149], v[202:205], v[70:73]
	v_mfma_f32_16x16x32_bf16 v[66:69], v[154:157], v[202:205], v[66:69]
	v_mfma_f32_16x16x32_bf16 v[134:137], v[150:153], v[182:185], v[134:137]
	v_mfma_f32_16x16x32_bf16 v[130:133], v[158:161], v[182:185], v[130:133]
	v_mfma_f32_16x16x32_bf16 v[102:105], v[150:153], v[190:193], v[102:105]
	v_mfma_f32_16x16x32_bf16 v[98:101], v[158:161], v[190:193], v[98:101]
	v_mfma_f32_16x16x32_bf16 v[86:89], v[150:153], v[198:201], v[86:89]
	v_mfma_f32_16x16x32_bf16 v[82:85], v[158:161], v[198:201], v[82:85]
	v_mfma_f32_16x16x32_bf16 v[70:73], v[150:153], v[214:217], v[70:73]
	v_mfma_f32_16x16x32_bf16 v[66:69], v[158:161], v[214:217], v[66:69]
	s_setprio 0
	s_barrier
	s_add_i32 s44, s93, s54
	v_lshl_add_u64 v[218:219], v[218:219], 0, s[28:29]
	s_mov_b32 m0, s44
	ds_read_b128 v[178:181], v211 offset:49152
	ds_read_b128 v[182:185], v211 offset:50176
	ds_read_b128 v[186:189], v211 offset:51200
	ds_read_b128 v[190:193], v211 offset:52224
	ds_read_b128 v[194:197], v211 offset:53248
	ds_read_b128 v[198:201], v211 offset:54272
	ds_read_b128 v[202:205], v211 offset:55296
	ds_read_b128 v[214:217], v211 offset:56320
	global_load_lds_dwordx4 v[218:219], off
	v_lshl_add_u64 v[218:219], v[220:221], 0, s[28:29]
	s_add_i32 m0, s44, 0x2000
	s_add_i32 s44, s94, s54
	global_load_lds_dwordx4 v[218:219], off
	v_lshl_add_u64 v[218:219], v[222:223], 0, s[28:29]
	s_mov_b32 m0, s44
	s_nop 0
	global_load_lds_dwordx4 v[218:219], off
	v_lshl_add_u64 v[218:219], v[224:225], 0, s[28:29]
	s_add_i32 m0, s44, 0x2000
	s_nop 0
	global_load_lds_dwordx4 v[218:219], off
	v_lshl_add_u64 v[218:219], s[42:43], 0, v[162:163]
	s_mov_b32 m0, s65
	s_nop 0
	global_load_lds_dwordx4 v[218:219], off
	v_lshl_add_u64 v[218:219], s[42:43], 0, v[166:167]
	s_mov_b32 m0, s80
	s_nop 0
	global_load_lds_dwordx4 v[218:219], off
	s_waitcnt vmcnt(8)
	s_waitcnt lgkmcnt(0)
	s_setprio 1
	s_waitcnt lgkmcnt(0)
	v_mfma_f32_16x16x32_bf16 v[62:65], v[114:117], v[178:181], v[62:65]
	v_mfma_f32_16x16x32_bf16 v[58:61], v[122:125], v[178:181], v[58:61]
	v_mfma_f32_16x16x32_bf16 v[46:49], v[114:117], v[186:189], v[46:49]
	v_mfma_f32_16x16x32_bf16 v[42:45], v[122:125], v[186:189], v[42:45]
	s_barrier
	v_mfma_f32_16x16x32_bf16 v[30:33], v[114:117], v[194:197], v[30:33]
	v_mfma_f32_16x16x32_bf16 v[26:29], v[122:125], v[194:197], v[26:29]
	v_mfma_f32_16x16x32_bf16 v[14:17], v[114:117], v[202:205], v[14:17]
	v_mfma_f32_16x16x32_bf16 v[10:13], v[122:125], v[202:205], v[10:13]
	v_mfma_f32_16x16x32_bf16 v[62:65], v[118:121], v[182:185], v[62:65]
	v_mfma_f32_16x16x32_bf16 v[58:61], v[126:129], v[182:185], v[58:61]
	v_mfma_f32_16x16x32_bf16 v[46:49], v[118:121], v[190:193], v[46:49]
	v_mfma_f32_16x16x32_bf16 v[42:45], v[126:129], v[190:193], v[42:45]
	v_mfma_f32_16x16x32_bf16 v[30:33], v[118:121], v[198:201], v[30:33]
	v_mfma_f32_16x16x32_bf16 v[26:29], v[126:129], v[198:201], v[26:29]
	v_mfma_f32_16x16x32_bf16 v[14:17], v[118:121], v[214:217], v[14:17]
	v_mfma_f32_16x16x32_bf16 v[10:13], v[126:129], v[214:217], v[10:13]
	s_setprio 0
	s_setprio 1
	v_mfma_f32_16x16x32_bf16 v[54:57], v[146:149], v[178:181], v[54:57]
	v_mfma_f32_16x16x32_bf16 v[50:53], v[154:157], v[178:181], v[50:53]
	v_mfma_f32_16x16x32_bf16 v[38:41], v[146:149], v[186:189], v[38:41]
	v_mfma_f32_16x16x32_bf16 v[34:37], v[154:157], v[186:189], v[34:37]
	v_mfma_f32_16x16x32_bf16 v[22:25], v[146:149], v[194:197], v[22:25]
	v_mfma_f32_16x16x32_bf16 v[18:21], v[154:157], v[194:197], v[18:21]
	v_mfma_f32_16x16x32_bf16 v[6:9], v[146:149], v[202:205], v[6:9]
	v_mfma_f32_16x16x32_bf16 v[2:5], v[154:157], v[202:205], v[2:5]
	v_mfma_f32_16x16x32_bf16 v[54:57], v[150:153], v[182:185], v[54:57]
	v_mfma_f32_16x16x32_bf16 v[50:53], v[158:161], v[182:185], v[50:53]
	v_mfma_f32_16x16x32_bf16 v[38:41], v[150:153], v[190:193], v[38:41]
	v_mfma_f32_16x16x32_bf16 v[34:37], v[158:161], v[190:193], v[34:37]
	v_mfma_f32_16x16x32_bf16 v[22:25], v[150:153], v[198:201], v[22:25]
	v_mfma_f32_16x16x32_bf16 v[18:21], v[158:161], v[198:201], v[18:21]
	v_mfma_f32_16x16x32_bf16 v[6:9], v[150:153], v[214:217], v[6:9]
	v_mfma_f32_16x16x32_bf16 v[2:5], v[158:161], v[214:217], v[2:5]
	s_setprio 0
	s_barrier
	s_add_u32 s90, s90, 0x100
	s_addc_u32 s91, s91, 0
	s_add_u32 s38, s38, 0x10000
	s_addc_u32 s39, s39, 0
	s_cmp_ge_i32 s92, s64
	s_mov_b32 s42, s92
	s_cbranch_scc0 .LBB0_1170

.LBB0_1276:
	ds_read_b128 v[114:117], v171
	ds_read_b128 v[118:121], v171 offset:1024
	ds_read_b128 v[122:125], v171 offset:2048
	ds_read_b128 v[130:133], v171 offset:3072
	ds_read_b128 v[162:165], v172
	ds_read_b128 v[176:179], v172 offset:1024
	ds_read_b128 v[180:183], v172 offset:2048
	ds_read_b128 v[184:187], v172 offset:3072
	s_add_i32 s82, s30, 2
	s_add_u32 s83, s2, 0x80
	s_addc_u32 s31, s3, 0
	s_cmp_eq_u32 s58, s30
	s_cselect_b32 s30, s26, s83
	s_cselect_b32 s31, s27, s31
	s_cselect_b32 s85, s29, s35
	s_cselect_b32 s84, s28, s34
	v_lshl_add_u64 v[220:221], s[2:3], 0, v[154:155]
	s_add_i32 m0, s44, 0xc000
	ds_read_b128 v[188:191], v173
	ds_read_b128 v[192:195], v173 offset:1024
	ds_read_b128 v[196:199], v173 offset:2048
	ds_read_b128 v[200:203], v173 offset:3072
	ds_read_b128 v[204:207], v173 offset:4096
	ds_read_b128 v[208:211], v173 offset:5120
	ds_read_b128 v[212:215], v173 offset:6144
	ds_read_b128 v[216:219], v173 offset:7168
	global_load_lds_dwordx4 v[220:221], off
	v_lshl_add_u64 v[220:221], s[2:3], 0, v[156:157]
	s_add_i32 m0, s44, 0xe000
	s_nop 0
	global_load_lds_dwordx4 v[220:221], off
	s_waitcnt vmcnt(8)
	s_waitcnt lgkmcnt(0)
	s_setprio 1
	s_waitcnt lgkmcnt(0)
	v_mfma_f32_16x16x32_bf16 v[142:145], v[114:117], v[188:191], v[142:145]
	v_mfma_f32_16x16x32_bf16 v[138:141], v[122:125], v[188:191], v[138:141]
	v_mfma_f32_16x16x32_bf16 v[110:113], v[114:117], v[196:199], v[110:113]
	v_mfma_f32_16x16x32_bf16 v[106:109], v[122:125], v[196:199], v[106:109]
	s_barrier
	v_mfma_f32_16x16x32_bf16 v[94:97], v[114:117], v[204:207], v[94:97]
	v_mfma_f32_16x16x32_bf16 v[90:93], v[122:125], v[204:207], v[90:93]
	v_mfma_f32_16x16x32_bf16 v[78:81], v[114:117], v[212:215], v[78:81]
	v_mfma_f32_16x16x32_bf16 v[74:77], v[122:125], v[212:215], v[74:77]
	v_mfma_f32_16x16x32_bf16 v[142:145], v[118:121], v[192:195], v[142:145]
	v_mfma_f32_16x16x32_bf16 v[138:141], v[130:133], v[192:195], v[138:141]
	v_mfma_f32_16x16x32_bf16 v[110:113], v[118:121], v[200:203], v[110:113]
	v_mfma_f32_16x16x32_bf16 v[106:109], v[130:133], v[200:203], v[106:109]
	v_mfma_f32_16x16x32_bf16 v[94:97], v[118:121], v[208:211], v[94:97]
	v_mfma_f32_16x16x32_bf16 v[90:93], v[130:133], v[208:211], v[90:93]
	v_mfma_f32_16x16x32_bf16 v[78:81], v[118:121], v[216:219], v[78:81]
	v_mfma_f32_16x16x32_bf16 v[74:77], v[130:133], v[216:219], v[74:77]
	s_setprio 0
	s_setprio 1
	v_mfma_f32_16x16x32_bf16 v[134:137], v[162:165], v[188:191], v[134:137]
	v_mfma_f32_16x16x32_bf16 v[126:129], v[180:183], v[188:191], v[126:129]
	v_mfma_f32_16x16x32_bf16 v[102:105], v[162:165], v[196:199], v[102:105]
	v_mfma_f32_16x16x32_bf16 v[98:101], v[180:183], v[196:199], v[98:101]
	v_mfma_f32_16x16x32_bf16 v[86:89], v[162:165], v[204:207], v[86:89]
	v_mfma_f32_16x16x32_bf16 v[82:85], v[180:183], v[204:207], v[82:85]
	v_mfma_f32_16x16x32_bf16 v[70:73], v[162:165], v[212:215], v[70:73]
	v_mfma_f32_16x16x32_bf16 v[66:69], v[180:183], v[212:215], v[66:69]
	v_mfma_f32_16x16x32_bf16 v[134:137], v[176:179], v[192:195], v[134:137]
	v_mfma_f32_16x16x32_bf16 v[126:129], v[184:187], v[192:195], v[126:129]
	v_mfma_f32_16x16x32_bf16 v[102:105], v[176:179], v[200:203], v[102:105]
	v_mfma_f32_16x16x32_bf16 v[98:101], v[184:187], v[200:203], v[98:101]
	v_mfma_f32_16x16x32_bf16 v[86:89], v[176:179], v[208:211], v[86:89]
	v_mfma_f32_16x16x32_bf16 v[82:85], v[184:187], v[208:211], v[82:85]
	v_mfma_f32_16x16x32_bf16 v[70:73], v[176:179], v[216:219], v[70:73]
	v_mfma_f32_16x16x32_bf16 v[66:69], v[184:187], v[216:219], v[66:69]
	s_setprio 0
	s_barrier
	s_add_i32 s83, s61, s37
	v_lshl_add_u64 v[220:221], s[84:85], 0, v[148:149]
	s_mov_b32 m0, s83
	ds_read_b128 v[188:191], v173 offset:16384
	ds_read_b128 v[192:195], v173 offset:17408
	ds_read_b128 v[196:199], v173 offset:18432
	ds_read_b128 v[200:203], v173 offset:19456
	ds_read_b128 v[204:207], v173 offset:20480
	ds_read_b128 v[208:211], v173 offset:21504
	ds_read_b128 v[212:215], v173 offset:22528
	ds_read_b128 v[216:219], v173 offset:23552
	global_load_lds_dwordx4 v[220:221], off
	s_add_i32 m0, s83, 0x2000
	v_lshl_add_u64 v[222:223], s[84:85], 0, v[152:153]
	s_add_u32 s84, s84, s6
	s_addc_u32 s85, s85, s7
	s_add_i32 s83, s62, s37
	global_load_lds_dwordx4 v[222:223], off
	v_lshl_add_u64 v[224:225], s[84:85], 0, v[148:149]
	s_mov_b32 m0, s83
	v_lshl_add_u64 v[226:227], s[84:85], 0, v[152:153]
	global_load_lds_dwordx4 v[224:225], off
	s_add_i32 m0, s83, 0x2000
	v_lshl_add_u64 v[228:229], s[30:31], 0, v[146:147]
	global_load_lds_dwordx4 v[226:227], off
	s_mov_b32 m0, s44
	v_lshl_add_u64 v[230:231], s[30:31], 0, v[150:151]
	global_load_lds_dwordx4 v[228:229], off
	s_mov_b32 m0, s45
	s_nop 0
	global_load_lds_dwordx4 v[230:231], off
	s_waitcnt vmcnt(8)
	s_waitcnt lgkmcnt(0)
	s_setprio 1
	s_waitcnt lgkmcnt(0)
	v_mfma_f32_16x16x32_bf16 v[62:65], v[114:117], v[188:191], v[62:65]
	v_mfma_f32_16x16x32_bf16 v[58:61], v[122:125], v[188:191], v[58:61]
	v_mfma_f32_16x16x32_bf16 v[46:49], v[114:117], v[196:199], v[46:49]
	v_mfma_f32_16x16x32_bf16 v[42:45], v[122:125], v[196:199], v[42:45]
	s_barrier
	v_mfma_f32_16x16x32_bf16 v[30:33], v[114:117], v[204:207], v[30:33]
	v_mfma_f32_16x16x32_bf16 v[26:29], v[122:125], v[204:207], v[26:29]
	v_mfma_f32_16x16x32_bf16 v[14:17], v[114:117], v[212:215], v[14:17]
	v_mfma_f32_16x16x32_bf16 v[10:13], v[122:125], v[212:215], v[10:13]
	v_mfma_f32_16x16x32_bf16 v[62:65], v[118:121], v[192:195], v[62:65]
	v_mfma_f32_16x16x32_bf16 v[58:61], v[130:133], v[192:195], v[58:61]
	v_mfma_f32_16x16x32_bf16 v[46:49], v[118:121], v[200:203], v[46:49]
	v_mfma_f32_16x16x32_bf16 v[42:45], v[130:133], v[200:203], v[42:45]
	v_mfma_f32_16x16x32_bf16 v[30:33], v[118:121], v[208:211], v[30:33]
	v_mfma_f32_16x16x32_bf16 v[26:29], v[130:133], v[208:211], v[26:29]
	v_mfma_f32_16x16x32_bf16 v[14:17], v[118:121], v[216:219], v[14:17]
	v_mfma_f32_16x16x32_bf16 v[10:13], v[130:133], v[216:219], v[10:13]
	s_setprio 0
	s_setprio 1
	v_mfma_f32_16x16x32_bf16 v[54:57], v[162:165], v[188:191], v[54:57]
	v_mfma_f32_16x16x32_bf16 v[50:53], v[180:183], v[188:191], v[50:53]
	v_mfma_f32_16x16x32_bf16 v[38:41], v[162:165], v[196:199], v[38:41]
	v_mfma_f32_16x16x32_bf16 v[34:37], v[180:183], v[196:199], v[34:37]
	v_mfma_f32_16x16x32_bf16 v[22:25], v[162:165], v[204:207], v[22:25]
	v_mfma_f32_16x16x32_bf16 v[18:21], v[180:183], v[204:207], v[18:21]
	v_mfma_f32_16x16x32_bf16 v[6:9], v[162:165], v[212:215], v[6:9]
	v_mfma_f32_16x16x32_bf16 v[2:5], v[180:183], v[212:215], v[2:5]
	v_mfma_f32_16x16x32_bf16 v[54:57], v[176:179], v[192:195], v[54:57]
	v_mfma_f32_16x16x32_bf16 v[50:53], v[184:187], v[192:195], v[50:53]
	v_mfma_f32_16x16x32_bf16 v[38:41], v[176:179], v[200:203], v[38:41]
	v_mfma_f32_16x16x32_bf16 v[34:37], v[184:187], v[200:203], v[34:37]
	v_mfma_f32_16x16x32_bf16 v[22:25], v[176:179], v[208:211], v[22:25]
	v_mfma_f32_16x16x32_bf16 v[18:21], v[184:187], v[208:211], v[18:21]
	v_mfma_f32_16x16x32_bf16 v[6:9], v[176:179], v[216:219], v[6:9]
	v_mfma_f32_16x16x32_bf16 v[2:5], v[184:187], v[216:219], v[2:5]
	s_setprio 0
	s_barrier
	s_add_i32 s83, 0, 0x18000
	s_add_i32 s84, 0, 0x1c000
	v_add_u32_e32 v130, s83, v168
	v_add_u32_e32 v166, s84, v168
	ds_read_b128 v[114:117], v130
	ds_read_b128 v[118:121], v130 offset:1024
	ds_read_b128 v[122:125], v130 offset:2048
	ds_read_b128 v[130:133], v130 offset:3072
	ds_read_b128 v[162:165], v166
	ds_read_b128 v[176:179], v166 offset:1024
	ds_read_b128 v[180:183], v166 offset:2048
	ds_read_b128 v[184:187], v166 offset:3072
	s_add_u32 s30, s30, s6
	s_addc_u32 s31, s31, s7
	s_mov_b32 m0, s46
	v_lshl_add_u64 v[232:233], s[30:31], 0, v[146:147]
	ds_read_b128 v[188:191], v173 offset:32768
	ds_read_b128 v[192:195], v173 offset:33792
	ds_read_b128 v[196:199], v173 offset:34816
	ds_read_b128 v[200:203], v173 offset:35840
	ds_read_b128 v[204:207], v173 offset:36864
	ds_read_b128 v[208:211], v173 offset:37888
	ds_read_b128 v[212:215], v173 offset:38912
	ds_read_b128 v[216:219], v173 offset:39936
	global_load_lds_dwordx4 v[232:233], off
	v_lshl_add_u64 v[232:233], s[30:31], 0, v[150:151]
	s_mov_b32 m0, s47
	s_nop 0
	global_load_lds_dwordx4 v[232:233], off
	s_waitcnt vmcnt(8)
	s_waitcnt lgkmcnt(0)
	s_setprio 1
	s_waitcnt lgkmcnt(0)
	v_mfma_f32_16x16x32_bf16 v[142:145], v[114:117], v[188:191], v[142:145]
	v_mfma_f32_16x16x32_bf16 v[138:141], v[122:125], v[188:191], v[138:141]
	v_mfma_f32_16x16x32_bf16 v[110:113], v[114:117], v[196:199], v[110:113]
	v_mfma_f32_16x16x32_bf16 v[106:109], v[122:125], v[196:199], v[106:109]
	s_barrier
	v_mfma_f32_16x16x32_bf16 v[94:97], v[114:117], v[204:207], v[94:97]
	v_mfma_f32_16x16x32_bf16 v[90:93], v[122:125], v[204:207], v[90:93]
	v_mfma_f32_16x16x32_bf16 v[78:81], v[114:117], v[212:215], v[78:81]
	v_mfma_f32_16x16x32_bf16 v[74:77], v[122:125], v[212:215], v[74:77]
	v_mfma_f32_16x16x32_bf16 v[142:145], v[118:121], v[192:195], v[142:145]
	v_mfma_f32_16x16x32_bf16 v[138:141], v[130:133], v[192:195], v[138:141]
	v_mfma_f32_16x16x32_bf16 v[110:113], v[118:121], v[200:203], v[110:113]
	v_mfma_f32_16x16x32_bf16 v[106:109], v[130:133], v[200:203], v[106:109]
	v_mfma_f32_16x16x32_bf16 v[94:97], v[118:121], v[208:211], v[94:97]
	v_mfma_f32_16x16x32_bf16 v[90:93], v[130:133], v[208:211], v[90:93]
	v_mfma_f32_16x16x32_bf16 v[78:81], v[118:121], v[216:219], v[78:81]
	v_mfma_f32_16x16x32_bf16 v[74:77], v[130:133], v[216:219], v[74:77]
	s_setprio 0
	s_setprio 1
	v_mfma_f32_16x16x32_bf16 v[134:137], v[162:165], v[188:191], v[134:137]
	v_mfma_f32_16x16x32_bf16 v[126:129], v[180:183], v[188:191], v[126:129]
	v_mfma_f32_16x16x32_bf16 v[102:105], v[162:165], v[196:199], v[102:105]
	v_mfma_f32_16x16x32_bf16 v[98:101], v[180:183], v[196:199], v[98:101]
	v_mfma_f32_16x16x32_bf16 v[86:89], v[162:165], v[204:207], v[86:89]
	v_mfma_f32_16x16x32_bf16 v[82:85], v[180:183], v[204:207], v[82:85]
	v_mfma_f32_16x16x32_bf16 v[70:73], v[162:165], v[212:215], v[70:73]
	v_mfma_f32_16x16x32_bf16 v[66:69], v[180:183], v[212:215], v[66:69]
	v_mfma_f32_16x16x32_bf16 v[134:137], v[176:179], v[192:195], v[134:137]
	v_mfma_f32_16x16x32_bf16 v[126:129], v[184:187], v[192:195], v[126:129]
	v_mfma_f32_16x16x32_bf16 v[102:105], v[176:179], v[200:203], v[102:105]
	v_mfma_f32_16x16x32_bf16 v[98:101], v[184:187], v[200:203], v[98:101]
	v_mfma_f32_16x16x32_bf16 v[86:89], v[176:179], v[208:211], v[86:89]
	v_mfma_f32_16x16x32_bf16 v[82:85], v[184:187], v[208:211], v[82:85]
	v_mfma_f32_16x16x32_bf16 v[70:73], v[176:179], v[216:219], v[70:73]
	v_mfma_f32_16x16x32_bf16 v[66:69], v[184:187], v[216:219], v[66:69]
	s_setprio 0
	s_barrier
	s_add_i32 s30, s83, s37
	v_lshl_add_u64 v[220:221], v[220:221], 0, s[20:21]
	s_mov_b32 m0, s30
	ds_read_b128 v[188:191], v173 offset:49152
	ds_read_b128 v[192:195], v173 offset:50176
	ds_read_b128 v[196:199], v173 offset:51200
	ds_read_b128 v[200:203], v173 offset:52224
	ds_read_b128 v[204:207], v173 offset:53248
	ds_read_b128 v[208:211], v173 offset:54272
	ds_read_b128 v[212:215], v173 offset:55296
	ds_read_b128 v[216:219], v173 offset:56320
	global_load_lds_dwordx4 v[220:221], off
	v_lshl_add_u64 v[220:221], v[222:223], 0, s[20:21]
	s_add_i32 m0, s30, 0x2000
	s_add_i32 s30, s84, s37
	global_load_lds_dwordx4 v[220:221], off
	v_lshl_add_u64 v[220:221], v[224:225], 0, s[20:21]
	s_mov_b32 m0, s30
	s_nop 0
	global_load_lds_dwordx4 v[220:221], off
	v_lshl_add_u64 v[220:221], v[226:227], 0, s[20:21]
	s_add_i32 m0, s30, 0x2000
	s_nop 0
	global_load_lds_dwordx4 v[220:221], off
	v_lshl_add_u64 v[220:221], v[228:229], 0, s[20:21]
	s_mov_b32 m0, s55
	s_nop 0
	global_load_lds_dwordx4 v[220:221], off
	v_lshl_add_u64 v[220:221], v[230:231], 0, s[20:21]
	s_mov_b32 m0, s56
	s_nop 0
	global_load_lds_dwordx4 v[220:221], off
	s_waitcnt vmcnt(8)
	s_waitcnt lgkmcnt(0)
	s_setprio 1
	s_waitcnt lgkmcnt(0)
	v_mfma_f32_16x16x32_bf16 v[62:65], v[114:117], v[188:191], v[62:65]
	v_mfma_f32_16x16x32_bf16 v[58:61], v[122:125], v[188:191], v[58:61]
	v_mfma_f32_16x16x32_bf16 v[46:49], v[114:117], v[196:199], v[46:49]
	v_mfma_f32_16x16x32_bf16 v[42:45], v[122:125], v[196:199], v[42:45]
	s_barrier
	v_mfma_f32_16x16x32_bf16 v[30:33], v[114:117], v[204:207], v[30:33]
	v_mfma_f32_16x16x32_bf16 v[26:29], v[122:125], v[204:207], v[26:29]
	v_mfma_f32_16x16x32_bf16 v[14:17], v[114:117], v[212:215], v[14:17]
	v_mfma_f32_16x16x32_bf16 v[10:13], v[122:125], v[212:215], v[10:13]
	v_mfma_f32_16x16x32_bf16 v[62:65], v[118:121], v[192:195], v[62:65]
	v_mfma_f32_16x16x32_bf16 v[58:61], v[130:133], v[192:195], v[58:61]
	v_mfma_f32_16x16x32_bf16 v[46:49], v[118:121], v[200:203], v[46:49]
	v_mfma_f32_16x16x32_bf16 v[42:45], v[130:133], v[200:203], v[42:45]
	v_mfma_f32_16x16x32_bf16 v[30:33], v[118:121], v[208:211], v[30:33]
	v_mfma_f32_16x16x32_bf16 v[26:29], v[130:133], v[208:211], v[26:29]
	v_mfma_f32_16x16x32_bf16 v[14:17], v[118:121], v[216:219], v[14:17]
	v_mfma_f32_16x16x32_bf16 v[10:13], v[130:133], v[216:219], v[10:13]
	s_setprio 0
	s_setprio 1
	v_mfma_f32_16x16x32_bf16 v[54:57], v[162:165], v[188:191], v[54:57]
	v_mfma_f32_16x16x32_bf16 v[50:53], v[180:183], v[188:191], v[50:53]
	v_mfma_f32_16x16x32_bf16 v[38:41], v[162:165], v[196:199], v[38:41]
	v_mfma_f32_16x16x32_bf16 v[34:37], v[180:183], v[196:199], v[34:37]
	v_mfma_f32_16x16x32_bf16 v[22:25], v[162:165], v[204:207], v[22:25]
	v_mfma_f32_16x16x32_bf16 v[18:21], v[180:183], v[204:207], v[18:21]
	v_mfma_f32_16x16x32_bf16 v[6:9], v[162:165], v[212:215], v[6:9]
	v_mfma_f32_16x16x32_bf16 v[2:5], v[180:183], v[212:215], v[2:5]
	v_mfma_f32_16x16x32_bf16 v[54:57], v[176:179], v[192:195], v[54:57]
	v_mfma_f32_16x16x32_bf16 v[50:53], v[184:187], v[192:195], v[50:53]
	v_mfma_f32_16x16x32_bf16 v[38:41], v[176:179], v[200:203], v[38:41]
	v_mfma_f32_16x16x32_bf16 v[34:37], v[184:187], v[200:203], v[34:37]
	v_mfma_f32_16x16x32_bf16 v[22:25], v[176:179], v[208:211], v[22:25]
	v_mfma_f32_16x16x32_bf16 v[18:21], v[184:187], v[208:211], v[18:21]
	v_mfma_f32_16x16x32_bf16 v[6:9], v[176:179], v[216:219], v[6:9]
	v_mfma_f32_16x16x32_bf16 v[2:5], v[184:187], v[216:219], v[2:5]
	s_setprio 0
	s_barrier
	s_add_u32 s2, s2, 0x100
	s_addc_u32 s3, s3, 0
	s_add_u32 s34, s34, 0x100
	s_addc_u32 s35, s35, 0
	s_cmp_ge_i32 s82, s57
	s_mov_b32 s30, s82
	s_cbranch_scc0 .LBB0_1276

.LBB0_1461:
	ds_read_b128 v[148:151], v168
	ds_read_b128 v[172:175], v168 offset:1024
	ds_read_b128 v[176:179], v168 offset:2048
	ds_read_b128 v[180:183], v168 offset:3072
	ds_read_b128 v[184:187], v169
	ds_read_b128 v[188:191], v169 offset:1024
	ds_read_b128 v[192:195], v169 offset:2048
	ds_read_b128 v[196:199], v169 offset:3072
	s_add_i32 s67, s26, 2
	s_add_u32 s68, s24, 0x80
	s_addc_u32 s27, s25, 0
	s_cmp_eq_u32 s50, s26
	s_cselect_b32 s26, s2, s68
	s_cselect_b32 s27, s3, s27
	s_cselect_b32 s69, s23, s66
	s_cselect_b32 s68, s22, s65
	v_lshl_add_u64 v[232:233], s[24:25], 0, v[140:141]
	s_add_i32 m0, s37, 0xc000
	ds_read_b128 v[200:203], v170
	ds_read_b128 v[204:207], v170 offset:1024
	ds_read_b128 v[208:211], v170 offset:2048
	ds_read_b128 v[212:215], v170 offset:3072
	ds_read_b128 v[216:219], v170 offset:4096
	ds_read_b128 v[220:223], v170 offset:5120
	ds_read_b128 v[224:227], v170 offset:6144
	ds_read_b128 v[228:231], v170 offset:7168
	global_load_lds_dwordx4 v[232:233], off
	v_lshl_add_u64 v[232:233], s[24:25], 0, v[142:143]
	s_add_i32 m0, s37, 0xe000
	s_nop 0
	global_load_lds_dwordx4 v[232:233], off
	s_waitcnt vmcnt(8)
	s_waitcnt lgkmcnt(0)
	s_setprio 1
	s_waitcnt lgkmcnt(0)
	v_mfma_f32_16x16x32_bf16 v[128:131], v[148:151], v[200:203], v[128:131]
	v_mfma_f32_16x16x32_bf16 v[124:127], v[176:179], v[200:203], v[124:127]
	v_mfma_f32_16x16x32_bf16 v[120:123], v[148:151], v[208:211], v[120:123]
	v_mfma_f32_16x16x32_bf16 v[116:119], v[176:179], v[208:211], v[116:119]
	s_barrier
	v_mfma_f32_16x16x32_bf16 v[112:115], v[148:151], v[216:219], v[112:115]
	v_mfma_f32_16x16x32_bf16 v[108:111], v[176:179], v[216:219], v[108:111]
	v_mfma_f32_16x16x32_bf16 v[104:107], v[148:151], v[224:227], v[104:107]
	v_mfma_f32_16x16x32_bf16 v[100:103], v[176:179], v[224:227], v[100:103]
	v_mfma_f32_16x16x32_bf16 v[128:131], v[172:175], v[204:207], v[128:131]
	v_mfma_f32_16x16x32_bf16 v[124:127], v[180:183], v[204:207], v[124:127]
	v_mfma_f32_16x16x32_bf16 v[120:123], v[172:175], v[212:215], v[120:123]
	v_mfma_f32_16x16x32_bf16 v[116:119], v[180:183], v[212:215], v[116:119]
	v_mfma_f32_16x16x32_bf16 v[112:115], v[172:175], v[220:223], v[112:115]
	v_mfma_f32_16x16x32_bf16 v[108:111], v[180:183], v[220:223], v[108:111]
	v_mfma_f32_16x16x32_bf16 v[104:107], v[172:175], v[228:231], v[104:107]
	v_mfma_f32_16x16x32_bf16 v[100:103], v[180:183], v[228:231], v[100:103]
	s_setprio 0
	s_setprio 1
	v_mfma_f32_16x16x32_bf16 v[64:67], v[184:187], v[200:203], v[64:67]
	v_mfma_f32_16x16x32_bf16 v[60:63], v[192:195], v[200:203], v[60:63]
	v_mfma_f32_16x16x32_bf16 v[56:59], v[184:187], v[208:211], v[56:59]
	v_mfma_f32_16x16x32_bf16 v[52:55], v[192:195], v[208:211], v[52:55]
	v_mfma_f32_16x16x32_bf16 v[48:51], v[184:187], v[216:219], v[48:51]
	v_mfma_f32_16x16x32_bf16 v[44:47], v[192:195], v[216:219], v[44:47]
	v_mfma_f32_16x16x32_bf16 v[40:43], v[184:187], v[224:227], v[40:43]
	v_mfma_f32_16x16x32_bf16 v[36:39], v[192:195], v[224:227], v[36:39]
	v_mfma_f32_16x16x32_bf16 v[64:67], v[188:191], v[204:207], v[64:67]
	v_mfma_f32_16x16x32_bf16 v[60:63], v[196:199], v[204:207], v[60:63]
	v_mfma_f32_16x16x32_bf16 v[56:59], v[188:191], v[212:215], v[56:59]
	v_mfma_f32_16x16x32_bf16 v[52:55], v[196:199], v[212:215], v[52:55]
	v_mfma_f32_16x16x32_bf16 v[48:51], v[188:191], v[220:223], v[48:51]
	v_mfma_f32_16x16x32_bf16 v[44:47], v[196:199], v[220:223], v[44:47]
	v_mfma_f32_16x16x32_bf16 v[40:43], v[188:191], v[228:231], v[40:43]
	v_mfma_f32_16x16x32_bf16 v[36:39], v[196:199], v[228:231], v[36:39]
	s_setprio 0
	s_barrier
	s_add_i32 s80, s57, s36
	v_lshl_add_u64 v[232:233], s[68:69], 0, v[134:135]
	s_mov_b32 m0, s80
	ds_read_b128 v[200:203], v170 offset:16384
	ds_read_b128 v[204:207], v170 offset:17408
	ds_read_b128 v[208:211], v170 offset:18432
	ds_read_b128 v[212:215], v170 offset:19456
	ds_read_b128 v[216:219], v170 offset:20480
	ds_read_b128 v[220:223], v170 offset:21504
	ds_read_b128 v[224:227], v170 offset:22528
	ds_read_b128 v[228:231], v170 offset:23552
	global_load_lds_dwordx4 v[232:233], off
	s_add_i32 m0, s80, 0x2000
	v_lshl_add_u64 v[234:235], s[68:69], 0, v[138:139]
	s_add_u32 s68, s68, s6
	s_addc_u32 s69, s69, s7
	s_add_i32 s80, s58, s36
	global_load_lds_dwordx4 v[234:235], off
	v_lshl_add_u64 v[236:237], s[68:69], 0, v[134:135]
	s_mov_b32 m0, s80
	v_lshl_add_u64 v[238:239], s[68:69], 0, v[138:139]
	global_load_lds_dwordx4 v[236:237], off
	s_add_i32 m0, s80, 0x2000
	v_lshl_add_u64 v[240:241], s[26:27], 0, v[132:133]
	global_load_lds_dwordx4 v[238:239], off
	s_mov_b32 m0, s37
	v_lshl_add_u64 v[242:243], s[26:27], 0, v[136:137]
	global_load_lds_dwordx4 v[240:241], off
	s_mov_b32 m0, s38
	s_nop 0
	global_load_lds_dwordx4 v[242:243], off
	s_waitcnt vmcnt(8)
	s_waitcnt lgkmcnt(0)
	s_setprio 1
	s_waitcnt lgkmcnt(0)
	v_mfma_f32_16x16x32_bf16 v[96:99], v[148:151], v[200:203], v[96:99]
	v_mfma_f32_16x16x32_bf16 v[92:95], v[176:179], v[200:203], v[92:95]
	v_mfma_f32_16x16x32_bf16 v[88:91], v[148:151], v[208:211], v[88:91]
	v_mfma_f32_16x16x32_bf16 v[84:87], v[176:179], v[208:211], v[84:87]
	s_barrier
	v_mfma_f32_16x16x32_bf16 v[80:83], v[148:151], v[216:219], v[80:83]
	v_mfma_f32_16x16x32_bf16 v[76:79], v[176:179], v[216:219], v[76:79]
	v_mfma_f32_16x16x32_bf16 v[72:75], v[148:151], v[224:227], v[72:75]
	v_mfma_f32_16x16x32_bf16 v[68:71], v[176:179], v[224:227], v[68:71]
	v_mfma_f32_16x16x32_bf16 v[96:99], v[172:175], v[204:207], v[96:99]
	v_mfma_f32_16x16x32_bf16 v[92:95], v[180:183], v[204:207], v[92:95]
	v_mfma_f32_16x16x32_bf16 v[88:91], v[172:175], v[212:215], v[88:91]
	v_mfma_f32_16x16x32_bf16 v[84:87], v[180:183], v[212:215], v[84:87]
	v_mfma_f32_16x16x32_bf16 v[80:83], v[172:175], v[220:223], v[80:83]
	v_mfma_f32_16x16x32_bf16 v[76:79], v[180:183], v[220:223], v[76:79]
	v_mfma_f32_16x16x32_bf16 v[72:75], v[172:175], v[228:231], v[72:75]
	v_mfma_f32_16x16x32_bf16 v[68:71], v[180:183], v[228:231], v[68:71]
	s_setprio 0
	s_setprio 1
	v_mfma_f32_16x16x32_bf16 v[32:35], v[184:187], v[200:203], v[32:35]
	v_mfma_f32_16x16x32_bf16 v[28:31], v[192:195], v[200:203], v[28:31]
	v_mfma_f32_16x16x32_bf16 v[24:27], v[184:187], v[208:211], v[24:27]
	v_mfma_f32_16x16x32_bf16 v[20:23], v[192:195], v[208:211], v[20:23]
	v_mfma_f32_16x16x32_bf16 v[16:19], v[184:187], v[216:219], v[16:19]
	v_mfma_f32_16x16x32_bf16 v[12:15], v[192:195], v[216:219], v[12:15]
	v_mfma_f32_16x16x32_bf16 v[8:11], v[184:187], v[224:227], v[8:11]
	v_mfma_f32_16x16x32_bf16 v[4:7], v[192:195], v[224:227], v[4:7]
	v_mfma_f32_16x16x32_bf16 v[32:35], v[188:191], v[204:207], v[32:35]
	v_mfma_f32_16x16x32_bf16 v[28:31], v[196:199], v[204:207], v[28:31]
	v_mfma_f32_16x16x32_bf16 v[24:27], v[188:191], v[212:215], v[24:27]
	v_mfma_f32_16x16x32_bf16 v[20:23], v[196:199], v[212:215], v[20:23]
	v_mfma_f32_16x16x32_bf16 v[16:19], v[188:191], v[220:223], v[16:19]
	v_mfma_f32_16x16x32_bf16 v[12:15], v[196:199], v[220:223], v[12:15]
	v_mfma_f32_16x16x32_bf16 v[8:11], v[188:191], v[228:231], v[8:11]
	v_mfma_f32_16x16x32_bf16 v[4:7], v[196:199], v[228:231], v[4:7]
	s_setprio 0
	s_barrier
	s_add_i32 s68, 0, 0x18000
	v_add_u32_e32 v3, s68, v166
	s_add_i32 s69, 0, 0x1c000
	ds_read_b128 v[148:151], v3
	ds_read_b128 v[172:175], v3 offset:1024
	ds_read_b128 v[176:179], v3 offset:2048
	ds_read_b128 v[180:183], v3 offset:3072
	v_add_u32_e32 v3, s69, v166
	ds_read_b128 v[184:187], v3
	ds_read_b128 v[188:191], v3 offset:1024
	ds_read_b128 v[192:195], v3 offset:2048
	ds_read_b128 v[196:199], v3 offset:3072
	s_add_u32 s26, s26, s6
	s_addc_u32 s27, s27, s7
	s_mov_b32 m0, s39
	v_lshl_add_u64 v[244:245], s[26:27], 0, v[132:133]
	ds_read_b128 v[200:203], v170 offset:32768
	ds_read_b128 v[204:207], v170 offset:33792
	ds_read_b128 v[208:211], v170 offset:34816
	ds_read_b128 v[212:215], v170 offset:35840
	ds_read_b128 v[216:219], v170 offset:36864
	ds_read_b128 v[220:223], v170 offset:37888
	ds_read_b128 v[224:227], v170 offset:38912
	ds_read_b128 v[228:231], v170 offset:39936
	global_load_lds_dwordx4 v[244:245], off
	v_lshl_add_u64 v[244:245], s[26:27], 0, v[136:137]
	s_mov_b32 m0, s42
	s_nop 0
	global_load_lds_dwordx4 v[244:245], off
	s_waitcnt vmcnt(8)
	s_waitcnt lgkmcnt(0)
	s_setprio 1
	s_waitcnt lgkmcnt(0)
	v_mfma_f32_16x16x32_bf16 v[128:131], v[148:151], v[200:203], v[128:131]
	v_mfma_f32_16x16x32_bf16 v[124:127], v[176:179], v[200:203], v[124:127]
	v_mfma_f32_16x16x32_bf16 v[120:123], v[148:151], v[208:211], v[120:123]
	v_mfma_f32_16x16x32_bf16 v[116:119], v[176:179], v[208:211], v[116:119]
	s_barrier
	v_mfma_f32_16x16x32_bf16 v[112:115], v[148:151], v[216:219], v[112:115]
	v_mfma_f32_16x16x32_bf16 v[108:111], v[176:179], v[216:219], v[108:111]
	v_mfma_f32_16x16x32_bf16 v[104:107], v[148:151], v[224:227], v[104:107]
	v_mfma_f32_16x16x32_bf16 v[100:103], v[176:179], v[224:227], v[100:103]
	v_mfma_f32_16x16x32_bf16 v[128:131], v[172:175], v[204:207], v[128:131]
	v_mfma_f32_16x16x32_bf16 v[124:127], v[180:183], v[204:207], v[124:127]
	v_mfma_f32_16x16x32_bf16 v[120:123], v[172:175], v[212:215], v[120:123]
	v_mfma_f32_16x16x32_bf16 v[116:119], v[180:183], v[212:215], v[116:119]
	v_mfma_f32_16x16x32_bf16 v[112:115], v[172:175], v[220:223], v[112:115]
	v_mfma_f32_16x16x32_bf16 v[108:111], v[180:183], v[220:223], v[108:111]
	v_mfma_f32_16x16x32_bf16 v[104:107], v[172:175], v[228:231], v[104:107]
	v_mfma_f32_16x16x32_bf16 v[100:103], v[180:183], v[228:231], v[100:103]
	s_setprio 0
	s_setprio 1
	v_mfma_f32_16x16x32_bf16 v[64:67], v[184:187], v[200:203], v[64:67]
	v_mfma_f32_16x16x32_bf16 v[60:63], v[192:195], v[200:203], v[60:63]
	v_mfma_f32_16x16x32_bf16 v[56:59], v[184:187], v[208:211], v[56:59]
	v_mfma_f32_16x16x32_bf16 v[52:55], v[192:195], v[208:211], v[52:55]
	v_mfma_f32_16x16x32_bf16 v[48:51], v[184:187], v[216:219], v[48:51]
	v_mfma_f32_16x16x32_bf16 v[44:47], v[192:195], v[216:219], v[44:47]
	v_mfma_f32_16x16x32_bf16 v[40:43], v[184:187], v[224:227], v[40:43]
	v_mfma_f32_16x16x32_bf16 v[36:39], v[192:195], v[224:227], v[36:39]
	v_mfma_f32_16x16x32_bf16 v[64:67], v[188:191], v[204:207], v[64:67]
	v_mfma_f32_16x16x32_bf16 v[60:63], v[196:199], v[204:207], v[60:63]
	v_mfma_f32_16x16x32_bf16 v[56:59], v[188:191], v[212:215], v[56:59]
	v_mfma_f32_16x16x32_bf16 v[52:55], v[196:199], v[212:215], v[52:55]
	v_mfma_f32_16x16x32_bf16 v[48:51], v[188:191], v[220:223], v[48:51]
	v_mfma_f32_16x16x32_bf16 v[44:47], v[196:199], v[220:223], v[44:47]
	v_mfma_f32_16x16x32_bf16 v[40:43], v[188:191], v[228:231], v[40:43]
	v_mfma_f32_16x16x32_bf16 v[36:39], v[196:199], v[228:231], v[36:39]
	s_setprio 0
	s_barrier
	s_add_i32 s26, s68, s36
	v_lshl_add_u64 v[232:233], v[232:233], 0, s[16:17]
	s_mov_b32 m0, s26
	ds_read_b128 v[200:203], v170 offset:49152
	ds_read_b128 v[204:207], v170 offset:50176
	ds_read_b128 v[208:211], v170 offset:51200
	ds_read_b128 v[212:215], v170 offset:52224
	ds_read_b128 v[216:219], v170 offset:53248
	ds_read_b128 v[220:223], v170 offset:54272
	ds_read_b128 v[224:227], v170 offset:55296
	ds_read_b128 v[228:231], v170 offset:56320
	global_load_lds_dwordx4 v[232:233], off
	v_lshl_add_u64 v[232:233], v[234:235], 0, s[16:17]
	s_add_i32 m0, s26, 0x2000
	s_add_i32 s26, s69, s36
	global_load_lds_dwordx4 v[232:233], off
	v_lshl_add_u64 v[232:233], v[236:237], 0, s[16:17]
	s_mov_b32 m0, s26
	s_nop 0
	global_load_lds_dwordx4 v[232:233], off
	v_lshl_add_u64 v[232:233], v[238:239], 0, s[16:17]
	s_add_i32 m0, s26, 0x2000
	s_nop 0
	global_load_lds_dwordx4 v[232:233], off
	v_lshl_add_u64 v[232:233], v[240:241], 0, s[16:17]
	s_mov_b32 m0, s44
	s_nop 0
	global_load_lds_dwordx4 v[232:233], off
	v_lshl_add_u64 v[232:233], v[242:243], 0, s[16:17]
	s_mov_b32 m0, s45
	s_nop 0
	global_load_lds_dwordx4 v[232:233], off
	s_waitcnt vmcnt(8)
	s_waitcnt lgkmcnt(0)
	s_setprio 1
	s_waitcnt lgkmcnt(0)
	v_mfma_f32_16x16x32_bf16 v[96:99], v[148:151], v[200:203], v[96:99]
	v_mfma_f32_16x16x32_bf16 v[92:95], v[176:179], v[200:203], v[92:95]
	v_mfma_f32_16x16x32_bf16 v[88:91], v[148:151], v[208:211], v[88:91]
	v_mfma_f32_16x16x32_bf16 v[84:87], v[176:179], v[208:211], v[84:87]
	s_barrier
	v_mfma_f32_16x16x32_bf16 v[80:83], v[148:151], v[216:219], v[80:83]
	v_mfma_f32_16x16x32_bf16 v[76:79], v[176:179], v[216:219], v[76:79]
	v_mfma_f32_16x16x32_bf16 v[72:75], v[148:151], v[224:227], v[72:75]
	v_mfma_f32_16x16x32_bf16 v[68:71], v[176:179], v[224:227], v[68:71]
	v_mfma_f32_16x16x32_bf16 v[96:99], v[172:175], v[204:207], v[96:99]
	v_mfma_f32_16x16x32_bf16 v[92:95], v[180:183], v[204:207], v[92:95]
	v_mfma_f32_16x16x32_bf16 v[88:91], v[172:175], v[212:215], v[88:91]
	v_mfma_f32_16x16x32_bf16 v[84:87], v[180:183], v[212:215], v[84:87]
	v_mfma_f32_16x16x32_bf16 v[80:83], v[172:175], v[220:223], v[80:83]
	v_mfma_f32_16x16x32_bf16 v[76:79], v[180:183], v[220:223], v[76:79]
	v_mfma_f32_16x16x32_bf16 v[72:75], v[172:175], v[228:231], v[72:75]
	v_mfma_f32_16x16x32_bf16 v[68:71], v[180:183], v[228:231], v[68:71]
	s_setprio 0
	s_setprio 1
	v_mfma_f32_16x16x32_bf16 v[32:35], v[184:187], v[200:203], v[32:35]
	v_mfma_f32_16x16x32_bf16 v[28:31], v[192:195], v[200:203], v[28:31]
	v_mfma_f32_16x16x32_bf16 v[24:27], v[184:187], v[208:211], v[24:27]
	v_mfma_f32_16x16x32_bf16 v[20:23], v[192:195], v[208:211], v[20:23]
	v_mfma_f32_16x16x32_bf16 v[16:19], v[184:187], v[216:219], v[16:19]
	v_mfma_f32_16x16x32_bf16 v[12:15], v[192:195], v[216:219], v[12:15]
	v_mfma_f32_16x16x32_bf16 v[8:11], v[184:187], v[224:227], v[8:11]
	v_mfma_f32_16x16x32_bf16 v[4:7], v[192:195], v[224:227], v[4:7]
	v_mfma_f32_16x16x32_bf16 v[32:35], v[188:191], v[204:207], v[32:35]
	v_mfma_f32_16x16x32_bf16 v[28:31], v[196:199], v[204:207], v[28:31]
	v_mfma_f32_16x16x32_bf16 v[24:27], v[188:191], v[212:215], v[24:27]
	v_mfma_f32_16x16x32_bf16 v[20:23], v[196:199], v[212:215], v[20:23]
	v_mfma_f32_16x16x32_bf16 v[16:19], v[188:191], v[220:223], v[16:19]
	v_mfma_f32_16x16x32_bf16 v[12:15], v[196:199], v[220:223], v[12:15]
	v_mfma_f32_16x16x32_bf16 v[8:11], v[188:191], v[228:231], v[8:11]
	v_mfma_f32_16x16x32_bf16 v[4:7], v[196:199], v[228:231], v[4:7]
	s_setprio 0
	s_barrier
	s_add_u32 s24, s24, 0x100
	s_addc_u32 s25, s25, 0
	s_add_u32 s65, s65, 0x100
	s_addc_u32 s66, s66, 0
	s_cmp_ge_i32 s67, s46
	s_mov_b32 s26, s67
	s_cbranch_scc0 .LBB0_1461

.LBB0_1514:
	ds_read_b128 v[152:155], v149
	ds_read_b128 v[156:159], v149 offset:1024
	ds_read_b128 v[160:163], v149 offset:2048
	ds_read_b128 v[164:167], v149 offset:3072
	ds_read_b128 v[168:171], v150
	ds_read_b128 v[172:175], v150 offset:1024
	ds_read_b128 v[176:179], v150 offset:2048
	ds_read_b128 v[180:183], v150 offset:3072
	s_add_i32 s69, s36, 2
	s_add_u32 s80, s34, 0x80
	s_addc_u32 s37, s35, 0
	s_cmp_eq_u32 s59, s36
	s_cselect_b32 s36, s2, s80
	s_cselect_b32 s37, s3, s37
	s_cselect_b32 s81, s31, s68
	s_cselect_b32 s80, s30, s67
	v_lshl_add_u64 v[216:217], s[34:35], 0, v[138:139]
	s_add_i32 m0, s47, 0xc000
	ds_read_b128 v[184:187], v151
	ds_read_b128 v[188:191], v151 offset:1024
	ds_read_b128 v[192:195], v151 offset:2048
	ds_read_b128 v[196:199], v151 offset:3072
	ds_read_b128 v[200:203], v151 offset:4096
	ds_read_b128 v[204:207], v151 offset:5120
	ds_read_b128 v[208:211], v151 offset:6144
	ds_read_b128 v[212:215], v151 offset:7168
	global_load_lds_dwordx4 v[216:217], off
	v_lshl_add_u64 v[216:217], s[34:35], 0, v[140:141]
	s_add_i32 m0, s47, 0xe000
	s_nop 0
	global_load_lds_dwordx4 v[216:217], off
	s_waitcnt vmcnt(8)
	s_waitcnt lgkmcnt(0)
	s_setprio 1
	s_waitcnt lgkmcnt(0)
	v_mfma_f32_16x16x32_bf16 v[122:125], v[152:155], v[184:187], v[122:125]
	v_mfma_f32_16x16x32_bf16 v[126:129], v[160:163], v[184:187], v[126:129]
	v_mfma_f32_16x16x32_bf16 v[110:113], v[152:155], v[192:195], v[110:113]
	v_mfma_f32_16x16x32_bf16 v[106:109], v[160:163], v[192:195], v[106:109]
	s_barrier
	v_mfma_f32_16x16x32_bf16 v[94:97], v[152:155], v[200:203], v[94:97]
	v_mfma_f32_16x16x32_bf16 v[90:93], v[160:163], v[200:203], v[90:93]
	v_mfma_f32_16x16x32_bf16 v[78:81], v[152:155], v[208:211], v[78:81]
	v_mfma_f32_16x16x32_bf16 v[74:77], v[160:163], v[208:211], v[74:77]
	v_mfma_f32_16x16x32_bf16 v[122:125], v[156:159], v[188:191], v[122:125]
	v_mfma_f32_16x16x32_bf16 v[126:129], v[164:167], v[188:191], v[126:129]
	v_mfma_f32_16x16x32_bf16 v[110:113], v[156:159], v[196:199], v[110:113]
	v_mfma_f32_16x16x32_bf16 v[106:109], v[164:167], v[196:199], v[106:109]
	v_mfma_f32_16x16x32_bf16 v[94:97], v[156:159], v[204:207], v[94:97]
	v_mfma_f32_16x16x32_bf16 v[90:93], v[164:167], v[204:207], v[90:93]
	v_mfma_f32_16x16x32_bf16 v[78:81], v[156:159], v[212:215], v[78:81]
	v_mfma_f32_16x16x32_bf16 v[74:77], v[164:167], v[212:215], v[74:77]
	s_setprio 0
	s_setprio 1
	v_mfma_f32_16x16x32_bf16 v[118:121], v[168:171], v[184:187], v[118:121]
	v_mfma_f32_16x16x32_bf16 v[114:117], v[176:179], v[184:187], v[114:117]
	v_mfma_f32_16x16x32_bf16 v[102:105], v[168:171], v[192:195], v[102:105]
	v_mfma_f32_16x16x32_bf16 v[98:101], v[176:179], v[192:195], v[98:101]
	v_mfma_f32_16x16x32_bf16 v[86:89], v[168:171], v[200:203], v[86:89]
	v_mfma_f32_16x16x32_bf16 v[82:85], v[176:179], v[200:203], v[82:85]
	v_mfma_f32_16x16x32_bf16 v[70:73], v[168:171], v[208:211], v[70:73]
	v_mfma_f32_16x16x32_bf16 v[66:69], v[176:179], v[208:211], v[66:69]
	v_mfma_f32_16x16x32_bf16 v[118:121], v[172:175], v[188:191], v[118:121]
	v_mfma_f32_16x16x32_bf16 v[114:117], v[180:183], v[188:191], v[114:117]
	v_mfma_f32_16x16x32_bf16 v[102:105], v[172:175], v[196:199], v[102:105]
	v_mfma_f32_16x16x32_bf16 v[98:101], v[180:183], v[196:199], v[98:101]
	v_mfma_f32_16x16x32_bf16 v[86:89], v[172:175], v[204:207], v[86:89]
	v_mfma_f32_16x16x32_bf16 v[82:85], v[180:183], v[204:207], v[82:85]
	v_mfma_f32_16x16x32_bf16 v[70:73], v[172:175], v[212:215], v[70:73]
	v_mfma_f32_16x16x32_bf16 v[66:69], v[180:183], v[212:215], v[66:69]
	s_setprio 0
	s_barrier
	s_add_i32 s82, s61, s44
	v_lshl_add_u64 v[216:217], s[80:81], 0, v[134:135]
	s_mov_b32 m0, s82
	ds_read_b128 v[184:187], v151 offset:16384
	ds_read_b128 v[188:191], v151 offset:17408
	ds_read_b128 v[192:195], v151 offset:18432
	ds_read_b128 v[196:199], v151 offset:19456
	ds_read_b128 v[200:203], v151 offset:20480
	ds_read_b128 v[204:207], v151 offset:21504
	ds_read_b128 v[208:211], v151 offset:22528
	ds_read_b128 v[212:215], v151 offset:23552
	global_load_lds_dwordx4 v[216:217], off
	s_add_i32 m0, s82, 0x2000
	v_lshl_add_u64 v[218:219], s[80:81], 0, v[130:131]
	s_add_u32 s80, s80, s6
	s_addc_u32 s81, s81, s7
	s_add_i32 s82, s62, s44
	global_load_lds_dwordx4 v[218:219], off
	v_lshl_add_u64 v[220:221], s[80:81], 0, v[134:135]
	s_mov_b32 m0, s82
	v_lshl_add_u64 v[222:223], s[80:81], 0, v[130:131]
	global_load_lds_dwordx4 v[220:221], off
	s_add_i32 m0, s82, 0x2000
	v_lshl_add_u64 v[224:225], s[36:37], 0, v[136:137]
	global_load_lds_dwordx4 v[222:223], off
	s_mov_b32 m0, s47
	v_lshl_add_u64 v[226:227], s[36:37], 0, v[132:133]
	global_load_lds_dwordx4 v[224:225], off
	s_mov_b32 m0, s50
	s_nop 0
	global_load_lds_dwordx4 v[226:227], off
	s_waitcnt vmcnt(8)
	s_waitcnt lgkmcnt(0)
	s_setprio 1
	s_waitcnt lgkmcnt(0)
	v_mfma_f32_16x16x32_bf16 v[62:65], v[152:155], v[184:187], v[62:65]
	v_mfma_f32_16x16x32_bf16 v[58:61], v[160:163], v[184:187], v[58:61]
	v_mfma_f32_16x16x32_bf16 v[46:49], v[152:155], v[192:195], v[46:49]
	v_mfma_f32_16x16x32_bf16 v[42:45], v[160:163], v[192:195], v[42:45]
	s_barrier
	v_mfma_f32_16x16x32_bf16 v[30:33], v[152:155], v[200:203], v[30:33]
	v_mfma_f32_16x16x32_bf16 v[26:29], v[160:163], v[200:203], v[26:29]
	v_mfma_f32_16x16x32_bf16 v[14:17], v[152:155], v[208:211], v[14:17]
	v_mfma_f32_16x16x32_bf16 v[10:13], v[160:163], v[208:211], v[10:13]
	v_mfma_f32_16x16x32_bf16 v[62:65], v[156:159], v[188:191], v[62:65]
	v_mfma_f32_16x16x32_bf16 v[58:61], v[164:167], v[188:191], v[58:61]
	v_mfma_f32_16x16x32_bf16 v[46:49], v[156:159], v[196:199], v[46:49]
	v_mfma_f32_16x16x32_bf16 v[42:45], v[164:167], v[196:199], v[42:45]
	v_mfma_f32_16x16x32_bf16 v[30:33], v[156:159], v[204:207], v[30:33]
	v_mfma_f32_16x16x32_bf16 v[26:29], v[164:167], v[204:207], v[26:29]
	v_mfma_f32_16x16x32_bf16 v[14:17], v[156:159], v[212:215], v[14:17]
	v_mfma_f32_16x16x32_bf16 v[10:13], v[164:167], v[212:215], v[10:13]
	s_setprio 0
	s_setprio 1
	v_mfma_f32_16x16x32_bf16 v[54:57], v[168:171], v[184:187], v[54:57]
	v_mfma_f32_16x16x32_bf16 v[50:53], v[176:179], v[184:187], v[50:53]
	v_mfma_f32_16x16x32_bf16 v[38:41], v[168:171], v[192:195], v[38:41]
	v_mfma_f32_16x16x32_bf16 v[34:37], v[176:179], v[192:195], v[34:37]
	v_mfma_f32_16x16x32_bf16 v[22:25], v[168:171], v[200:203], v[22:25]
	v_mfma_f32_16x16x32_bf16 v[18:21], v[176:179], v[200:203], v[18:21]
	v_mfma_f32_16x16x32_bf16 v[6:9], v[168:171], v[208:211], v[6:9]
	v_mfma_f32_16x16x32_bf16 v[2:5], v[176:179], v[208:211], v[2:5]
	v_mfma_f32_16x16x32_bf16 v[54:57], v[172:175], v[188:191], v[54:57]
	v_mfma_f32_16x16x32_bf16 v[50:53], v[180:183], v[188:191], v[50:53]
	v_mfma_f32_16x16x32_bf16 v[38:41], v[172:175], v[196:199], v[38:41]
	v_mfma_f32_16x16x32_bf16 v[34:37], v[180:183], v[196:199], v[34:37]
	v_mfma_f32_16x16x32_bf16 v[22:25], v[172:175], v[204:207], v[22:25]
	v_mfma_f32_16x16x32_bf16 v[18:21], v[180:183], v[204:207], v[18:21]
	v_mfma_f32_16x16x32_bf16 v[6:9], v[172:175], v[212:215], v[6:9]
	v_mfma_f32_16x16x32_bf16 v[2:5], v[180:183], v[212:215], v[2:5]
	s_setprio 0
	s_barrier
	s_add_i32 s80, 0, 0x18000
	s_add_i32 s81, 0, 0x1c000
	v_add_u32_e32 v164, s80, v147
	v_add_u32_e32 v180, s81, v147
	ds_read_b128 v[152:155], v164
	ds_read_b128 v[156:159], v164 offset:1024
	ds_read_b128 v[160:163], v164 offset:2048
	ds_read_b128 v[164:167], v164 offset:3072
	ds_read_b128 v[168:171], v180
	ds_read_b128 v[172:175], v180 offset:1024
	ds_read_b128 v[176:179], v180 offset:2048
	ds_read_b128 v[180:183], v180 offset:3072
	s_add_u32 s36, s36, s6
	s_addc_u32 s37, s37, s7
	s_mov_b32 m0, s51
	v_lshl_add_u64 v[228:229], s[36:37], 0, v[136:137]
	ds_read_b128 v[184:187], v151 offset:32768
	ds_read_b128 v[188:191], v151 offset:33792
	ds_read_b128 v[192:195], v151 offset:34816
	ds_read_b128 v[196:199], v151 offset:35840
	ds_read_b128 v[200:203], v151 offset:36864
	ds_read_b128 v[204:207], v151 offset:37888
	ds_read_b128 v[208:211], v151 offset:38912
	ds_read_b128 v[212:215], v151 offset:39936
	global_load_lds_dwordx4 v[228:229], off
	v_lshl_add_u64 v[228:229], s[36:37], 0, v[132:133]
	s_mov_b32 m0, s54
	s_nop 0
	global_load_lds_dwordx4 v[228:229], off
	s_waitcnt vmcnt(8)
	s_waitcnt lgkmcnt(0)
	s_setprio 1
	s_waitcnt lgkmcnt(0)
	v_mfma_f32_16x16x32_bf16 v[122:125], v[152:155], v[184:187], v[122:125]
	v_mfma_f32_16x16x32_bf16 v[126:129], v[160:163], v[184:187], v[126:129]
	v_mfma_f32_16x16x32_bf16 v[110:113], v[152:155], v[192:195], v[110:113]
	v_mfma_f32_16x16x32_bf16 v[106:109], v[160:163], v[192:195], v[106:109]
	s_barrier
	v_mfma_f32_16x16x32_bf16 v[94:97], v[152:155], v[200:203], v[94:97]
	v_mfma_f32_16x16x32_bf16 v[90:93], v[160:163], v[200:203], v[90:93]
	v_mfma_f32_16x16x32_bf16 v[78:81], v[152:155], v[208:211], v[78:81]
	v_mfma_f32_16x16x32_bf16 v[74:77], v[160:163], v[208:211], v[74:77]
	v_mfma_f32_16x16x32_bf16 v[122:125], v[156:159], v[188:191], v[122:125]
	v_mfma_f32_16x16x32_bf16 v[126:129], v[164:167], v[188:191], v[126:129]
	v_mfma_f32_16x16x32_bf16 v[110:113], v[156:159], v[196:199], v[110:113]
	v_mfma_f32_16x16x32_bf16 v[106:109], v[164:167], v[196:199], v[106:109]
	v_mfma_f32_16x16x32_bf16 v[94:97], v[156:159], v[204:207], v[94:97]
	v_mfma_f32_16x16x32_bf16 v[90:93], v[164:167], v[204:207], v[90:93]
	v_mfma_f32_16x16x32_bf16 v[78:81], v[156:159], v[212:215], v[78:81]
	v_mfma_f32_16x16x32_bf16 v[74:77], v[164:167], v[212:215], v[74:77]
	s_setprio 0
	s_setprio 1
	v_mfma_f32_16x16x32_bf16 v[118:121], v[168:171], v[184:187], v[118:121]
	v_mfma_f32_16x16x32_bf16 v[114:117], v[176:179], v[184:187], v[114:117]
	v_mfma_f32_16x16x32_bf16 v[102:105], v[168:171], v[192:195], v[102:105]
	v_mfma_f32_16x16x32_bf16 v[98:101], v[176:179], v[192:195], v[98:101]
	v_mfma_f32_16x16x32_bf16 v[86:89], v[168:171], v[200:203], v[86:89]
	v_mfma_f32_16x16x32_bf16 v[82:85], v[176:179], v[200:203], v[82:85]
	v_mfma_f32_16x16x32_bf16 v[70:73], v[168:171], v[208:211], v[70:73]
	v_mfma_f32_16x16x32_bf16 v[66:69], v[176:179], v[208:211], v[66:69]
	v_mfma_f32_16x16x32_bf16 v[118:121], v[172:175], v[188:191], v[118:121]
	v_mfma_f32_16x16x32_bf16 v[114:117], v[180:183], v[188:191], v[114:117]
	v_mfma_f32_16x16x32_bf16 v[102:105], v[172:175], v[196:199], v[102:105]
	v_mfma_f32_16x16x32_bf16 v[98:101], v[180:183], v[196:199], v[98:101]
	v_mfma_f32_16x16x32_bf16 v[86:89], v[172:175], v[204:207], v[86:89]
	v_mfma_f32_16x16x32_bf16 v[82:85], v[180:183], v[204:207], v[82:85]
	v_mfma_f32_16x16x32_bf16 v[70:73], v[172:175], v[212:215], v[70:73]
	v_mfma_f32_16x16x32_bf16 v[66:69], v[180:183], v[212:215], v[66:69]
	s_setprio 0
	s_barrier
	s_add_i32 s36, s80, s44
	v_lshl_add_u64 v[216:217], v[216:217], 0, s[16:17]
	s_mov_b32 m0, s36
	ds_read_b128 v[184:187], v151 offset:49152
	ds_read_b128 v[188:191], v151 offset:50176
	ds_read_b128 v[192:195], v151 offset:51200
	ds_read_b128 v[196:199], v151 offset:52224
	ds_read_b128 v[200:203], v151 offset:53248
	ds_read_b128 v[204:207], v151 offset:54272
	ds_read_b128 v[208:211], v151 offset:55296
	ds_read_b128 v[212:215], v151 offset:56320
	global_load_lds_dwordx4 v[216:217], off
	v_lshl_add_u64 v[216:217], v[218:219], 0, s[16:17]
	s_add_i32 m0, s36, 0x2000
	s_add_i32 s36, s81, s44
	global_load_lds_dwordx4 v[216:217], off
	v_lshl_add_u64 v[216:217], v[220:221], 0, s[16:17]
	s_mov_b32 m0, s36
	s_nop 0
	global_load_lds_dwordx4 v[216:217], off
	v_lshl_add_u64 v[216:217], v[222:223], 0, s[16:17]
	s_add_i32 m0, s36, 0x2000
	s_nop 0
	global_load_lds_dwordx4 v[216:217], off
	v_lshl_add_u64 v[216:217], v[224:225], 0, s[16:17]
	s_mov_b32 m0, s56
	s_nop 0
	global_load_lds_dwordx4 v[216:217], off
	v_lshl_add_u64 v[216:217], v[226:227], 0, s[16:17]
	s_mov_b32 m0, s57
	s_nop 0
	global_load_lds_dwordx4 v[216:217], off
	s_waitcnt vmcnt(8)
	s_waitcnt lgkmcnt(0)
	s_setprio 1
	s_waitcnt lgkmcnt(0)
	v_mfma_f32_16x16x32_bf16 v[62:65], v[152:155], v[184:187], v[62:65]
	v_mfma_f32_16x16x32_bf16 v[58:61], v[160:163], v[184:187], v[58:61]
	v_mfma_f32_16x16x32_bf16 v[46:49], v[152:155], v[192:195], v[46:49]
	v_mfma_f32_16x16x32_bf16 v[42:45], v[160:163], v[192:195], v[42:45]
	s_barrier
	v_mfma_f32_16x16x32_bf16 v[30:33], v[152:155], v[200:203], v[30:33]
	v_mfma_f32_16x16x32_bf16 v[26:29], v[160:163], v[200:203], v[26:29]
	v_mfma_f32_16x16x32_bf16 v[14:17], v[152:155], v[208:211], v[14:17]
	v_mfma_f32_16x16x32_bf16 v[10:13], v[160:163], v[208:211], v[10:13]
	v_mfma_f32_16x16x32_bf16 v[62:65], v[156:159], v[188:191], v[62:65]
	v_mfma_f32_16x16x32_bf16 v[58:61], v[164:167], v[188:191], v[58:61]
	v_mfma_f32_16x16x32_bf16 v[46:49], v[156:159], v[196:199], v[46:49]
	v_mfma_f32_16x16x32_bf16 v[42:45], v[164:167], v[196:199], v[42:45]
	v_mfma_f32_16x16x32_bf16 v[30:33], v[156:159], v[204:207], v[30:33]
	v_mfma_f32_16x16x32_bf16 v[26:29], v[164:167], v[204:207], v[26:29]
	v_mfma_f32_16x16x32_bf16 v[14:17], v[156:159], v[212:215], v[14:17]
	v_mfma_f32_16x16x32_bf16 v[10:13], v[164:167], v[212:215], v[10:13]
	s_setprio 0
	s_setprio 1
	v_mfma_f32_16x16x32_bf16 v[54:57], v[168:171], v[184:187], v[54:57]
	v_mfma_f32_16x16x32_bf16 v[50:53], v[176:179], v[184:187], v[50:53]
	v_mfma_f32_16x16x32_bf16 v[38:41], v[168:171], v[192:195], v[38:41]
	v_mfma_f32_16x16x32_bf16 v[34:37], v[176:179], v[192:195], v[34:37]
	v_mfma_f32_16x16x32_bf16 v[22:25], v[168:171], v[200:203], v[22:25]
	v_mfma_f32_16x16x32_bf16 v[18:21], v[176:179], v[200:203], v[18:21]
	v_mfma_f32_16x16x32_bf16 v[6:9], v[168:171], v[208:211], v[6:9]
	v_mfma_f32_16x16x32_bf16 v[2:5], v[176:179], v[208:211], v[2:5]
	v_mfma_f32_16x16x32_bf16 v[54:57], v[172:175], v[188:191], v[54:57]
	v_mfma_f32_16x16x32_bf16 v[50:53], v[180:183], v[188:191], v[50:53]
	v_mfma_f32_16x16x32_bf16 v[38:41], v[172:175], v[196:199], v[38:41]
	v_mfma_f32_16x16x32_bf16 v[34:37], v[180:183], v[196:199], v[34:37]
	v_mfma_f32_16x16x32_bf16 v[22:25], v[172:175], v[204:207], v[22:25]
	v_mfma_f32_16x16x32_bf16 v[18:21], v[180:183], v[204:207], v[18:21]
	v_mfma_f32_16x16x32_bf16 v[6:9], v[172:175], v[212:215], v[6:9]
	v_mfma_f32_16x16x32_bf16 v[2:5], v[180:183], v[212:215], v[2:5]
	s_setprio 0
	s_barrier
	s_add_u32 s34, s34, 0x100
	s_addc_u32 s35, s35, 0
	s_add_u32 s67, s67, 0x100
	s_addc_u32 s68, s68, 0
	s_cmp_ge_i32 s69, s58
	s_mov_b32 s36, s69
	s_cbranch_scc0 .LBB0_1514

.LBB0_1754:
	v_add_u32_e32 v158, s80, v229
	v_add_u32_e32 v174, s81, v229
	ds_read_b128 v[146:149], v158
	ds_read_b128 v[150:153], v158 offset:1024
	ds_read_b128 v[154:157], v158 offset:2048
	ds_read_b128 v[158:161], v158 offset:3072
	ds_read_b128 v[162:165], v174
	ds_read_b128 v[166:169], v174 offset:1024
	ds_read_b128 v[170:173], v174 offset:2048
	ds_read_b128 v[174:177], v174 offset:3072
	s_add_i32 s88, s44, 2
	s_add_u32 s89, s42, 0x80
	s_addc_u32 s45, s43, 0
	s_cmp_eq_u32 s67, s44
	s_cselect_b32 s44, s4, s89
	s_cselect_b32 s45, s5, s45
	s_cselect_b32 s91, s39, s87
	s_cselect_b32 s90, s38, s86
	v_lshl_add_u64 v[210:211], s[42:43], 0, v[138:139]
	s_add_i32 m0, s55, 0xc000
	ds_read_b128 v[178:181], v231
	ds_read_b128 v[182:185], v231 offset:1024
	ds_read_b128 v[186:189], v231 offset:2048
	ds_read_b128 v[190:193], v231 offset:3072
	ds_read_b128 v[194:197], v231 offset:4096
	ds_read_b128 v[198:201], v231 offset:5120
	ds_read_b128 v[202:205], v231 offset:6144
	ds_read_b128 v[206:209], v231 offset:7168
	global_load_lds_dwordx4 v[210:211], off
	v_lshl_add_u64 v[210:211], s[42:43], 0, v[140:141]
	s_add_i32 m0, s55, 0xe000
	s_nop 0
	global_load_lds_dwordx4 v[210:211], off
	s_waitcnt vmcnt(8)
	s_waitcnt lgkmcnt(0)
	s_setprio 1
	s_waitcnt lgkmcnt(0)
	v_mfma_i32_16x16x64_i8 v[126:129], v[146:149], v[178:181], v[126:129]
	v_mfma_i32_16x16x64_i8 v[122:125], v[154:157], v[178:181], v[122:125]
	v_mfma_i32_16x16x64_i8 v[118:121], v[146:149], v[186:189], v[118:121]
	v_mfma_i32_16x16x64_i8 v[114:117], v[154:157], v[186:189], v[114:117]
	s_barrier
	v_mfma_i32_16x16x64_i8 v[106:109], v[146:149], v[194:197], v[106:109]
	v_mfma_i32_16x16x64_i8 v[98:101], v[154:157], v[194:197], v[98:101]
	v_mfma_i32_16x16x64_i8 v[90:93], v[146:149], v[202:205], v[90:93]
	v_mfma_i32_16x16x64_i8 v[82:85], v[154:157], v[202:205], v[82:85]
	v_mfma_i32_16x16x64_i8 v[126:129], v[150:153], v[182:185], v[126:129]
	v_mfma_i32_16x16x64_i8 v[122:125], v[158:161], v[182:185], v[122:125]
	v_mfma_i32_16x16x64_i8 v[118:121], v[150:153], v[190:193], v[118:121]
	v_mfma_i32_16x16x64_i8 v[114:117], v[158:161], v[190:193], v[114:117]
	v_mfma_i32_16x16x64_i8 v[106:109], v[150:153], v[198:201], v[106:109]
	v_mfma_i32_16x16x64_i8 v[98:101], v[158:161], v[198:201], v[98:101]
	v_mfma_i32_16x16x64_i8 v[90:93], v[150:153], v[206:209], v[90:93]
	v_mfma_i32_16x16x64_i8 v[82:85], v[158:161], v[206:209], v[82:85]
	s_setprio 0
	s_setprio 1
	v_mfma_i32_16x16x64_i8 v[110:113], v[162:165], v[178:181], v[110:113]
	v_mfma_i32_16x16x64_i8 v[102:105], v[170:173], v[178:181], v[102:105]
	v_mfma_i32_16x16x64_i8 v[94:97], v[162:165], v[186:189], v[94:97]
	v_mfma_i32_16x16x64_i8 v[86:89], v[170:173], v[186:189], v[86:89]
	v_mfma_i32_16x16x64_i8 v[78:81], v[162:165], v[194:197], v[78:81]
	v_mfma_i32_16x16x64_i8 v[74:77], v[170:173], v[194:197], v[74:77]
	v_mfma_i32_16x16x64_i8 v[70:73], v[162:165], v[202:205], v[70:73]
	v_mfma_i32_16x16x64_i8 v[66:69], v[170:173], v[202:205], v[66:69]
	v_mfma_i32_16x16x64_i8 v[110:113], v[166:169], v[182:185], v[110:113]
	v_mfma_i32_16x16x64_i8 v[102:105], v[174:177], v[182:185], v[102:105]
	v_mfma_i32_16x16x64_i8 v[94:97], v[166:169], v[190:193], v[94:97]
	v_mfma_i32_16x16x64_i8 v[86:89], v[174:177], v[190:193], v[86:89]
	v_mfma_i32_16x16x64_i8 v[78:81], v[166:169], v[198:201], v[78:81]
	v_mfma_i32_16x16x64_i8 v[74:77], v[174:177], v[198:201], v[74:77]
	v_mfma_i32_16x16x64_i8 v[70:73], v[166:169], v[206:209], v[70:73]
	v_mfma_i32_16x16x64_i8 v[66:69], v[174:177], v[206:209], v[66:69]
	s_setprio 0
	s_barrier
	s_add_i32 s89, s80, s54
	v_lshl_add_u64 v[210:211], s[90:91], 0, v[132:133]
	s_mov_b32 m0, s89
	ds_read_b128 v[178:181], v231 offset:16384
	ds_read_b128 v[182:185], v231 offset:17408
	ds_read_b128 v[186:189], v231 offset:18432
	ds_read_b128 v[190:193], v231 offset:19456
	ds_read_b128 v[194:197], v231 offset:20480
	ds_read_b128 v[198:201], v231 offset:21504
	ds_read_b128 v[202:205], v231 offset:22528
	ds_read_b128 v[206:209], v231 offset:23552
	global_load_lds_dwordx4 v[210:211], off
	s_add_i32 m0, s89, 0x2000
	v_lshl_add_u64 v[212:213], s[90:91], 0, v[136:137]
	s_add_u32 s90, s90, s8
	s_addc_u32 s91, s91, s9
	s_add_i32 s89, s81, s54
	global_load_lds_dwordx4 v[212:213], off
	v_lshl_add_u64 v[214:215], s[90:91], 0, v[132:133]
	s_mov_b32 m0, s89
	v_lshl_add_u64 v[216:217], s[90:91], 0, v[136:137]
	global_load_lds_dwordx4 v[214:215], off
	s_add_i32 m0, s89, 0x2000
	v_lshl_add_u64 v[218:219], s[44:45], 0, v[130:131]
	global_load_lds_dwordx4 v[216:217], off
	s_mov_b32 m0, s55
	v_lshl_add_u64 v[220:221], s[44:45], 0, v[134:135]
	global_load_lds_dwordx4 v[218:219], off
	s_mov_b32 m0, s56
	s_nop 0
	global_load_lds_dwordx4 v[220:221], off
	s_waitcnt vmcnt(8)
	s_waitcnt lgkmcnt(0)
	s_setprio 1
	s_waitcnt lgkmcnt(0)
	v_mfma_i32_16x16x64_i8 v[62:65], v[146:149], v[178:181], v[62:65]
	v_mfma_i32_16x16x64_i8 v[58:61], v[154:157], v[178:181], v[58:61]
	v_mfma_i32_16x16x64_i8 v[54:57], v[146:149], v[186:189], v[54:57]
	v_mfma_i32_16x16x64_i8 v[50:53], v[154:157], v[186:189], v[50:53]
	s_barrier
	v_mfma_i32_16x16x64_i8 v[42:45], v[146:149], v[194:197], v[42:45]
	v_mfma_i32_16x16x64_i8 v[34:37], v[154:157], v[194:197], v[34:37]
	v_mfma_i32_16x16x64_i8 v[26:29], v[146:149], v[202:205], v[26:29]
	v_mfma_i32_16x16x64_i8 v[18:21], v[154:157], v[202:205], v[18:21]
	v_mfma_i32_16x16x64_i8 v[62:65], v[150:153], v[182:185], v[62:65]
	v_mfma_i32_16x16x64_i8 v[58:61], v[158:161], v[182:185], v[58:61]
	v_mfma_i32_16x16x64_i8 v[54:57], v[150:153], v[190:193], v[54:57]
	v_mfma_i32_16x16x64_i8 v[50:53], v[158:161], v[190:193], v[50:53]
	v_mfma_i32_16x16x64_i8 v[42:45], v[150:153], v[198:201], v[42:45]
	v_mfma_i32_16x16x64_i8 v[34:37], v[158:161], v[198:201], v[34:37]
	v_mfma_i32_16x16x64_i8 v[26:29], v[150:153], v[206:209], v[26:29]
	v_mfma_i32_16x16x64_i8 v[18:21], v[158:161], v[206:209], v[18:21]
	s_setprio 0
	s_setprio 1
	v_mfma_i32_16x16x64_i8 v[46:49], v[162:165], v[178:181], v[46:49]
	v_mfma_i32_16x16x64_i8 v[38:41], v[170:173], v[178:181], v[38:41]
	v_mfma_i32_16x16x64_i8 v[30:33], v[162:165], v[186:189], v[30:33]
	v_mfma_i32_16x16x64_i8 v[22:25], v[170:173], v[186:189], v[22:25]
	v_mfma_i32_16x16x64_i8 v[14:17], v[162:165], v[194:197], v[14:17]
	v_mfma_i32_16x16x64_i8 v[10:13], v[170:173], v[194:197], v[10:13]
	v_mfma_i32_16x16x64_i8 v[6:9], v[162:165], v[202:205], v[6:9]
	v_mfma_i32_16x16x64_i8 v[2:5], v[170:173], v[202:205], v[2:5]
	v_mfma_i32_16x16x64_i8 v[46:49], v[166:169], v[182:185], v[46:49]
	v_mfma_i32_16x16x64_i8 v[38:41], v[174:177], v[182:185], v[38:41]
	v_mfma_i32_16x16x64_i8 v[30:33], v[166:169], v[190:193], v[30:33]
	v_mfma_i32_16x16x64_i8 v[22:25], v[174:177], v[190:193], v[22:25]
	v_mfma_i32_16x16x64_i8 v[14:17], v[166:169], v[198:201], v[14:17]
	v_mfma_i32_16x16x64_i8 v[10:13], v[174:177], v[198:201], v[10:13]
	v_mfma_i32_16x16x64_i8 v[6:9], v[166:169], v[206:209], v[6:9]
	v_mfma_i32_16x16x64_i8 v[2:5], v[174:177], v[206:209], v[2:5]
	s_setprio 0
	s_barrier
	s_add_i32 s89, 0, 0x18000
	s_add_i32 s90, 0, 0x1c000
	v_add_u32_e32 v158, s89, v229
	v_add_u32_e32 v174, s90, v229
	ds_read_b128 v[146:149], v158
	ds_read_b128 v[150:153], v158 offset:1024
	ds_read_b128 v[154:157], v158 offset:2048
	ds_read_b128 v[158:161], v158 offset:3072
	ds_read_b128 v[162:165], v174
	ds_read_b128 v[166:169], v174 offset:1024
	ds_read_b128 v[170:173], v174 offset:2048
	ds_read_b128 v[174:177], v174 offset:3072
	s_add_u32 s44, s44, s8
	s_addc_u32 s45, s45, s9
	s_mov_b32 m0, s57
	v_lshl_add_u64 v[222:223], s[44:45], 0, v[130:131]
	ds_read_b128 v[178:181], v231 offset:32768
	ds_read_b128 v[182:185], v231 offset:33792
	ds_read_b128 v[186:189], v231 offset:34816
	ds_read_b128 v[190:193], v231 offset:35840
	ds_read_b128 v[194:197], v231 offset:36864
	ds_read_b128 v[198:201], v231 offset:37888
	ds_read_b128 v[202:205], v231 offset:38912
	ds_read_b128 v[206:209], v231 offset:39936
	global_load_lds_dwordx4 v[222:223], off
	v_lshl_add_u64 v[222:223], s[44:45], 0, v[134:135]
	s_mov_b32 m0, s58
	s_nop 0
	global_load_lds_dwordx4 v[222:223], off
	s_waitcnt vmcnt(8)
	s_waitcnt lgkmcnt(0)
	s_setprio 1
	s_waitcnt lgkmcnt(0)
	v_mfma_i32_16x16x64_i8 v[126:129], v[146:149], v[178:181], v[126:129]
	v_mfma_i32_16x16x64_i8 v[122:125], v[154:157], v[178:181], v[122:125]
	v_mfma_i32_16x16x64_i8 v[118:121], v[146:149], v[186:189], v[118:121]
	v_mfma_i32_16x16x64_i8 v[114:117], v[154:157], v[186:189], v[114:117]
	s_barrier
	v_mfma_i32_16x16x64_i8 v[106:109], v[146:149], v[194:197], v[106:109]
	v_mfma_i32_16x16x64_i8 v[98:101], v[154:157], v[194:197], v[98:101]
	v_mfma_i32_16x16x64_i8 v[90:93], v[146:149], v[202:205], v[90:93]
	v_mfma_i32_16x16x64_i8 v[82:85], v[154:157], v[202:205], v[82:85]
	v_mfma_i32_16x16x64_i8 v[126:129], v[150:153], v[182:185], v[126:129]
	v_mfma_i32_16x16x64_i8 v[122:125], v[158:161], v[182:185], v[122:125]
	v_mfma_i32_16x16x64_i8 v[118:121], v[150:153], v[190:193], v[118:121]
	v_mfma_i32_16x16x64_i8 v[114:117], v[158:161], v[190:193], v[114:117]
	v_mfma_i32_16x16x64_i8 v[106:109], v[150:153], v[198:201], v[106:109]
	v_mfma_i32_16x16x64_i8 v[98:101], v[158:161], v[198:201], v[98:101]
	v_mfma_i32_16x16x64_i8 v[90:93], v[150:153], v[206:209], v[90:93]
	v_mfma_i32_16x16x64_i8 v[82:85], v[158:161], v[206:209], v[82:85]
	s_setprio 0
	s_setprio 1
	v_mfma_i32_16x16x64_i8 v[110:113], v[162:165], v[178:181], v[110:113]
	v_mfma_i32_16x16x64_i8 v[102:105], v[170:173], v[178:181], v[102:105]
	v_mfma_i32_16x16x64_i8 v[94:97], v[162:165], v[186:189], v[94:97]
	v_mfma_i32_16x16x64_i8 v[86:89], v[170:173], v[186:189], v[86:89]
	v_mfma_i32_16x16x64_i8 v[78:81], v[162:165], v[194:197], v[78:81]
	v_mfma_i32_16x16x64_i8 v[74:77], v[170:173], v[194:197], v[74:77]
	v_mfma_i32_16x16x64_i8 v[70:73], v[162:165], v[202:205], v[70:73]
	v_mfma_i32_16x16x64_i8 v[66:69], v[170:173], v[202:205], v[66:69]
	v_mfma_i32_16x16x64_i8 v[110:113], v[166:169], v[182:185], v[110:113]
	v_mfma_i32_16x16x64_i8 v[102:105], v[174:177], v[182:185], v[102:105]
	v_mfma_i32_16x16x64_i8 v[94:97], v[166:169], v[190:193], v[94:97]
	v_mfma_i32_16x16x64_i8 v[86:89], v[174:177], v[190:193], v[86:89]
	v_mfma_i32_16x16x64_i8 v[78:81], v[166:169], v[198:201], v[78:81]
	v_mfma_i32_16x16x64_i8 v[74:77], v[174:177], v[198:201], v[74:77]
	v_mfma_i32_16x16x64_i8 v[70:73], v[166:169], v[206:209], v[70:73]
	v_mfma_i32_16x16x64_i8 v[66:69], v[174:177], v[206:209], v[66:69]
	s_setprio 0
	s_barrier
	s_add_i32 s44, s89, s54
	v_lshl_add_u64 v[210:211], v[210:211], 0, s[30:31]
	s_mov_b32 m0, s44
	ds_read_b128 v[178:181], v231 offset:49152
	ds_read_b128 v[182:185], v231 offset:50176
	ds_read_b128 v[186:189], v231 offset:51200
	ds_read_b128 v[190:193], v231 offset:52224
	ds_read_b128 v[194:197], v231 offset:53248
	ds_read_b128 v[198:201], v231 offset:54272
	ds_read_b128 v[202:205], v231 offset:55296
	ds_read_b128 v[206:209], v231 offset:56320
	global_load_lds_dwordx4 v[210:211], off
	v_lshl_add_u64 v[210:211], v[212:213], 0, s[30:31]
	s_add_i32 m0, s44, 0x2000
	s_add_i32 s44, s90, s54
	global_load_lds_dwordx4 v[210:211], off
	v_lshl_add_u64 v[210:211], v[214:215], 0, s[30:31]
	s_mov_b32 m0, s44
	s_nop 0
	global_load_lds_dwordx4 v[210:211], off
	v_lshl_add_u64 v[210:211], v[216:217], 0, s[30:31]
	s_add_i32 m0, s44, 0x2000
	s_nop 0
	global_load_lds_dwordx4 v[210:211], off
	v_lshl_add_u64 v[210:211], v[218:219], 0, s[30:31]
	s_mov_b32 m0, s63
	s_nop 0
	global_load_lds_dwordx4 v[210:211], off
	v_lshl_add_u64 v[210:211], v[220:221], 0, s[30:31]
	s_mov_b32 m0, s64
	s_nop 0
	global_load_lds_dwordx4 v[210:211], off
	s_waitcnt vmcnt(8)
	s_waitcnt lgkmcnt(0)
	s_setprio 1
	s_waitcnt lgkmcnt(0)
	v_mfma_i32_16x16x64_i8 v[62:65], v[146:149], v[178:181], v[62:65]
	v_mfma_i32_16x16x64_i8 v[58:61], v[154:157], v[178:181], v[58:61]
	v_mfma_i32_16x16x64_i8 v[54:57], v[146:149], v[186:189], v[54:57]
	v_mfma_i32_16x16x64_i8 v[50:53], v[154:157], v[186:189], v[50:53]
	s_barrier
	v_mfma_i32_16x16x64_i8 v[42:45], v[146:149], v[194:197], v[42:45]
	v_mfma_i32_16x16x64_i8 v[34:37], v[154:157], v[194:197], v[34:37]
	v_mfma_i32_16x16x64_i8 v[26:29], v[146:149], v[202:205], v[26:29]
	v_mfma_i32_16x16x64_i8 v[18:21], v[154:157], v[202:205], v[18:21]
	v_mfma_i32_16x16x64_i8 v[62:65], v[150:153], v[182:185], v[62:65]
	v_mfma_i32_16x16x64_i8 v[58:61], v[158:161], v[182:185], v[58:61]
	v_mfma_i32_16x16x64_i8 v[54:57], v[150:153], v[190:193], v[54:57]
	v_mfma_i32_16x16x64_i8 v[50:53], v[158:161], v[190:193], v[50:53]
	v_mfma_i32_16x16x64_i8 v[42:45], v[150:153], v[198:201], v[42:45]
	v_mfma_i32_16x16x64_i8 v[34:37], v[158:161], v[198:201], v[34:37]
	v_mfma_i32_16x16x64_i8 v[26:29], v[150:153], v[206:209], v[26:29]
	v_mfma_i32_16x16x64_i8 v[18:21], v[158:161], v[206:209], v[18:21]
	s_setprio 0
	s_setprio 1
	v_mfma_i32_16x16x64_i8 v[46:49], v[162:165], v[178:181], v[46:49]
	v_mfma_i32_16x16x64_i8 v[38:41], v[170:173], v[178:181], v[38:41]
	v_mfma_i32_16x16x64_i8 v[30:33], v[162:165], v[186:189], v[30:33]
	v_mfma_i32_16x16x64_i8 v[22:25], v[170:173], v[186:189], v[22:25]
	v_mfma_i32_16x16x64_i8 v[14:17], v[162:165], v[194:197], v[14:17]
	v_mfma_i32_16x16x64_i8 v[10:13], v[170:173], v[194:197], v[10:13]
	v_mfma_i32_16x16x64_i8 v[6:9], v[162:165], v[202:205], v[6:9]
	v_mfma_i32_16x16x64_i8 v[2:5], v[170:173], v[202:205], v[2:5]
	v_mfma_i32_16x16x64_i8 v[46:49], v[166:169], v[182:185], v[46:49]
	v_mfma_i32_16x16x64_i8 v[38:41], v[174:177], v[182:185], v[38:41]
	v_mfma_i32_16x16x64_i8 v[30:33], v[166:169], v[190:193], v[30:33]
	v_mfma_i32_16x16x64_i8 v[22:25], v[174:177], v[190:193], v[22:25]
	v_mfma_i32_16x16x64_i8 v[14:17], v[166:169], v[198:201], v[14:17]
	v_mfma_i32_16x16x64_i8 v[10:13], v[174:177], v[198:201], v[10:13]
	v_mfma_i32_16x16x64_i8 v[6:9], v[166:169], v[206:209], v[6:9]
	v_mfma_i32_16x16x64_i8 v[2:5], v[174:177], v[206:209], v[2:5]
	s_setprio 0
	s_barrier
	s_add_u32 s42, s42, 0x100
	s_addc_u32 s43, s43, 0
	s_add_u32 s86, s86, 0x100
	s_addc_u32 s87, s87, 0
	s_cmp_ge_i32 s88, s66
	s_mov_b32 s44, s88
	s_cbranch_scc0 .LBB0_1754
	v_cvt_f32_i32_e32 v214, v126
	v_cvt_f32_i32_e32 v215, v127
	v_cvt_f32_i32_e32 v212, v128
	v_cvt_f32_i32_e32 v213, v129
	v_cvt_f32_i32_e32 v218, v122
	v_cvt_f32_i32_e32 v219, v123
	v_cvt_f32_i32_e32 v216, v124
	v_cvt_f32_i32_e32 v217, v125
	v_cvt_f32_i32_e32 v222, v110
	v_cvt_f32_i32_e32 v223, v111
	v_cvt_f32_i32_e32 v220, v112
	v_cvt_f32_i32_e32 v221, v113
	v_cvt_f32_i32_e32 v226, v102
	v_cvt_f32_i32_e32 v227, v103
	v_cvt_f32_i32_e32 v224, v104
	v_cvt_f32_i32_e32 v225, v105
	v_cvt_f32_i32_e32 v194, v118
	v_cvt_f32_i32_e32 v195, v119
	v_cvt_f32_i32_e32 v192, v120
	v_cvt_f32_i32_e32 v193, v121
	v_cvt_f32_i32_e32 v200, v114
	v_cvt_f32_i32_e32 v201, v115
	v_cvt_f32_i32_e32 v198, v116
	v_cvt_f32_i32_e32 v199, v117
	v_cvt_f32_i32_e32 v206, v94
	v_cvt_f32_i32_e32 v207, v95
	v_cvt_f32_i32_e32 v202, v96
	v_cvt_f32_i32_e32 v203, v97
	v_cvt_f32_i32_e32 v208, v86
	v_cvt_f32_i32_e32 v209, v87
	v_cvt_f32_i32_e32 v204, v88
	v_cvt_f32_i32_e32 v205, v89
	v_cvt_f32_i32_e32 v178, v106
	v_cvt_f32_i32_e32 v179, v107
	v_cvt_f32_i32_e32 v176, v108
	v_cvt_f32_i32_e32 v177, v109
	v_cvt_f32_i32_e32 v182, v98
	v_cvt_f32_i32_e32 v183, v99
	v_cvt_f32_i32_e32 v180, v100
	v_cvt_f32_i32_e32 v181, v101
	v_cvt_f32_i32_e32 v188, v78
	v_cvt_f32_i32_e32 v189, v79
	v_cvt_f32_i32_e32 v184, v80
	v_cvt_f32_i32_e32 v185, v81
	v_cvt_f32_i32_e32 v190, v74
	v_cvt_f32_i32_e32 v191, v75
	v_cvt_f32_i32_e32 v186, v76
	v_cvt_f32_i32_e32 v187, v77
	v_cvt_f32_i32_e32 v162, v90
	v_cvt_f32_i32_e32 v163, v91
	v_cvt_f32_i32_e32 v160, v92
	v_cvt_f32_i32_e32 v161, v93
	v_cvt_f32_i32_e32 v166, v82
	v_cvt_f32_i32_e32 v167, v83
	v_cvt_f32_i32_e32 v164, v84
	v_cvt_f32_i32_e32 v165, v85
	v_cvt_f32_i32_e32 v172, v70
	v_cvt_f32_i32_e32 v173, v71
	v_cvt_f32_i32_e32 v168, v72
	v_cvt_f32_i32_e32 v169, v73
	v_cvt_f32_i32_e32 v174, v66
	v_cvt_f32_i32_e32 v175, v67
	v_cvt_f32_i32_e32 v170, v68
	v_cvt_f32_i32_e32 v171, v69
	v_cvt_f32_i32_e32 v146, v62
	v_cvt_f32_i32_e32 v147, v63
	v_cvt_f32_i32_e32 v128, v64
	v_cvt_f32_i32_e32 v129, v65
	v_cvt_f32_i32_e32 v150, v58
	v_cvt_f32_i32_e32 v151, v59
	v_cvt_f32_i32_e32 v148, v60
	v_cvt_f32_i32_e32 v149, v61
	v_cvt_f32_i32_e32 v156, v46
	v_cvt_f32_i32_e32 v157, v47
	v_cvt_f32_i32_e32 v152, v48
	v_cvt_f32_i32_e32 v153, v49
	v_cvt_f32_i32_e32 v158, v38
	v_cvt_f32_i32_e32 v159, v39
	v_cvt_f32_i32_e32 v154, v40
	v_cvt_f32_i32_e32 v155, v41
	v_cvt_f32_i32_e32 v114, v54
	v_cvt_f32_i32_e32 v115, v55
	v_cvt_f32_i32_e32 v112, v56
	v_cvt_f32_i32_e32 v113, v57
	v_cvt_f32_i32_e32 v118, v50
	v_cvt_f32_i32_e32 v119, v51
	v_cvt_f32_i32_e32 v116, v52
	v_cvt_f32_i32_e32 v117, v53
	v_cvt_f32_i32_e32 v124, v30
	v_cvt_f32_i32_e32 v125, v31
	v_cvt_f32_i32_e32 v120, v32
	v_cvt_f32_i32_e32 v121, v33
	v_cvt_f32_i32_e32 v126, v22
	v_cvt_f32_i32_e32 v127, v23
	v_cvt_f32_i32_e32 v122, v24
	v_cvt_f32_i32_e32 v123, v25
	v_cvt_f32_i32_e32 v64, v42
	v_cvt_f32_i32_e32 v65, v43
	v_cvt_f32_i32_e32 v62, v44
	v_cvt_f32_i32_e32 v63, v45
	v_cvt_f32_i32_e32 v68, v34
	v_cvt_f32_i32_e32 v69, v35
	v_cvt_f32_i32_e32 v66, v36
	v_cvt_f32_i32_e32 v67, v37
	v_cvt_f32_i32_e32 v74, v14
	v_cvt_f32_i32_e32 v75, v15
	v_cvt_f32_i32_e32 v70, v16
	v_cvt_f32_i32_e32 v71, v17
	v_cvt_f32_i32_e32 v76, v10
	v_cvt_f32_i32_e32 v77, v11
	v_cvt_f32_i32_e32 v72, v12
	v_cvt_f32_i32_e32 v73, v13
	v_cvt_f32_i32_e32 v48, v26
	v_cvt_f32_i32_e32 v49, v27
	v_cvt_f32_i32_e32 v46, v28
	v_cvt_f32_i32_e32 v47, v29
	v_cvt_f32_i32_e32 v52, v18
	v_cvt_f32_i32_e32 v53, v19
	v_cvt_f32_i32_e32 v50, v20
	v_cvt_f32_i32_e32 v51, v21
	v_cvt_f32_i32_e32 v58, v6
	v_cvt_f32_i32_e32 v59, v7
	v_cvt_f32_i32_e32 v54, v8
	v_cvt_f32_i32_e32 v55, v9
	v_cvt_f32_i32_e32 v60, v2
	v_cvt_f32_i32_e32 v61, v3
	v_cvt_f32_i32_e32 v56, v4
	v_cvt_f32_i32_e32 v57, v5

.LBB0_1939:
	v_add_u32_e32 v138, s62, v188
	ds_read_b128 v[148:151], v138
	ds_read_b128 v[152:155], v138 offset:1024
	ds_read_b128 v[156:159], v138 offset:2048
	ds_read_b128 v[160:163], v138 offset:3072
	v_add_u32_e32 v138, s63, v188
	ds_read_b128 v[164:167], v138
	ds_read_b128 v[168:171], v138 offset:1024
	ds_read_b128 v[172:175], v138 offset:2048
	ds_read_b128 v[176:179], v138 offset:3072
	s_add_i32 s66, s28, 2
	s_add_u32 s67, s26, 0x80
	s_addc_u32 s29, s27, 0
	s_cmp_eq_u32 s60, s28
	s_cselect_b32 s28, s2, s67
	s_cselect_b32 s29, s3, s29
	s_cselect_b32 s69, s25, s35
	s_cselect_b32 s68, s24, s34
	v_lshl_add_u64 v[184:185], s[26:27], 0, v[140:141]
	s_add_i32 m0, s44, 0xc000
	ds_read_b128 v[180:183], v189
	ds_read_b128 v[190:193], v189 offset:1024
	ds_read_b128 v[194:197], v189 offset:2048
	ds_read_b128 v[198:201], v189 offset:3072
	ds_read_b128 v[202:205], v189 offset:4096
	ds_read_b128 v[206:209], v189 offset:5120
	ds_read_b128 v[210:213], v189 offset:6144
	ds_read_b128 v[214:217], v189 offset:7168
	global_load_lds_dwordx4 v[184:185], off
	v_lshl_add_u64 v[184:185], s[26:27], 0, v[142:143]
	s_add_i32 m0, s44, 0xe000
	s_nop 0
	global_load_lds_dwordx4 v[184:185], off
	s_waitcnt vmcnt(8)
	s_waitcnt lgkmcnt(0)
	s_setprio 1
	s_waitcnt lgkmcnt(0)
	v_mfma_i32_16x16x64_i8 v[126:129], v[148:151], v[180:183], v[126:129]
	v_mfma_i32_16x16x64_i8 v[122:125], v[156:159], v[180:183], v[122:125]
	v_mfma_i32_16x16x64_i8 v[118:121], v[148:151], v[194:197], v[118:121]
	v_mfma_i32_16x16x64_i8 v[114:117], v[156:159], v[194:197], v[114:117]
	s_barrier
	v_mfma_i32_16x16x64_i8 v[106:109], v[148:151], v[202:205], v[106:109]
	v_mfma_i32_16x16x64_i8 v[98:101], v[156:159], v[202:205], v[98:101]
	v_mfma_i32_16x16x64_i8 v[90:93], v[148:151], v[210:213], v[90:93]
	v_mfma_i32_16x16x64_i8 v[82:85], v[156:159], v[210:213], v[82:85]
	v_mfma_i32_16x16x64_i8 v[126:129], v[152:155], v[190:193], v[126:129]
	v_mfma_i32_16x16x64_i8 v[122:125], v[160:163], v[190:193], v[122:125]
	v_mfma_i32_16x16x64_i8 v[118:121], v[152:155], v[198:201], v[118:121]
	v_mfma_i32_16x16x64_i8 v[114:117], v[160:163], v[198:201], v[114:117]
	v_mfma_i32_16x16x64_i8 v[106:109], v[152:155], v[206:209], v[106:109]
	v_mfma_i32_16x16x64_i8 v[98:101], v[160:163], v[206:209], v[98:101]
	v_mfma_i32_16x16x64_i8 v[90:93], v[152:155], v[214:217], v[90:93]
	v_mfma_i32_16x16x64_i8 v[82:85], v[160:163], v[214:217], v[82:85]
	s_setprio 0
	s_setprio 1
	v_mfma_i32_16x16x64_i8 v[110:113], v[164:167], v[180:183], v[110:113]
	v_mfma_i32_16x16x64_i8 v[102:105], v[172:175], v[180:183], v[102:105]
	v_mfma_i32_16x16x64_i8 v[94:97], v[164:167], v[194:197], v[94:97]
	v_mfma_i32_16x16x64_i8 v[86:89], v[172:175], v[194:197], v[86:89]
	v_mfma_i32_16x16x64_i8 v[78:81], v[164:167], v[202:205], v[78:81]
	v_mfma_i32_16x16x64_i8 v[74:77], v[172:175], v[202:205], v[74:77]
	v_mfma_i32_16x16x64_i8 v[70:73], v[164:167], v[210:213], v[70:73]
	v_mfma_i32_16x16x64_i8 v[66:69], v[172:175], v[210:213], v[66:69]
	v_mfma_i32_16x16x64_i8 v[110:113], v[168:171], v[190:193], v[110:113]
	v_mfma_i32_16x16x64_i8 v[102:105], v[176:179], v[190:193], v[102:105]
	v_mfma_i32_16x16x64_i8 v[94:97], v[168:171], v[198:201], v[94:97]
	v_mfma_i32_16x16x64_i8 v[86:89], v[176:179], v[198:201], v[86:89]
	v_mfma_i32_16x16x64_i8 v[78:81], v[168:171], v[206:209], v[78:81]
	v_mfma_i32_16x16x64_i8 v[74:77], v[176:179], v[206:209], v[74:77]
	v_mfma_i32_16x16x64_i8 v[70:73], v[168:171], v[214:217], v[70:73]
	v_mfma_i32_16x16x64_i8 v[66:69], v[176:179], v[214:217], v[66:69]
	s_setprio 0
	s_barrier
	s_add_i32 s67, s62, s43
	v_lshl_add_u64 v[184:185], s[68:69], 0, v[132:133]
	s_mov_b32 m0, s67
	ds_read_b128 v[180:183], v189 offset:16384
	ds_read_b128 v[190:193], v189 offset:17408
	ds_read_b128 v[194:197], v189 offset:18432
	ds_read_b128 v[198:201], v189 offset:19456
	ds_read_b128 v[202:205], v189 offset:20480
	ds_read_b128 v[206:209], v189 offset:21504
	ds_read_b128 v[210:213], v189 offset:22528
	ds_read_b128 v[214:217], v189 offset:23552
	global_load_lds_dwordx4 v[184:185], off
	s_add_i32 m0, s67, 0x2000
	v_lshl_add_u64 v[218:219], s[68:69], 0, v[136:137]
	s_add_u32 s68, s68, s6
	s_addc_u32 s69, s69, s7
	s_add_i32 s67, s63, s43
	global_load_lds_dwordx4 v[218:219], off
	v_lshl_add_u64 v[220:221], s[68:69], 0, v[132:133]
	s_mov_b32 m0, s67
	v_lshl_add_u64 v[222:223], s[68:69], 0, v[136:137]
	global_load_lds_dwordx4 v[220:221], off
	s_add_i32 m0, s67, 0x2000
	v_lshl_add_u64 v[224:225], s[28:29], 0, v[130:131]
	global_load_lds_dwordx4 v[222:223], off
	s_mov_b32 m0, s44
	v_lshl_add_u64 v[226:227], s[28:29], 0, v[134:135]
	global_load_lds_dwordx4 v[224:225], off
	s_mov_b32 m0, s45
	s_nop 0
	global_load_lds_dwordx4 v[226:227], off
	s_waitcnt vmcnt(8)
	s_waitcnt lgkmcnt(0)
	s_setprio 1
	s_waitcnt lgkmcnt(0)
	v_mfma_i32_16x16x64_i8 v[62:65], v[148:151], v[180:183], v[62:65]
	v_mfma_i32_16x16x64_i8 v[58:61], v[156:159], v[180:183], v[58:61]
	v_mfma_i32_16x16x64_i8 v[54:57], v[148:151], v[194:197], v[54:57]
	v_mfma_i32_16x16x64_i8 v[50:53], v[156:159], v[194:197], v[50:53]
	s_barrier
	v_mfma_i32_16x16x64_i8 v[42:45], v[148:151], v[202:205], v[42:45]
	v_mfma_i32_16x16x64_i8 v[34:37], v[156:159], v[202:205], v[34:37]
	v_mfma_i32_16x16x64_i8 v[26:29], v[148:151], v[210:213], v[26:29]
	v_mfma_i32_16x16x64_i8 v[18:21], v[156:159], v[210:213], v[18:21]
	v_mfma_i32_16x16x64_i8 v[62:65], v[152:155], v[190:193], v[62:65]
	v_mfma_i32_16x16x64_i8 v[58:61], v[160:163], v[190:193], v[58:61]
	v_mfma_i32_16x16x64_i8 v[54:57], v[152:155], v[198:201], v[54:57]
	v_mfma_i32_16x16x64_i8 v[50:53], v[160:163], v[198:201], v[50:53]
	v_mfma_i32_16x16x64_i8 v[42:45], v[152:155], v[206:209], v[42:45]
	v_mfma_i32_16x16x64_i8 v[34:37], v[160:163], v[206:209], v[34:37]
	v_mfma_i32_16x16x64_i8 v[26:29], v[152:155], v[214:217], v[26:29]
	v_mfma_i32_16x16x64_i8 v[18:21], v[160:163], v[214:217], v[18:21]
	s_setprio 0
	s_setprio 1
	v_mfma_i32_16x16x64_i8 v[46:49], v[164:167], v[180:183], v[46:49]
	v_mfma_i32_16x16x64_i8 v[38:41], v[172:175], v[180:183], v[38:41]
	v_mfma_i32_16x16x64_i8 v[30:33], v[164:167], v[194:197], v[30:33]
	v_mfma_i32_16x16x64_i8 v[22:25], v[172:175], v[194:197], v[22:25]
	v_mfma_i32_16x16x64_i8 v[14:17], v[164:167], v[202:205], v[14:17]
	v_mfma_i32_16x16x64_i8 v[10:13], v[172:175], v[202:205], v[10:13]
	v_mfma_i32_16x16x64_i8 v[6:9], v[164:167], v[210:213], v[6:9]
	v_mfma_i32_16x16x64_i8 v[2:5], v[172:175], v[210:213], v[2:5]
	v_mfma_i32_16x16x64_i8 v[46:49], v[168:171], v[190:193], v[46:49]
	v_mfma_i32_16x16x64_i8 v[38:41], v[176:179], v[190:193], v[38:41]
	v_mfma_i32_16x16x64_i8 v[30:33], v[168:171], v[198:201], v[30:33]
	v_mfma_i32_16x16x64_i8 v[22:25], v[176:179], v[198:201], v[22:25]
	v_mfma_i32_16x16x64_i8 v[14:17], v[168:171], v[206:209], v[14:17]
	v_mfma_i32_16x16x64_i8 v[10:13], v[176:179], v[206:209], v[10:13]
	v_mfma_i32_16x16x64_i8 v[6:9], v[168:171], v[214:217], v[6:9]
	v_mfma_i32_16x16x64_i8 v[2:5], v[176:179], v[214:217], v[2:5]
	s_setprio 0
	s_barrier
	s_add_i32 s67, 0, 0x18000
	v_add_u32_e32 v138, s67, v188
	s_add_i32 s68, 0, 0x1c000
	ds_read_b128 v[148:151], v138
	ds_read_b128 v[152:155], v138 offset:1024
	ds_read_b128 v[156:159], v138 offset:2048
	ds_read_b128 v[160:163], v138 offset:3072
	v_add_u32_e32 v138, s68, v188
	ds_read_b128 v[164:167], v138
	ds_read_b128 v[168:171], v138 offset:1024
	ds_read_b128 v[172:175], v138 offset:2048
	ds_read_b128 v[176:179], v138 offset:3072
	s_add_u32 s28, s28, s6
	s_addc_u32 s29, s29, s7
	s_mov_b32 m0, s46
	v_lshl_add_u64 v[228:229], s[28:29], 0, v[130:131]
	ds_read_b128 v[180:183], v189 offset:32768
	ds_read_b128 v[190:193], v189 offset:33792
	ds_read_b128 v[194:197], v189 offset:34816
	ds_read_b128 v[198:201], v189 offset:35840
	ds_read_b128 v[202:205], v189 offset:36864
	ds_read_b128 v[206:209], v189 offset:37888
	ds_read_b128 v[210:213], v189 offset:38912
	ds_read_b128 v[214:217], v189 offset:39936
	global_load_lds_dwordx4 v[228:229], off
	v_lshl_add_u64 v[228:229], s[28:29], 0, v[134:135]
	s_mov_b32 m0, s47
	s_nop 0
	global_load_lds_dwordx4 v[228:229], off
	s_waitcnt vmcnt(8)
	s_waitcnt lgkmcnt(0)
	s_setprio 1
	s_waitcnt lgkmcnt(0)
	v_mfma_i32_16x16x64_i8 v[126:129], v[148:151], v[180:183], v[126:129]
	v_mfma_i32_16x16x64_i8 v[122:125], v[156:159], v[180:183], v[122:125]
	v_mfma_i32_16x16x64_i8 v[118:121], v[148:151], v[194:197], v[118:121]
	v_mfma_i32_16x16x64_i8 v[114:117], v[156:159], v[194:197], v[114:117]
	s_barrier
	v_mfma_i32_16x16x64_i8 v[106:109], v[148:151], v[202:205], v[106:109]
	v_mfma_i32_16x16x64_i8 v[98:101], v[156:159], v[202:205], v[98:101]
	v_mfma_i32_16x16x64_i8 v[90:93], v[148:151], v[210:213], v[90:93]
	v_mfma_i32_16x16x64_i8 v[82:85], v[156:159], v[210:213], v[82:85]
	v_mfma_i32_16x16x64_i8 v[126:129], v[152:155], v[190:193], v[126:129]
	v_mfma_i32_16x16x64_i8 v[122:125], v[160:163], v[190:193], v[122:125]
	v_mfma_i32_16x16x64_i8 v[118:121], v[152:155], v[198:201], v[118:121]
	v_mfma_i32_16x16x64_i8 v[114:117], v[160:163], v[198:201], v[114:117]
	v_mfma_i32_16x16x64_i8 v[106:109], v[152:155], v[206:209], v[106:109]
	v_mfma_i32_16x16x64_i8 v[98:101], v[160:163], v[206:209], v[98:101]
	v_mfma_i32_16x16x64_i8 v[90:93], v[152:155], v[214:217], v[90:93]
	v_mfma_i32_16x16x64_i8 v[82:85], v[160:163], v[214:217], v[82:85]
	s_setprio 0
	s_setprio 1
	v_mfma_i32_16x16x64_i8 v[110:113], v[164:167], v[180:183], v[110:113]
	v_mfma_i32_16x16x64_i8 v[102:105], v[172:175], v[180:183], v[102:105]
	v_mfma_i32_16x16x64_i8 v[94:97], v[164:167], v[194:197], v[94:97]
	v_mfma_i32_16x16x64_i8 v[86:89], v[172:175], v[194:197], v[86:89]
	v_mfma_i32_16x16x64_i8 v[78:81], v[164:167], v[202:205], v[78:81]
	v_mfma_i32_16x16x64_i8 v[74:77], v[172:175], v[202:205], v[74:77]
	v_mfma_i32_16x16x64_i8 v[70:73], v[164:167], v[210:213], v[70:73]
	v_mfma_i32_16x16x64_i8 v[66:69], v[172:175], v[210:213], v[66:69]
	v_mfma_i32_16x16x64_i8 v[110:113], v[168:171], v[190:193], v[110:113]
	v_mfma_i32_16x16x64_i8 v[102:105], v[176:179], v[190:193], v[102:105]
	v_mfma_i32_16x16x64_i8 v[94:97], v[168:171], v[198:201], v[94:97]
	v_mfma_i32_16x16x64_i8 v[86:89], v[176:179], v[198:201], v[86:89]
	v_mfma_i32_16x16x64_i8 v[78:81], v[168:171], v[206:209], v[78:81]
	v_mfma_i32_16x16x64_i8 v[74:77], v[176:179], v[206:209], v[74:77]
	v_mfma_i32_16x16x64_i8 v[70:73], v[168:171], v[214:217], v[70:73]
	v_mfma_i32_16x16x64_i8 v[66:69], v[176:179], v[214:217], v[66:69]
	s_setprio 0
	s_barrier
	s_add_i32 s28, s67, s43
	v_lshl_add_u64 v[184:185], v[184:185], 0, s[18:19]
	s_mov_b32 m0, s28
	ds_read_b128 v[180:183], v189 offset:49152
	ds_read_b128 v[190:193], v189 offset:50176
	ds_read_b128 v[194:197], v189 offset:51200
	ds_read_b128 v[198:201], v189 offset:52224
	ds_read_b128 v[202:205], v189 offset:53248
	ds_read_b128 v[206:209], v189 offset:54272
	ds_read_b128 v[210:213], v189 offset:55296
	ds_read_b128 v[214:217], v189 offset:56320
	global_load_lds_dwordx4 v[184:185], off
	v_lshl_add_u64 v[184:185], v[218:219], 0, s[18:19]
	s_add_i32 m0, s28, 0x2000
	s_add_i32 s28, s68, s43
	global_load_lds_dwordx4 v[184:185], off
	v_lshl_add_u64 v[184:185], v[220:221], 0, s[18:19]
	s_mov_b32 m0, s28
	s_nop 0
	global_load_lds_dwordx4 v[184:185], off
	v_lshl_add_u64 v[184:185], v[222:223], 0, s[18:19]
	s_add_i32 m0, s28, 0x2000
	s_nop 0
	global_load_lds_dwordx4 v[184:185], off
	v_lshl_add_u64 v[184:185], v[224:225], 0, s[18:19]
	s_mov_b32 m0, s55
	s_nop 0
	global_load_lds_dwordx4 v[184:185], off
	v_lshl_add_u64 v[184:185], v[226:227], 0, s[18:19]
	s_mov_b32 m0, s56
	s_nop 0
	global_load_lds_dwordx4 v[184:185], off
	s_waitcnt vmcnt(8)
	s_waitcnt lgkmcnt(0)
	s_setprio 1
	s_waitcnt lgkmcnt(0)
	v_mfma_i32_16x16x64_i8 v[62:65], v[148:151], v[180:183], v[62:65]
	v_mfma_i32_16x16x64_i8 v[58:61], v[156:159], v[180:183], v[58:61]
	v_mfma_i32_16x16x64_i8 v[54:57], v[148:151], v[194:197], v[54:57]
	v_mfma_i32_16x16x64_i8 v[50:53], v[156:159], v[194:197], v[50:53]
	s_barrier
	v_mfma_i32_16x16x64_i8 v[42:45], v[148:151], v[202:205], v[42:45]
	v_mfma_i32_16x16x64_i8 v[34:37], v[156:159], v[202:205], v[34:37]
	v_mfma_i32_16x16x64_i8 v[26:29], v[148:151], v[210:213], v[26:29]
	v_mfma_i32_16x16x64_i8 v[18:21], v[156:159], v[210:213], v[18:21]
	v_mfma_i32_16x16x64_i8 v[62:65], v[152:155], v[190:193], v[62:65]
	v_mfma_i32_16x16x64_i8 v[58:61], v[160:163], v[190:193], v[58:61]
	v_mfma_i32_16x16x64_i8 v[54:57], v[152:155], v[198:201], v[54:57]
	v_mfma_i32_16x16x64_i8 v[50:53], v[160:163], v[198:201], v[50:53]
	v_mfma_i32_16x16x64_i8 v[42:45], v[152:155], v[206:209], v[42:45]
	v_mfma_i32_16x16x64_i8 v[34:37], v[160:163], v[206:209], v[34:37]
	v_mfma_i32_16x16x64_i8 v[26:29], v[152:155], v[214:217], v[26:29]
	v_mfma_i32_16x16x64_i8 v[18:21], v[160:163], v[214:217], v[18:21]
	s_setprio 0
	s_setprio 1
	v_mfma_i32_16x16x64_i8 v[46:49], v[164:167], v[180:183], v[46:49]
	v_mfma_i32_16x16x64_i8 v[38:41], v[172:175], v[180:183], v[38:41]
	v_mfma_i32_16x16x64_i8 v[30:33], v[164:167], v[194:197], v[30:33]
	v_mfma_i32_16x16x64_i8 v[22:25], v[172:175], v[194:197], v[22:25]
	v_mfma_i32_16x16x64_i8 v[14:17], v[164:167], v[202:205], v[14:17]
	v_mfma_i32_16x16x64_i8 v[10:13], v[172:175], v[202:205], v[10:13]
	v_mfma_i32_16x16x64_i8 v[6:9], v[164:167], v[210:213], v[6:9]
	v_mfma_i32_16x16x64_i8 v[2:5], v[172:175], v[210:213], v[2:5]
	v_mfma_i32_16x16x64_i8 v[46:49], v[168:171], v[190:193], v[46:49]
	v_mfma_i32_16x16x64_i8 v[38:41], v[176:179], v[190:193], v[38:41]
	v_mfma_i32_16x16x64_i8 v[30:33], v[168:171], v[198:201], v[30:33]
	v_mfma_i32_16x16x64_i8 v[22:25], v[176:179], v[198:201], v[22:25]
	v_mfma_i32_16x16x64_i8 v[14:17], v[168:171], v[206:209], v[14:17]
	v_mfma_i32_16x16x64_i8 v[10:13], v[176:179], v[206:209], v[10:13]
	v_mfma_i32_16x16x64_i8 v[6:9], v[168:171], v[214:217], v[6:9]
	v_mfma_i32_16x16x64_i8 v[2:5], v[176:179], v[214:217], v[2:5]
	s_setprio 0
	s_barrier
	s_add_u32 s26, s26, 0x100
	s_addc_u32 s27, s27, 0
	s_add_u32 s34, s34, 0x100
	s_addc_u32 s35, s35, 0
	s_cmp_ge_i32 s66, s57
	s_mov_b32 s28, s66
	s_cbranch_scc0 .LBB0_1939
	v_cvt_f32_i32_e32 v172, v126
	v_cvt_f32_i32_e32 v173, v127
	v_cvt_f32_i32_e32 v170, v128
	v_cvt_f32_i32_e32 v171, v129
	v_cvt_f32_i32_e32 v174, v122
	v_cvt_f32_i32_e32 v175, v123
	v_cvt_f32_i32_e32 v176, v124
	v_cvt_f32_i32_e32 v177, v125
	v_cvt_f32_i32_e32 v180, v110
	v_cvt_f32_i32_e32 v181, v111
	v_cvt_f32_i32_e32 v182, v112
	v_cvt_f32_i32_e32 v183, v113
	v_cvt_f32_i32_e32 v178, v102
	v_cvt_f32_i32_e32 v179, v103
	v_cvt_f32_i32_e32 v184, v104
	v_cvt_f32_i32_e32 v185, v105
	v_cvt_f32_i32_e32 v152, v118
	v_cvt_f32_i32_e32 v153, v119
	v_cvt_f32_i32_e32 v154, v120
	v_cvt_f32_i32_e32 v155, v121
	v_cvt_f32_i32_e32 v156, v114
	v_cvt_f32_i32_e32 v157, v115
	v_cvt_f32_i32_e32 v158, v116
	v_cvt_f32_i32_e32 v159, v117
	v_cvt_f32_i32_e32 v160, v94
	v_cvt_f32_i32_e32 v161, v95
	v_cvt_f32_i32_e32 v162, v96
	v_cvt_f32_i32_e32 v163, v97
	v_cvt_f32_i32_e32 v164, v86
	v_cvt_f32_i32_e32 v165, v87
	v_cvt_f32_i32_e32 v166, v88
	v_cvt_f32_i32_e32 v167, v89
	v_cvt_f32_i32_e32 v118, v106
	v_cvt_f32_i32_e32 v119, v107
	v_cvt_f32_i32_e32 v120, v108
	v_cvt_f32_i32_e32 v121, v109
	v_cvt_f32_i32_e32 v122, v98
	v_cvt_f32_i32_e32 v123, v99
	v_cvt_f32_i32_e32 v124, v100
	v_cvt_f32_i32_e32 v125, v101
	v_cvt_f32_i32_e32 v126, v78
	v_cvt_f32_i32_e32 v127, v79
	v_cvt_f32_i32_e32 v128, v80
	v_cvt_f32_i32_e32 v129, v81
	v_cvt_f32_i32_e32 v148, v74
	v_cvt_f32_i32_e32 v149, v75
	v_cvt_f32_i32_e32 v150, v76
	v_cvt_f32_i32_e32 v151, v77
	v_cvt_f32_i32_e32 v102, v90
	v_cvt_f32_i32_e32 v103, v91
	v_cvt_f32_i32_e32 v104, v92
	v_cvt_f32_i32_e32 v105, v93
	v_cvt_f32_i32_e32 v106, v82
	v_cvt_f32_i32_e32 v107, v83
	v_cvt_f32_i32_e32 v108, v84
	v_cvt_f32_i32_e32 v109, v85
	v_cvt_f32_i32_e32 v110, v70
	v_cvt_f32_i32_e32 v111, v71
	v_cvt_f32_i32_e32 v112, v72
	v_cvt_f32_i32_e32 v113, v73
	v_cvt_f32_i32_e32 v114, v66
	v_cvt_f32_i32_e32 v115, v67
	v_cvt_f32_i32_e32 v116, v68
	v_cvt_f32_i32_e32 v117, v69
	v_cvt_f32_i32_e32 v82, v62
	v_cvt_f32_i32_e32 v83, v63
	v_cvt_f32_i32_e32 v84, v64
	v_cvt_f32_i32_e32 v85, v65
	v_cvt_f32_i32_e32 v86, v58
	v_cvt_f32_i32_e32 v87, v59
	v_cvt_f32_i32_e32 v88, v60
	v_cvt_f32_i32_e32 v89, v61
	v_cvt_f32_i32_e32 v92, v46
	v_cvt_f32_i32_e32 v93, v47
	v_cvt_f32_i32_e32 v94, v48
	v_cvt_f32_i32_e32 v95, v49
	v_cvt_f32_i32_e32 v96, v38
	v_cvt_f32_i32_e32 v97, v39
	v_cvt_f32_i32_e32 v98, v40
	v_cvt_f32_i32_e32 v99, v41
	v_cvt_f32_i32_e32 v66, v54
	v_cvt_f32_i32_e32 v67, v55
	v_cvt_f32_i32_e32 v68, v56
	v_cvt_f32_i32_e32 v69, v57
	v_cvt_f32_i32_e32 v70, v50
	v_cvt_f32_i32_e32 v71, v51
	v_cvt_f32_i32_e32 v72, v52
	v_cvt_f32_i32_e32 v73, v53
	v_cvt_f32_i32_e32 v74, v30
	v_cvt_f32_i32_e32 v75, v31
	v_cvt_f32_i32_e32 v76, v32
	v_cvt_f32_i32_e32 v77, v33
	v_cvt_f32_i32_e32 v78, v22
	v_cvt_f32_i32_e32 v79, v23
	v_cvt_f32_i32_e32 v80, v24
	v_cvt_f32_i32_e32 v81, v25
	v_cvt_f32_i32_e32 v50, v42
	v_cvt_f32_i32_e32 v51, v43
	v_cvt_f32_i32_e32 v52, v44
	v_cvt_f32_i32_e32 v53, v45
	v_cvt_f32_i32_e32 v54, v34
	v_cvt_f32_i32_e32 v55, v35
	v_cvt_f32_i32_e32 v56, v36
	v_cvt_f32_i32_e32 v57, v37
	v_cvt_f32_i32_e32 v58, v14
	v_cvt_f32_i32_e32 v59, v15
	v_cvt_f32_i32_e32 v60, v16
	v_cvt_f32_i32_e32 v61, v17
	v_cvt_f32_i32_e32 v62, v10
	v_cvt_f32_i32_e32 v63, v11
	v_cvt_f32_i32_e32 v64, v12
	v_cvt_f32_i32_e32 v65, v13
	v_cvt_f32_i32_e32 v34, v26
	v_cvt_f32_i32_e32 v35, v27
	v_cvt_f32_i32_e32 v36, v28
	v_cvt_f32_i32_e32 v37, v29
	v_cvt_f32_i32_e32 v38, v18
	v_cvt_f32_i32_e32 v39, v19
	v_cvt_f32_i32_e32 v40, v20
	v_cvt_f32_i32_e32 v41, v21
	v_cvt_f32_i32_e32 v42, v6
	v_cvt_f32_i32_e32 v43, v7
	v_cvt_f32_i32_e32 v44, v8
	v_cvt_f32_i32_e32 v45, v9
	v_cvt_f32_i32_e32 v46, v2
	v_cvt_f32_i32_e32 v47, v3
	v_cvt_f32_i32_e32 v48, v4
	v_cvt_f32_i32_e32 v49, v5

.LBB0_2022:
	ds_read_b128 v[114:117], v209
	ds_read_b128 v[118:121], v209 offset:1024
	ds_read_b128 v[122:125], v209 offset:2048
	ds_read_b128 v[126:129], v209 offset:3072
	ds_read_b128 v[146:149], v210
	ds_read_b128 v[150:153], v210 offset:1024
	ds_read_b128 v[154:157], v210 offset:2048
	ds_read_b128 v[158:161], v210 offset:3072
	s_add_i32 s84, s36, 2
	s_add_u32 s37, s34, 0x4000
	s_addc_u32 s38, s35, 0
	s_cmp_eq_u32 s63, s36
	s_cselect_b32 s39, s5, s38
	s_cselect_b32 s38, s4, s37
	s_cselect_b32 s86, s30, s82
	s_cselect_b32 s87, s31, s83
	s_add_u32 s36, s38, 0x8000
	s_addc_u32 s37, s39, 0
	v_lshl_add_u64 v[218:219], s[34:35], 0, v[170:171]
	s_add_i32 m0, s47, 0xc000
	ds_read_b128 v[178:181], v211
	ds_read_b128 v[182:185], v211 offset:1024
	ds_read_b128 v[186:189], v211 offset:2048
	ds_read_b128 v[190:193], v211 offset:3072
	ds_read_b128 v[194:197], v211 offset:4096
	ds_read_b128 v[198:201], v211 offset:5120
	ds_read_b128 v[202:205], v211 offset:6144
	ds_read_b128 v[214:217], v211 offset:7168
	global_load_lds_dwordx4 v[218:219], off
	v_lshl_add_u64 v[218:219], s[34:35], 0, v[172:173]
	s_add_i32 m0, s47, 0xe000
	s_nop 0
	global_load_lds_dwordx4 v[218:219], off
	s_waitcnt vmcnt(8)
	s_waitcnt lgkmcnt(0)
	s_setprio 1
	s_waitcnt lgkmcnt(0)
	v_mfma_f32_16x16x32_bf16 v[142:145], v[114:117], v[178:181], v[142:145]
	v_mfma_f32_16x16x32_bf16 v[138:141], v[122:125], v[178:181], v[138:141]
	v_mfma_f32_16x16x32_bf16 v[110:113], v[114:117], v[186:189], v[110:113]
	v_mfma_f32_16x16x32_bf16 v[106:109], v[122:125], v[186:189], v[106:109]
	s_barrier
	v_mfma_f32_16x16x32_bf16 v[94:97], v[114:117], v[194:197], v[94:97]
	v_mfma_f32_16x16x32_bf16 v[90:93], v[122:125], v[194:197], v[90:93]
	v_mfma_f32_16x16x32_bf16 v[78:81], v[114:117], v[202:205], v[78:81]
	v_mfma_f32_16x16x32_bf16 v[74:77], v[122:125], v[202:205], v[74:77]
	v_mfma_f32_16x16x32_bf16 v[142:145], v[118:121], v[182:185], v[142:145]
	v_mfma_f32_16x16x32_bf16 v[138:141], v[126:129], v[182:185], v[138:141]
	v_mfma_f32_16x16x32_bf16 v[110:113], v[118:121], v[190:193], v[110:113]
	v_mfma_f32_16x16x32_bf16 v[106:109], v[126:129], v[190:193], v[106:109]
	v_mfma_f32_16x16x32_bf16 v[94:97], v[118:121], v[198:201], v[94:97]
	v_mfma_f32_16x16x32_bf16 v[90:93], v[126:129], v[198:201], v[90:93]
	v_mfma_f32_16x16x32_bf16 v[78:81], v[118:121], v[214:217], v[78:81]
	v_mfma_f32_16x16x32_bf16 v[74:77], v[126:129], v[214:217], v[74:77]
	s_setprio 0
	s_setprio 1
	v_mfma_f32_16x16x32_bf16 v[134:137], v[146:149], v[178:181], v[134:137]
	v_mfma_f32_16x16x32_bf16 v[130:133], v[154:157], v[178:181], v[130:133]
	v_mfma_f32_16x16x32_bf16 v[102:105], v[146:149], v[186:189], v[102:105]
	v_mfma_f32_16x16x32_bf16 v[98:101], v[154:157], v[186:189], v[98:101]
	v_mfma_f32_16x16x32_bf16 v[86:89], v[146:149], v[194:197], v[86:89]
	v_mfma_f32_16x16x32_bf16 v[82:85], v[154:157], v[194:197], v[82:85]
	v_mfma_f32_16x16x32_bf16 v[70:73], v[146:149], v[202:205], v[70:73]
	v_mfma_f32_16x16x32_bf16 v[66:69], v[154:157], v[202:205], v[66:69]
	v_mfma_f32_16x16x32_bf16 v[134:137], v[150:153], v[182:185], v[134:137]
	v_mfma_f32_16x16x32_bf16 v[130:133], v[158:161], v[182:185], v[130:133]
	v_mfma_f32_16x16x32_bf16 v[102:105], v[150:153], v[190:193], v[102:105]
	v_mfma_f32_16x16x32_bf16 v[98:101], v[158:161], v[190:193], v[98:101]
	v_mfma_f32_16x16x32_bf16 v[86:89], v[150:153], v[198:201], v[86:89]
	v_mfma_f32_16x16x32_bf16 v[82:85], v[158:161], v[198:201], v[82:85]
	v_mfma_f32_16x16x32_bf16 v[70:73], v[150:153], v[214:217], v[70:73]
	v_mfma_f32_16x16x32_bf16 v[66:69], v[158:161], v[214:217], v[66:69]
	s_setprio 0
	s_barrier
	s_add_i32 s85, s66, s46
	v_lshl_add_u64 v[218:219], s[86:87], 0, v[164:165]
	s_mov_b32 m0, s85
	ds_read_b128 v[178:181], v211 offset:16384
	ds_read_b128 v[182:185], v211 offset:17408
	ds_read_b128 v[186:189], v211 offset:18432
	ds_read_b128 v[190:193], v211 offset:19456
	ds_read_b128 v[194:197], v211 offset:20480
	ds_read_b128 v[198:201], v211 offset:21504
	ds_read_b128 v[202:205], v211 offset:22528
	ds_read_b128 v[214:217], v211 offset:23552
	global_load_lds_dwordx4 v[218:219], off
	s_add_i32 m0, s85, 0x2000
	v_lshl_add_u64 v[220:221], s[86:87], 0, v[168:169]
	s_add_u32 s86, s86, s8
	s_addc_u32 s87, s87, s9
	s_add_i32 s85, s67, s46
	global_load_lds_dwordx4 v[220:221], off
	v_lshl_add_u64 v[222:223], s[86:87], 0, v[164:165]
	s_mov_b32 m0, s85
	v_lshl_add_u64 v[224:225], s[86:87], 0, v[168:169]
	global_load_lds_dwordx4 v[222:223], off
	s_add_i32 m0, s85, 0x2000
	v_lshl_add_u64 v[226:227], s[38:39], 0, v[162:163]
	global_load_lds_dwordx4 v[224:225], off
	s_mov_b32 m0, s47
	s_nop 0
	global_load_lds_dwordx4 v[226:227], off
	v_lshl_add_u64 v[226:227], s[38:39], 0, v[166:167]
	s_mov_b32 m0, s50
	s_nop 0
	global_load_lds_dwordx4 v[226:227], off
	s_waitcnt vmcnt(8)
	s_waitcnt lgkmcnt(0)
	s_setprio 1
	s_waitcnt lgkmcnt(0)
	v_mfma_f32_16x16x32_bf16 v[62:65], v[114:117], v[178:181], v[62:65]
	v_mfma_f32_16x16x32_bf16 v[58:61], v[122:125], v[178:181], v[58:61]
	v_mfma_f32_16x16x32_bf16 v[46:49], v[114:117], v[186:189], v[46:49]
	v_mfma_f32_16x16x32_bf16 v[42:45], v[122:125], v[186:189], v[42:45]
	s_barrier
	v_mfma_f32_16x16x32_bf16 v[30:33], v[114:117], v[194:197], v[30:33]
	v_mfma_f32_16x16x32_bf16 v[26:29], v[122:125], v[194:197], v[26:29]
	v_mfma_f32_16x16x32_bf16 v[14:17], v[114:117], v[202:205], v[14:17]
	v_mfma_f32_16x16x32_bf16 v[10:13], v[122:125], v[202:205], v[10:13]
	v_mfma_f32_16x16x32_bf16 v[62:65], v[118:121], v[182:185], v[62:65]
	v_mfma_f32_16x16x32_bf16 v[58:61], v[126:129], v[182:185], v[58:61]
	v_mfma_f32_16x16x32_bf16 v[46:49], v[118:121], v[190:193], v[46:49]
	v_mfma_f32_16x16x32_bf16 v[42:45], v[126:129], v[190:193], v[42:45]
	v_mfma_f32_16x16x32_bf16 v[30:33], v[118:121], v[198:201], v[30:33]
	v_mfma_f32_16x16x32_bf16 v[26:29], v[126:129], v[198:201], v[26:29]
	v_mfma_f32_16x16x32_bf16 v[14:17], v[118:121], v[214:217], v[14:17]
	v_mfma_f32_16x16x32_bf16 v[10:13], v[126:129], v[214:217], v[10:13]
	s_setprio 0
	s_setprio 1
	v_mfma_f32_16x16x32_bf16 v[54:57], v[146:149], v[178:181], v[54:57]
	v_mfma_f32_16x16x32_bf16 v[50:53], v[154:157], v[178:181], v[50:53]
	v_mfma_f32_16x16x32_bf16 v[38:41], v[146:149], v[186:189], v[38:41]
	v_mfma_f32_16x16x32_bf16 v[34:37], v[154:157], v[186:189], v[34:37]
	v_mfma_f32_16x16x32_bf16 v[22:25], v[146:149], v[194:197], v[22:25]
	v_mfma_f32_16x16x32_bf16 v[18:21], v[154:157], v[194:197], v[18:21]
	v_mfma_f32_16x16x32_bf16 v[6:9], v[146:149], v[202:205], v[6:9]
	v_mfma_f32_16x16x32_bf16 v[2:5], v[154:157], v[202:205], v[2:5]
	v_mfma_f32_16x16x32_bf16 v[54:57], v[150:153], v[182:185], v[54:57]
	v_mfma_f32_16x16x32_bf16 v[50:53], v[158:161], v[182:185], v[50:53]
	v_mfma_f32_16x16x32_bf16 v[38:41], v[150:153], v[190:193], v[38:41]
	v_mfma_f32_16x16x32_bf16 v[34:37], v[158:161], v[190:193], v[34:37]
	v_mfma_f32_16x16x32_bf16 v[22:25], v[150:153], v[198:201], v[22:25]
	v_mfma_f32_16x16x32_bf16 v[18:21], v[158:161], v[198:201], v[18:21]
	v_mfma_f32_16x16x32_bf16 v[6:9], v[150:153], v[214:217], v[6:9]
	v_mfma_f32_16x16x32_bf16 v[2:5], v[158:161], v[214:217], v[2:5]
	s_setprio 0
	s_barrier
	s_add_i32 s85, 0, 0x18000
	s_add_i32 s86, 0, 0x1c000
	v_add_u32_e32 v126, s85, v207
	v_add_u32_e32 v158, s86, v207
	ds_read_b128 v[114:117], v126
	ds_read_b128 v[118:121], v126 offset:1024
	ds_read_b128 v[122:125], v126 offset:2048
	ds_read_b128 v[126:129], v126 offset:3072
	ds_read_b128 v[146:149], v158
	ds_read_b128 v[150:153], v158 offset:1024
	ds_read_b128 v[154:157], v158 offset:2048
	ds_read_b128 v[158:161], v158 offset:3072
	s_add_u32 s38, s38, 0x4000
	s_addc_u32 s39, s39, 0
	s_mov_b32 m0, s51
	v_lshl_add_u64 v[226:227], s[38:39], 0, v[162:163]
	ds_read_b128 v[178:181], v211 offset:32768
	ds_read_b128 v[182:185], v211 offset:33792
	ds_read_b128 v[186:189], v211 offset:34816
	ds_read_b128 v[190:193], v211 offset:35840
	ds_read_b128 v[194:197], v211 offset:36864
	ds_read_b128 v[198:201], v211 offset:37888
	ds_read_b128 v[202:205], v211 offset:38912
	ds_read_b128 v[214:217], v211 offset:39936
	global_load_lds_dwordx4 v[226:227], off
	v_lshl_add_u64 v[226:227], s[38:39], 0, v[166:167]
	s_mov_b32 m0, s54
	s_nop 0
	global_load_lds_dwordx4 v[226:227], off
	s_waitcnt vmcnt(8)
	s_waitcnt lgkmcnt(0)
	s_setprio 1
	s_waitcnt lgkmcnt(0)
	v_mfma_f32_16x16x32_bf16 v[142:145], v[114:117], v[178:181], v[142:145]
	v_mfma_f32_16x16x32_bf16 v[138:141], v[122:125], v[178:181], v[138:141]
	v_mfma_f32_16x16x32_bf16 v[110:113], v[114:117], v[186:189], v[110:113]
	v_mfma_f32_16x16x32_bf16 v[106:109], v[122:125], v[186:189], v[106:109]
	s_barrier
	v_mfma_f32_16x16x32_bf16 v[94:97], v[114:117], v[194:197], v[94:97]
	v_mfma_f32_16x16x32_bf16 v[90:93], v[122:125], v[194:197], v[90:93]
	v_mfma_f32_16x16x32_bf16 v[78:81], v[114:117], v[202:205], v[78:81]
	v_mfma_f32_16x16x32_bf16 v[74:77], v[122:125], v[202:205], v[74:77]
	v_mfma_f32_16x16x32_bf16 v[142:145], v[118:121], v[182:185], v[142:145]
	v_mfma_f32_16x16x32_bf16 v[138:141], v[126:129], v[182:185], v[138:141]
	v_mfma_f32_16x16x32_bf16 v[110:113], v[118:121], v[190:193], v[110:113]
	v_mfma_f32_16x16x32_bf16 v[106:109], v[126:129], v[190:193], v[106:109]
	v_mfma_f32_16x16x32_bf16 v[94:97], v[118:121], v[198:201], v[94:97]
	v_mfma_f32_16x16x32_bf16 v[90:93], v[126:129], v[198:201], v[90:93]
	v_mfma_f32_16x16x32_bf16 v[78:81], v[118:121], v[214:217], v[78:81]
	v_mfma_f32_16x16x32_bf16 v[74:77], v[126:129], v[214:217], v[74:77]
	s_setprio 0
	s_setprio 1
	v_mfma_f32_16x16x32_bf16 v[134:137], v[146:149], v[178:181], v[134:137]
	v_mfma_f32_16x16x32_bf16 v[130:133], v[154:157], v[178:181], v[130:133]
	v_mfma_f32_16x16x32_bf16 v[102:105], v[146:149], v[186:189], v[102:105]
	v_mfma_f32_16x16x32_bf16 v[98:101], v[154:157], v[186:189], v[98:101]
	v_mfma_f32_16x16x32_bf16 v[86:89], v[146:149], v[194:197], v[86:89]
	v_mfma_f32_16x16x32_bf16 v[82:85], v[154:157], v[194:197], v[82:85]
	v_mfma_f32_16x16x32_bf16 v[70:73], v[146:149], v[202:205], v[70:73]
	v_mfma_f32_16x16x32_bf16 v[66:69], v[154:157], v[202:205], v[66:69]
	v_mfma_f32_16x16x32_bf16 v[134:137], v[150:153], v[182:185], v[134:137]
	v_mfma_f32_16x16x32_bf16 v[130:133], v[158:161], v[182:185], v[130:133]
	v_mfma_f32_16x16x32_bf16 v[102:105], v[150:153], v[190:193], v[102:105]
	v_mfma_f32_16x16x32_bf16 v[98:101], v[158:161], v[190:193], v[98:101]
	v_mfma_f32_16x16x32_bf16 v[86:89], v[150:153], v[198:201], v[86:89]
	v_mfma_f32_16x16x32_bf16 v[82:85], v[158:161], v[198:201], v[82:85]
	v_mfma_f32_16x16x32_bf16 v[70:73], v[150:153], v[214:217], v[70:73]
	v_mfma_f32_16x16x32_bf16 v[66:69], v[158:161], v[214:217], v[66:69]
	s_setprio 0
	s_barrier
	s_add_i32 s38, s85, s46
	v_lshl_add_u64 v[218:219], v[218:219], 0, s[24:25]
	s_mov_b32 m0, s38
	ds_read_b128 v[178:181], v211 offset:49152
	ds_read_b128 v[182:185], v211 offset:50176
	ds_read_b128 v[186:189], v211 offset:51200
	ds_read_b128 v[190:193], v211 offset:52224
	ds_read_b128 v[194:197], v211 offset:53248
	ds_read_b128 v[198:201], v211 offset:54272
	ds_read_b128 v[202:205], v211 offset:55296
	ds_read_b128 v[214:217], v211 offset:56320
	global_load_lds_dwordx4 v[218:219], off
	v_lshl_add_u64 v[218:219], v[220:221], 0, s[24:25]
	s_add_i32 m0, s38, 0x2000
	s_add_i32 s38, s86, s46
	global_load_lds_dwordx4 v[218:219], off
	v_lshl_add_u64 v[218:219], v[222:223], 0, s[24:25]
	s_mov_b32 m0, s38
	s_nop 0
	global_load_lds_dwordx4 v[218:219], off
	v_lshl_add_u64 v[218:219], v[224:225], 0, s[24:25]
	s_add_i32 m0, s38, 0x2000
	s_nop 0
	global_load_lds_dwordx4 v[218:219], off
	v_lshl_add_u64 v[218:219], s[36:37], 0, v[162:163]
	s_mov_b32 m0, s61
	s_nop 0
	global_load_lds_dwordx4 v[218:219], off
	v_lshl_add_u64 v[218:219], s[36:37], 0, v[166:167]
	s_mov_b32 m0, s62
	s_nop 0
	global_load_lds_dwordx4 v[218:219], off
	s_waitcnt vmcnt(8)
	s_waitcnt lgkmcnt(0)
	s_setprio 1
	s_waitcnt lgkmcnt(0)
	v_mfma_f32_16x16x32_bf16 v[62:65], v[114:117], v[178:181], v[62:65]
	v_mfma_f32_16x16x32_bf16 v[58:61], v[122:125], v[178:181], v[58:61]
	v_mfma_f32_16x16x32_bf16 v[46:49], v[114:117], v[186:189], v[46:49]
	v_mfma_f32_16x16x32_bf16 v[42:45], v[122:125], v[186:189], v[42:45]
	s_barrier
	v_mfma_f32_16x16x32_bf16 v[30:33], v[114:117], v[194:197], v[30:33]
	v_mfma_f32_16x16x32_bf16 v[26:29], v[122:125], v[194:197], v[26:29]
	v_mfma_f32_16x16x32_bf16 v[14:17], v[114:117], v[202:205], v[14:17]
	v_mfma_f32_16x16x32_bf16 v[10:13], v[122:125], v[202:205], v[10:13]
	v_mfma_f32_16x16x32_bf16 v[62:65], v[118:121], v[182:185], v[62:65]
	v_mfma_f32_16x16x32_bf16 v[58:61], v[126:129], v[182:185], v[58:61]
	v_mfma_f32_16x16x32_bf16 v[46:49], v[118:121], v[190:193], v[46:49]
	v_mfma_f32_16x16x32_bf16 v[42:45], v[126:129], v[190:193], v[42:45]
	v_mfma_f32_16x16x32_bf16 v[30:33], v[118:121], v[198:201], v[30:33]
	v_mfma_f32_16x16x32_bf16 v[26:29], v[126:129], v[198:201], v[26:29]
	v_mfma_f32_16x16x32_bf16 v[14:17], v[118:121], v[214:217], v[14:17]
	v_mfma_f32_16x16x32_bf16 v[10:13], v[126:129], v[214:217], v[10:13]
	s_setprio 0
	s_setprio 1
	v_mfma_f32_16x16x32_bf16 v[54:57], v[146:149], v[178:181], v[54:57]
	v_mfma_f32_16x16x32_bf16 v[50:53], v[154:157], v[178:181], v[50:53]
	v_mfma_f32_16x16x32_bf16 v[38:41], v[146:149], v[186:189], v[38:41]
	v_mfma_f32_16x16x32_bf16 v[34:37], v[154:157], v[186:189], v[34:37]
	v_mfma_f32_16x16x32_bf16 v[22:25], v[146:149], v[194:197], v[22:25]
	v_mfma_f32_16x16x32_bf16 v[18:21], v[154:157], v[194:197], v[18:21]
	v_mfma_f32_16x16x32_bf16 v[6:9], v[146:149], v[202:205], v[6:9]
	v_mfma_f32_16x16x32_bf16 v[2:5], v[154:157], v[202:205], v[2:5]
	v_mfma_f32_16x16x32_bf16 v[54:57], v[150:153], v[182:185], v[54:57]
	v_mfma_f32_16x16x32_bf16 v[50:53], v[158:161], v[182:185], v[50:53]
	v_mfma_f32_16x16x32_bf16 v[38:41], v[150:153], v[190:193], v[38:41]
	v_mfma_f32_16x16x32_bf16 v[34:37], v[158:161], v[190:193], v[34:37]
	v_mfma_f32_16x16x32_bf16 v[22:25], v[150:153], v[198:201], v[22:25]
	v_mfma_f32_16x16x32_bf16 v[18:21], v[158:161], v[198:201], v[18:21]
	v_mfma_f32_16x16x32_bf16 v[6:9], v[150:153], v[214:217], v[6:9]
	v_mfma_f32_16x16x32_bf16 v[2:5], v[158:161], v[214:217], v[2:5]
	s_setprio 0
	s_barrier
	s_add_u32 s82, s82, 0x100
	s_addc_u32 s83, s83, 0
	s_add_u32 s34, s34, 0x10000
	s_addc_u32 s35, s35, 0
	s_cmp_ge_i32 s84, s60
	s_mov_b32 s36, s84
	s_cbranch_scc0 .LBB0_2022

.LBB0_2116:
	ds_read_b128 v[34:37], v186
	ds_read_b128 v[38:41], v186 offset:1024
	ds_read_b128 v[50:53], v186 offset:2048
	ds_read_b128 v[54:57], v186 offset:3072
	ds_read_b128 v[168:171], v187
	ds_read_b128 v[172:175], v187 offset:1024
	ds_read_b128 v[176:179], v187 offset:2048
	ds_read_b128 v[192:195], v187 offset:3072
	s_add_i32 s47, s4, 2
	s_add_u32 s50, s2, 0x80
	s_addc_u32 s5, s3, 0
	s_cmp_eq_u32 s85, s4
	s_cselect_b32 s4, s42, s50
	s_cselect_b32 s5, s43, s5
	s_cselect_b32 s51, s45, s7
	s_cselect_b32 s50, s44, s6
	v_lshl_add_u64 v[228:229], s[2:3], 0, v[160:161]
	s_add_i32 m0, s65, 0xc000
	ds_read_b128 v[196:199], v188
	ds_read_b128 v[200:203], v188 offset:1024
	ds_read_b128 v[204:207], v188 offset:2048
	ds_read_b128 v[208:211], v188 offset:3072
	ds_read_b128 v[212:215], v188 offset:4096
	ds_read_b128 v[216:219], v188 offset:5120
	ds_read_b128 v[220:223], v188 offset:6144
	ds_read_b128 v[224:227], v188 offset:7168
	global_load_lds_dwordx4 v[228:229], off
	v_lshl_add_u64 v[228:229], s[2:3], 0, v[162:163]
	s_add_i32 m0, s65, 0xe000
	s_nop 0
	global_load_lds_dwordx4 v[228:229], off
	s_waitcnt vmcnt(8)
	s_waitcnt lgkmcnt(0)
	s_setprio 1
	s_waitcnt lgkmcnt(0)
	v_mfma_f32_16x16x32_bf16 v[142:145], v[34:37], v[196:199], v[142:145]
	v_mfma_f32_16x16x32_bf16 v[138:141], v[50:53], v[196:199], v[138:141]
	v_mfma_f32_16x16x32_bf16 v[126:129], v[34:37], v[204:207], v[126:129]
	v_mfma_f32_16x16x32_bf16 v[122:125], v[50:53], v[204:207], v[122:125]
	s_barrier
	v_mfma_f32_16x16x32_bf16 v[110:113], v[34:37], v[212:215], v[110:113]
	v_mfma_f32_16x16x32_bf16 v[106:109], v[50:53], v[212:215], v[106:109]
	v_mfma_f32_16x16x32_bf16 v[94:97], v[34:37], v[220:223], v[94:97]
	v_mfma_f32_16x16x32_bf16 v[90:93], v[50:53], v[220:223], v[90:93]
	v_mfma_f32_16x16x32_bf16 v[142:145], v[38:41], v[200:203], v[142:145]
	v_mfma_f32_16x16x32_bf16 v[138:141], v[54:57], v[200:203], v[138:141]
	v_mfma_f32_16x16x32_bf16 v[126:129], v[38:41], v[208:211], v[126:129]
	v_mfma_f32_16x16x32_bf16 v[122:125], v[54:57], v[208:211], v[122:125]
	v_mfma_f32_16x16x32_bf16 v[110:113], v[38:41], v[216:219], v[110:113]
	v_mfma_f32_16x16x32_bf16 v[106:109], v[54:57], v[216:219], v[106:109]
	v_mfma_f32_16x16x32_bf16 v[94:97], v[38:41], v[224:227], v[94:97]
	v_mfma_f32_16x16x32_bf16 v[90:93], v[54:57], v[224:227], v[90:93]
	s_setprio 0
	s_setprio 1
	v_mfma_f32_16x16x32_bf16 v[134:137], v[168:171], v[196:199], v[134:137]
	v_mfma_f32_16x16x32_bf16 v[130:133], v[176:179], v[196:199], v[130:133]
	v_mfma_f32_16x16x32_bf16 v[118:121], v[168:171], v[204:207], v[118:121]
	v_mfma_f32_16x16x32_bf16 v[114:117], v[176:179], v[204:207], v[114:117]
	v_mfma_f32_16x16x32_bf16 v[102:105], v[168:171], v[212:215], v[102:105]
	v_mfma_f32_16x16x32_bf16 v[98:101], v[176:179], v[212:215], v[98:101]
	v_mfma_f32_16x16x32_bf16 v[86:89], v[168:171], v[220:223], v[86:89]
	v_mfma_f32_16x16x32_bf16 v[82:85], v[176:179], v[220:223], v[82:85]
	v_mfma_f32_16x16x32_bf16 v[134:137], v[172:175], v[200:203], v[134:137]
	v_mfma_f32_16x16x32_bf16 v[130:133], v[192:195], v[200:203], v[130:133]
	v_mfma_f32_16x16x32_bf16 v[118:121], v[172:175], v[208:211], v[118:121]
	v_mfma_f32_16x16x32_bf16 v[114:117], v[192:195], v[208:211], v[114:117]
	v_mfma_f32_16x16x32_bf16 v[102:105], v[172:175], v[216:219], v[102:105]
	v_mfma_f32_16x16x32_bf16 v[98:101], v[192:195], v[216:219], v[98:101]
	v_mfma_f32_16x16x32_bf16 v[86:89], v[172:175], v[224:227], v[86:89]
	v_mfma_f32_16x16x32_bf16 v[82:85], v[192:195], v[224:227], v[82:85]
	s_setprio 0
	s_barrier
	s_add_i32 s55, s88, s62
	v_lshl_add_u64 v[228:229], s[50:51], 0, v[148:149]
	s_mov_b32 m0, s55
	ds_read_b128 v[196:199], v188 offset:16384
	ds_read_b128 v[200:203], v188 offset:17408
	ds_read_b128 v[204:207], v188 offset:18432
	ds_read_b128 v[208:211], v188 offset:19456
	ds_read_b128 v[212:215], v188 offset:20480
	ds_read_b128 v[216:219], v188 offset:21504
	ds_read_b128 v[220:223], v188 offset:22528
	ds_read_b128 v[224:227], v188 offset:23552
	global_load_lds_dwordx4 v[228:229], off
	s_add_i32 m0, s55, 0x2000
	v_lshl_add_u64 v[230:231], s[50:51], 0, v[152:153]
	s_add_u32 s50, s50, s14
	s_addc_u32 s51, s51, s15
	s_add_i32 s55, s89, s62
	global_load_lds_dwordx4 v[230:231], off
	v_lshl_add_u64 v[232:233], s[50:51], 0, v[148:149]
	s_mov_b32 m0, s55
	v_lshl_add_u64 v[234:235], s[50:51], 0, v[152:153]
	global_load_lds_dwordx4 v[232:233], off
	s_add_i32 m0, s55, 0x2000
	v_lshl_add_u64 v[236:237], s[4:5], 0, v[146:147]
	global_load_lds_dwordx4 v[234:235], off
	s_mov_b32 m0, s65
	v_lshl_add_u64 v[238:239], s[4:5], 0, v[150:151]
	global_load_lds_dwordx4 v[236:237], off
	s_mov_b32 m0, s66
	s_nop 0
	global_load_lds_dwordx4 v[238:239], off
	s_waitcnt vmcnt(8)
	s_waitcnt lgkmcnt(0)
	s_setprio 1
	s_waitcnt lgkmcnt(0)
	v_mfma_f32_16x16x32_bf16 v[78:81], v[34:37], v[196:199], v[78:81]
	v_mfma_f32_16x16x32_bf16 v[74:77], v[50:53], v[196:199], v[74:77]
	v_mfma_f32_16x16x32_bf16 v[62:65], v[34:37], v[204:207], v[62:65]
	v_mfma_f32_16x16x32_bf16 v[58:61], v[50:53], v[204:207], v[58:61]
	s_barrier
	v_mfma_f32_16x16x32_bf16 v[30:33], v[34:37], v[212:215], v[30:33]
	v_mfma_f32_16x16x32_bf16 v[26:29], v[50:53], v[212:215], v[26:29]
	v_mfma_f32_16x16x32_bf16 v[14:17], v[34:37], v[220:223], v[14:17]
	v_mfma_f32_16x16x32_bf16 v[10:13], v[50:53], v[220:223], v[10:13]
	v_mfma_f32_16x16x32_bf16 v[78:81], v[38:41], v[200:203], v[78:81]
	v_mfma_f32_16x16x32_bf16 v[74:77], v[54:57], v[200:203], v[74:77]
	v_mfma_f32_16x16x32_bf16 v[62:65], v[38:41], v[208:211], v[62:65]
	v_mfma_f32_16x16x32_bf16 v[58:61], v[54:57], v[208:211], v[58:61]
	v_mfma_f32_16x16x32_bf16 v[30:33], v[38:41], v[216:219], v[30:33]
	v_mfma_f32_16x16x32_bf16 v[26:29], v[54:57], v[216:219], v[26:29]
	v_mfma_f32_16x16x32_bf16 v[14:17], v[38:41], v[224:227], v[14:17]
	v_mfma_f32_16x16x32_bf16 v[10:13], v[54:57], v[224:227], v[10:13]
	s_setprio 0
	s_setprio 1
	v_mfma_f32_16x16x32_bf16 v[46:49], v[168:171], v[204:207], v[46:49]
	v_mfma_f32_16x16x32_bf16 v[42:45], v[176:179], v[204:207], v[42:45]
	v_mfma_f32_16x16x32_bf16 v[22:25], v[168:171], v[212:215], v[22:25]
	v_mfma_f32_16x16x32_bf16 v[18:21], v[176:179], v[212:215], v[18:21]
	v_mfma_f32_16x16x32_bf16 v[6:9], v[168:171], v[220:223], v[6:9]
	v_mfma_f32_16x16x32_bf16 v[2:5], v[176:179], v[220:223], v[2:5]
	v_mfma_f32_16x16x32_bf16 v[34:37], v[168:171], v[196:199], v[70:73]
	v_mfma_f32_16x16x32_bf16 v[38:41], v[176:179], v[196:199], v[66:69]
	v_mfma_f32_16x16x32_bf16 v[46:49], v[172:175], v[208:211], v[46:49]
	v_mfma_f32_16x16x32_bf16 v[42:45], v[192:195], v[208:211], v[42:45]
	v_mfma_f32_16x16x32_bf16 v[22:25], v[172:175], v[216:219], v[22:25]
	v_mfma_f32_16x16x32_bf16 v[18:21], v[192:195], v[216:219], v[18:21]
	v_mfma_f32_16x16x32_bf16 v[6:9], v[172:175], v[224:227], v[6:9]
	v_mfma_f32_16x16x32_bf16 v[2:5], v[192:195], v[224:227], v[2:5]
	v_mfma_f32_16x16x32_bf16 v[34:37], v[172:175], v[200:203], v[34:37]
	v_mfma_f32_16x16x32_bf16 v[38:41], v[192:195], v[200:203], v[38:41]
	s_setprio 0
	s_barrier
	s_add_i32 s50, 0, 0x18000
	s_add_i32 s51, 0, 0x1c000
	v_add_u32_e32 v70, s50, v184
	v_add_u32_e32 v154, s51, v184
	ds_read_b128 v[50:53], v70
	ds_read_b128 v[54:57], v70 offset:1024
	ds_read_b128 v[66:69], v70 offset:2048
	ds_read_b128 v[70:73], v70 offset:3072
	ds_read_b128 v[168:171], v154
	ds_read_b128 v[172:175], v154 offset:1024
	ds_read_b128 v[176:179], v154 offset:2048
	ds_read_b128 v[192:195], v154 offset:3072
	s_add_u32 s4, s4, s14
	s_addc_u32 s5, s5, s15
	s_mov_b32 m0, s67
	v_lshl_add_u64 v[240:241], s[4:5], 0, v[146:147]
	ds_read_b128 v[196:199], v188 offset:32768
	ds_read_b128 v[200:203], v188 offset:33792
	ds_read_b128 v[204:207], v188 offset:34816
	ds_read_b128 v[208:211], v188 offset:35840
	ds_read_b128 v[212:215], v188 offset:36864
	ds_read_b128 v[216:219], v188 offset:37888
	ds_read_b128 v[220:223], v188 offset:38912
	ds_read_b128 v[224:227], v188 offset:39936
	global_load_lds_dwordx4 v[240:241], off
	v_lshl_add_u64 v[240:241], s[4:5], 0, v[150:151]
	s_mov_b32 m0, s68
	s_nop 0
	global_load_lds_dwordx4 v[240:241], off
	s_waitcnt vmcnt(8)
	s_waitcnt lgkmcnt(0)
	s_setprio 1
	s_waitcnt lgkmcnt(0)
	v_mfma_f32_16x16x32_bf16 v[142:145], v[50:53], v[196:199], v[142:145]
	v_mfma_f32_16x16x32_bf16 v[138:141], v[66:69], v[196:199], v[138:141]
	v_mfma_f32_16x16x32_bf16 v[126:129], v[50:53], v[204:207], v[126:129]
	v_mfma_f32_16x16x32_bf16 v[122:125], v[66:69], v[204:207], v[122:125]
	s_barrier
	v_mfma_f32_16x16x32_bf16 v[110:113], v[50:53], v[212:215], v[110:113]
	v_mfma_f32_16x16x32_bf16 v[106:109], v[66:69], v[212:215], v[106:109]
	v_mfma_f32_16x16x32_bf16 v[94:97], v[50:53], v[220:223], v[94:97]
	v_mfma_f32_16x16x32_bf16 v[90:93], v[66:69], v[220:223], v[90:93]
	v_mfma_f32_16x16x32_bf16 v[142:145], v[54:57], v[200:203], v[142:145]
	v_mfma_f32_16x16x32_bf16 v[138:141], v[70:73], v[200:203], v[138:141]
	v_mfma_f32_16x16x32_bf16 v[126:129], v[54:57], v[208:211], v[126:129]
	v_mfma_f32_16x16x32_bf16 v[122:125], v[70:73], v[208:211], v[122:125]
	v_mfma_f32_16x16x32_bf16 v[110:113], v[54:57], v[216:219], v[110:113]
	v_mfma_f32_16x16x32_bf16 v[106:109], v[70:73], v[216:219], v[106:109]
	v_mfma_f32_16x16x32_bf16 v[94:97], v[54:57], v[224:227], v[94:97]
	v_mfma_f32_16x16x32_bf16 v[90:93], v[70:73], v[224:227], v[90:93]
	s_setprio 0
	s_setprio 1
	v_mfma_f32_16x16x32_bf16 v[134:137], v[168:171], v[196:199], v[134:137]
	v_mfma_f32_16x16x32_bf16 v[130:133], v[176:179], v[196:199], v[130:133]
	v_mfma_f32_16x16x32_bf16 v[118:121], v[168:171], v[204:207], v[118:121]
	v_mfma_f32_16x16x32_bf16 v[114:117], v[176:179], v[204:207], v[114:117]
	v_mfma_f32_16x16x32_bf16 v[102:105], v[168:171], v[212:215], v[102:105]
	v_mfma_f32_16x16x32_bf16 v[98:101], v[176:179], v[212:215], v[98:101]
	v_mfma_f32_16x16x32_bf16 v[86:89], v[168:171], v[220:223], v[86:89]
	v_mfma_f32_16x16x32_bf16 v[82:85], v[176:179], v[220:223], v[82:85]
	v_mfma_f32_16x16x32_bf16 v[134:137], v[172:175], v[200:203], v[134:137]
	v_mfma_f32_16x16x32_bf16 v[130:133], v[192:195], v[200:203], v[130:133]
	v_mfma_f32_16x16x32_bf16 v[118:121], v[172:175], v[208:211], v[118:121]
	v_mfma_f32_16x16x32_bf16 v[114:117], v[192:195], v[208:211], v[114:117]
	v_mfma_f32_16x16x32_bf16 v[102:105], v[172:175], v[216:219], v[102:105]
	v_mfma_f32_16x16x32_bf16 v[98:101], v[192:195], v[216:219], v[98:101]
	v_mfma_f32_16x16x32_bf16 v[86:89], v[172:175], v[224:227], v[86:89]
	v_mfma_f32_16x16x32_bf16 v[82:85], v[192:195], v[224:227], v[82:85]
	s_setprio 0
	s_barrier
	s_add_i32 s4, s50, s62
	v_lshl_add_u64 v[228:229], v[228:229], 0, s[28:29]
	s_mov_b32 m0, s4
	ds_read_b128 v[196:199], v188 offset:49152
	ds_read_b128 v[200:203], v188 offset:50176
	ds_read_b128 v[204:207], v188 offset:51200
	ds_read_b128 v[208:211], v188 offset:52224
	ds_read_b128 v[212:215], v188 offset:53248
	ds_read_b128 v[216:219], v188 offset:54272
	ds_read_b128 v[220:223], v188 offset:55296
	ds_read_b128 v[224:227], v188 offset:56320
	global_load_lds_dwordx4 v[228:229], off
	v_lshl_add_u64 v[228:229], v[230:231], 0, s[28:29]
	s_add_i32 m0, s4, 0x2000
	s_add_i32 s4, s51, s62
	global_load_lds_dwordx4 v[228:229], off
	v_lshl_add_u64 v[228:229], v[232:233], 0, s[28:29]
	s_mov_b32 m0, s4
	s_nop 0
	global_load_lds_dwordx4 v[228:229], off
	v_lshl_add_u64 v[228:229], v[234:235], 0, s[28:29]
	s_add_i32 m0, s4, 0x2000
	s_nop 0
	global_load_lds_dwordx4 v[228:229], off
	v_lshl_add_u64 v[228:229], v[236:237], 0, s[28:29]
	s_mov_b32 m0, s82
	s_nop 0
	global_load_lds_dwordx4 v[228:229], off
	v_lshl_add_u64 v[228:229], v[238:239], 0, s[28:29]
	s_mov_b32 m0, s83
	s_nop 0
	global_load_lds_dwordx4 v[228:229], off
	s_waitcnt vmcnt(8)
	s_waitcnt lgkmcnt(0)
	s_setprio 1
	s_waitcnt lgkmcnt(0)
	v_mfma_f32_16x16x32_bf16 v[78:81], v[50:53], v[196:199], v[78:81]
	v_mfma_f32_16x16x32_bf16 v[74:77], v[66:69], v[196:199], v[74:77]
	v_mfma_f32_16x16x32_bf16 v[62:65], v[50:53], v[204:207], v[62:65]
	v_mfma_f32_16x16x32_bf16 v[58:61], v[66:69], v[204:207], v[58:61]
	s_barrier
	v_mfma_f32_16x16x32_bf16 v[30:33], v[50:53], v[212:215], v[30:33]
	v_mfma_f32_16x16x32_bf16 v[26:29], v[66:69], v[212:215], v[26:29]
	v_mfma_f32_16x16x32_bf16 v[14:17], v[50:53], v[220:223], v[14:17]
	v_mfma_f32_16x16x32_bf16 v[10:13], v[66:69], v[220:223], v[10:13]
	v_mfma_f32_16x16x32_bf16 v[78:81], v[54:57], v[200:203], v[78:81]
	v_mfma_f32_16x16x32_bf16 v[74:77], v[70:73], v[200:203], v[74:77]
	v_mfma_f32_16x16x32_bf16 v[62:65], v[54:57], v[208:211], v[62:65]
	v_mfma_f32_16x16x32_bf16 v[58:61], v[70:73], v[208:211], v[58:61]
	v_mfma_f32_16x16x32_bf16 v[30:33], v[54:57], v[216:219], v[30:33]
	v_mfma_f32_16x16x32_bf16 v[26:29], v[70:73], v[216:219], v[26:29]
	v_mfma_f32_16x16x32_bf16 v[14:17], v[54:57], v[224:227], v[14:17]
	v_mfma_f32_16x16x32_bf16 v[10:13], v[70:73], v[224:227], v[10:13]
	s_setprio 0
	s_setprio 1
	v_mfma_f32_16x16x32_bf16 v[34:37], v[168:171], v[196:199], v[34:37]
	v_mfma_f32_16x16x32_bf16 v[70:73], v[172:175], v[200:203], v[34:37]
	v_mfma_f32_16x16x32_bf16 v[34:37], v[176:179], v[196:199], v[38:41]
	v_mfma_f32_16x16x32_bf16 v[66:69], v[192:195], v[200:203], v[34:37]
	v_mfma_f32_16x16x32_bf16 v[34:37], v[168:171], v[204:207], v[46:49]
	v_mfma_f32_16x16x32_bf16 v[46:49], v[172:175], v[208:211], v[34:37]
	v_mfma_f32_16x16x32_bf16 v[34:37], v[176:179], v[204:207], v[42:45]
	v_mfma_f32_16x16x32_bf16 v[22:25], v[168:171], v[212:215], v[22:25]
	v_mfma_f32_16x16x32_bf16 v[18:21], v[176:179], v[212:215], v[18:21]
	v_mfma_f32_16x16x32_bf16 v[6:9], v[168:171], v[220:223], v[6:9]
	v_mfma_f32_16x16x32_bf16 v[2:5], v[176:179], v[220:223], v[2:5]
	v_mfma_f32_16x16x32_bf16 v[42:45], v[192:195], v[208:211], v[34:37]
	v_mfma_f32_16x16x32_bf16 v[22:25], v[172:175], v[216:219], v[22:25]
	v_mfma_f32_16x16x32_bf16 v[18:21], v[192:195], v[216:219], v[18:21]
	v_mfma_f32_16x16x32_bf16 v[6:9], v[172:175], v[224:227], v[6:9]
	v_mfma_f32_16x16x32_bf16 v[2:5], v[192:195], v[224:227], v[2:5]
	s_setprio 0
	s_barrier
	s_add_u32 s2, s2, 0x100
	s_addc_u32 s3, s3, 0
	s_add_u32 s6, s6, 0x100
	s_addc_u32 s7, s7, 0
	s_cmp_ge_i32 s47, s84
	s_mov_b32 s4, s47
	s_cbranch_scc0 .LBB0_2116

.LBB0_2764:
	v_add_u32_e32 v158, s68, v229
	v_add_u32_e32 v174, s69, v229
	ds_read_b128 v[146:149], v158
	ds_read_b128 v[150:153], v158 offset:1024
	ds_read_b128 v[154:157], v158 offset:2048
	ds_read_b128 v[158:161], v158 offset:3072
	ds_read_b128 v[162:165], v174
	ds_read_b128 v[166:169], v174 offset:1024
	ds_read_b128 v[170:173], v174 offset:2048
	ds_read_b128 v[174:177], v174 offset:3072
	s_add_i32 s84, s42, 2
	s_add_u32 s85, s40, 0x80
	s_addc_u32 s43, s41, 0
	s_cmp_eq_u32 s65, s42
	s_cselect_b32 s42, s4, s85
	s_cselect_b32 s43, s5, s43
	s_cselect_b32 s87, s39, s83
	s_cselect_b32 s86, s38, s82
	v_lshl_add_u64 v[210:211], s[40:41], 0, v[138:139]
	s_add_i32 m0, s51, 0xc000
	ds_read_b128 v[178:181], v231
	ds_read_b128 v[182:185], v231 offset:1024
	ds_read_b128 v[186:189], v231 offset:2048
	ds_read_b128 v[190:193], v231 offset:3072
	ds_read_b128 v[194:197], v231 offset:4096
	ds_read_b128 v[198:201], v231 offset:5120
	ds_read_b128 v[202:205], v231 offset:6144
	ds_read_b128 v[206:209], v231 offset:7168
	global_load_lds_dwordx4 v[210:211], off
	v_lshl_add_u64 v[210:211], s[40:41], 0, v[140:141]
	s_add_i32 m0, s51, 0xe000
	s_nop 0
	global_load_lds_dwordx4 v[210:211], off
	s_waitcnt vmcnt(8)
	s_waitcnt lgkmcnt(0)
	s_setprio 1
	s_waitcnt lgkmcnt(0)
	v_mfma_i32_16x16x64_i8 v[126:129], v[146:149], v[178:181], v[126:129]
	v_mfma_i32_16x16x64_i8 v[122:125], v[154:157], v[178:181], v[122:125]
	v_mfma_i32_16x16x64_i8 v[118:121], v[146:149], v[186:189], v[118:121]
	v_mfma_i32_16x16x64_i8 v[114:117], v[154:157], v[186:189], v[114:117]
	s_barrier
	v_mfma_i32_16x16x64_i8 v[106:109], v[146:149], v[194:197], v[106:109]
	v_mfma_i32_16x16x64_i8 v[98:101], v[154:157], v[194:197], v[98:101]
	v_mfma_i32_16x16x64_i8 v[90:93], v[146:149], v[202:205], v[90:93]
	v_mfma_i32_16x16x64_i8 v[82:85], v[154:157], v[202:205], v[82:85]
	v_mfma_i32_16x16x64_i8 v[126:129], v[150:153], v[182:185], v[126:129]
	v_mfma_i32_16x16x64_i8 v[122:125], v[158:161], v[182:185], v[122:125]
	v_mfma_i32_16x16x64_i8 v[118:121], v[150:153], v[190:193], v[118:121]
	v_mfma_i32_16x16x64_i8 v[114:117], v[158:161], v[190:193], v[114:117]
	v_mfma_i32_16x16x64_i8 v[106:109], v[150:153], v[198:201], v[106:109]
	v_mfma_i32_16x16x64_i8 v[98:101], v[158:161], v[198:201], v[98:101]
	v_mfma_i32_16x16x64_i8 v[90:93], v[150:153], v[206:209], v[90:93]
	v_mfma_i32_16x16x64_i8 v[82:85], v[158:161], v[206:209], v[82:85]
	s_setprio 0
	s_setprio 1
	v_mfma_i32_16x16x64_i8 v[110:113], v[162:165], v[178:181], v[110:113]
	v_mfma_i32_16x16x64_i8 v[102:105], v[170:173], v[178:181], v[102:105]
	v_mfma_i32_16x16x64_i8 v[94:97], v[162:165], v[186:189], v[94:97]
	v_mfma_i32_16x16x64_i8 v[86:89], v[170:173], v[186:189], v[86:89]
	v_mfma_i32_16x16x64_i8 v[78:81], v[162:165], v[194:197], v[78:81]
	v_mfma_i32_16x16x64_i8 v[74:77], v[170:173], v[194:197], v[74:77]
	v_mfma_i32_16x16x64_i8 v[70:73], v[162:165], v[202:205], v[70:73]
	v_mfma_i32_16x16x64_i8 v[66:69], v[170:173], v[202:205], v[66:69]
	v_mfma_i32_16x16x64_i8 v[110:113], v[166:169], v[182:185], v[110:113]
	v_mfma_i32_16x16x64_i8 v[102:105], v[174:177], v[182:185], v[102:105]
	v_mfma_i32_16x16x64_i8 v[94:97], v[166:169], v[190:193], v[94:97]
	v_mfma_i32_16x16x64_i8 v[86:89], v[174:177], v[190:193], v[86:89]
	v_mfma_i32_16x16x64_i8 v[78:81], v[166:169], v[198:201], v[78:81]
	v_mfma_i32_16x16x64_i8 v[74:77], v[174:177], v[198:201], v[74:77]
	v_mfma_i32_16x16x64_i8 v[70:73], v[166:169], v[206:209], v[70:73]
	v_mfma_i32_16x16x64_i8 v[66:69], v[174:177], v[206:209], v[66:69]
	s_setprio 0
	s_barrier
	s_add_i32 s85, s68, s50
	v_lshl_add_u64 v[210:211], s[86:87], 0, v[132:133]
	s_mov_b32 m0, s85
	ds_read_b128 v[178:181], v231 offset:16384
	ds_read_b128 v[182:185], v231 offset:17408
	ds_read_b128 v[186:189], v231 offset:18432
	ds_read_b128 v[190:193], v231 offset:19456
	ds_read_b128 v[194:197], v231 offset:20480
	ds_read_b128 v[198:201], v231 offset:21504
	ds_read_b128 v[202:205], v231 offset:22528
	ds_read_b128 v[206:209], v231 offset:23552
	global_load_lds_dwordx4 v[210:211], off
	s_add_i32 m0, s85, 0x2000
	v_lshl_add_u64 v[212:213], s[86:87], 0, v[136:137]
	s_add_u32 s86, s86, s8
	s_addc_u32 s87, s87, s9
	s_add_i32 s85, s69, s50
	global_load_lds_dwordx4 v[212:213], off
	v_lshl_add_u64 v[214:215], s[86:87], 0, v[132:133]
	s_mov_b32 m0, s85
	v_lshl_add_u64 v[216:217], s[86:87], 0, v[136:137]
	global_load_lds_dwordx4 v[214:215], off
	s_add_i32 m0, s85, 0x2000
	v_lshl_add_u64 v[218:219], s[42:43], 0, v[130:131]
	global_load_lds_dwordx4 v[216:217], off
	s_mov_b32 m0, s51
	v_lshl_add_u64 v[220:221], s[42:43], 0, v[134:135]
	global_load_lds_dwordx4 v[218:219], off
	s_mov_b32 m0, s54
	s_nop 0
	global_load_lds_dwordx4 v[220:221], off
	s_waitcnt vmcnt(8)
	s_waitcnt lgkmcnt(0)
	s_setprio 1
	s_waitcnt lgkmcnt(0)
	v_mfma_i32_16x16x64_i8 v[62:65], v[146:149], v[178:181], v[62:65]
	v_mfma_i32_16x16x64_i8 v[58:61], v[154:157], v[178:181], v[58:61]
	v_mfma_i32_16x16x64_i8 v[54:57], v[146:149], v[186:189], v[54:57]
	v_mfma_i32_16x16x64_i8 v[50:53], v[154:157], v[186:189], v[50:53]
	s_barrier
	v_mfma_i32_16x16x64_i8 v[42:45], v[146:149], v[194:197], v[42:45]
	v_mfma_i32_16x16x64_i8 v[34:37], v[154:157], v[194:197], v[34:37]
	v_mfma_i32_16x16x64_i8 v[26:29], v[146:149], v[202:205], v[26:29]
	v_mfma_i32_16x16x64_i8 v[18:21], v[154:157], v[202:205], v[18:21]
	v_mfma_i32_16x16x64_i8 v[62:65], v[150:153], v[182:185], v[62:65]
	v_mfma_i32_16x16x64_i8 v[58:61], v[158:161], v[182:185], v[58:61]
	v_mfma_i32_16x16x64_i8 v[54:57], v[150:153], v[190:193], v[54:57]
	v_mfma_i32_16x16x64_i8 v[50:53], v[158:161], v[190:193], v[50:53]
	v_mfma_i32_16x16x64_i8 v[42:45], v[150:153], v[198:201], v[42:45]
	v_mfma_i32_16x16x64_i8 v[34:37], v[158:161], v[198:201], v[34:37]
	v_mfma_i32_16x16x64_i8 v[26:29], v[150:153], v[206:209], v[26:29]
	v_mfma_i32_16x16x64_i8 v[18:21], v[158:161], v[206:209], v[18:21]
	s_setprio 0
	s_setprio 1
	v_mfma_i32_16x16x64_i8 v[46:49], v[162:165], v[178:181], v[46:49]
	v_mfma_i32_16x16x64_i8 v[38:41], v[170:173], v[178:181], v[38:41]
	v_mfma_i32_16x16x64_i8 v[30:33], v[162:165], v[186:189], v[30:33]
	v_mfma_i32_16x16x64_i8 v[22:25], v[170:173], v[186:189], v[22:25]
	v_mfma_i32_16x16x64_i8 v[14:17], v[162:165], v[194:197], v[14:17]
	v_mfma_i32_16x16x64_i8 v[10:13], v[170:173], v[194:197], v[10:13]
	v_mfma_i32_16x16x64_i8 v[6:9], v[162:165], v[202:205], v[6:9]
	v_mfma_i32_16x16x64_i8 v[2:5], v[170:173], v[202:205], v[2:5]
	v_mfma_i32_16x16x64_i8 v[46:49], v[166:169], v[182:185], v[46:49]
	v_mfma_i32_16x16x64_i8 v[38:41], v[174:177], v[182:185], v[38:41]
	v_mfma_i32_16x16x64_i8 v[30:33], v[166:169], v[190:193], v[30:33]
	v_mfma_i32_16x16x64_i8 v[22:25], v[174:177], v[190:193], v[22:25]
	v_mfma_i32_16x16x64_i8 v[14:17], v[166:169], v[198:201], v[14:17]
	v_mfma_i32_16x16x64_i8 v[10:13], v[174:177], v[198:201], v[10:13]
	v_mfma_i32_16x16x64_i8 v[6:9], v[166:169], v[206:209], v[6:9]
	v_mfma_i32_16x16x64_i8 v[2:5], v[174:177], v[206:209], v[2:5]
	s_setprio 0
	s_barrier
	s_add_i32 s85, 0, 0x18000
	s_add_i32 s86, 0, 0x1c000
	v_add_u32_e32 v158, s85, v229
	v_add_u32_e32 v174, s86, v229
	ds_read_b128 v[146:149], v158
	ds_read_b128 v[150:153], v158 offset:1024
	ds_read_b128 v[154:157], v158 offset:2048
	ds_read_b128 v[158:161], v158 offset:3072
	ds_read_b128 v[162:165], v174
	ds_read_b128 v[166:169], v174 offset:1024
	ds_read_b128 v[170:173], v174 offset:2048
	ds_read_b128 v[174:177], v174 offset:3072
	s_add_u32 s42, s42, s8
	s_addc_u32 s43, s43, s9
	s_mov_b32 m0, s55
	v_lshl_add_u64 v[222:223], s[42:43], 0, v[130:131]
	ds_read_b128 v[178:181], v231 offset:32768
	ds_read_b128 v[182:185], v231 offset:33792
	ds_read_b128 v[186:189], v231 offset:34816
	ds_read_b128 v[190:193], v231 offset:35840
	ds_read_b128 v[194:197], v231 offset:36864
	ds_read_b128 v[198:201], v231 offset:37888
	ds_read_b128 v[202:205], v231 offset:38912
	ds_read_b128 v[206:209], v231 offset:39936
	global_load_lds_dwordx4 v[222:223], off
	v_lshl_add_u64 v[222:223], s[42:43], 0, v[134:135]
	s_mov_b32 m0, s56
	s_nop 0
	global_load_lds_dwordx4 v[222:223], off
	s_waitcnt vmcnt(8)
	s_waitcnt lgkmcnt(0)
	s_setprio 1
	s_waitcnt lgkmcnt(0)
	v_mfma_i32_16x16x64_i8 v[126:129], v[146:149], v[178:181], v[126:129]
	v_mfma_i32_16x16x64_i8 v[122:125], v[154:157], v[178:181], v[122:125]
	v_mfma_i32_16x16x64_i8 v[118:121], v[146:149], v[186:189], v[118:121]
	v_mfma_i32_16x16x64_i8 v[114:117], v[154:157], v[186:189], v[114:117]
	s_barrier
	v_mfma_i32_16x16x64_i8 v[106:109], v[146:149], v[194:197], v[106:109]
	v_mfma_i32_16x16x64_i8 v[98:101], v[154:157], v[194:197], v[98:101]
	v_mfma_i32_16x16x64_i8 v[90:93], v[146:149], v[202:205], v[90:93]
	v_mfma_i32_16x16x64_i8 v[82:85], v[154:157], v[202:205], v[82:85]
	v_mfma_i32_16x16x64_i8 v[126:129], v[150:153], v[182:185], v[126:129]
	v_mfma_i32_16x16x64_i8 v[122:125], v[158:161], v[182:185], v[122:125]
	v_mfma_i32_16x16x64_i8 v[118:121], v[150:153], v[190:193], v[118:121]
	v_mfma_i32_16x16x64_i8 v[114:117], v[158:161], v[190:193], v[114:117]
	v_mfma_i32_16x16x64_i8 v[106:109], v[150:153], v[198:201], v[106:109]
	v_mfma_i32_16x16x64_i8 v[98:101], v[158:161], v[198:201], v[98:101]
	v_mfma_i32_16x16x64_i8 v[90:93], v[150:153], v[206:209], v[90:93]
	v_mfma_i32_16x16x64_i8 v[82:85], v[158:161], v[206:209], v[82:85]
	s_setprio 0
	s_setprio 1
	v_mfma_i32_16x16x64_i8 v[110:113], v[162:165], v[178:181], v[110:113]
	v_mfma_i32_16x16x64_i8 v[102:105], v[170:173], v[178:181], v[102:105]
	v_mfma_i32_16x16x64_i8 v[94:97], v[162:165], v[186:189], v[94:97]
	v_mfma_i32_16x16x64_i8 v[86:89], v[170:173], v[186:189], v[86:89]
	v_mfma_i32_16x16x64_i8 v[78:81], v[162:165], v[194:197], v[78:81]
	v_mfma_i32_16x16x64_i8 v[74:77], v[170:173], v[194:197], v[74:77]
	v_mfma_i32_16x16x64_i8 v[70:73], v[162:165], v[202:205], v[70:73]
	v_mfma_i32_16x16x64_i8 v[66:69], v[170:173], v[202:205], v[66:69]
	v_mfma_i32_16x16x64_i8 v[110:113], v[166:169], v[182:185], v[110:113]
	v_mfma_i32_16x16x64_i8 v[102:105], v[174:177], v[182:185], v[102:105]
	v_mfma_i32_16x16x64_i8 v[94:97], v[166:169], v[190:193], v[94:97]
	v_mfma_i32_16x16x64_i8 v[86:89], v[174:177], v[190:193], v[86:89]
	v_mfma_i32_16x16x64_i8 v[78:81], v[166:169], v[198:201], v[78:81]
	v_mfma_i32_16x16x64_i8 v[74:77], v[174:177], v[198:201], v[74:77]
	v_mfma_i32_16x16x64_i8 v[70:73], v[166:169], v[206:209], v[70:73]
	v_mfma_i32_16x16x64_i8 v[66:69], v[174:177], v[206:209], v[66:69]
	s_setprio 0
	s_barrier
	s_add_i32 s42, s85, s50
	v_lshl_add_u64 v[210:211], v[210:211], 0, s[30:31]
	s_mov_b32 m0, s42
	ds_read_b128 v[178:181], v231 offset:49152
	ds_read_b128 v[182:185], v231 offset:50176
	ds_read_b128 v[186:189], v231 offset:51200
	ds_read_b128 v[190:193], v231 offset:52224
	ds_read_b128 v[194:197], v231 offset:53248
	ds_read_b128 v[198:201], v231 offset:54272
	ds_read_b128 v[202:205], v231 offset:55296
	ds_read_b128 v[206:209], v231 offset:56320
	global_load_lds_dwordx4 v[210:211], off
	v_lshl_add_u64 v[210:211], v[212:213], 0, s[30:31]
	s_add_i32 m0, s42, 0x2000
	s_add_i32 s42, s86, s50
	global_load_lds_dwordx4 v[210:211], off
	v_lshl_add_u64 v[210:211], v[214:215], 0, s[30:31]
	s_mov_b32 m0, s42
	s_nop 0
	global_load_lds_dwordx4 v[210:211], off
	v_lshl_add_u64 v[210:211], v[216:217], 0, s[30:31]
	s_add_i32 m0, s42, 0x2000
	s_nop 0
	global_load_lds_dwordx4 v[210:211], off
	v_lshl_add_u64 v[210:211], v[218:219], 0, s[30:31]
	s_mov_b32 m0, s61
	s_nop 0
	global_load_lds_dwordx4 v[210:211], off
	v_lshl_add_u64 v[210:211], v[220:221], 0, s[30:31]
	s_mov_b32 m0, s62
	s_nop 0
	global_load_lds_dwordx4 v[210:211], off
	s_waitcnt vmcnt(8)
	s_waitcnt lgkmcnt(0)
	s_setprio 1
	s_waitcnt lgkmcnt(0)
	v_mfma_i32_16x16x64_i8 v[62:65], v[146:149], v[178:181], v[62:65]
	v_mfma_i32_16x16x64_i8 v[58:61], v[154:157], v[178:181], v[58:61]
	v_mfma_i32_16x16x64_i8 v[54:57], v[146:149], v[186:189], v[54:57]
	v_mfma_i32_16x16x64_i8 v[50:53], v[154:157], v[186:189], v[50:53]
	s_barrier
	v_mfma_i32_16x16x64_i8 v[42:45], v[146:149], v[194:197], v[42:45]
	v_mfma_i32_16x16x64_i8 v[34:37], v[154:157], v[194:197], v[34:37]
	v_mfma_i32_16x16x64_i8 v[26:29], v[146:149], v[202:205], v[26:29]
	v_mfma_i32_16x16x64_i8 v[18:21], v[154:157], v[202:205], v[18:21]
	v_mfma_i32_16x16x64_i8 v[62:65], v[150:153], v[182:185], v[62:65]
	v_mfma_i32_16x16x64_i8 v[58:61], v[158:161], v[182:185], v[58:61]
	v_mfma_i32_16x16x64_i8 v[54:57], v[150:153], v[190:193], v[54:57]
	v_mfma_i32_16x16x64_i8 v[50:53], v[158:161], v[190:193], v[50:53]
	v_mfma_i32_16x16x64_i8 v[42:45], v[150:153], v[198:201], v[42:45]
	v_mfma_i32_16x16x64_i8 v[34:37], v[158:161], v[198:201], v[34:37]
	v_mfma_i32_16x16x64_i8 v[26:29], v[150:153], v[206:209], v[26:29]
	v_mfma_i32_16x16x64_i8 v[18:21], v[158:161], v[206:209], v[18:21]
	s_setprio 0
	s_setprio 1
	v_mfma_i32_16x16x64_i8 v[46:49], v[162:165], v[178:181], v[46:49]
	v_mfma_i32_16x16x64_i8 v[38:41], v[170:173], v[178:181], v[38:41]
	v_mfma_i32_16x16x64_i8 v[30:33], v[162:165], v[186:189], v[30:33]
	v_mfma_i32_16x16x64_i8 v[22:25], v[170:173], v[186:189], v[22:25]
	v_mfma_i32_16x16x64_i8 v[14:17], v[162:165], v[194:197], v[14:17]
	v_mfma_i32_16x16x64_i8 v[10:13], v[170:173], v[194:197], v[10:13]
	v_mfma_i32_16x16x64_i8 v[6:9], v[162:165], v[202:205], v[6:9]
	v_mfma_i32_16x16x64_i8 v[2:5], v[170:173], v[202:205], v[2:5]
	v_mfma_i32_16x16x64_i8 v[46:49], v[166:169], v[182:185], v[46:49]
	v_mfma_i32_16x16x64_i8 v[38:41], v[174:177], v[182:185], v[38:41]
	v_mfma_i32_16x16x64_i8 v[30:33], v[166:169], v[190:193], v[30:33]
	v_mfma_i32_16x16x64_i8 v[22:25], v[174:177], v[190:193], v[22:25]
	v_mfma_i32_16x16x64_i8 v[14:17], v[166:169], v[198:201], v[14:17]
	v_mfma_i32_16x16x64_i8 v[10:13], v[174:177], v[198:201], v[10:13]
	v_mfma_i32_16x16x64_i8 v[6:9], v[166:169], v[206:209], v[6:9]
	v_mfma_i32_16x16x64_i8 v[2:5], v[174:177], v[206:209], v[2:5]
	s_setprio 0
	s_barrier
	s_add_u32 s40, s40, 0x100
	s_addc_u32 s41, s41, 0
	s_add_u32 s82, s82, 0x100
	s_addc_u32 s83, s83, 0
	s_cmp_ge_i32 s84, s64
	s_mov_b32 s42, s84
	s_cbranch_scc0 .LBB0_2764
	v_cvt_f32_i32_e32 v214, v126
	v_cvt_f32_i32_e32 v215, v127
	v_cvt_f32_i32_e32 v212, v128
	v_cvt_f32_i32_e32 v213, v129
	v_cvt_f32_i32_e32 v218, v122
	v_cvt_f32_i32_e32 v219, v123
	v_cvt_f32_i32_e32 v216, v124
	v_cvt_f32_i32_e32 v217, v125
	v_cvt_f32_i32_e32 v222, v110
	v_cvt_f32_i32_e32 v223, v111
	v_cvt_f32_i32_e32 v220, v112
	v_cvt_f32_i32_e32 v221, v113
	v_cvt_f32_i32_e32 v226, v102
	v_cvt_f32_i32_e32 v227, v103
	v_cvt_f32_i32_e32 v224, v104
	v_cvt_f32_i32_e32 v225, v105
	v_cvt_f32_i32_e32 v194, v118
	v_cvt_f32_i32_e32 v195, v119
	v_cvt_f32_i32_e32 v192, v120
	v_cvt_f32_i32_e32 v193, v121
	v_cvt_f32_i32_e32 v200, v114
	v_cvt_f32_i32_e32 v201, v115
	v_cvt_f32_i32_e32 v198, v116
	v_cvt_f32_i32_e32 v199, v117
	v_cvt_f32_i32_e32 v206, v94
	v_cvt_f32_i32_e32 v207, v95
	v_cvt_f32_i32_e32 v202, v96
	v_cvt_f32_i32_e32 v203, v97
	v_cvt_f32_i32_e32 v208, v86
	v_cvt_f32_i32_e32 v209, v87
	v_cvt_f32_i32_e32 v204, v88
	v_cvt_f32_i32_e32 v205, v89
	v_cvt_f32_i32_e32 v178, v106
	v_cvt_f32_i32_e32 v179, v107
	v_cvt_f32_i32_e32 v176, v108
	v_cvt_f32_i32_e32 v177, v109
	v_cvt_f32_i32_e32 v182, v98
	v_cvt_f32_i32_e32 v183, v99
	v_cvt_f32_i32_e32 v180, v100
	v_cvt_f32_i32_e32 v181, v101
	v_cvt_f32_i32_e32 v188, v78
	v_cvt_f32_i32_e32 v189, v79
	v_cvt_f32_i32_e32 v184, v80
	v_cvt_f32_i32_e32 v185, v81
	v_cvt_f32_i32_e32 v190, v74
	v_cvt_f32_i32_e32 v191, v75
	v_cvt_f32_i32_e32 v186, v76
	v_cvt_f32_i32_e32 v187, v77
	v_cvt_f32_i32_e32 v162, v90
	v_cvt_f32_i32_e32 v163, v91
	v_cvt_f32_i32_e32 v160, v92
	v_cvt_f32_i32_e32 v161, v93
	v_cvt_f32_i32_e32 v166, v82
	v_cvt_f32_i32_e32 v167, v83
	v_cvt_f32_i32_e32 v164, v84
	v_cvt_f32_i32_e32 v165, v85
	v_cvt_f32_i32_e32 v172, v70
	v_cvt_f32_i32_e32 v173, v71
	v_cvt_f32_i32_e32 v168, v72
	v_cvt_f32_i32_e32 v169, v73
	v_cvt_f32_i32_e32 v174, v66
	v_cvt_f32_i32_e32 v175, v67
	v_cvt_f32_i32_e32 v170, v68
	v_cvt_f32_i32_e32 v171, v69
	v_cvt_f32_i32_e32 v146, v62
	v_cvt_f32_i32_e32 v147, v63
	v_cvt_f32_i32_e32 v128, v64
	v_cvt_f32_i32_e32 v129, v65
	v_cvt_f32_i32_e32 v150, v58
	v_cvt_f32_i32_e32 v151, v59
	v_cvt_f32_i32_e32 v148, v60
	v_cvt_f32_i32_e32 v149, v61
	v_cvt_f32_i32_e32 v156, v46
	v_cvt_f32_i32_e32 v157, v47
	v_cvt_f32_i32_e32 v152, v48
	v_cvt_f32_i32_e32 v153, v49
	v_cvt_f32_i32_e32 v158, v38
	v_cvt_f32_i32_e32 v159, v39
	v_cvt_f32_i32_e32 v154, v40
	v_cvt_f32_i32_e32 v155, v41
	v_cvt_f32_i32_e32 v114, v54
	v_cvt_f32_i32_e32 v115, v55
	v_cvt_f32_i32_e32 v112, v56
	v_cvt_f32_i32_e32 v113, v57
	v_cvt_f32_i32_e32 v118, v50
	v_cvt_f32_i32_e32 v119, v51
	v_cvt_f32_i32_e32 v116, v52
	v_cvt_f32_i32_e32 v117, v53
	v_cvt_f32_i32_e32 v124, v30
	v_cvt_f32_i32_e32 v125, v31
	v_cvt_f32_i32_e32 v120, v32
	v_cvt_f32_i32_e32 v121, v33
	v_cvt_f32_i32_e32 v126, v22
	v_cvt_f32_i32_e32 v127, v23
	v_cvt_f32_i32_e32 v122, v24
	v_cvt_f32_i32_e32 v123, v25
	v_cvt_f32_i32_e32 v64, v42
	v_cvt_f32_i32_e32 v65, v43
	v_cvt_f32_i32_e32 v62, v44
	v_cvt_f32_i32_e32 v63, v45
	v_cvt_f32_i32_e32 v68, v34
	v_cvt_f32_i32_e32 v69, v35
	v_cvt_f32_i32_e32 v66, v36
	v_cvt_f32_i32_e32 v67, v37
	v_cvt_f32_i32_e32 v74, v14
	v_cvt_f32_i32_e32 v75, v15
	v_cvt_f32_i32_e32 v70, v16
	v_cvt_f32_i32_e32 v71, v17
	v_cvt_f32_i32_e32 v76, v10
	v_cvt_f32_i32_e32 v77, v11
	v_cvt_f32_i32_e32 v72, v12
	v_cvt_f32_i32_e32 v73, v13
	v_cvt_f32_i32_e32 v48, v26
	v_cvt_f32_i32_e32 v49, v27
	v_cvt_f32_i32_e32 v46, v28
	v_cvt_f32_i32_e32 v47, v29
	v_cvt_f32_i32_e32 v52, v18
	v_cvt_f32_i32_e32 v53, v19
	v_cvt_f32_i32_e32 v50, v20
	v_cvt_f32_i32_e32 v51, v21
	v_cvt_f32_i32_e32 v58, v6
	v_cvt_f32_i32_e32 v59, v7
	v_cvt_f32_i32_e32 v54, v8
	v_cvt_f32_i32_e32 v55, v9
	v_cvt_f32_i32_e32 v60, v2
	v_cvt_f32_i32_e32 v61, v3
	v_cvt_f32_i32_e32 v56, v4
	v_cvt_f32_i32_e32 v57, v5

.LBB0_2949:
	v_add_u32_e32 v138, s60, v188
	ds_read_b128 v[148:151], v138
	ds_read_b128 v[152:155], v138 offset:1024
	ds_read_b128 v[156:159], v138 offset:2048
	ds_read_b128 v[160:163], v138 offset:3072
	v_add_u32_e32 v138, s61, v188
	ds_read_b128 v[164:167], v138
	ds_read_b128 v[168:171], v138 offset:1024
	ds_read_b128 v[172:175], v138 offset:2048
	ds_read_b128 v[176:179], v138 offset:3072
	s_add_i32 s64, s28, 2
	s_add_u32 s65, s26, 0x80
	s_addc_u32 s29, s27, 0
	s_cmp_eq_u32 s58, s28
	s_cselect_b32 s28, s2, s65
	s_cselect_b32 s29, s3, s29
	s_cselect_b32 s67, s25, s35
	s_cselect_b32 s66, s24, s34
	v_lshl_add_u64 v[184:185], s[26:27], 0, v[140:141]
	s_add_i32 m0, s42, 0xc000
	ds_read_b128 v[180:183], v189
	ds_read_b128 v[190:193], v189 offset:1024
	ds_read_b128 v[194:197], v189 offset:2048
	ds_read_b128 v[198:201], v189 offset:3072
	ds_read_b128 v[202:205], v189 offset:4096
	ds_read_b128 v[206:209], v189 offset:5120
	ds_read_b128 v[210:213], v189 offset:6144
	ds_read_b128 v[214:217], v189 offset:7168
	global_load_lds_dwordx4 v[184:185], off
	v_lshl_add_u64 v[184:185], s[26:27], 0, v[142:143]
	s_add_i32 m0, s42, 0xe000
	s_nop 0
	global_load_lds_dwordx4 v[184:185], off
	s_waitcnt vmcnt(8)
	s_waitcnt lgkmcnt(0)
	s_setprio 1
	s_waitcnt lgkmcnt(0)
	v_mfma_i32_16x16x64_i8 v[126:129], v[148:151], v[180:183], v[126:129]
	v_mfma_i32_16x16x64_i8 v[122:125], v[156:159], v[180:183], v[122:125]
	v_mfma_i32_16x16x64_i8 v[118:121], v[148:151], v[194:197], v[118:121]
	v_mfma_i32_16x16x64_i8 v[114:117], v[156:159], v[194:197], v[114:117]
	s_barrier
	v_mfma_i32_16x16x64_i8 v[106:109], v[148:151], v[202:205], v[106:109]
	v_mfma_i32_16x16x64_i8 v[98:101], v[156:159], v[202:205], v[98:101]
	v_mfma_i32_16x16x64_i8 v[90:93], v[148:151], v[210:213], v[90:93]
	v_mfma_i32_16x16x64_i8 v[82:85], v[156:159], v[210:213], v[82:85]
	v_mfma_i32_16x16x64_i8 v[126:129], v[152:155], v[190:193], v[126:129]
	v_mfma_i32_16x16x64_i8 v[122:125], v[160:163], v[190:193], v[122:125]
	v_mfma_i32_16x16x64_i8 v[118:121], v[152:155], v[198:201], v[118:121]
	v_mfma_i32_16x16x64_i8 v[114:117], v[160:163], v[198:201], v[114:117]
	v_mfma_i32_16x16x64_i8 v[106:109], v[152:155], v[206:209], v[106:109]
	v_mfma_i32_16x16x64_i8 v[98:101], v[160:163], v[206:209], v[98:101]
	v_mfma_i32_16x16x64_i8 v[90:93], v[152:155], v[214:217], v[90:93]
	v_mfma_i32_16x16x64_i8 v[82:85], v[160:163], v[214:217], v[82:85]
	s_setprio 0
	s_setprio 1
	v_mfma_i32_16x16x64_i8 v[110:113], v[164:167], v[180:183], v[110:113]
	v_mfma_i32_16x16x64_i8 v[102:105], v[172:175], v[180:183], v[102:105]
	v_mfma_i32_16x16x64_i8 v[94:97], v[164:167], v[194:197], v[94:97]
	v_mfma_i32_16x16x64_i8 v[86:89], v[172:175], v[194:197], v[86:89]
	v_mfma_i32_16x16x64_i8 v[78:81], v[164:167], v[202:205], v[78:81]
	v_mfma_i32_16x16x64_i8 v[74:77], v[172:175], v[202:205], v[74:77]
	v_mfma_i32_16x16x64_i8 v[70:73], v[164:167], v[210:213], v[70:73]
	v_mfma_i32_16x16x64_i8 v[66:69], v[172:175], v[210:213], v[66:69]
	v_mfma_i32_16x16x64_i8 v[110:113], v[168:171], v[190:193], v[110:113]
	v_mfma_i32_16x16x64_i8 v[102:105], v[176:179], v[190:193], v[102:105]
	v_mfma_i32_16x16x64_i8 v[94:97], v[168:171], v[198:201], v[94:97]
	v_mfma_i32_16x16x64_i8 v[86:89], v[176:179], v[198:201], v[86:89]
	v_mfma_i32_16x16x64_i8 v[78:81], v[168:171], v[206:209], v[78:81]
	v_mfma_i32_16x16x64_i8 v[74:77], v[176:179], v[206:209], v[74:77]
	v_mfma_i32_16x16x64_i8 v[70:73], v[168:171], v[214:217], v[70:73]
	v_mfma_i32_16x16x64_i8 v[66:69], v[176:179], v[214:217], v[66:69]
	s_setprio 0
	s_barrier
	s_add_i32 s65, s60, s41
	v_lshl_add_u64 v[184:185], s[66:67], 0, v[132:133]
	s_mov_b32 m0, s65
	ds_read_b128 v[180:183], v189 offset:16384
	ds_read_b128 v[190:193], v189 offset:17408
	ds_read_b128 v[194:197], v189 offset:18432
	ds_read_b128 v[198:201], v189 offset:19456
	ds_read_b128 v[202:205], v189 offset:20480
	ds_read_b128 v[206:209], v189 offset:21504
	ds_read_b128 v[210:213], v189 offset:22528
	ds_read_b128 v[214:217], v189 offset:23552
	global_load_lds_dwordx4 v[184:185], off
	s_add_i32 m0, s65, 0x2000
	v_lshl_add_u64 v[218:219], s[66:67], 0, v[136:137]
	s_add_u32 s66, s66, s6
	s_addc_u32 s67, s67, s7
	s_add_i32 s65, s61, s41
	global_load_lds_dwordx4 v[218:219], off
	v_lshl_add_u64 v[220:221], s[66:67], 0, v[132:133]
	s_mov_b32 m0, s65
	v_lshl_add_u64 v[222:223], s[66:67], 0, v[136:137]
	global_load_lds_dwordx4 v[220:221], off
	s_add_i32 m0, s65, 0x2000
	v_lshl_add_u64 v[224:225], s[28:29], 0, v[130:131]
	global_load_lds_dwordx4 v[222:223], off
	s_mov_b32 m0, s42
	v_lshl_add_u64 v[226:227], s[28:29], 0, v[134:135]
	global_load_lds_dwordx4 v[224:225], off
	s_mov_b32 m0, s43
	s_nop 0
	global_load_lds_dwordx4 v[226:227], off
	s_waitcnt vmcnt(8)
	s_waitcnt lgkmcnt(0)
	s_setprio 1
	s_waitcnt lgkmcnt(0)
	v_mfma_i32_16x16x64_i8 v[62:65], v[148:151], v[180:183], v[62:65]
	v_mfma_i32_16x16x64_i8 v[58:61], v[156:159], v[180:183], v[58:61]
	v_mfma_i32_16x16x64_i8 v[54:57], v[148:151], v[194:197], v[54:57]
	v_mfma_i32_16x16x64_i8 v[50:53], v[156:159], v[194:197], v[50:53]
	s_barrier
	v_mfma_i32_16x16x64_i8 v[42:45], v[148:151], v[202:205], v[42:45]
	v_mfma_i32_16x16x64_i8 v[34:37], v[156:159], v[202:205], v[34:37]
	v_mfma_i32_16x16x64_i8 v[26:29], v[148:151], v[210:213], v[26:29]
	v_mfma_i32_16x16x64_i8 v[18:21], v[156:159], v[210:213], v[18:21]
	v_mfma_i32_16x16x64_i8 v[62:65], v[152:155], v[190:193], v[62:65]
	v_mfma_i32_16x16x64_i8 v[58:61], v[160:163], v[190:193], v[58:61]
	v_mfma_i32_16x16x64_i8 v[54:57], v[152:155], v[198:201], v[54:57]
	v_mfma_i32_16x16x64_i8 v[50:53], v[160:163], v[198:201], v[50:53]
	v_mfma_i32_16x16x64_i8 v[42:45], v[152:155], v[206:209], v[42:45]
	v_mfma_i32_16x16x64_i8 v[34:37], v[160:163], v[206:209], v[34:37]
	v_mfma_i32_16x16x64_i8 v[26:29], v[152:155], v[214:217], v[26:29]
	v_mfma_i32_16x16x64_i8 v[18:21], v[160:163], v[214:217], v[18:21]
	s_setprio 0
	s_setprio 1
	v_mfma_i32_16x16x64_i8 v[46:49], v[164:167], v[180:183], v[46:49]
	v_mfma_i32_16x16x64_i8 v[38:41], v[172:175], v[180:183], v[38:41]
	v_mfma_i32_16x16x64_i8 v[30:33], v[164:167], v[194:197], v[30:33]
	v_mfma_i32_16x16x64_i8 v[22:25], v[172:175], v[194:197], v[22:25]
	v_mfma_i32_16x16x64_i8 v[14:17], v[164:167], v[202:205], v[14:17]
	v_mfma_i32_16x16x64_i8 v[10:13], v[172:175], v[202:205], v[10:13]
	v_mfma_i32_16x16x64_i8 v[6:9], v[164:167], v[210:213], v[6:9]
	v_mfma_i32_16x16x64_i8 v[2:5], v[172:175], v[210:213], v[2:5]
	v_mfma_i32_16x16x64_i8 v[46:49], v[168:171], v[190:193], v[46:49]
	v_mfma_i32_16x16x64_i8 v[38:41], v[176:179], v[190:193], v[38:41]
	v_mfma_i32_16x16x64_i8 v[30:33], v[168:171], v[198:201], v[30:33]
	v_mfma_i32_16x16x64_i8 v[22:25], v[176:179], v[198:201], v[22:25]
	v_mfma_i32_16x16x64_i8 v[14:17], v[168:171], v[206:209], v[14:17]
	v_mfma_i32_16x16x64_i8 v[10:13], v[176:179], v[206:209], v[10:13]
	v_mfma_i32_16x16x64_i8 v[6:9], v[168:171], v[214:217], v[6:9]
	v_mfma_i32_16x16x64_i8 v[2:5], v[176:179], v[214:217], v[2:5]
	s_setprio 0
	s_barrier
	s_add_i32 s65, 0, 0x18000
	v_add_u32_e32 v138, s65, v188
	s_add_i32 s66, 0, 0x1c000
	ds_read_b128 v[148:151], v138
	ds_read_b128 v[152:155], v138 offset:1024
	ds_read_b128 v[156:159], v138 offset:2048
	ds_read_b128 v[160:163], v138 offset:3072
	v_add_u32_e32 v138, s66, v188
	ds_read_b128 v[164:167], v138
	ds_read_b128 v[168:171], v138 offset:1024
	ds_read_b128 v[172:175], v138 offset:2048
	ds_read_b128 v[176:179], v138 offset:3072
	s_add_u32 s28, s28, s6
	s_addc_u32 s29, s29, s7
	s_mov_b32 m0, s44
	v_lshl_add_u64 v[228:229], s[28:29], 0, v[130:131]
	ds_read_b128 v[180:183], v189 offset:32768
	ds_read_b128 v[190:193], v189 offset:33792
	ds_read_b128 v[194:197], v189 offset:34816
	ds_read_b128 v[198:201], v189 offset:35840
	ds_read_b128 v[202:205], v189 offset:36864
	ds_read_b128 v[206:209], v189 offset:37888
	ds_read_b128 v[210:213], v189 offset:38912
	ds_read_b128 v[214:217], v189 offset:39936
	global_load_lds_dwordx4 v[228:229], off
	v_lshl_add_u64 v[228:229], s[28:29], 0, v[134:135]
	s_mov_b32 m0, s45
	s_nop 0
	global_load_lds_dwordx4 v[228:229], off
	s_waitcnt vmcnt(8)
	s_waitcnt lgkmcnt(0)
	s_setprio 1
	s_waitcnt lgkmcnt(0)
	v_mfma_i32_16x16x64_i8 v[126:129], v[148:151], v[180:183], v[126:129]
	v_mfma_i32_16x16x64_i8 v[122:125], v[156:159], v[180:183], v[122:125]
	v_mfma_i32_16x16x64_i8 v[118:121], v[148:151], v[194:197], v[118:121]
	v_mfma_i32_16x16x64_i8 v[114:117], v[156:159], v[194:197], v[114:117]
	s_barrier
	v_mfma_i32_16x16x64_i8 v[106:109], v[148:151], v[202:205], v[106:109]
	v_mfma_i32_16x16x64_i8 v[98:101], v[156:159], v[202:205], v[98:101]
	v_mfma_i32_16x16x64_i8 v[90:93], v[148:151], v[210:213], v[90:93]
	v_mfma_i32_16x16x64_i8 v[82:85], v[156:159], v[210:213], v[82:85]
	v_mfma_i32_16x16x64_i8 v[126:129], v[152:155], v[190:193], v[126:129]
	v_mfma_i32_16x16x64_i8 v[122:125], v[160:163], v[190:193], v[122:125]
	v_mfma_i32_16x16x64_i8 v[118:121], v[152:155], v[198:201], v[118:121]
	v_mfma_i32_16x16x64_i8 v[114:117], v[160:163], v[198:201], v[114:117]
	v_mfma_i32_16x16x64_i8 v[106:109], v[152:155], v[206:209], v[106:109]
	v_mfma_i32_16x16x64_i8 v[98:101], v[160:163], v[206:209], v[98:101]
	v_mfma_i32_16x16x64_i8 v[90:93], v[152:155], v[214:217], v[90:93]
	v_mfma_i32_16x16x64_i8 v[82:85], v[160:163], v[214:217], v[82:85]
	s_setprio 0
	s_setprio 1
	v_mfma_i32_16x16x64_i8 v[110:113], v[164:167], v[180:183], v[110:113]
	v_mfma_i32_16x16x64_i8 v[102:105], v[172:175], v[180:183], v[102:105]
	v_mfma_i32_16x16x64_i8 v[94:97], v[164:167], v[194:197], v[94:97]
	v_mfma_i32_16x16x64_i8 v[86:89], v[172:175], v[194:197], v[86:89]
	v_mfma_i32_16x16x64_i8 v[78:81], v[164:167], v[202:205], v[78:81]
	v_mfma_i32_16x16x64_i8 v[74:77], v[172:175], v[202:205], v[74:77]
	v_mfma_i32_16x16x64_i8 v[70:73], v[164:167], v[210:213], v[70:73]
	v_mfma_i32_16x16x64_i8 v[66:69], v[172:175], v[210:213], v[66:69]
	v_mfma_i32_16x16x64_i8 v[110:113], v[168:171], v[190:193], v[110:113]
	v_mfma_i32_16x16x64_i8 v[102:105], v[176:179], v[190:193], v[102:105]
	v_mfma_i32_16x16x64_i8 v[94:97], v[168:171], v[198:201], v[94:97]
	v_mfma_i32_16x16x64_i8 v[86:89], v[176:179], v[198:201], v[86:89]
	v_mfma_i32_16x16x64_i8 v[78:81], v[168:171], v[206:209], v[78:81]
	v_mfma_i32_16x16x64_i8 v[74:77], v[176:179], v[206:209], v[74:77]
	v_mfma_i32_16x16x64_i8 v[70:73], v[168:171], v[214:217], v[70:73]
	v_mfma_i32_16x16x64_i8 v[66:69], v[176:179], v[214:217], v[66:69]
	s_setprio 0
	s_barrier
	s_add_i32 s28, s65, s41
	v_lshl_add_u64 v[184:185], v[184:185], 0, s[18:19]
	s_mov_b32 m0, s28
	ds_read_b128 v[180:183], v189 offset:49152
	ds_read_b128 v[190:193], v189 offset:50176
	ds_read_b128 v[194:197], v189 offset:51200
	ds_read_b128 v[198:201], v189 offset:52224
	ds_read_b128 v[202:205], v189 offset:53248
	ds_read_b128 v[206:209], v189 offset:54272
	ds_read_b128 v[210:213], v189 offset:55296
	ds_read_b128 v[214:217], v189 offset:56320
	global_load_lds_dwordx4 v[184:185], off
	v_lshl_add_u64 v[184:185], v[218:219], 0, s[18:19]
	s_add_i32 m0, s28, 0x2000
	s_add_i32 s28, s66, s41
	global_load_lds_dwordx4 v[184:185], off
	v_lshl_add_u64 v[184:185], v[220:221], 0, s[18:19]
	s_mov_b32 m0, s28
	s_nop 0
	global_load_lds_dwordx4 v[184:185], off
	v_lshl_add_u64 v[184:185], v[222:223], 0, s[18:19]
	s_add_i32 m0, s28, 0x2000
	s_nop 0
	global_load_lds_dwordx4 v[184:185], off
	v_lshl_add_u64 v[184:185], v[224:225], 0, s[18:19]
	s_mov_b32 m0, s51
	s_nop 0
	global_load_lds_dwordx4 v[184:185], off
	v_lshl_add_u64 v[184:185], v[226:227], 0, s[18:19]
	s_mov_b32 m0, s54
	s_nop 0
	global_load_lds_dwordx4 v[184:185], off
	s_waitcnt vmcnt(8)
	s_waitcnt lgkmcnt(0)
	s_setprio 1
	s_waitcnt lgkmcnt(0)
	v_mfma_i32_16x16x64_i8 v[62:65], v[148:151], v[180:183], v[62:65]
	v_mfma_i32_16x16x64_i8 v[58:61], v[156:159], v[180:183], v[58:61]
	v_mfma_i32_16x16x64_i8 v[54:57], v[148:151], v[194:197], v[54:57]
	v_mfma_i32_16x16x64_i8 v[50:53], v[156:159], v[194:197], v[50:53]
	s_barrier
	v_mfma_i32_16x16x64_i8 v[42:45], v[148:151], v[202:205], v[42:45]
	v_mfma_i32_16x16x64_i8 v[34:37], v[156:159], v[202:205], v[34:37]
	v_mfma_i32_16x16x64_i8 v[26:29], v[148:151], v[210:213], v[26:29]
	v_mfma_i32_16x16x64_i8 v[18:21], v[156:159], v[210:213], v[18:21]
	v_mfma_i32_16x16x64_i8 v[62:65], v[152:155], v[190:193], v[62:65]
	v_mfma_i32_16x16x64_i8 v[58:61], v[160:163], v[190:193], v[58:61]
	v_mfma_i32_16x16x64_i8 v[54:57], v[152:155], v[198:201], v[54:57]
	v_mfma_i32_16x16x64_i8 v[50:53], v[160:163], v[198:201], v[50:53]
	v_mfma_i32_16x16x64_i8 v[42:45], v[152:155], v[206:209], v[42:45]
	v_mfma_i32_16x16x64_i8 v[34:37], v[160:163], v[206:209], v[34:37]
	v_mfma_i32_16x16x64_i8 v[26:29], v[152:155], v[214:217], v[26:29]
	v_mfma_i32_16x16x64_i8 v[18:21], v[160:163], v[214:217], v[18:21]
	s_setprio 0
	s_setprio 1
	v_mfma_i32_16x16x64_i8 v[46:49], v[164:167], v[180:183], v[46:49]
	v_mfma_i32_16x16x64_i8 v[38:41], v[172:175], v[180:183], v[38:41]
	v_mfma_i32_16x16x64_i8 v[30:33], v[164:167], v[194:197], v[30:33]
	v_mfma_i32_16x16x64_i8 v[22:25], v[172:175], v[194:197], v[22:25]
	v_mfma_i32_16x16x64_i8 v[14:17], v[164:167], v[202:205], v[14:17]
	v_mfma_i32_16x16x64_i8 v[10:13], v[172:175], v[202:205], v[10:13]
	v_mfma_i32_16x16x64_i8 v[6:9], v[164:167], v[210:213], v[6:9]
	v_mfma_i32_16x16x64_i8 v[2:5], v[172:175], v[210:213], v[2:5]
	v_mfma_i32_16x16x64_i8 v[46:49], v[168:171], v[190:193], v[46:49]
	v_mfma_i32_16x16x64_i8 v[38:41], v[176:179], v[190:193], v[38:41]
	v_mfma_i32_16x16x64_i8 v[30:33], v[168:171], v[198:201], v[30:33]
	v_mfma_i32_16x16x64_i8 v[22:25], v[176:179], v[198:201], v[22:25]
	v_mfma_i32_16x16x64_i8 v[14:17], v[168:171], v[206:209], v[14:17]
	v_mfma_i32_16x16x64_i8 v[10:13], v[176:179], v[206:209], v[10:13]
	v_mfma_i32_16x16x64_i8 v[6:9], v[168:171], v[214:217], v[6:9]
	v_mfma_i32_16x16x64_i8 v[2:5], v[176:179], v[214:217], v[2:5]
	s_setprio 0
	s_barrier
	s_add_u32 s26, s26, 0x100
	s_addc_u32 s27, s27, 0
	s_add_u32 s34, s34, 0x100
	s_addc_u32 s35, s35, 0
	s_cmp_ge_i32 s64, s55
	s_mov_b32 s28, s64
	s_cbranch_scc0 .LBB0_2949
	v_cvt_f32_i32_e32 v172, v126
	v_cvt_f32_i32_e32 v173, v127
	v_cvt_f32_i32_e32 v170, v128
	v_cvt_f32_i32_e32 v171, v129
	v_cvt_f32_i32_e32 v174, v122
	v_cvt_f32_i32_e32 v175, v123
	v_cvt_f32_i32_e32 v176, v124
	v_cvt_f32_i32_e32 v177, v125
	v_cvt_f32_i32_e32 v180, v110
	v_cvt_f32_i32_e32 v181, v111
	v_cvt_f32_i32_e32 v182, v112
	v_cvt_f32_i32_e32 v183, v113
	v_cvt_f32_i32_e32 v178, v102
	v_cvt_f32_i32_e32 v179, v103
	v_cvt_f32_i32_e32 v184, v104
	v_cvt_f32_i32_e32 v185, v105
	v_cvt_f32_i32_e32 v152, v118
	v_cvt_f32_i32_e32 v153, v119
	v_cvt_f32_i32_e32 v154, v120
	v_cvt_f32_i32_e32 v155, v121
	v_cvt_f32_i32_e32 v156, v114
	v_cvt_f32_i32_e32 v157, v115
	v_cvt_f32_i32_e32 v158, v116
	v_cvt_f32_i32_e32 v159, v117
	v_cvt_f32_i32_e32 v160, v94
	v_cvt_f32_i32_e32 v161, v95
	v_cvt_f32_i32_e32 v162, v96
	v_cvt_f32_i32_e32 v163, v97
	v_cvt_f32_i32_e32 v164, v86
	v_cvt_f32_i32_e32 v165, v87
	v_cvt_f32_i32_e32 v166, v88
	v_cvt_f32_i32_e32 v167, v89
	v_cvt_f32_i32_e32 v118, v106
	v_cvt_f32_i32_e32 v119, v107
	v_cvt_f32_i32_e32 v120, v108
	v_cvt_f32_i32_e32 v121, v109
	v_cvt_f32_i32_e32 v122, v98
	v_cvt_f32_i32_e32 v123, v99
	v_cvt_f32_i32_e32 v124, v100
	v_cvt_f32_i32_e32 v125, v101
	v_cvt_f32_i32_e32 v126, v78
	v_cvt_f32_i32_e32 v127, v79
	v_cvt_f32_i32_e32 v128, v80
	v_cvt_f32_i32_e32 v129, v81
	v_cvt_f32_i32_e32 v148, v74
	v_cvt_f32_i32_e32 v149, v75
	v_cvt_f32_i32_e32 v150, v76
	v_cvt_f32_i32_e32 v151, v77
	v_cvt_f32_i32_e32 v102, v90
	v_cvt_f32_i32_e32 v103, v91
	v_cvt_f32_i32_e32 v104, v92
	v_cvt_f32_i32_e32 v105, v93
	v_cvt_f32_i32_e32 v106, v82
	v_cvt_f32_i32_e32 v107, v83
	v_cvt_f32_i32_e32 v108, v84
	v_cvt_f32_i32_e32 v109, v85
	v_cvt_f32_i32_e32 v110, v70
	v_cvt_f32_i32_e32 v111, v71
	v_cvt_f32_i32_e32 v112, v72
	v_cvt_f32_i32_e32 v113, v73
	v_cvt_f32_i32_e32 v114, v66
	v_cvt_f32_i32_e32 v115, v67
	v_cvt_f32_i32_e32 v116, v68
	v_cvt_f32_i32_e32 v117, v69
	v_cvt_f32_i32_e32 v82, v62
	v_cvt_f32_i32_e32 v83, v63
	v_cvt_f32_i32_e32 v84, v64
	v_cvt_f32_i32_e32 v85, v65
	v_cvt_f32_i32_e32 v86, v58
	v_cvt_f32_i32_e32 v87, v59
	v_cvt_f32_i32_e32 v88, v60
	v_cvt_f32_i32_e32 v89, v61
	v_cvt_f32_i32_e32 v92, v46
	v_cvt_f32_i32_e32 v93, v47
	v_cvt_f32_i32_e32 v94, v48
	v_cvt_f32_i32_e32 v95, v49
	v_cvt_f32_i32_e32 v96, v38
	v_cvt_f32_i32_e32 v97, v39
	v_cvt_f32_i32_e32 v98, v40
	v_cvt_f32_i32_e32 v99, v41
	v_cvt_f32_i32_e32 v66, v54
	v_cvt_f32_i32_e32 v67, v55
	v_cvt_f32_i32_e32 v68, v56
	v_cvt_f32_i32_e32 v69, v57
	v_cvt_f32_i32_e32 v70, v50
	v_cvt_f32_i32_e32 v71, v51
	v_cvt_f32_i32_e32 v72, v52
	v_cvt_f32_i32_e32 v73, v53
	v_cvt_f32_i32_e32 v74, v30
	v_cvt_f32_i32_e32 v75, v31
	v_cvt_f32_i32_e32 v76, v32
	v_cvt_f32_i32_e32 v77, v33
	v_cvt_f32_i32_e32 v78, v22
	v_cvt_f32_i32_e32 v79, v23
	v_cvt_f32_i32_e32 v80, v24
	v_cvt_f32_i32_e32 v81, v25
	v_cvt_f32_i32_e32 v50, v42
	v_cvt_f32_i32_e32 v51, v43
	v_cvt_f32_i32_e32 v52, v44
	v_cvt_f32_i32_e32 v53, v45
	v_cvt_f32_i32_e32 v54, v34
	v_cvt_f32_i32_e32 v55, v35
	v_cvt_f32_i32_e32 v56, v36
	v_cvt_f32_i32_e32 v57, v37
	v_cvt_f32_i32_e32 v58, v14
	v_cvt_f32_i32_e32 v59, v15
	v_cvt_f32_i32_e32 v60, v16
	v_cvt_f32_i32_e32 v61, v17
	v_cvt_f32_i32_e32 v62, v10
	v_cvt_f32_i32_e32 v63, v11
	v_cvt_f32_i32_e32 v64, v12
	v_cvt_f32_i32_e32 v65, v13
	v_cvt_f32_i32_e32 v34, v26
	v_cvt_f32_i32_e32 v35, v27
	v_cvt_f32_i32_e32 v36, v28
	v_cvt_f32_i32_e32 v37, v29
	v_cvt_f32_i32_e32 v38, v18
	v_cvt_f32_i32_e32 v39, v19
	v_cvt_f32_i32_e32 v40, v20
	v_cvt_f32_i32_e32 v41, v21
	v_cvt_f32_i32_e32 v42, v6
	v_cvt_f32_i32_e32 v43, v7
	v_cvt_f32_i32_e32 v44, v8
	v_cvt_f32_i32_e32 v45, v9
	v_cvt_f32_i32_e32 v46, v2
	v_cvt_f32_i32_e32 v47, v3
	v_cvt_f32_i32_e32 v48, v4
	v_cvt_f32_i32_e32 v49, v5

.LBB0_3032:
	ds_read_b128 v[114:117], v209
	ds_read_b128 v[118:121], v209 offset:1024
	ds_read_b128 v[122:125], v209 offset:2048
	ds_read_b128 v[126:129], v209 offset:3072
	ds_read_b128 v[146:149], v210
	ds_read_b128 v[150:153], v210 offset:1024
	ds_read_b128 v[154:157], v210 offset:2048
	ds_read_b128 v[158:161], v210 offset:3072
	s_add_i32 s80, s36, 2
	s_add_u32 s37, s34, 0x4000
	s_addc_u32 s38, s35, 0
	s_cmp_eq_u32 s61, s36
	s_cselect_b32 s39, s5, s38
	s_cselect_b32 s38, s4, s37
	s_cselect_b32 s82, s30, s70
	s_cselect_b32 s83, s31, s71
	s_add_u32 s36, s38, 0x8000
	s_addc_u32 s37, s39, 0
	v_lshl_add_u64 v[218:219], s[34:35], 0, v[170:171]
	s_add_i32 m0, s45, 0xc000
	ds_read_b128 v[178:181], v211
	ds_read_b128 v[182:185], v211 offset:1024
	ds_read_b128 v[186:189], v211 offset:2048
	ds_read_b128 v[190:193], v211 offset:3072
	ds_read_b128 v[194:197], v211 offset:4096
	ds_read_b128 v[198:201], v211 offset:5120
	ds_read_b128 v[202:205], v211 offset:6144
	ds_read_b128 v[214:217], v211 offset:7168
	global_load_lds_dwordx4 v[218:219], off
	v_lshl_add_u64 v[218:219], s[34:35], 0, v[172:173]
	s_add_i32 m0, s45, 0xe000
	s_nop 0
	global_load_lds_dwordx4 v[218:219], off
	s_waitcnt vmcnt(8)
	s_waitcnt lgkmcnt(0)
	s_setprio 1
	s_waitcnt lgkmcnt(0)
	v_mfma_f32_16x16x32_bf16 v[142:145], v[114:117], v[178:181], v[142:145]
	v_mfma_f32_16x16x32_bf16 v[138:141], v[122:125], v[178:181], v[138:141]
	v_mfma_f32_16x16x32_bf16 v[110:113], v[114:117], v[186:189], v[110:113]
	v_mfma_f32_16x16x32_bf16 v[106:109], v[122:125], v[186:189], v[106:109]
	s_barrier
	v_mfma_f32_16x16x32_bf16 v[94:97], v[114:117], v[194:197], v[94:97]
	v_mfma_f32_16x16x32_bf16 v[90:93], v[122:125], v[194:197], v[90:93]
	v_mfma_f32_16x16x32_bf16 v[78:81], v[114:117], v[202:205], v[78:81]
	v_mfma_f32_16x16x32_bf16 v[74:77], v[122:125], v[202:205], v[74:77]
	v_mfma_f32_16x16x32_bf16 v[142:145], v[118:121], v[182:185], v[142:145]
	v_mfma_f32_16x16x32_bf16 v[138:141], v[126:129], v[182:185], v[138:141]
	v_mfma_f32_16x16x32_bf16 v[110:113], v[118:121], v[190:193], v[110:113]
	v_mfma_f32_16x16x32_bf16 v[106:109], v[126:129], v[190:193], v[106:109]
	v_mfma_f32_16x16x32_bf16 v[94:97], v[118:121], v[198:201], v[94:97]
	v_mfma_f32_16x16x32_bf16 v[90:93], v[126:129], v[198:201], v[90:93]
	v_mfma_f32_16x16x32_bf16 v[78:81], v[118:121], v[214:217], v[78:81]
	v_mfma_f32_16x16x32_bf16 v[74:77], v[126:129], v[214:217], v[74:77]
	s_setprio 0
	s_setprio 1
	v_mfma_f32_16x16x32_bf16 v[134:137], v[146:149], v[178:181], v[134:137]
	v_mfma_f32_16x16x32_bf16 v[130:133], v[154:157], v[178:181], v[130:133]
	v_mfma_f32_16x16x32_bf16 v[102:105], v[146:149], v[186:189], v[102:105]
	v_mfma_f32_16x16x32_bf16 v[98:101], v[154:157], v[186:189], v[98:101]
	v_mfma_f32_16x16x32_bf16 v[86:89], v[146:149], v[194:197], v[86:89]
	v_mfma_f32_16x16x32_bf16 v[82:85], v[154:157], v[194:197], v[82:85]
	v_mfma_f32_16x16x32_bf16 v[70:73], v[146:149], v[202:205], v[70:73]
	v_mfma_f32_16x16x32_bf16 v[66:69], v[154:157], v[202:205], v[66:69]
	v_mfma_f32_16x16x32_bf16 v[134:137], v[150:153], v[182:185], v[134:137]
	v_mfma_f32_16x16x32_bf16 v[130:133], v[158:161], v[182:185], v[130:133]
	v_mfma_f32_16x16x32_bf16 v[102:105], v[150:153], v[190:193], v[102:105]
	v_mfma_f32_16x16x32_bf16 v[98:101], v[158:161], v[190:193], v[98:101]
	v_mfma_f32_16x16x32_bf16 v[86:89], v[150:153], v[198:201], v[86:89]
	v_mfma_f32_16x16x32_bf16 v[82:85], v[158:161], v[198:201], v[82:85]
	v_mfma_f32_16x16x32_bf16 v[70:73], v[150:153], v[214:217], v[70:73]
	v_mfma_f32_16x16x32_bf16 v[66:69], v[158:161], v[214:217], v[66:69]
	s_setprio 0
	s_barrier
	s_add_i32 s81, s64, s44
	v_lshl_add_u64 v[218:219], s[82:83], 0, v[164:165]
	s_mov_b32 m0, s81
	ds_read_b128 v[178:181], v211 offset:16384
	ds_read_b128 v[182:185], v211 offset:17408
	ds_read_b128 v[186:189], v211 offset:18432
	ds_read_b128 v[190:193], v211 offset:19456
	ds_read_b128 v[194:197], v211 offset:20480
	ds_read_b128 v[198:201], v211 offset:21504
	ds_read_b128 v[202:205], v211 offset:22528
	ds_read_b128 v[214:217], v211 offset:23552
	global_load_lds_dwordx4 v[218:219], off
	s_add_i32 m0, s81, 0x2000
	v_lshl_add_u64 v[220:221], s[82:83], 0, v[168:169]
	s_add_u32 s82, s82, s8
	s_addc_u32 s83, s83, s9
	s_add_i32 s81, s65, s44
	global_load_lds_dwordx4 v[220:221], off
	v_lshl_add_u64 v[222:223], s[82:83], 0, v[164:165]
	s_mov_b32 m0, s81
	v_lshl_add_u64 v[224:225], s[82:83], 0, v[168:169]
	global_load_lds_dwordx4 v[222:223], off
	s_add_i32 m0, s81, 0x2000
	v_lshl_add_u64 v[226:227], s[38:39], 0, v[162:163]
	global_load_lds_dwordx4 v[224:225], off
	s_mov_b32 m0, s45
	s_nop 0
	global_load_lds_dwordx4 v[226:227], off
	v_lshl_add_u64 v[226:227], s[38:39], 0, v[166:167]
	s_mov_b32 m0, s46
	s_nop 0
	global_load_lds_dwordx4 v[226:227], off
	s_waitcnt vmcnt(8)
	s_waitcnt lgkmcnt(0)
	s_setprio 1
	s_waitcnt lgkmcnt(0)
	v_mfma_f32_16x16x32_bf16 v[62:65], v[114:117], v[178:181], v[62:65]
	v_mfma_f32_16x16x32_bf16 v[58:61], v[122:125], v[178:181], v[58:61]
	v_mfma_f32_16x16x32_bf16 v[46:49], v[114:117], v[186:189], v[46:49]
	v_mfma_f32_16x16x32_bf16 v[42:45], v[122:125], v[186:189], v[42:45]
	s_barrier
	v_mfma_f32_16x16x32_bf16 v[30:33], v[114:117], v[194:197], v[30:33]
	v_mfma_f32_16x16x32_bf16 v[26:29], v[122:125], v[194:197], v[26:29]
	v_mfma_f32_16x16x32_bf16 v[14:17], v[114:117], v[202:205], v[14:17]
	v_mfma_f32_16x16x32_bf16 v[10:13], v[122:125], v[202:205], v[10:13]
	v_mfma_f32_16x16x32_bf16 v[62:65], v[118:121], v[182:185], v[62:65]
	v_mfma_f32_16x16x32_bf16 v[58:61], v[126:129], v[182:185], v[58:61]
	v_mfma_f32_16x16x32_bf16 v[46:49], v[118:121], v[190:193], v[46:49]
	v_mfma_f32_16x16x32_bf16 v[42:45], v[126:129], v[190:193], v[42:45]
	v_mfma_f32_16x16x32_bf16 v[30:33], v[118:121], v[198:201], v[30:33]
	v_mfma_f32_16x16x32_bf16 v[26:29], v[126:129], v[198:201], v[26:29]
	v_mfma_f32_16x16x32_bf16 v[14:17], v[118:121], v[214:217], v[14:17]
	v_mfma_f32_16x16x32_bf16 v[10:13], v[126:129], v[214:217], v[10:13]
	s_setprio 0
	s_setprio 1
	v_mfma_f32_16x16x32_bf16 v[54:57], v[146:149], v[178:181], v[54:57]
	v_mfma_f32_16x16x32_bf16 v[50:53], v[154:157], v[178:181], v[50:53]
	v_mfma_f32_16x16x32_bf16 v[38:41], v[146:149], v[186:189], v[38:41]
	v_mfma_f32_16x16x32_bf16 v[34:37], v[154:157], v[186:189], v[34:37]
	v_mfma_f32_16x16x32_bf16 v[22:25], v[146:149], v[194:197], v[22:25]
	v_mfma_f32_16x16x32_bf16 v[18:21], v[154:157], v[194:197], v[18:21]
	v_mfma_f32_16x16x32_bf16 v[6:9], v[146:149], v[202:205], v[6:9]
	v_mfma_f32_16x16x32_bf16 v[2:5], v[154:157], v[202:205], v[2:5]
	v_mfma_f32_16x16x32_bf16 v[54:57], v[150:153], v[182:185], v[54:57]
	v_mfma_f32_16x16x32_bf16 v[50:53], v[158:161], v[182:185], v[50:53]
	v_mfma_f32_16x16x32_bf16 v[38:41], v[150:153], v[190:193], v[38:41]
	v_mfma_f32_16x16x32_bf16 v[34:37], v[158:161], v[190:193], v[34:37]
	v_mfma_f32_16x16x32_bf16 v[22:25], v[150:153], v[198:201], v[22:25]
	v_mfma_f32_16x16x32_bf16 v[18:21], v[158:161], v[198:201], v[18:21]
	v_mfma_f32_16x16x32_bf16 v[6:9], v[150:153], v[214:217], v[6:9]
	v_mfma_f32_16x16x32_bf16 v[2:5], v[158:161], v[214:217], v[2:5]
	s_setprio 0
	s_barrier
	s_add_i32 s81, 0, 0x18000
	s_add_i32 s82, 0, 0x1c000
	v_add_u32_e32 v126, s81, v207
	v_add_u32_e32 v158, s82, v207
	ds_read_b128 v[114:117], v126
	ds_read_b128 v[118:121], v126 offset:1024
	ds_read_b128 v[122:125], v126 offset:2048
	ds_read_b128 v[126:129], v126 offset:3072
	ds_read_b128 v[146:149], v158
	ds_read_b128 v[150:153], v158 offset:1024
	ds_read_b128 v[154:157], v158 offset:2048
	ds_read_b128 v[158:161], v158 offset:3072
	s_add_u32 s38, s38, 0x4000
	s_addc_u32 s39, s39, 0
	s_mov_b32 m0, s47
	v_lshl_add_u64 v[226:227], s[38:39], 0, v[162:163]
	ds_read_b128 v[178:181], v211 offset:32768
	ds_read_b128 v[182:185], v211 offset:33792
	ds_read_b128 v[186:189], v211 offset:34816
	ds_read_b128 v[190:193], v211 offset:35840
	ds_read_b128 v[194:197], v211 offset:36864
	ds_read_b128 v[198:201], v211 offset:37888
	ds_read_b128 v[202:205], v211 offset:38912
	ds_read_b128 v[214:217], v211 offset:39936
	global_load_lds_dwordx4 v[226:227], off
	v_lshl_add_u64 v[226:227], s[38:39], 0, v[166:167]
	s_mov_b32 m0, s50
	s_nop 0
	global_load_lds_dwordx4 v[226:227], off
	s_waitcnt vmcnt(8)
	s_waitcnt lgkmcnt(0)
	s_setprio 1
	s_waitcnt lgkmcnt(0)
	v_mfma_f32_16x16x32_bf16 v[142:145], v[114:117], v[178:181], v[142:145]
	v_mfma_f32_16x16x32_bf16 v[138:141], v[122:125], v[178:181], v[138:141]
	v_mfma_f32_16x16x32_bf16 v[110:113], v[114:117], v[186:189], v[110:113]
	v_mfma_f32_16x16x32_bf16 v[106:109], v[122:125], v[186:189], v[106:109]
	s_barrier
	v_mfma_f32_16x16x32_bf16 v[94:97], v[114:117], v[194:197], v[94:97]
	v_mfma_f32_16x16x32_bf16 v[90:93], v[122:125], v[194:197], v[90:93]
	v_mfma_f32_16x16x32_bf16 v[78:81], v[114:117], v[202:205], v[78:81]
	v_mfma_f32_16x16x32_bf16 v[74:77], v[122:125], v[202:205], v[74:77]
	v_mfma_f32_16x16x32_bf16 v[142:145], v[118:121], v[182:185], v[142:145]
	v_mfma_f32_16x16x32_bf16 v[138:141], v[126:129], v[182:185], v[138:141]
	v_mfma_f32_16x16x32_bf16 v[110:113], v[118:121], v[190:193], v[110:113]
	v_mfma_f32_16x16x32_bf16 v[106:109], v[126:129], v[190:193], v[106:109]
	v_mfma_f32_16x16x32_bf16 v[94:97], v[118:121], v[198:201], v[94:97]
	v_mfma_f32_16x16x32_bf16 v[90:93], v[126:129], v[198:201], v[90:93]
	v_mfma_f32_16x16x32_bf16 v[78:81], v[118:121], v[214:217], v[78:81]
	v_mfma_f32_16x16x32_bf16 v[74:77], v[126:129], v[214:217], v[74:77]
	s_setprio 0
	s_setprio 1
	v_mfma_f32_16x16x32_bf16 v[134:137], v[146:149], v[178:181], v[134:137]
	v_mfma_f32_16x16x32_bf16 v[130:133], v[154:157], v[178:181], v[130:133]
	v_mfma_f32_16x16x32_bf16 v[102:105], v[146:149], v[186:189], v[102:105]
	v_mfma_f32_16x16x32_bf16 v[98:101], v[154:157], v[186:189], v[98:101]
	v_mfma_f32_16x16x32_bf16 v[86:89], v[146:149], v[194:197], v[86:89]
	v_mfma_f32_16x16x32_bf16 v[82:85], v[154:157], v[194:197], v[82:85]
	v_mfma_f32_16x16x32_bf16 v[70:73], v[146:149], v[202:205], v[70:73]
	v_mfma_f32_16x16x32_bf16 v[66:69], v[154:157], v[202:205], v[66:69]
	v_mfma_f32_16x16x32_bf16 v[134:137], v[150:153], v[182:185], v[134:137]
	v_mfma_f32_16x16x32_bf16 v[130:133], v[158:161], v[182:185], v[130:133]
	v_mfma_f32_16x16x32_bf16 v[102:105], v[150:153], v[190:193], v[102:105]
	v_mfma_f32_16x16x32_bf16 v[98:101], v[158:161], v[190:193], v[98:101]
	v_mfma_f32_16x16x32_bf16 v[86:89], v[150:153], v[198:201], v[86:89]
	v_mfma_f32_16x16x32_bf16 v[82:85], v[158:161], v[198:201], v[82:85]
	v_mfma_f32_16x16x32_bf16 v[70:73], v[150:153], v[214:217], v[70:73]
	v_mfma_f32_16x16x32_bf16 v[66:69], v[158:161], v[214:217], v[66:69]
	s_setprio 0
	s_barrier
	s_add_i32 s38, s81, s44
	v_lshl_add_u64 v[218:219], v[218:219], 0, s[24:25]
	s_mov_b32 m0, s38
	ds_read_b128 v[178:181], v211 offset:49152
	ds_read_b128 v[182:185], v211 offset:50176
	ds_read_b128 v[186:189], v211 offset:51200
	ds_read_b128 v[190:193], v211 offset:52224
	ds_read_b128 v[194:197], v211 offset:53248
	ds_read_b128 v[198:201], v211 offset:54272
	ds_read_b128 v[202:205], v211 offset:55296
	ds_read_b128 v[214:217], v211 offset:56320
	global_load_lds_dwordx4 v[218:219], off
	v_lshl_add_u64 v[218:219], v[220:221], 0, s[24:25]
	s_add_i32 m0, s38, 0x2000
	s_add_i32 s38, s82, s44
	global_load_lds_dwordx4 v[218:219], off
	v_lshl_add_u64 v[218:219], v[222:223], 0, s[24:25]
	s_mov_b32 m0, s38
	s_nop 0
	global_load_lds_dwordx4 v[218:219], off
	v_lshl_add_u64 v[218:219], v[224:225], 0, s[24:25]
	s_add_i32 m0, s38, 0x2000
	s_nop 0
	global_load_lds_dwordx4 v[218:219], off
	v_lshl_add_u64 v[218:219], s[36:37], 0, v[162:163]
	s_mov_b32 m0, s59
	s_nop 0
	global_load_lds_dwordx4 v[218:219], off
	v_lshl_add_u64 v[218:219], s[36:37], 0, v[166:167]
	s_mov_b32 m0, s60
	s_nop 0
	global_load_lds_dwordx4 v[218:219], off
	s_waitcnt vmcnt(8)
	s_waitcnt lgkmcnt(0)
	s_setprio 1
	s_waitcnt lgkmcnt(0)
	v_mfma_f32_16x16x32_bf16 v[62:65], v[114:117], v[178:181], v[62:65]
	v_mfma_f32_16x16x32_bf16 v[58:61], v[122:125], v[178:181], v[58:61]
	v_mfma_f32_16x16x32_bf16 v[46:49], v[114:117], v[186:189], v[46:49]
	v_mfma_f32_16x16x32_bf16 v[42:45], v[122:125], v[186:189], v[42:45]
	s_barrier
	v_mfma_f32_16x16x32_bf16 v[30:33], v[114:117], v[194:197], v[30:33]
	v_mfma_f32_16x16x32_bf16 v[26:29], v[122:125], v[194:197], v[26:29]
	v_mfma_f32_16x16x32_bf16 v[14:17], v[114:117], v[202:205], v[14:17]
	v_mfma_f32_16x16x32_bf16 v[10:13], v[122:125], v[202:205], v[10:13]
	v_mfma_f32_16x16x32_bf16 v[62:65], v[118:121], v[182:185], v[62:65]
	v_mfma_f32_16x16x32_bf16 v[58:61], v[126:129], v[182:185], v[58:61]
	v_mfma_f32_16x16x32_bf16 v[46:49], v[118:121], v[190:193], v[46:49]
	v_mfma_f32_16x16x32_bf16 v[42:45], v[126:129], v[190:193], v[42:45]
	v_mfma_f32_16x16x32_bf16 v[30:33], v[118:121], v[198:201], v[30:33]
	v_mfma_f32_16x16x32_bf16 v[26:29], v[126:129], v[198:201], v[26:29]
	v_mfma_f32_16x16x32_bf16 v[14:17], v[118:121], v[214:217], v[14:17]
	v_mfma_f32_16x16x32_bf16 v[10:13], v[126:129], v[214:217], v[10:13]
	s_setprio 0
	s_setprio 1
	v_mfma_f32_16x16x32_bf16 v[54:57], v[146:149], v[178:181], v[54:57]
	v_mfma_f32_16x16x32_bf16 v[50:53], v[154:157], v[178:181], v[50:53]
	v_mfma_f32_16x16x32_bf16 v[38:41], v[146:149], v[186:189], v[38:41]
	v_mfma_f32_16x16x32_bf16 v[34:37], v[154:157], v[186:189], v[34:37]
	v_mfma_f32_16x16x32_bf16 v[22:25], v[146:149], v[194:197], v[22:25]
	v_mfma_f32_16x16x32_bf16 v[18:21], v[154:157], v[194:197], v[18:21]
	v_mfma_f32_16x16x32_bf16 v[6:9], v[146:149], v[202:205], v[6:9]
	v_mfma_f32_16x16x32_bf16 v[2:5], v[154:157], v[202:205], v[2:5]
	v_mfma_f32_16x16x32_bf16 v[54:57], v[150:153], v[182:185], v[54:57]
	v_mfma_f32_16x16x32_bf16 v[50:53], v[158:161], v[182:185], v[50:53]
	v_mfma_f32_16x16x32_bf16 v[38:41], v[150:153], v[190:193], v[38:41]
	v_mfma_f32_16x16x32_bf16 v[34:37], v[158:161], v[190:193], v[34:37]
	v_mfma_f32_16x16x32_bf16 v[22:25], v[150:153], v[198:201], v[22:25]
	v_mfma_f32_16x16x32_bf16 v[18:21], v[158:161], v[198:201], v[18:21]
	v_mfma_f32_16x16x32_bf16 v[6:9], v[150:153], v[214:217], v[6:9]
	v_mfma_f32_16x16x32_bf16 v[2:5], v[158:161], v[214:217], v[2:5]
	s_setprio 0
	s_barrier
	s_add_u32 s70, s70, 0x100
	s_addc_u32 s71, s71, 0
	s_add_u32 s34, s34, 0x10000
	s_addc_u32 s35, s35, 0
	s_cmp_ge_i32 s80, s58
	s_mov_b32 s36, s80
	s_cbranch_scc0 .LBB0_3032

.LBB0_3126:
	ds_read_b128 v[34:37], v196
	ds_read_b128 v[38:41], v196 offset:1024
	ds_read_b128 v[50:53], v196 offset:2048
	ds_read_b128 v[54:57], v196 offset:3072
	ds_read_b128 v[146:149], v197
	ds_read_b128 v[150:153], v197 offset:1024
	ds_read_b128 v[184:187], v197 offset:2048
	ds_read_b128 v[188:191], v197 offset:3072
	s_add_i32 s11, s6, 2
	s_add_u32 s12, s4, 0x80
	s_addc_u32 s7, s5, 0
	s_cmp_eq_u32 s84, s6
	s_cselect_b32 s6, s44, s12
	s_cselect_b32 s7, s45, s7
	s_cselect_b32 s13, s47, s9
	s_cselect_b32 s12, s46, s8
	v_lshl_add_u64 v[192:193], s[4:5], 0, v[174:175]
	s_add_i32 m0, s66, 0xc000
	ds_read_b128 v[200:203], v198
	ds_read_b128 v[204:207], v198 offset:1024
	ds_read_b128 v[208:211], v198 offset:2048
	ds_read_b128 v[212:215], v198 offset:3072
	ds_read_b128 v[216:219], v198 offset:4096
	ds_read_b128 v[220:223], v198 offset:5120
	ds_read_b128 v[224:227], v198 offset:6144
	ds_read_b128 v[228:231], v198 offset:7168
	global_load_lds_dwordx4 v[192:193], off
	v_lshl_add_u64 v[192:193], s[4:5], 0, v[176:177]
	s_add_i32 m0, s66, 0xe000
	s_nop 0
	global_load_lds_dwordx4 v[192:193], off
	s_waitcnt vmcnt(8)
	s_waitcnt lgkmcnt(0)
	s_setprio 1
	s_waitcnt lgkmcnt(0)
	v_mfma_f32_16x16x32_bf16 v[142:145], v[34:37], v[200:203], v[142:145]
	v_mfma_f32_16x16x32_bf16 v[138:141], v[50:53], v[200:203], v[138:141]
	v_mfma_f32_16x16x32_bf16 v[126:129], v[34:37], v[208:211], v[126:129]
	v_mfma_f32_16x16x32_bf16 v[122:125], v[50:53], v[208:211], v[122:125]
	s_barrier
	v_mfma_f32_16x16x32_bf16 v[110:113], v[34:37], v[216:219], v[110:113]
	v_mfma_f32_16x16x32_bf16 v[106:109], v[50:53], v[216:219], v[106:109]
	v_mfma_f32_16x16x32_bf16 v[94:97], v[34:37], v[224:227], v[94:97]
	v_mfma_f32_16x16x32_bf16 v[90:93], v[50:53], v[224:227], v[90:93]
	v_mfma_f32_16x16x32_bf16 v[142:145], v[38:41], v[204:207], v[142:145]
	v_mfma_f32_16x16x32_bf16 v[138:141], v[54:57], v[204:207], v[138:141]
	v_mfma_f32_16x16x32_bf16 v[126:129], v[38:41], v[212:215], v[126:129]
	v_mfma_f32_16x16x32_bf16 v[122:125], v[54:57], v[212:215], v[122:125]
	v_mfma_f32_16x16x32_bf16 v[110:113], v[38:41], v[220:223], v[110:113]
	v_mfma_f32_16x16x32_bf16 v[106:109], v[54:57], v[220:223], v[106:109]
	v_mfma_f32_16x16x32_bf16 v[94:97], v[38:41], v[228:231], v[94:97]
	v_mfma_f32_16x16x32_bf16 v[90:93], v[54:57], v[228:231], v[90:93]
	s_setprio 0
	s_setprio 1
	v_mfma_f32_16x16x32_bf16 v[134:137], v[146:149], v[200:203], v[134:137]
	v_mfma_f32_16x16x32_bf16 v[130:133], v[184:187], v[200:203], v[130:133]
	v_mfma_f32_16x16x32_bf16 v[118:121], v[146:149], v[208:211], v[118:121]
	v_mfma_f32_16x16x32_bf16 v[114:117], v[184:187], v[208:211], v[114:117]
	v_mfma_f32_16x16x32_bf16 v[102:105], v[146:149], v[216:219], v[102:105]
	v_mfma_f32_16x16x32_bf16 v[98:101], v[184:187], v[216:219], v[98:101]
	v_mfma_f32_16x16x32_bf16 v[86:89], v[146:149], v[224:227], v[86:89]
	v_mfma_f32_16x16x32_bf16 v[82:85], v[184:187], v[224:227], v[82:85]
	v_mfma_f32_16x16x32_bf16 v[134:137], v[150:153], v[204:207], v[134:137]
	v_mfma_f32_16x16x32_bf16 v[130:133], v[188:191], v[204:207], v[130:133]
	v_mfma_f32_16x16x32_bf16 v[118:121], v[150:153], v[212:215], v[118:121]
	v_mfma_f32_16x16x32_bf16 v[114:117], v[188:191], v[212:215], v[114:117]
	v_mfma_f32_16x16x32_bf16 v[102:105], v[150:153], v[220:223], v[102:105]
	v_mfma_f32_16x16x32_bf16 v[98:101], v[188:191], v[220:223], v[98:101]
	v_mfma_f32_16x16x32_bf16 v[86:89], v[150:153], v[228:231], v[86:89]
	v_mfma_f32_16x16x32_bf16 v[82:85], v[188:191], v[228:231], v[82:85]
	s_setprio 0
	s_barrier
	s_add_i32 s20, s88, s61
	v_lshl_add_u64 v[192:193], s[12:13], 0, v[156:157]
	s_mov_b32 m0, s20
	ds_read_b128 v[200:203], v198 offset:16384
	ds_read_b128 v[204:207], v198 offset:17408
	ds_read_b128 v[208:211], v198 offset:18432
	ds_read_b128 v[212:215], v198 offset:19456
	ds_read_b128 v[216:219], v198 offset:20480
	ds_read_b128 v[220:223], v198 offset:21504
	ds_read_b128 v[224:227], v198 offset:22528
	ds_read_b128 v[228:231], v198 offset:23552
	global_load_lds_dwordx4 v[192:193], off
	s_add_i32 m0, s20, 0x2000
	v_lshl_add_u64 v[232:233], s[12:13], 0, v[160:161]
	s_add_u32 s12, s12, s16
	s_addc_u32 s13, s13, s17
	s_add_i32 s20, s89, s61
	global_load_lds_dwordx4 v[232:233], off
	v_lshl_add_u64 v[234:235], s[12:13], 0, v[156:157]
	s_mov_b32 m0, s20
	v_lshl_add_u64 v[236:237], s[12:13], 0, v[160:161]
	global_load_lds_dwordx4 v[234:235], off
	s_add_i32 m0, s20, 0x2000
	v_lshl_add_u64 v[238:239], s[6:7], 0, v[154:155]
	global_load_lds_dwordx4 v[236:237], off
	s_mov_b32 m0, s66
	v_lshl_add_u64 v[240:241], s[6:7], 0, v[158:159]
	global_load_lds_dwordx4 v[238:239], off
	s_mov_b32 m0, s68
	s_nop 0
	global_load_lds_dwordx4 v[240:241], off
	s_waitcnt vmcnt(8)
	s_waitcnt lgkmcnt(0)
	s_setprio 1
	s_waitcnt lgkmcnt(0)
	v_mfma_f32_16x16x32_bf16 v[78:81], v[34:37], v[200:203], v[78:81]
	v_mfma_f32_16x16x32_bf16 v[74:77], v[50:53], v[200:203], v[74:77]
	v_mfma_f32_16x16x32_bf16 v[62:65], v[34:37], v[208:211], v[62:65]
	v_mfma_f32_16x16x32_bf16 v[58:61], v[50:53], v[208:211], v[58:61]
	s_barrier
	v_mfma_f32_16x16x32_bf16 v[30:33], v[34:37], v[216:219], v[30:33]
	v_mfma_f32_16x16x32_bf16 v[26:29], v[50:53], v[216:219], v[26:29]
	v_mfma_f32_16x16x32_bf16 v[14:17], v[34:37], v[224:227], v[14:17]
	v_mfma_f32_16x16x32_bf16 v[10:13], v[50:53], v[224:227], v[10:13]
	v_mfma_f32_16x16x32_bf16 v[78:81], v[38:41], v[204:207], v[78:81]
	v_mfma_f32_16x16x32_bf16 v[74:77], v[54:57], v[204:207], v[74:77]
	v_mfma_f32_16x16x32_bf16 v[62:65], v[38:41], v[212:215], v[62:65]
	v_mfma_f32_16x16x32_bf16 v[58:61], v[54:57], v[212:215], v[58:61]
	v_mfma_f32_16x16x32_bf16 v[30:33], v[38:41], v[220:223], v[30:33]
	v_mfma_f32_16x16x32_bf16 v[26:29], v[54:57], v[220:223], v[26:29]
	v_mfma_f32_16x16x32_bf16 v[14:17], v[38:41], v[228:231], v[14:17]
	v_mfma_f32_16x16x32_bf16 v[10:13], v[54:57], v[228:231], v[10:13]
	s_setprio 0
	s_setprio 1
	v_mfma_f32_16x16x32_bf16 v[46:49], v[146:149], v[208:211], v[46:49]
	v_mfma_f32_16x16x32_bf16 v[42:45], v[184:187], v[208:211], v[42:45]
	v_mfma_f32_16x16x32_bf16 v[22:25], v[146:149], v[216:219], v[22:25]
	v_mfma_f32_16x16x32_bf16 v[18:21], v[184:187], v[216:219], v[18:21]
	v_mfma_f32_16x16x32_bf16 v[6:9], v[146:149], v[224:227], v[6:9]
	v_mfma_f32_16x16x32_bf16 v[2:5], v[184:187], v[224:227], v[2:5]
	v_mfma_f32_16x16x32_bf16 v[34:37], v[146:149], v[200:203], v[70:73]
	v_mfma_f32_16x16x32_bf16 v[38:41], v[184:187], v[200:203], v[66:69]
	v_mfma_f32_16x16x32_bf16 v[46:49], v[150:153], v[212:215], v[46:49]
	v_mfma_f32_16x16x32_bf16 v[42:45], v[188:191], v[212:215], v[42:45]
	v_mfma_f32_16x16x32_bf16 v[22:25], v[150:153], v[220:223], v[22:25]
	v_mfma_f32_16x16x32_bf16 v[18:21], v[188:191], v[220:223], v[18:21]
	v_mfma_f32_16x16x32_bf16 v[6:9], v[150:153], v[228:231], v[6:9]
	v_mfma_f32_16x16x32_bf16 v[2:5], v[188:191], v[228:231], v[2:5]
	v_mfma_f32_16x16x32_bf16 v[34:37], v[150:153], v[204:207], v[34:37]
	v_mfma_f32_16x16x32_bf16 v[38:41], v[188:191], v[204:207], v[38:41]
	s_setprio 0
	s_barrier
	s_add_i32 s12, 0, 0x18000
	s_add_i32 s13, 0, 0x1c000
	v_add_u32_e32 v70, s12, v194
	v_add_u32_e32 v162, s13, v194
	ds_read_b128 v[50:53], v70
	ds_read_b128 v[54:57], v70 offset:1024
	ds_read_b128 v[66:69], v70 offset:2048
	ds_read_b128 v[70:73], v70 offset:3072
	ds_read_b128 v[146:149], v162
	ds_read_b128 v[150:153], v162 offset:1024
	ds_read_b128 v[184:187], v162 offset:2048
	ds_read_b128 v[188:191], v162 offset:3072
	s_add_u32 s6, s6, s16
	s_addc_u32 s7, s7, s17
	s_mov_b32 m0, s69
	v_lshl_add_u64 v[242:243], s[6:7], 0, v[154:155]
	ds_read_b128 v[200:203], v198 offset:32768
	ds_read_b128 v[204:207], v198 offset:33792
	ds_read_b128 v[208:211], v198 offset:34816
	ds_read_b128 v[212:215], v198 offset:35840
	ds_read_b128 v[216:219], v198 offset:36864
	ds_read_b128 v[220:223], v198 offset:37888
	ds_read_b128 v[224:227], v198 offset:38912
	ds_read_b128 v[228:231], v198 offset:39936
	global_load_lds_dwordx4 v[242:243], off
	v_lshl_add_u64 v[242:243], s[6:7], 0, v[158:159]
	s_mov_b32 m0, s70
	s_nop 0
	global_load_lds_dwordx4 v[242:243], off
	s_waitcnt vmcnt(8)
	s_waitcnt lgkmcnt(0)
	s_setprio 1
	s_waitcnt lgkmcnt(0)
	v_mfma_f32_16x16x32_bf16 v[142:145], v[50:53], v[200:203], v[142:145]
	v_mfma_f32_16x16x32_bf16 v[138:141], v[66:69], v[200:203], v[138:141]
	v_mfma_f32_16x16x32_bf16 v[126:129], v[50:53], v[208:211], v[126:129]
	v_mfma_f32_16x16x32_bf16 v[122:125], v[66:69], v[208:211], v[122:125]
	s_barrier
	v_mfma_f32_16x16x32_bf16 v[110:113], v[50:53], v[216:219], v[110:113]
	v_mfma_f32_16x16x32_bf16 v[106:109], v[66:69], v[216:219], v[106:109]
	v_mfma_f32_16x16x32_bf16 v[94:97], v[50:53], v[224:227], v[94:97]
	v_mfma_f32_16x16x32_bf16 v[90:93], v[66:69], v[224:227], v[90:93]
	v_mfma_f32_16x16x32_bf16 v[142:145], v[54:57], v[204:207], v[142:145]
	v_mfma_f32_16x16x32_bf16 v[138:141], v[70:73], v[204:207], v[138:141]
	v_mfma_f32_16x16x32_bf16 v[126:129], v[54:57], v[212:215], v[126:129]
	v_mfma_f32_16x16x32_bf16 v[122:125], v[70:73], v[212:215], v[122:125]
	v_mfma_f32_16x16x32_bf16 v[110:113], v[54:57], v[220:223], v[110:113]
	v_mfma_f32_16x16x32_bf16 v[106:109], v[70:73], v[220:223], v[106:109]
	v_mfma_f32_16x16x32_bf16 v[94:97], v[54:57], v[228:231], v[94:97]
	v_mfma_f32_16x16x32_bf16 v[90:93], v[70:73], v[228:231], v[90:93]
	s_setprio 0
	s_setprio 1
	v_mfma_f32_16x16x32_bf16 v[134:137], v[146:149], v[200:203], v[134:137]
	v_mfma_f32_16x16x32_bf16 v[130:133], v[184:187], v[200:203], v[130:133]
	v_mfma_f32_16x16x32_bf16 v[118:121], v[146:149], v[208:211], v[118:121]
	v_mfma_f32_16x16x32_bf16 v[114:117], v[184:187], v[208:211], v[114:117]
	v_mfma_f32_16x16x32_bf16 v[102:105], v[146:149], v[216:219], v[102:105]
	v_mfma_f32_16x16x32_bf16 v[98:101], v[184:187], v[216:219], v[98:101]
	v_mfma_f32_16x16x32_bf16 v[86:89], v[146:149], v[224:227], v[86:89]
	v_mfma_f32_16x16x32_bf16 v[82:85], v[184:187], v[224:227], v[82:85]
	v_mfma_f32_16x16x32_bf16 v[134:137], v[150:153], v[204:207], v[134:137]
	v_mfma_f32_16x16x32_bf16 v[130:133], v[188:191], v[204:207], v[130:133]
	v_mfma_f32_16x16x32_bf16 v[118:121], v[150:153], v[212:215], v[118:121]
	v_mfma_f32_16x16x32_bf16 v[114:117], v[188:191], v[212:215], v[114:117]
	v_mfma_f32_16x16x32_bf16 v[102:105], v[150:153], v[220:223], v[102:105]
	v_mfma_f32_16x16x32_bf16 v[98:101], v[188:191], v[220:223], v[98:101]
	v_mfma_f32_16x16x32_bf16 v[86:89], v[150:153], v[228:231], v[86:89]
	v_mfma_f32_16x16x32_bf16 v[82:85], v[188:191], v[228:231], v[82:85]
	s_setprio 0
	s_barrier
	s_add_i32 s6, s12, s61
	v_lshl_add_u64 v[192:193], v[192:193], 0, s[38:39]
	s_mov_b32 m0, s6
	ds_read_b128 v[200:203], v198 offset:49152
	ds_read_b128 v[204:207], v198 offset:50176
	ds_read_b128 v[208:211], v198 offset:51200
	ds_read_b128 v[212:215], v198 offset:52224
	ds_read_b128 v[216:219], v198 offset:53248
	ds_read_b128 v[220:223], v198 offset:54272
	ds_read_b128 v[224:227], v198 offset:55296
	ds_read_b128 v[228:231], v198 offset:56320
	global_load_lds_dwordx4 v[192:193], off
	v_lshl_add_u64 v[192:193], v[232:233], 0, s[38:39]
	s_add_i32 m0, s6, 0x2000
	s_add_i32 s6, s13, s61
	global_load_lds_dwordx4 v[192:193], off
	v_lshl_add_u64 v[192:193], v[234:235], 0, s[38:39]
	s_mov_b32 m0, s6
	s_nop 0
	global_load_lds_dwordx4 v[192:193], off
	v_lshl_add_u64 v[192:193], v[236:237], 0, s[38:39]
	s_add_i32 m0, s6, 0x2000
	s_nop 0
	global_load_lds_dwordx4 v[192:193], off
	v_lshl_add_u64 v[192:193], v[238:239], 0, s[38:39]
	s_mov_b32 m0, s81
	s_nop 0
	global_load_lds_dwordx4 v[192:193], off
	v_lshl_add_u64 v[192:193], v[240:241], 0, s[38:39]
	s_mov_b32 m0, s82
	s_nop 0
	global_load_lds_dwordx4 v[192:193], off
	s_waitcnt vmcnt(8)
	s_waitcnt lgkmcnt(0)
	s_setprio 1
	s_waitcnt lgkmcnt(0)
	v_mfma_f32_16x16x32_bf16 v[78:81], v[50:53], v[200:203], v[78:81]
	v_mfma_f32_16x16x32_bf16 v[74:77], v[66:69], v[200:203], v[74:77]
	v_mfma_f32_16x16x32_bf16 v[62:65], v[50:53], v[208:211], v[62:65]
	v_mfma_f32_16x16x32_bf16 v[58:61], v[66:69], v[208:211], v[58:61]
	s_barrier
	v_mfma_f32_16x16x32_bf16 v[30:33], v[50:53], v[216:219], v[30:33]
	v_mfma_f32_16x16x32_bf16 v[26:29], v[66:69], v[216:219], v[26:29]
	v_mfma_f32_16x16x32_bf16 v[14:17], v[50:53], v[224:227], v[14:17]
	v_mfma_f32_16x16x32_bf16 v[10:13], v[66:69], v[224:227], v[10:13]
	v_mfma_f32_16x16x32_bf16 v[78:81], v[54:57], v[204:207], v[78:81]
	v_mfma_f32_16x16x32_bf16 v[74:77], v[70:73], v[204:207], v[74:77]
	v_mfma_f32_16x16x32_bf16 v[62:65], v[54:57], v[212:215], v[62:65]
	v_mfma_f32_16x16x32_bf16 v[58:61], v[70:73], v[212:215], v[58:61]
	v_mfma_f32_16x16x32_bf16 v[30:33], v[54:57], v[220:223], v[30:33]
	v_mfma_f32_16x16x32_bf16 v[26:29], v[70:73], v[220:223], v[26:29]
	v_mfma_f32_16x16x32_bf16 v[14:17], v[54:57], v[228:231], v[14:17]
	v_mfma_f32_16x16x32_bf16 v[10:13], v[70:73], v[228:231], v[10:13]
	s_setprio 0
	s_setprio 1
	v_mfma_f32_16x16x32_bf16 v[34:37], v[146:149], v[200:203], v[34:37]
	v_mfma_f32_16x16x32_bf16 v[70:73], v[150:153], v[204:207], v[34:37]
	v_mfma_f32_16x16x32_bf16 v[34:37], v[184:187], v[200:203], v[38:41]
	v_mfma_f32_16x16x32_bf16 v[66:69], v[188:191], v[204:207], v[34:37]
	v_mfma_f32_16x16x32_bf16 v[34:37], v[146:149], v[208:211], v[46:49]
	v_mfma_f32_16x16x32_bf16 v[46:49], v[150:153], v[212:215], v[34:37]
	v_mfma_f32_16x16x32_bf16 v[34:37], v[184:187], v[208:211], v[42:45]
	v_mfma_f32_16x16x32_bf16 v[22:25], v[146:149], v[216:219], v[22:25]
	v_mfma_f32_16x16x32_bf16 v[18:21], v[184:187], v[216:219], v[18:21]
	v_mfma_f32_16x16x32_bf16 v[6:9], v[146:149], v[224:227], v[6:9]
	v_mfma_f32_16x16x32_bf16 v[2:5], v[184:187], v[224:227], v[2:5]
	v_mfma_f32_16x16x32_bf16 v[42:45], v[188:191], v[212:215], v[34:37]
	v_mfma_f32_16x16x32_bf16 v[22:25], v[150:153], v[220:223], v[22:25]
	v_mfma_f32_16x16x32_bf16 v[18:21], v[188:191], v[220:223], v[18:21]
	v_mfma_f32_16x16x32_bf16 v[6:9], v[150:153], v[228:231], v[6:9]
	v_mfma_f32_16x16x32_bf16 v[2:5], v[188:191], v[228:231], v[2:5]
	s_setprio 0
	s_barrier
	s_add_u32 s4, s4, 0x100
	s_addc_u32 s5, s5, 0
	s_add_u32 s8, s8, 0x100
	s_addc_u32 s9, s9, 0
	s_cmp_ge_i32 s11, s83
	s_mov_b32 s6, s11
	s_cbranch_scc0 .LBB0_3126

.LBB0_3613:
	v_add_u32_e32 v158, s64, v229
	v_add_u32_e32 v174, s65, v229
	ds_read_b128 v[146:149], v158
	ds_read_b128 v[150:153], v158 offset:1024
	ds_read_b128 v[154:157], v158 offset:2048
	ds_read_b128 v[158:161], v158 offset:3072
	ds_read_b128 v[162:165], v174
	ds_read_b128 v[166:169], v174 offset:1024
	ds_read_b128 v[170:173], v174 offset:2048
	ds_read_b128 v[174:177], v174 offset:3072
	s_add_i32 s80, s42, 2
	s_add_u32 s81, s40, 0x80
	s_addc_u32 s43, s41, 0
	s_cmp_eq_u32 s61, s42
	s_cselect_b32 s42, s4, s81
	s_cselect_b32 s43, s5, s43
	s_cselect_b32 s83, s39, s71
	s_cselect_b32 s82, s38, s70
	v_lshl_add_u64 v[210:211], s[40:41], 0, v[138:139]
	s_add_i32 m0, s51, 0xc000
	ds_read_b128 v[178:181], v231
	ds_read_b128 v[182:185], v231 offset:1024
	ds_read_b128 v[186:189], v231 offset:2048
	ds_read_b128 v[190:193], v231 offset:3072
	ds_read_b128 v[194:197], v231 offset:4096
	ds_read_b128 v[198:201], v231 offset:5120
	ds_read_b128 v[202:205], v231 offset:6144
	ds_read_b128 v[206:209], v231 offset:7168
	global_load_lds_dwordx4 v[210:211], off
	v_lshl_add_u64 v[210:211], s[40:41], 0, v[140:141]
	s_add_i32 m0, s51, 0xe000
	s_nop 0
	global_load_lds_dwordx4 v[210:211], off
	s_waitcnt vmcnt(8)
	s_waitcnt lgkmcnt(0)
	s_setprio 1
	s_waitcnt lgkmcnt(0)
	v_mfma_i32_16x16x64_i8 v[126:129], v[146:149], v[178:181], v[126:129]
	v_mfma_i32_16x16x64_i8 v[122:125], v[154:157], v[178:181], v[122:125]
	v_mfma_i32_16x16x64_i8 v[118:121], v[146:149], v[186:189], v[118:121]
	v_mfma_i32_16x16x64_i8 v[114:117], v[154:157], v[186:189], v[114:117]
	s_barrier
	v_mfma_i32_16x16x64_i8 v[106:109], v[146:149], v[194:197], v[106:109]
	v_mfma_i32_16x16x64_i8 v[98:101], v[154:157], v[194:197], v[98:101]
	v_mfma_i32_16x16x64_i8 v[90:93], v[146:149], v[202:205], v[90:93]
	v_mfma_i32_16x16x64_i8 v[82:85], v[154:157], v[202:205], v[82:85]
	v_mfma_i32_16x16x64_i8 v[126:129], v[150:153], v[182:185], v[126:129]
	v_mfma_i32_16x16x64_i8 v[122:125], v[158:161], v[182:185], v[122:125]
	v_mfma_i32_16x16x64_i8 v[118:121], v[150:153], v[190:193], v[118:121]
	v_mfma_i32_16x16x64_i8 v[114:117], v[158:161], v[190:193], v[114:117]
	v_mfma_i32_16x16x64_i8 v[106:109], v[150:153], v[198:201], v[106:109]
	v_mfma_i32_16x16x64_i8 v[98:101], v[158:161], v[198:201], v[98:101]
	v_mfma_i32_16x16x64_i8 v[90:93], v[150:153], v[206:209], v[90:93]
	v_mfma_i32_16x16x64_i8 v[82:85], v[158:161], v[206:209], v[82:85]
	s_setprio 0
	s_setprio 1
	v_mfma_i32_16x16x64_i8 v[110:113], v[162:165], v[178:181], v[110:113]
	v_mfma_i32_16x16x64_i8 v[102:105], v[170:173], v[178:181], v[102:105]
	v_mfma_i32_16x16x64_i8 v[94:97], v[162:165], v[186:189], v[94:97]
	v_mfma_i32_16x16x64_i8 v[86:89], v[170:173], v[186:189], v[86:89]
	v_mfma_i32_16x16x64_i8 v[78:81], v[162:165], v[194:197], v[78:81]
	v_mfma_i32_16x16x64_i8 v[74:77], v[170:173], v[194:197], v[74:77]
	v_mfma_i32_16x16x64_i8 v[70:73], v[162:165], v[202:205], v[70:73]
	v_mfma_i32_16x16x64_i8 v[66:69], v[170:173], v[202:205], v[66:69]
	v_mfma_i32_16x16x64_i8 v[110:113], v[166:169], v[182:185], v[110:113]
	v_mfma_i32_16x16x64_i8 v[102:105], v[174:177], v[182:185], v[102:105]
	v_mfma_i32_16x16x64_i8 v[94:97], v[166:169], v[190:193], v[94:97]
	v_mfma_i32_16x16x64_i8 v[86:89], v[174:177], v[190:193], v[86:89]
	v_mfma_i32_16x16x64_i8 v[78:81], v[166:169], v[198:201], v[78:81]
	v_mfma_i32_16x16x64_i8 v[74:77], v[174:177], v[198:201], v[74:77]
	v_mfma_i32_16x16x64_i8 v[70:73], v[166:169], v[206:209], v[70:73]
	v_mfma_i32_16x16x64_i8 v[66:69], v[174:177], v[206:209], v[66:69]
	s_setprio 0
	s_barrier
	s_add_i32 s81, s64, s50
	v_lshl_add_u64 v[210:211], s[82:83], 0, v[132:133]
	s_mov_b32 m0, s81
	ds_read_b128 v[178:181], v231 offset:16384
	ds_read_b128 v[182:185], v231 offset:17408
	ds_read_b128 v[186:189], v231 offset:18432
	ds_read_b128 v[190:193], v231 offset:19456
	ds_read_b128 v[194:197], v231 offset:20480
	ds_read_b128 v[198:201], v231 offset:21504
	ds_read_b128 v[202:205], v231 offset:22528
	ds_read_b128 v[206:209], v231 offset:23552
	global_load_lds_dwordx4 v[210:211], off
	s_add_i32 m0, s81, 0x2000
	v_lshl_add_u64 v[212:213], s[82:83], 0, v[136:137]
	s_add_u32 s82, s82, s8
	s_addc_u32 s83, s83, s9
	s_add_i32 s81, s65, s50
	global_load_lds_dwordx4 v[212:213], off
	v_lshl_add_u64 v[214:215], s[82:83], 0, v[132:133]
	s_mov_b32 m0, s81
	v_lshl_add_u64 v[216:217], s[82:83], 0, v[136:137]
	global_load_lds_dwordx4 v[214:215], off
	s_add_i32 m0, s81, 0x2000
	v_lshl_add_u64 v[218:219], s[42:43], 0, v[130:131]
	global_load_lds_dwordx4 v[216:217], off
	s_mov_b32 m0, s51
	v_lshl_add_u64 v[220:221], s[42:43], 0, v[134:135]
	global_load_lds_dwordx4 v[218:219], off
	s_mov_b32 m0, s52
	s_nop 0
	global_load_lds_dwordx4 v[220:221], off
	s_waitcnt vmcnt(8)
	s_waitcnt lgkmcnt(0)
	s_setprio 1
	s_waitcnt lgkmcnt(0)
	v_mfma_i32_16x16x64_i8 v[62:65], v[146:149], v[178:181], v[62:65]
	v_mfma_i32_16x16x64_i8 v[58:61], v[154:157], v[178:181], v[58:61]
	v_mfma_i32_16x16x64_i8 v[54:57], v[146:149], v[186:189], v[54:57]
	v_mfma_i32_16x16x64_i8 v[50:53], v[154:157], v[186:189], v[50:53]
	s_barrier
	v_mfma_i32_16x16x64_i8 v[42:45], v[146:149], v[194:197], v[42:45]
	v_mfma_i32_16x16x64_i8 v[34:37], v[154:157], v[194:197], v[34:37]
	v_mfma_i32_16x16x64_i8 v[26:29], v[146:149], v[202:205], v[26:29]
	v_mfma_i32_16x16x64_i8 v[18:21], v[154:157], v[202:205], v[18:21]
	v_mfma_i32_16x16x64_i8 v[62:65], v[150:153], v[182:185], v[62:65]
	v_mfma_i32_16x16x64_i8 v[58:61], v[158:161], v[182:185], v[58:61]
	v_mfma_i32_16x16x64_i8 v[54:57], v[150:153], v[190:193], v[54:57]
	v_mfma_i32_16x16x64_i8 v[50:53], v[158:161], v[190:193], v[50:53]
	v_mfma_i32_16x16x64_i8 v[42:45], v[150:153], v[198:201], v[42:45]
	v_mfma_i32_16x16x64_i8 v[34:37], v[158:161], v[198:201], v[34:37]
	v_mfma_i32_16x16x64_i8 v[26:29], v[150:153], v[206:209], v[26:29]
	v_mfma_i32_16x16x64_i8 v[18:21], v[158:161], v[206:209], v[18:21]
	s_setprio 0
	s_setprio 1
	v_mfma_i32_16x16x64_i8 v[46:49], v[162:165], v[178:181], v[46:49]
	v_mfma_i32_16x16x64_i8 v[38:41], v[170:173], v[178:181], v[38:41]
	v_mfma_i32_16x16x64_i8 v[30:33], v[162:165], v[186:189], v[30:33]
	v_mfma_i32_16x16x64_i8 v[22:25], v[170:173], v[186:189], v[22:25]
	v_mfma_i32_16x16x64_i8 v[14:17], v[162:165], v[194:197], v[14:17]
	v_mfma_i32_16x16x64_i8 v[10:13], v[170:173], v[194:197], v[10:13]
	v_mfma_i32_16x16x64_i8 v[6:9], v[162:165], v[202:205], v[6:9]
	v_mfma_i32_16x16x64_i8 v[2:5], v[170:173], v[202:205], v[2:5]
	v_mfma_i32_16x16x64_i8 v[46:49], v[166:169], v[182:185], v[46:49]
	v_mfma_i32_16x16x64_i8 v[38:41], v[174:177], v[182:185], v[38:41]
	v_mfma_i32_16x16x64_i8 v[30:33], v[166:169], v[190:193], v[30:33]
	v_mfma_i32_16x16x64_i8 v[22:25], v[174:177], v[190:193], v[22:25]
	v_mfma_i32_16x16x64_i8 v[14:17], v[166:169], v[198:201], v[14:17]
	v_mfma_i32_16x16x64_i8 v[10:13], v[174:177], v[198:201], v[10:13]
	v_mfma_i32_16x16x64_i8 v[6:9], v[166:169], v[206:209], v[6:9]
	v_mfma_i32_16x16x64_i8 v[2:5], v[174:177], v[206:209], v[2:5]
	s_setprio 0
	s_barrier
	s_add_i32 s81, 0, 0x18000
	s_add_i32 s82, 0, 0x1c000
	v_add_u32_e32 v158, s81, v229
	v_add_u32_e32 v174, s82, v229
	ds_read_b128 v[146:149], v158
	ds_read_b128 v[150:153], v158 offset:1024
	ds_read_b128 v[154:157], v158 offset:2048
	ds_read_b128 v[158:161], v158 offset:3072
	ds_read_b128 v[162:165], v174
	ds_read_b128 v[166:169], v174 offset:1024
	ds_read_b128 v[170:173], v174 offset:2048
	ds_read_b128 v[174:177], v174 offset:3072
	s_add_u32 s42, s42, s8
	s_addc_u32 s43, s43, s9
	s_mov_b32 m0, s53
	v_lshl_add_u64 v[222:223], s[42:43], 0, v[130:131]
	ds_read_b128 v[178:181], v231 offset:32768
	ds_read_b128 v[182:185], v231 offset:33792
	ds_read_b128 v[186:189], v231 offset:34816
	ds_read_b128 v[190:193], v231 offset:35840
	ds_read_b128 v[194:197], v231 offset:36864
	ds_read_b128 v[198:201], v231 offset:37888
	ds_read_b128 v[202:205], v231 offset:38912
	ds_read_b128 v[206:209], v231 offset:39936
	global_load_lds_dwordx4 v[222:223], off
	v_lshl_add_u64 v[222:223], s[42:43], 0, v[134:135]
	s_mov_b32 m0, s54
	s_nop 0
	global_load_lds_dwordx4 v[222:223], off
	s_waitcnt vmcnt(8)
	s_waitcnt lgkmcnt(0)
	s_setprio 1
	s_waitcnt lgkmcnt(0)
	v_mfma_i32_16x16x64_i8 v[126:129], v[146:149], v[178:181], v[126:129]
	v_mfma_i32_16x16x64_i8 v[122:125], v[154:157], v[178:181], v[122:125]
	v_mfma_i32_16x16x64_i8 v[118:121], v[146:149], v[186:189], v[118:121]
	v_mfma_i32_16x16x64_i8 v[114:117], v[154:157], v[186:189], v[114:117]
	s_barrier
	v_mfma_i32_16x16x64_i8 v[106:109], v[146:149], v[194:197], v[106:109]
	v_mfma_i32_16x16x64_i8 v[98:101], v[154:157], v[194:197], v[98:101]
	v_mfma_i32_16x16x64_i8 v[90:93], v[146:149], v[202:205], v[90:93]
	v_mfma_i32_16x16x64_i8 v[82:85], v[154:157], v[202:205], v[82:85]
	v_mfma_i32_16x16x64_i8 v[126:129], v[150:153], v[182:185], v[126:129]
	v_mfma_i32_16x16x64_i8 v[122:125], v[158:161], v[182:185], v[122:125]
	v_mfma_i32_16x16x64_i8 v[118:121], v[150:153], v[190:193], v[118:121]
	v_mfma_i32_16x16x64_i8 v[114:117], v[158:161], v[190:193], v[114:117]
	v_mfma_i32_16x16x64_i8 v[106:109], v[150:153], v[198:201], v[106:109]
	v_mfma_i32_16x16x64_i8 v[98:101], v[158:161], v[198:201], v[98:101]
	v_mfma_i32_16x16x64_i8 v[90:93], v[150:153], v[206:209], v[90:93]
	v_mfma_i32_16x16x64_i8 v[82:85], v[158:161], v[206:209], v[82:85]
	s_setprio 0
	s_setprio 1
	v_mfma_i32_16x16x64_i8 v[110:113], v[162:165], v[178:181], v[110:113]
	v_mfma_i32_16x16x64_i8 v[102:105], v[170:173], v[178:181], v[102:105]
	v_mfma_i32_16x16x64_i8 v[94:97], v[162:165], v[186:189], v[94:97]
	v_mfma_i32_16x16x64_i8 v[86:89], v[170:173], v[186:189], v[86:89]
	v_mfma_i32_16x16x64_i8 v[78:81], v[162:165], v[194:197], v[78:81]
	v_mfma_i32_16x16x64_i8 v[74:77], v[170:173], v[194:197], v[74:77]
	v_mfma_i32_16x16x64_i8 v[70:73], v[162:165], v[202:205], v[70:73]
	v_mfma_i32_16x16x64_i8 v[66:69], v[170:173], v[202:205], v[66:69]
	v_mfma_i32_16x16x64_i8 v[110:113], v[166:169], v[182:185], v[110:113]
	v_mfma_i32_16x16x64_i8 v[102:105], v[174:177], v[182:185], v[102:105]
	v_mfma_i32_16x16x64_i8 v[94:97], v[166:169], v[190:193], v[94:97]
	v_mfma_i32_16x16x64_i8 v[86:89], v[174:177], v[190:193], v[86:89]
	v_mfma_i32_16x16x64_i8 v[78:81], v[166:169], v[198:201], v[78:81]
	v_mfma_i32_16x16x64_i8 v[74:77], v[174:177], v[198:201], v[74:77]
	v_mfma_i32_16x16x64_i8 v[70:73], v[166:169], v[206:209], v[70:73]
	v_mfma_i32_16x16x64_i8 v[66:69], v[174:177], v[206:209], v[66:69]
	s_setprio 0
	s_barrier
	s_add_i32 s42, s81, s50
	v_lshl_add_u64 v[210:211], v[210:211], 0, s[30:31]
	s_mov_b32 m0, s42
	ds_read_b128 v[178:181], v231 offset:49152
	ds_read_b128 v[182:185], v231 offset:50176
	ds_read_b128 v[186:189], v231 offset:51200
	ds_read_b128 v[190:193], v231 offset:52224
	ds_read_b128 v[194:197], v231 offset:53248
	ds_read_b128 v[198:201], v231 offset:54272
	ds_read_b128 v[202:205], v231 offset:55296
	ds_read_b128 v[206:209], v231 offset:56320
	global_load_lds_dwordx4 v[210:211], off
	v_lshl_add_u64 v[210:211], v[212:213], 0, s[30:31]
	s_add_i32 m0, s42, 0x2000
	s_add_i32 s42, s82, s50
	global_load_lds_dwordx4 v[210:211], off
	v_lshl_add_u64 v[210:211], v[214:215], 0, s[30:31]
	s_mov_b32 m0, s42
	s_nop 0
	global_load_lds_dwordx4 v[210:211], off
	v_lshl_add_u64 v[210:211], v[216:217], 0, s[30:31]
	s_add_i32 m0, s42, 0x2000
	s_nop 0
	global_load_lds_dwordx4 v[210:211], off
	v_lshl_add_u64 v[210:211], v[218:219], 0, s[30:31]
	s_mov_b32 m0, s57
	s_nop 0
	global_load_lds_dwordx4 v[210:211], off
	v_lshl_add_u64 v[210:211], v[220:221], 0, s[30:31]
	s_mov_b32 m0, s58
	s_nop 0
	global_load_lds_dwordx4 v[210:211], off
	s_waitcnt vmcnt(8)
	s_waitcnt lgkmcnt(0)
	s_setprio 1
	s_waitcnt lgkmcnt(0)
	v_mfma_i32_16x16x64_i8 v[62:65], v[146:149], v[178:181], v[62:65]
	v_mfma_i32_16x16x64_i8 v[58:61], v[154:157], v[178:181], v[58:61]
	v_mfma_i32_16x16x64_i8 v[54:57], v[146:149], v[186:189], v[54:57]
	v_mfma_i32_16x16x64_i8 v[50:53], v[154:157], v[186:189], v[50:53]
	s_barrier
	v_mfma_i32_16x16x64_i8 v[42:45], v[146:149], v[194:197], v[42:45]
	v_mfma_i32_16x16x64_i8 v[34:37], v[154:157], v[194:197], v[34:37]
	v_mfma_i32_16x16x64_i8 v[26:29], v[146:149], v[202:205], v[26:29]
	v_mfma_i32_16x16x64_i8 v[18:21], v[154:157], v[202:205], v[18:21]
	v_mfma_i32_16x16x64_i8 v[62:65], v[150:153], v[182:185], v[62:65]
	v_mfma_i32_16x16x64_i8 v[58:61], v[158:161], v[182:185], v[58:61]
	v_mfma_i32_16x16x64_i8 v[54:57], v[150:153], v[190:193], v[54:57]
	v_mfma_i32_16x16x64_i8 v[50:53], v[158:161], v[190:193], v[50:53]
	v_mfma_i32_16x16x64_i8 v[42:45], v[150:153], v[198:201], v[42:45]
	v_mfma_i32_16x16x64_i8 v[34:37], v[158:161], v[198:201], v[34:37]
	v_mfma_i32_16x16x64_i8 v[26:29], v[150:153], v[206:209], v[26:29]
	v_mfma_i32_16x16x64_i8 v[18:21], v[158:161], v[206:209], v[18:21]
	s_setprio 0
	s_setprio 1
	v_mfma_i32_16x16x64_i8 v[46:49], v[162:165], v[178:181], v[46:49]
	v_mfma_i32_16x16x64_i8 v[38:41], v[170:173], v[178:181], v[38:41]
	v_mfma_i32_16x16x64_i8 v[30:33], v[162:165], v[186:189], v[30:33]
	v_mfma_i32_16x16x64_i8 v[22:25], v[170:173], v[186:189], v[22:25]
	v_mfma_i32_16x16x64_i8 v[14:17], v[162:165], v[194:197], v[14:17]
	v_mfma_i32_16x16x64_i8 v[10:13], v[170:173], v[194:197], v[10:13]
	v_mfma_i32_16x16x64_i8 v[6:9], v[162:165], v[202:205], v[6:9]
	v_mfma_i32_16x16x64_i8 v[2:5], v[170:173], v[202:205], v[2:5]
	v_mfma_i32_16x16x64_i8 v[46:49], v[166:169], v[182:185], v[46:49]
	v_mfma_i32_16x16x64_i8 v[38:41], v[174:177], v[182:185], v[38:41]
	v_mfma_i32_16x16x64_i8 v[30:33], v[166:169], v[190:193], v[30:33]
	v_mfma_i32_16x16x64_i8 v[22:25], v[174:177], v[190:193], v[22:25]
	v_mfma_i32_16x16x64_i8 v[14:17], v[166:169], v[198:201], v[14:17]
	v_mfma_i32_16x16x64_i8 v[10:13], v[174:177], v[198:201], v[10:13]
	v_mfma_i32_16x16x64_i8 v[6:9], v[166:169], v[206:209], v[6:9]
	v_mfma_i32_16x16x64_i8 v[2:5], v[174:177], v[206:209], v[2:5]
	s_setprio 0
	s_barrier
	s_add_u32 s40, s40, 0x100
	s_addc_u32 s41, s41, 0
	s_add_u32 s70, s70, 0x100
	s_addc_u32 s71, s71, 0
	s_cmp_ge_i32 s80, s60
	s_mov_b32 s42, s80
	s_cbranch_scc0 .LBB0_3613
	v_cvt_f32_i32_e32 v214, v126
	v_cvt_f32_i32_e32 v215, v127
	v_cvt_f32_i32_e32 v212, v128
	v_cvt_f32_i32_e32 v213, v129
	v_cvt_f32_i32_e32 v218, v122
	v_cvt_f32_i32_e32 v219, v123
	v_cvt_f32_i32_e32 v216, v124
	v_cvt_f32_i32_e32 v217, v125
	v_cvt_f32_i32_e32 v222, v110
	v_cvt_f32_i32_e32 v223, v111
	v_cvt_f32_i32_e32 v220, v112
	v_cvt_f32_i32_e32 v221, v113
	v_cvt_f32_i32_e32 v226, v102
	v_cvt_f32_i32_e32 v227, v103
	v_cvt_f32_i32_e32 v224, v104
	v_cvt_f32_i32_e32 v225, v105
	v_cvt_f32_i32_e32 v194, v118
	v_cvt_f32_i32_e32 v195, v119
	v_cvt_f32_i32_e32 v192, v120
	v_cvt_f32_i32_e32 v193, v121
	v_cvt_f32_i32_e32 v200, v114
	v_cvt_f32_i32_e32 v201, v115
	v_cvt_f32_i32_e32 v198, v116
	v_cvt_f32_i32_e32 v199, v117
	v_cvt_f32_i32_e32 v206, v94
	v_cvt_f32_i32_e32 v207, v95
	v_cvt_f32_i32_e32 v202, v96
	v_cvt_f32_i32_e32 v203, v97
	v_cvt_f32_i32_e32 v208, v86
	v_cvt_f32_i32_e32 v209, v87
	v_cvt_f32_i32_e32 v204, v88
	v_cvt_f32_i32_e32 v205, v89
	v_cvt_f32_i32_e32 v178, v106
	v_cvt_f32_i32_e32 v179, v107
	v_cvt_f32_i32_e32 v176, v108
	v_cvt_f32_i32_e32 v177, v109
	v_cvt_f32_i32_e32 v182, v98
	v_cvt_f32_i32_e32 v183, v99
	v_cvt_f32_i32_e32 v180, v100
	v_cvt_f32_i32_e32 v181, v101
	v_cvt_f32_i32_e32 v188, v78
	v_cvt_f32_i32_e32 v189, v79
	v_cvt_f32_i32_e32 v184, v80
	v_cvt_f32_i32_e32 v185, v81
	v_cvt_f32_i32_e32 v190, v74
	v_cvt_f32_i32_e32 v191, v75
	v_cvt_f32_i32_e32 v186, v76
	v_cvt_f32_i32_e32 v187, v77
	v_cvt_f32_i32_e32 v162, v90
	v_cvt_f32_i32_e32 v163, v91
	v_cvt_f32_i32_e32 v160, v92
	v_cvt_f32_i32_e32 v161, v93
	v_cvt_f32_i32_e32 v166, v82
	v_cvt_f32_i32_e32 v167, v83
	v_cvt_f32_i32_e32 v164, v84
	v_cvt_f32_i32_e32 v165, v85
	v_cvt_f32_i32_e32 v172, v70
	v_cvt_f32_i32_e32 v173, v71
	v_cvt_f32_i32_e32 v168, v72
	v_cvt_f32_i32_e32 v169, v73
	v_cvt_f32_i32_e32 v174, v66
	v_cvt_f32_i32_e32 v175, v67
	v_cvt_f32_i32_e32 v170, v68
	v_cvt_f32_i32_e32 v171, v69
	v_cvt_f32_i32_e32 v146, v62
	v_cvt_f32_i32_e32 v147, v63
	v_cvt_f32_i32_e32 v128, v64
	v_cvt_f32_i32_e32 v129, v65
	v_cvt_f32_i32_e32 v150, v58
	v_cvt_f32_i32_e32 v151, v59
	v_cvt_f32_i32_e32 v148, v60
	v_cvt_f32_i32_e32 v149, v61
	v_cvt_f32_i32_e32 v156, v46
	v_cvt_f32_i32_e32 v157, v47
	v_cvt_f32_i32_e32 v152, v48
	v_cvt_f32_i32_e32 v153, v49
	v_cvt_f32_i32_e32 v158, v38
	v_cvt_f32_i32_e32 v159, v39
	v_cvt_f32_i32_e32 v154, v40
	v_cvt_f32_i32_e32 v155, v41
	v_cvt_f32_i32_e32 v114, v54
	v_cvt_f32_i32_e32 v115, v55
	v_cvt_f32_i32_e32 v112, v56
	v_cvt_f32_i32_e32 v113, v57
	v_cvt_f32_i32_e32 v118, v50
	v_cvt_f32_i32_e32 v119, v51
	v_cvt_f32_i32_e32 v116, v52
	v_cvt_f32_i32_e32 v117, v53
	v_cvt_f32_i32_e32 v124, v30
	v_cvt_f32_i32_e32 v125, v31
	v_cvt_f32_i32_e32 v120, v32
	v_cvt_f32_i32_e32 v121, v33
	v_cvt_f32_i32_e32 v126, v22
	v_cvt_f32_i32_e32 v127, v23
	v_cvt_f32_i32_e32 v122, v24
	v_cvt_f32_i32_e32 v123, v25
	v_cvt_f32_i32_e32 v64, v42
	v_cvt_f32_i32_e32 v65, v43
	v_cvt_f32_i32_e32 v62, v44
	v_cvt_f32_i32_e32 v63, v45
	v_cvt_f32_i32_e32 v68, v34
	v_cvt_f32_i32_e32 v69, v35
	v_cvt_f32_i32_e32 v66, v36
	v_cvt_f32_i32_e32 v67, v37
	v_cvt_f32_i32_e32 v74, v14
	v_cvt_f32_i32_e32 v75, v15
	v_cvt_f32_i32_e32 v70, v16
	v_cvt_f32_i32_e32 v71, v17
	v_cvt_f32_i32_e32 v76, v10
	v_cvt_f32_i32_e32 v77, v11
	v_cvt_f32_i32_e32 v72, v12
	v_cvt_f32_i32_e32 v73, v13
	v_cvt_f32_i32_e32 v48, v26
	v_cvt_f32_i32_e32 v49, v27
	v_cvt_f32_i32_e32 v46, v28
	v_cvt_f32_i32_e32 v47, v29
	v_cvt_f32_i32_e32 v52, v18
	v_cvt_f32_i32_e32 v53, v19
	v_cvt_f32_i32_e32 v50, v20
	v_cvt_f32_i32_e32 v51, v21
	v_cvt_f32_i32_e32 v58, v6
	v_cvt_f32_i32_e32 v59, v7
	v_cvt_f32_i32_e32 v54, v8
	v_cvt_f32_i32_e32 v55, v9
	v_cvt_f32_i32_e32 v60, v2
	v_cvt_f32_i32_e32 v61, v3
	v_cvt_f32_i32_e32 v56, v4
	v_cvt_f32_i32_e32 v57, v5

.LBB0_3798:
	v_add_u32_e32 v138, s56, v188
	ds_read_b128 v[148:151], v138
	ds_read_b128 v[152:155], v138 offset:1024
	ds_read_b128 v[156:159], v138 offset:2048
	ds_read_b128 v[160:163], v138 offset:3072
	v_add_u32_e32 v138, s57, v188
	ds_read_b128 v[164:167], v138
	ds_read_b128 v[168:171], v138 offset:1024
	ds_read_b128 v[172:175], v138 offset:2048
	ds_read_b128 v[176:179], v138 offset:3072
	s_add_i32 s60, s28, 2
	s_add_u32 s61, s26, 0x80
	s_addc_u32 s29, s27, 0
	s_cmp_eq_u32 s54, s28
	s_cselect_b32 s28, s2, s61
	s_cselect_b32 s29, s3, s29
	s_cselect_b32 s63, s25, s35
	s_cselect_b32 s62, s24, s34
	v_lshl_add_u64 v[184:185], s[26:27], 0, v[140:141]
	s_add_i32 m0, s42, 0xc000
	ds_read_b128 v[180:183], v189
	ds_read_b128 v[190:193], v189 offset:1024
	ds_read_b128 v[194:197], v189 offset:2048
	ds_read_b128 v[198:201], v189 offset:3072
	ds_read_b128 v[202:205], v189 offset:4096
	ds_read_b128 v[206:209], v189 offset:5120
	ds_read_b128 v[210:213], v189 offset:6144
	ds_read_b128 v[214:217], v189 offset:7168
	global_load_lds_dwordx4 v[184:185], off
	v_lshl_add_u64 v[184:185], s[26:27], 0, v[142:143]
	s_add_i32 m0, s42, 0xe000
	s_nop 0
	global_load_lds_dwordx4 v[184:185], off
	s_waitcnt vmcnt(8)
	s_waitcnt lgkmcnt(0)
	s_setprio 1
	s_waitcnt lgkmcnt(0)
	v_mfma_i32_16x16x64_i8 v[126:129], v[148:151], v[180:183], v[126:129]
	v_mfma_i32_16x16x64_i8 v[122:125], v[156:159], v[180:183], v[122:125]
	v_mfma_i32_16x16x64_i8 v[118:121], v[148:151], v[194:197], v[118:121]
	v_mfma_i32_16x16x64_i8 v[114:117], v[156:159], v[194:197], v[114:117]
	s_barrier
	v_mfma_i32_16x16x64_i8 v[106:109], v[148:151], v[202:205], v[106:109]
	v_mfma_i32_16x16x64_i8 v[98:101], v[156:159], v[202:205], v[98:101]
	v_mfma_i32_16x16x64_i8 v[90:93], v[148:151], v[210:213], v[90:93]
	v_mfma_i32_16x16x64_i8 v[82:85], v[156:159], v[210:213], v[82:85]
	v_mfma_i32_16x16x64_i8 v[126:129], v[152:155], v[190:193], v[126:129]
	v_mfma_i32_16x16x64_i8 v[122:125], v[160:163], v[190:193], v[122:125]
	v_mfma_i32_16x16x64_i8 v[118:121], v[152:155], v[198:201], v[118:121]
	v_mfma_i32_16x16x64_i8 v[114:117], v[160:163], v[198:201], v[114:117]
	v_mfma_i32_16x16x64_i8 v[106:109], v[152:155], v[206:209], v[106:109]
	v_mfma_i32_16x16x64_i8 v[98:101], v[160:163], v[206:209], v[98:101]
	v_mfma_i32_16x16x64_i8 v[90:93], v[152:155], v[214:217], v[90:93]
	v_mfma_i32_16x16x64_i8 v[82:85], v[160:163], v[214:217], v[82:85]
	s_setprio 0
	s_setprio 1
	v_mfma_i32_16x16x64_i8 v[110:113], v[164:167], v[180:183], v[110:113]
	v_mfma_i32_16x16x64_i8 v[102:105], v[172:175], v[180:183], v[102:105]
	v_mfma_i32_16x16x64_i8 v[94:97], v[164:167], v[194:197], v[94:97]
	v_mfma_i32_16x16x64_i8 v[86:89], v[172:175], v[194:197], v[86:89]
	v_mfma_i32_16x16x64_i8 v[78:81], v[164:167], v[202:205], v[78:81]
	v_mfma_i32_16x16x64_i8 v[74:77], v[172:175], v[202:205], v[74:77]
	v_mfma_i32_16x16x64_i8 v[70:73], v[164:167], v[210:213], v[70:73]
	v_mfma_i32_16x16x64_i8 v[66:69], v[172:175], v[210:213], v[66:69]
	v_mfma_i32_16x16x64_i8 v[110:113], v[168:171], v[190:193], v[110:113]
	v_mfma_i32_16x16x64_i8 v[102:105], v[176:179], v[190:193], v[102:105]
	v_mfma_i32_16x16x64_i8 v[94:97], v[168:171], v[198:201], v[94:97]
	v_mfma_i32_16x16x64_i8 v[86:89], v[176:179], v[198:201], v[86:89]
	v_mfma_i32_16x16x64_i8 v[78:81], v[168:171], v[206:209], v[78:81]
	v_mfma_i32_16x16x64_i8 v[74:77], v[176:179], v[206:209], v[74:77]
	v_mfma_i32_16x16x64_i8 v[70:73], v[168:171], v[214:217], v[70:73]
	v_mfma_i32_16x16x64_i8 v[66:69], v[176:179], v[214:217], v[66:69]
	s_setprio 0
	s_barrier
	s_add_i32 s61, s56, s41
	v_lshl_add_u64 v[184:185], s[62:63], 0, v[132:133]
	s_mov_b32 m0, s61
	ds_read_b128 v[180:183], v189 offset:16384
	ds_read_b128 v[190:193], v189 offset:17408
	ds_read_b128 v[194:197], v189 offset:18432
	ds_read_b128 v[198:201], v189 offset:19456
	ds_read_b128 v[202:205], v189 offset:20480
	ds_read_b128 v[206:209], v189 offset:21504
	ds_read_b128 v[210:213], v189 offset:22528
	ds_read_b128 v[214:217], v189 offset:23552
	global_load_lds_dwordx4 v[184:185], off
	s_add_i32 m0, s61, 0x2000
	v_lshl_add_u64 v[218:219], s[62:63], 0, v[136:137]
	s_add_u32 s62, s62, s6
	s_addc_u32 s63, s63, s7
	s_add_i32 s61, s57, s41
	global_load_lds_dwordx4 v[218:219], off
	v_lshl_add_u64 v[220:221], s[62:63], 0, v[132:133]
	s_mov_b32 m0, s61
	v_lshl_add_u64 v[222:223], s[62:63], 0, v[136:137]
	global_load_lds_dwordx4 v[220:221], off
	s_add_i32 m0, s61, 0x2000
	v_lshl_add_u64 v[224:225], s[28:29], 0, v[130:131]
	global_load_lds_dwordx4 v[222:223], off
	s_mov_b32 m0, s42
	v_lshl_add_u64 v[226:227], s[28:29], 0, v[134:135]
	global_load_lds_dwordx4 v[224:225], off
	s_mov_b32 m0, s43
	s_nop 0
	global_load_lds_dwordx4 v[226:227], off
	s_waitcnt vmcnt(8)
	s_waitcnt lgkmcnt(0)
	s_setprio 1
	s_waitcnt lgkmcnt(0)
	v_mfma_i32_16x16x64_i8 v[62:65], v[148:151], v[180:183], v[62:65]
	v_mfma_i32_16x16x64_i8 v[58:61], v[156:159], v[180:183], v[58:61]
	v_mfma_i32_16x16x64_i8 v[54:57], v[148:151], v[194:197], v[54:57]
	v_mfma_i32_16x16x64_i8 v[50:53], v[156:159], v[194:197], v[50:53]
	s_barrier
	v_mfma_i32_16x16x64_i8 v[42:45], v[148:151], v[202:205], v[42:45]
	v_mfma_i32_16x16x64_i8 v[34:37], v[156:159], v[202:205], v[34:37]
	v_mfma_i32_16x16x64_i8 v[26:29], v[148:151], v[210:213], v[26:29]
	v_mfma_i32_16x16x64_i8 v[18:21], v[156:159], v[210:213], v[18:21]
	v_mfma_i32_16x16x64_i8 v[62:65], v[152:155], v[190:193], v[62:65]
	v_mfma_i32_16x16x64_i8 v[58:61], v[160:163], v[190:193], v[58:61]
	v_mfma_i32_16x16x64_i8 v[54:57], v[152:155], v[198:201], v[54:57]
	v_mfma_i32_16x16x64_i8 v[50:53], v[160:163], v[198:201], v[50:53]
	v_mfma_i32_16x16x64_i8 v[42:45], v[152:155], v[206:209], v[42:45]
	v_mfma_i32_16x16x64_i8 v[34:37], v[160:163], v[206:209], v[34:37]
	v_mfma_i32_16x16x64_i8 v[26:29], v[152:155], v[214:217], v[26:29]
	v_mfma_i32_16x16x64_i8 v[18:21], v[160:163], v[214:217], v[18:21]
	s_setprio 0
	s_setprio 1
	v_mfma_i32_16x16x64_i8 v[46:49], v[164:167], v[180:183], v[46:49]
	v_mfma_i32_16x16x64_i8 v[38:41], v[172:175], v[180:183], v[38:41]
	v_mfma_i32_16x16x64_i8 v[30:33], v[164:167], v[194:197], v[30:33]
	v_mfma_i32_16x16x64_i8 v[22:25], v[172:175], v[194:197], v[22:25]
	v_mfma_i32_16x16x64_i8 v[14:17], v[164:167], v[202:205], v[14:17]
	v_mfma_i32_16x16x64_i8 v[10:13], v[172:175], v[202:205], v[10:13]
	v_mfma_i32_16x16x64_i8 v[6:9], v[164:167], v[210:213], v[6:9]
	v_mfma_i32_16x16x64_i8 v[2:5], v[172:175], v[210:213], v[2:5]
	v_mfma_i32_16x16x64_i8 v[46:49], v[168:171], v[190:193], v[46:49]
	v_mfma_i32_16x16x64_i8 v[38:41], v[176:179], v[190:193], v[38:41]
	v_mfma_i32_16x16x64_i8 v[30:33], v[168:171], v[198:201], v[30:33]
	v_mfma_i32_16x16x64_i8 v[22:25], v[176:179], v[198:201], v[22:25]
	v_mfma_i32_16x16x64_i8 v[14:17], v[168:171], v[206:209], v[14:17]
	v_mfma_i32_16x16x64_i8 v[10:13], v[176:179], v[206:209], v[10:13]
	v_mfma_i32_16x16x64_i8 v[6:9], v[168:171], v[214:217], v[6:9]
	v_mfma_i32_16x16x64_i8 v[2:5], v[176:179], v[214:217], v[2:5]
	s_setprio 0
	s_barrier
	s_add_i32 s61, 0, 0x18000
	v_add_u32_e32 v138, s61, v188
	s_add_i32 s62, 0, 0x1c000
	ds_read_b128 v[148:151], v138
	ds_read_b128 v[152:155], v138 offset:1024
	ds_read_b128 v[156:159], v138 offset:2048
	ds_read_b128 v[160:163], v138 offset:3072
	v_add_u32_e32 v138, s62, v188
	ds_read_b128 v[164:167], v138
	ds_read_b128 v[168:171], v138 offset:1024
	ds_read_b128 v[172:175], v138 offset:2048
	ds_read_b128 v[176:179], v138 offset:3072
	s_add_u32 s28, s28, s6
	s_addc_u32 s29, s29, s7
	s_mov_b32 m0, s44
	v_lshl_add_u64 v[228:229], s[28:29], 0, v[130:131]
	ds_read_b128 v[180:183], v189 offset:32768
	ds_read_b128 v[190:193], v189 offset:33792
	ds_read_b128 v[194:197], v189 offset:34816
	ds_read_b128 v[198:201], v189 offset:35840
	ds_read_b128 v[202:205], v189 offset:36864
	ds_read_b128 v[206:209], v189 offset:37888
	ds_read_b128 v[210:213], v189 offset:38912
	ds_read_b128 v[214:217], v189 offset:39936
	global_load_lds_dwordx4 v[228:229], off
	v_lshl_add_u64 v[228:229], s[28:29], 0, v[134:135]
	s_mov_b32 m0, s45
	s_nop 0
	global_load_lds_dwordx4 v[228:229], off
	s_waitcnt vmcnt(8)
	s_waitcnt lgkmcnt(0)
	s_setprio 1
	s_waitcnt lgkmcnt(0)
	v_mfma_i32_16x16x64_i8 v[126:129], v[148:151], v[180:183], v[126:129]
	v_mfma_i32_16x16x64_i8 v[122:125], v[156:159], v[180:183], v[122:125]
	v_mfma_i32_16x16x64_i8 v[118:121], v[148:151], v[194:197], v[118:121]
	v_mfma_i32_16x16x64_i8 v[114:117], v[156:159], v[194:197], v[114:117]
	s_barrier
	v_mfma_i32_16x16x64_i8 v[106:109], v[148:151], v[202:205], v[106:109]
	v_mfma_i32_16x16x64_i8 v[98:101], v[156:159], v[202:205], v[98:101]
	v_mfma_i32_16x16x64_i8 v[90:93], v[148:151], v[210:213], v[90:93]
	v_mfma_i32_16x16x64_i8 v[82:85], v[156:159], v[210:213], v[82:85]
	v_mfma_i32_16x16x64_i8 v[126:129], v[152:155], v[190:193], v[126:129]
	v_mfma_i32_16x16x64_i8 v[122:125], v[160:163], v[190:193], v[122:125]
	v_mfma_i32_16x16x64_i8 v[118:121], v[152:155], v[198:201], v[118:121]
	v_mfma_i32_16x16x64_i8 v[114:117], v[160:163], v[198:201], v[114:117]
	v_mfma_i32_16x16x64_i8 v[106:109], v[152:155], v[206:209], v[106:109]
	v_mfma_i32_16x16x64_i8 v[98:101], v[160:163], v[206:209], v[98:101]
	v_mfma_i32_16x16x64_i8 v[90:93], v[152:155], v[214:217], v[90:93]
	v_mfma_i32_16x16x64_i8 v[82:85], v[160:163], v[214:217], v[82:85]
	s_setprio 0
	s_setprio 1
	v_mfma_i32_16x16x64_i8 v[110:113], v[164:167], v[180:183], v[110:113]
	v_mfma_i32_16x16x64_i8 v[102:105], v[172:175], v[180:183], v[102:105]
	v_mfma_i32_16x16x64_i8 v[94:97], v[164:167], v[194:197], v[94:97]
	v_mfma_i32_16x16x64_i8 v[86:89], v[172:175], v[194:197], v[86:89]
	v_mfma_i32_16x16x64_i8 v[78:81], v[164:167], v[202:205], v[78:81]
	v_mfma_i32_16x16x64_i8 v[74:77], v[172:175], v[202:205], v[74:77]
	v_mfma_i32_16x16x64_i8 v[70:73], v[164:167], v[210:213], v[70:73]
	v_mfma_i32_16x16x64_i8 v[66:69], v[172:175], v[210:213], v[66:69]
	v_mfma_i32_16x16x64_i8 v[110:113], v[168:171], v[190:193], v[110:113]
	v_mfma_i32_16x16x64_i8 v[102:105], v[176:179], v[190:193], v[102:105]
	v_mfma_i32_16x16x64_i8 v[94:97], v[168:171], v[198:201], v[94:97]
	v_mfma_i32_16x16x64_i8 v[86:89], v[176:179], v[198:201], v[86:89]
	v_mfma_i32_16x16x64_i8 v[78:81], v[168:171], v[206:209], v[78:81]
	v_mfma_i32_16x16x64_i8 v[74:77], v[176:179], v[206:209], v[74:77]
	v_mfma_i32_16x16x64_i8 v[70:73], v[168:171], v[214:217], v[70:73]
	v_mfma_i32_16x16x64_i8 v[66:69], v[176:179], v[214:217], v[66:69]
	s_setprio 0
	s_barrier
	s_add_i32 s28, s61, s41
	v_lshl_add_u64 v[184:185], v[184:185], 0, s[18:19]
	s_mov_b32 m0, s28
	ds_read_b128 v[180:183], v189 offset:49152
	ds_read_b128 v[190:193], v189 offset:50176
	ds_read_b128 v[194:197], v189 offset:51200
	ds_read_b128 v[198:201], v189 offset:52224
	ds_read_b128 v[202:205], v189 offset:53248
	ds_read_b128 v[206:209], v189 offset:54272
	ds_read_b128 v[210:213], v189 offset:55296
	ds_read_b128 v[214:217], v189 offset:56320
	global_load_lds_dwordx4 v[184:185], off
	v_lshl_add_u64 v[184:185], v[218:219], 0, s[18:19]
	s_add_i32 m0, s28, 0x2000
	s_add_i32 s28, s62, s41
	global_load_lds_dwordx4 v[184:185], off
	v_lshl_add_u64 v[184:185], v[220:221], 0, s[18:19]
	s_mov_b32 m0, s28
	s_nop 0
	global_load_lds_dwordx4 v[184:185], off
	v_lshl_add_u64 v[184:185], v[222:223], 0, s[18:19]
	s_add_i32 m0, s28, 0x2000
	s_nop 0
	global_load_lds_dwordx4 v[184:185], off
	v_lshl_add_u64 v[184:185], v[224:225], 0, s[18:19]
	s_mov_b32 m0, s49
	s_nop 0
	global_load_lds_dwordx4 v[184:185], off
	v_lshl_add_u64 v[184:185], v[226:227], 0, s[18:19]
	s_mov_b32 m0, s50
	s_nop 0
	global_load_lds_dwordx4 v[184:185], off
	s_waitcnt vmcnt(8)
	s_waitcnt lgkmcnt(0)
	s_setprio 1
	s_waitcnt lgkmcnt(0)
	v_mfma_i32_16x16x64_i8 v[62:65], v[148:151], v[180:183], v[62:65]
	v_mfma_i32_16x16x64_i8 v[58:61], v[156:159], v[180:183], v[58:61]
	v_mfma_i32_16x16x64_i8 v[54:57], v[148:151], v[194:197], v[54:57]
	v_mfma_i32_16x16x64_i8 v[50:53], v[156:159], v[194:197], v[50:53]
	s_barrier
	v_mfma_i32_16x16x64_i8 v[42:45], v[148:151], v[202:205], v[42:45]
	v_mfma_i32_16x16x64_i8 v[34:37], v[156:159], v[202:205], v[34:37]
	v_mfma_i32_16x16x64_i8 v[26:29], v[148:151], v[210:213], v[26:29]
	v_mfma_i32_16x16x64_i8 v[18:21], v[156:159], v[210:213], v[18:21]
	v_mfma_i32_16x16x64_i8 v[62:65], v[152:155], v[190:193], v[62:65]
	v_mfma_i32_16x16x64_i8 v[58:61], v[160:163], v[190:193], v[58:61]
	v_mfma_i32_16x16x64_i8 v[54:57], v[152:155], v[198:201], v[54:57]
	v_mfma_i32_16x16x64_i8 v[50:53], v[160:163], v[198:201], v[50:53]
	v_mfma_i32_16x16x64_i8 v[42:45], v[152:155], v[206:209], v[42:45]
	v_mfma_i32_16x16x64_i8 v[34:37], v[160:163], v[206:209], v[34:37]
	v_mfma_i32_16x16x64_i8 v[26:29], v[152:155], v[214:217], v[26:29]
	v_mfma_i32_16x16x64_i8 v[18:21], v[160:163], v[214:217], v[18:21]
	s_setprio 0
	s_setprio 1
	v_mfma_i32_16x16x64_i8 v[46:49], v[164:167], v[180:183], v[46:49]
	v_mfma_i32_16x16x64_i8 v[38:41], v[172:175], v[180:183], v[38:41]
	v_mfma_i32_16x16x64_i8 v[30:33], v[164:167], v[194:197], v[30:33]
	v_mfma_i32_16x16x64_i8 v[22:25], v[172:175], v[194:197], v[22:25]
	v_mfma_i32_16x16x64_i8 v[14:17], v[164:167], v[202:205], v[14:17]
	v_mfma_i32_16x16x64_i8 v[10:13], v[172:175], v[202:205], v[10:13]
	v_mfma_i32_16x16x64_i8 v[6:9], v[164:167], v[210:213], v[6:9]
	v_mfma_i32_16x16x64_i8 v[2:5], v[172:175], v[210:213], v[2:5]
	v_mfma_i32_16x16x64_i8 v[46:49], v[168:171], v[190:193], v[46:49]
	v_mfma_i32_16x16x64_i8 v[38:41], v[176:179], v[190:193], v[38:41]
	v_mfma_i32_16x16x64_i8 v[30:33], v[168:171], v[198:201], v[30:33]
	v_mfma_i32_16x16x64_i8 v[22:25], v[176:179], v[198:201], v[22:25]
	v_mfma_i32_16x16x64_i8 v[14:17], v[168:171], v[206:209], v[14:17]
	v_mfma_i32_16x16x64_i8 v[10:13], v[176:179], v[206:209], v[10:13]
	v_mfma_i32_16x16x64_i8 v[6:9], v[168:171], v[214:217], v[6:9]
	v_mfma_i32_16x16x64_i8 v[2:5], v[176:179], v[214:217], v[2:5]
	s_setprio 0
	s_barrier
	s_add_u32 s26, s26, 0x100
	s_addc_u32 s27, s27, 0
	s_add_u32 s34, s34, 0x100
	s_addc_u32 s35, s35, 0
	s_cmp_ge_i32 s60, s51
	s_mov_b32 s28, s60
	s_cbranch_scc0 .LBB0_3798
	v_cvt_f32_i32_e32 v172, v126
	v_cvt_f32_i32_e32 v173, v127
	v_cvt_f32_i32_e32 v170, v128
	v_cvt_f32_i32_e32 v171, v129
	v_cvt_f32_i32_e32 v174, v122
	v_cvt_f32_i32_e32 v175, v123
	v_cvt_f32_i32_e32 v176, v124
	v_cvt_f32_i32_e32 v177, v125
	v_cvt_f32_i32_e32 v180, v110
	v_cvt_f32_i32_e32 v181, v111
	v_cvt_f32_i32_e32 v182, v112
	v_cvt_f32_i32_e32 v183, v113
	v_cvt_f32_i32_e32 v178, v102
	v_cvt_f32_i32_e32 v179, v103
	v_cvt_f32_i32_e32 v184, v104
	v_cvt_f32_i32_e32 v185, v105
	v_cvt_f32_i32_e32 v152, v118
	v_cvt_f32_i32_e32 v153, v119
	v_cvt_f32_i32_e32 v154, v120
	v_cvt_f32_i32_e32 v155, v121
	v_cvt_f32_i32_e32 v156, v114
	v_cvt_f32_i32_e32 v157, v115
	v_cvt_f32_i32_e32 v158, v116
	v_cvt_f32_i32_e32 v159, v117
	v_cvt_f32_i32_e32 v160, v94
	v_cvt_f32_i32_e32 v161, v95
	v_cvt_f32_i32_e32 v162, v96
	v_cvt_f32_i32_e32 v163, v97
	v_cvt_f32_i32_e32 v164, v86
	v_cvt_f32_i32_e32 v165, v87
	v_cvt_f32_i32_e32 v166, v88
	v_cvt_f32_i32_e32 v167, v89
	v_cvt_f32_i32_e32 v118, v106
	v_cvt_f32_i32_e32 v119, v107
	v_cvt_f32_i32_e32 v120, v108
	v_cvt_f32_i32_e32 v121, v109
	v_cvt_f32_i32_e32 v122, v98
	v_cvt_f32_i32_e32 v123, v99
	v_cvt_f32_i32_e32 v124, v100
	v_cvt_f32_i32_e32 v125, v101
	v_cvt_f32_i32_e32 v126, v78
	v_cvt_f32_i32_e32 v127, v79
	v_cvt_f32_i32_e32 v128, v80
	v_cvt_f32_i32_e32 v129, v81
	v_cvt_f32_i32_e32 v148, v74
	v_cvt_f32_i32_e32 v149, v75
	v_cvt_f32_i32_e32 v150, v76
	v_cvt_f32_i32_e32 v151, v77
	v_cvt_f32_i32_e32 v102, v90
	v_cvt_f32_i32_e32 v103, v91
	v_cvt_f32_i32_e32 v104, v92
	v_cvt_f32_i32_e32 v105, v93
	v_cvt_f32_i32_e32 v106, v82
	v_cvt_f32_i32_e32 v107, v83
	v_cvt_f32_i32_e32 v108, v84
	v_cvt_f32_i32_e32 v109, v85
	v_cvt_f32_i32_e32 v110, v70
	v_cvt_f32_i32_e32 v111, v71
	v_cvt_f32_i32_e32 v112, v72
	v_cvt_f32_i32_e32 v113, v73
	v_cvt_f32_i32_e32 v114, v66
	v_cvt_f32_i32_e32 v115, v67
	v_cvt_f32_i32_e32 v116, v68
	v_cvt_f32_i32_e32 v117, v69
	v_cvt_f32_i32_e32 v82, v62
	v_cvt_f32_i32_e32 v83, v63
	v_cvt_f32_i32_e32 v84, v64
	v_cvt_f32_i32_e32 v85, v65
	v_cvt_f32_i32_e32 v86, v58
	v_cvt_f32_i32_e32 v87, v59
	v_cvt_f32_i32_e32 v88, v60
	v_cvt_f32_i32_e32 v89, v61
	v_cvt_f32_i32_e32 v92, v46
	v_cvt_f32_i32_e32 v93, v47
	v_cvt_f32_i32_e32 v94, v48
	v_cvt_f32_i32_e32 v95, v49
	v_cvt_f32_i32_e32 v96, v38
	v_cvt_f32_i32_e32 v97, v39
	v_cvt_f32_i32_e32 v98, v40
	v_cvt_f32_i32_e32 v99, v41
	v_cvt_f32_i32_e32 v66, v54
	v_cvt_f32_i32_e32 v67, v55
	v_cvt_f32_i32_e32 v68, v56
	v_cvt_f32_i32_e32 v69, v57
	v_cvt_f32_i32_e32 v70, v50
	v_cvt_f32_i32_e32 v71, v51
	v_cvt_f32_i32_e32 v72, v52
	v_cvt_f32_i32_e32 v73, v53
	v_cvt_f32_i32_e32 v74, v30
	v_cvt_f32_i32_e32 v75, v31
	v_cvt_f32_i32_e32 v76, v32
	v_cvt_f32_i32_e32 v77, v33
	v_cvt_f32_i32_e32 v78, v22
	v_cvt_f32_i32_e32 v79, v23
	v_cvt_f32_i32_e32 v80, v24
	v_cvt_f32_i32_e32 v81, v25
	v_cvt_f32_i32_e32 v50, v42
	v_cvt_f32_i32_e32 v51, v43
	v_cvt_f32_i32_e32 v52, v44
	v_cvt_f32_i32_e32 v53, v45
	v_cvt_f32_i32_e32 v54, v34
	v_cvt_f32_i32_e32 v55, v35
	v_cvt_f32_i32_e32 v56, v36
	v_cvt_f32_i32_e32 v57, v37
	v_cvt_f32_i32_e32 v58, v14
	v_cvt_f32_i32_e32 v59, v15
	v_cvt_f32_i32_e32 v60, v16
	v_cvt_f32_i32_e32 v61, v17
	v_cvt_f32_i32_e32 v62, v10
	v_cvt_f32_i32_e32 v63, v11
	v_cvt_f32_i32_e32 v64, v12
	v_cvt_f32_i32_e32 v65, v13
	v_cvt_f32_i32_e32 v34, v26
	v_cvt_f32_i32_e32 v35, v27
	v_cvt_f32_i32_e32 v36, v28
	v_cvt_f32_i32_e32 v37, v29
	v_cvt_f32_i32_e32 v38, v18
	v_cvt_f32_i32_e32 v39, v19
	v_cvt_f32_i32_e32 v40, v20
	v_cvt_f32_i32_e32 v41, v21
	v_cvt_f32_i32_e32 v42, v6
	v_cvt_f32_i32_e32 v43, v7
	v_cvt_f32_i32_e32 v44, v8
	v_cvt_f32_i32_e32 v45, v9
	v_cvt_f32_i32_e32 v46, v2
	v_cvt_f32_i32_e32 v47, v3
	v_cvt_f32_i32_e32 v48, v4
	v_cvt_f32_i32_e32 v49, v5

.LBB0_3879:
	ds_read_b128 v[130:133], v169
	ds_read_b128 v[134:137], v169 offset:1024
	ds_read_b128 v[138:141], v169 offset:2048
	ds_read_b128 v[142:145], v169 offset:3072
	ds_read_b128 v[162:165], v170
	ds_read_b128 v[172:175], v170 offset:1024
	ds_read_b128 v[176:179], v170 offset:2048
	ds_read_b128 v[180:183], v170 offset:3072
	s_add_i32 s59, s26, 2
	s_add_u32 s27, s24, 0x4000
	s_addc_u32 s28, s25, 0
	s_cmp_eq_u32 s48, s26
	s_cselect_b32 s29, s3, s28
	s_cselect_b32 s28, s2, s27
	s_cselect_b32 s60, s22, s57
	s_cselect_b32 s61, s23, s58
	s_add_u32 s26, s28, 0x8000
	s_addc_u32 s27, s29, 0
	v_lshl_add_u64 v[216:217], s[24:25], 0, v[154:155]
	s_add_i32 m0, s38, 0xc000
	ds_read_b128 v[184:187], v171
	ds_read_b128 v[188:191], v171 offset:1024
	ds_read_b128 v[192:195], v171 offset:2048
	ds_read_b128 v[196:199], v171 offset:3072
	ds_read_b128 v[200:203], v171 offset:4096
	ds_read_b128 v[204:207], v171 offset:5120
	ds_read_b128 v[208:211], v171 offset:6144
	ds_read_b128 v[212:215], v171 offset:7168
	global_load_lds_dwordx4 v[216:217], off
	v_lshl_add_u64 v[216:217], s[24:25], 0, v[156:157]
	s_add_i32 m0, s38, 0xe000
	s_nop 0
	global_load_lds_dwordx4 v[216:217], off
	s_waitcnt vmcnt(8)
	s_waitcnt lgkmcnt(0)
	s_setprio 1
	s_waitcnt lgkmcnt(0)
	v_mfma_f32_16x16x32_bf16 v[126:129], v[130:133], v[184:187], v[126:129]
	v_mfma_f32_16x16x32_bf16 v[122:125], v[138:141], v[184:187], v[122:125]
	v_mfma_f32_16x16x32_bf16 v[110:113], v[130:133], v[192:195], v[110:113]
	v_mfma_f32_16x16x32_bf16 v[106:109], v[138:141], v[192:195], v[106:109]
	s_barrier
	v_mfma_f32_16x16x32_bf16 v[94:97], v[130:133], v[200:203], v[94:97]
	v_mfma_f32_16x16x32_bf16 v[90:93], v[138:141], v[200:203], v[90:93]
	v_mfma_f32_16x16x32_bf16 v[78:81], v[130:133], v[208:211], v[78:81]
	v_mfma_f32_16x16x32_bf16 v[74:77], v[138:141], v[208:211], v[74:77]
	v_mfma_f32_16x16x32_bf16 v[126:129], v[134:137], v[188:191], v[126:129]
	v_mfma_f32_16x16x32_bf16 v[122:125], v[142:145], v[188:191], v[122:125]
	v_mfma_f32_16x16x32_bf16 v[110:113], v[134:137], v[196:199], v[110:113]
	v_mfma_f32_16x16x32_bf16 v[106:109], v[142:145], v[196:199], v[106:109]
	v_mfma_f32_16x16x32_bf16 v[94:97], v[134:137], v[204:207], v[94:97]
	v_mfma_f32_16x16x32_bf16 v[90:93], v[142:145], v[204:207], v[90:93]
	v_mfma_f32_16x16x32_bf16 v[78:81], v[134:137], v[212:215], v[78:81]
	v_mfma_f32_16x16x32_bf16 v[74:77], v[142:145], v[212:215], v[74:77]
	s_setprio 0
	s_setprio 1
	v_mfma_f32_16x16x32_bf16 v[118:121], v[162:165], v[184:187], v[118:121]
	v_mfma_f32_16x16x32_bf16 v[114:117], v[176:179], v[184:187], v[114:117]
	v_mfma_f32_16x16x32_bf16 v[102:105], v[162:165], v[192:195], v[102:105]
	v_mfma_f32_16x16x32_bf16 v[98:101], v[176:179], v[192:195], v[98:101]
	v_mfma_f32_16x16x32_bf16 v[86:89], v[162:165], v[200:203], v[86:89]
	v_mfma_f32_16x16x32_bf16 v[82:85], v[176:179], v[200:203], v[82:85]
	v_mfma_f32_16x16x32_bf16 v[70:73], v[162:165], v[208:211], v[70:73]
	v_mfma_f32_16x16x32_bf16 v[66:69], v[176:179], v[208:211], v[66:69]
	v_mfma_f32_16x16x32_bf16 v[118:121], v[172:175], v[188:191], v[118:121]
	v_mfma_f32_16x16x32_bf16 v[114:117], v[180:183], v[188:191], v[114:117]
	v_mfma_f32_16x16x32_bf16 v[102:105], v[172:175], v[196:199], v[102:105]
	v_mfma_f32_16x16x32_bf16 v[98:101], v[180:183], v[196:199], v[98:101]
	v_mfma_f32_16x16x32_bf16 v[86:89], v[172:175], v[204:207], v[86:89]
	v_mfma_f32_16x16x32_bf16 v[82:85], v[180:183], v[204:207], v[82:85]
	v_mfma_f32_16x16x32_bf16 v[70:73], v[172:175], v[212:215], v[70:73]
	v_mfma_f32_16x16x32_bf16 v[66:69], v[180:183], v[212:215], v[66:69]
	s_setprio 0
	s_barrier
	s_add_i32 s62, s50, s37
	v_lshl_add_u64 v[216:217], s[60:61], 0, v[148:149]
	s_mov_b32 m0, s62
	ds_read_b128 v[184:187], v171 offset:16384
	ds_read_b128 v[188:191], v171 offset:17408
	ds_read_b128 v[192:195], v171 offset:18432
	ds_read_b128 v[196:199], v171 offset:19456
	ds_read_b128 v[200:203], v171 offset:20480
	ds_read_b128 v[204:207], v171 offset:21504
	ds_read_b128 v[208:211], v171 offset:22528
	ds_read_b128 v[212:215], v171 offset:23552
	global_load_lds_dwordx4 v[216:217], off
	s_add_i32 m0, s62, 0x2000
	v_lshl_add_u64 v[218:219], s[60:61], 0, v[152:153]
	s_add_u32 s60, s60, s6
	s_addc_u32 s61, s61, s7
	s_add_i32 s62, s51, s37
	global_load_lds_dwordx4 v[218:219], off
	v_lshl_add_u64 v[220:221], s[60:61], 0, v[148:149]
	s_mov_b32 m0, s62
	v_lshl_add_u64 v[222:223], s[60:61], 0, v[152:153]
	global_load_lds_dwordx4 v[220:221], off
	s_add_i32 m0, s62, 0x2000
	v_lshl_add_u64 v[224:225], s[28:29], 0, v[146:147]
	global_load_lds_dwordx4 v[222:223], off
	s_mov_b32 m0, s38
	s_nop 0
	global_load_lds_dwordx4 v[224:225], off
	v_lshl_add_u64 v[224:225], s[28:29], 0, v[150:151]
	s_mov_b32 m0, s39
	s_nop 0
	global_load_lds_dwordx4 v[224:225], off
	s_waitcnt vmcnt(8)
	s_waitcnt lgkmcnt(0)
	s_setprio 1
	s_waitcnt lgkmcnt(0)
	v_mfma_f32_16x16x32_bf16 v[62:65], v[130:133], v[184:187], v[62:65]
	v_mfma_f32_16x16x32_bf16 v[58:61], v[138:141], v[184:187], v[58:61]
	v_mfma_f32_16x16x32_bf16 v[46:49], v[130:133], v[192:195], v[46:49]
	v_mfma_f32_16x16x32_bf16 v[42:45], v[138:141], v[192:195], v[42:45]
	s_barrier
	v_mfma_f32_16x16x32_bf16 v[30:33], v[130:133], v[200:203], v[30:33]
	v_mfma_f32_16x16x32_bf16 v[26:29], v[138:141], v[200:203], v[26:29]
	v_mfma_f32_16x16x32_bf16 v[14:17], v[130:133], v[208:211], v[14:17]
	v_mfma_f32_16x16x32_bf16 v[10:13], v[138:141], v[208:211], v[10:13]
	v_mfma_f32_16x16x32_bf16 v[62:65], v[134:137], v[188:191], v[62:65]
	v_mfma_f32_16x16x32_bf16 v[58:61], v[142:145], v[188:191], v[58:61]
	v_mfma_f32_16x16x32_bf16 v[46:49], v[134:137], v[196:199], v[46:49]
	v_mfma_f32_16x16x32_bf16 v[42:45], v[142:145], v[196:199], v[42:45]
	v_mfma_f32_16x16x32_bf16 v[30:33], v[134:137], v[204:207], v[30:33]
	v_mfma_f32_16x16x32_bf16 v[26:29], v[142:145], v[204:207], v[26:29]
	v_mfma_f32_16x16x32_bf16 v[14:17], v[134:137], v[212:215], v[14:17]
	v_mfma_f32_16x16x32_bf16 v[10:13], v[142:145], v[212:215], v[10:13]
	s_setprio 0
	s_setprio 1
	v_mfma_f32_16x16x32_bf16 v[54:57], v[162:165], v[184:187], v[54:57]
	v_mfma_f32_16x16x32_bf16 v[50:53], v[176:179], v[184:187], v[50:53]
	v_mfma_f32_16x16x32_bf16 v[38:41], v[162:165], v[192:195], v[38:41]
	v_mfma_f32_16x16x32_bf16 v[34:37], v[176:179], v[192:195], v[34:37]
	v_mfma_f32_16x16x32_bf16 v[22:25], v[162:165], v[200:203], v[22:25]
	v_mfma_f32_16x16x32_bf16 v[18:21], v[176:179], v[200:203], v[18:21]
	v_mfma_f32_16x16x32_bf16 v[6:9], v[162:165], v[208:211], v[6:9]
	v_mfma_f32_16x16x32_bf16 v[2:5], v[176:179], v[208:211], v[2:5]
	v_mfma_f32_16x16x32_bf16 v[54:57], v[172:175], v[188:191], v[54:57]
	v_mfma_f32_16x16x32_bf16 v[50:53], v[180:183], v[188:191], v[50:53]
	v_mfma_f32_16x16x32_bf16 v[38:41], v[172:175], v[196:199], v[38:41]
	v_mfma_f32_16x16x32_bf16 v[34:37], v[180:183], v[196:199], v[34:37]
	v_mfma_f32_16x16x32_bf16 v[22:25], v[172:175], v[204:207], v[22:25]
	v_mfma_f32_16x16x32_bf16 v[18:21], v[180:183], v[204:207], v[18:21]
	v_mfma_f32_16x16x32_bf16 v[6:9], v[172:175], v[212:215], v[6:9]
	v_mfma_f32_16x16x32_bf16 v[2:5], v[180:183], v[212:215], v[2:5]
	s_setprio 0
	s_barrier
	s_add_i32 s60, 0, 0x18000
	s_add_i32 s61, 0, 0x1c000
	v_add_u32_e32 v142, s60, v167
	v_add_u32_e32 v180, s61, v167
	ds_read_b128 v[130:133], v142
	ds_read_b128 v[134:137], v142 offset:1024
	ds_read_b128 v[138:141], v142 offset:2048
	ds_read_b128 v[142:145], v142 offset:3072
	ds_read_b128 v[162:165], v180
	ds_read_b128 v[172:175], v180 offset:1024
	ds_read_b128 v[176:179], v180 offset:2048
	ds_read_b128 v[180:183], v180 offset:3072
	s_add_u32 s28, s28, 0x4000
	s_addc_u32 s29, s29, 0
	s_mov_b32 m0, s40
	v_lshl_add_u64 v[224:225], s[28:29], 0, v[146:147]
	ds_read_b128 v[184:187], v171 offset:32768
	ds_read_b128 v[188:191], v171 offset:33792
	ds_read_b128 v[192:195], v171 offset:34816
	ds_read_b128 v[196:199], v171 offset:35840
	ds_read_b128 v[200:203], v171 offset:36864
	ds_read_b128 v[204:207], v171 offset:37888
	ds_read_b128 v[208:211], v171 offset:38912
	ds_read_b128 v[212:215], v171 offset:39936
	global_load_lds_dwordx4 v[224:225], off
	v_lshl_add_u64 v[224:225], s[28:29], 0, v[150:151]
	s_mov_b32 m0, s41
	s_nop 0
	global_load_lds_dwordx4 v[224:225], off
	s_waitcnt vmcnt(8)
	s_waitcnt lgkmcnt(0)
	s_setprio 1
	s_waitcnt lgkmcnt(0)
	v_mfma_f32_16x16x32_bf16 v[126:129], v[130:133], v[184:187], v[126:129]
	v_mfma_f32_16x16x32_bf16 v[122:125], v[138:141], v[184:187], v[122:125]
	v_mfma_f32_16x16x32_bf16 v[110:113], v[130:133], v[192:195], v[110:113]
	v_mfma_f32_16x16x32_bf16 v[106:109], v[138:141], v[192:195], v[106:109]
	s_barrier
	v_mfma_f32_16x16x32_bf16 v[94:97], v[130:133], v[200:203], v[94:97]
	v_mfma_f32_16x16x32_bf16 v[90:93], v[138:141], v[200:203], v[90:93]
	v_mfma_f32_16x16x32_bf16 v[78:81], v[130:133], v[208:211], v[78:81]
	v_mfma_f32_16x16x32_bf16 v[74:77], v[138:141], v[208:211], v[74:77]
	v_mfma_f32_16x16x32_bf16 v[126:129], v[134:137], v[188:191], v[126:129]
	v_mfma_f32_16x16x32_bf16 v[122:125], v[142:145], v[188:191], v[122:125]
	v_mfma_f32_16x16x32_bf16 v[110:113], v[134:137], v[196:199], v[110:113]
	v_mfma_f32_16x16x32_bf16 v[106:109], v[142:145], v[196:199], v[106:109]
	v_mfma_f32_16x16x32_bf16 v[94:97], v[134:137], v[204:207], v[94:97]
	v_mfma_f32_16x16x32_bf16 v[90:93], v[142:145], v[204:207], v[90:93]
	v_mfma_f32_16x16x32_bf16 v[78:81], v[134:137], v[212:215], v[78:81]
	v_mfma_f32_16x16x32_bf16 v[74:77], v[142:145], v[212:215], v[74:77]
	s_setprio 0
	s_setprio 1
	v_mfma_f32_16x16x32_bf16 v[118:121], v[162:165], v[184:187], v[118:121]
	v_mfma_f32_16x16x32_bf16 v[114:117], v[176:179], v[184:187], v[114:117]
	v_mfma_f32_16x16x32_bf16 v[102:105], v[162:165], v[192:195], v[102:105]
	v_mfma_f32_16x16x32_bf16 v[98:101], v[176:179], v[192:195], v[98:101]
	v_mfma_f32_16x16x32_bf16 v[86:89], v[162:165], v[200:203], v[86:89]
	v_mfma_f32_16x16x32_bf16 v[82:85], v[176:179], v[200:203], v[82:85]
	v_mfma_f32_16x16x32_bf16 v[70:73], v[162:165], v[208:211], v[70:73]
	v_mfma_f32_16x16x32_bf16 v[66:69], v[176:179], v[208:211], v[66:69]
	v_mfma_f32_16x16x32_bf16 v[118:121], v[172:175], v[188:191], v[118:121]
	v_mfma_f32_16x16x32_bf16 v[114:117], v[180:183], v[188:191], v[114:117]
	v_mfma_f32_16x16x32_bf16 v[102:105], v[172:175], v[196:199], v[102:105]
	v_mfma_f32_16x16x32_bf16 v[98:101], v[180:183], v[196:199], v[98:101]
	v_mfma_f32_16x16x32_bf16 v[86:89], v[172:175], v[204:207], v[86:89]
	v_mfma_f32_16x16x32_bf16 v[82:85], v[180:183], v[204:207], v[82:85]
	v_mfma_f32_16x16x32_bf16 v[70:73], v[172:175], v[212:215], v[70:73]
	v_mfma_f32_16x16x32_bf16 v[66:69], v[180:183], v[212:215], v[66:69]
	s_setprio 0
	s_barrier
	s_add_i32 s28, s60, s37
	v_lshl_add_u64 v[216:217], v[216:217], 0, s[14:15]
	s_mov_b32 m0, s28
	ds_read_b128 v[184:187], v171 offset:49152
	ds_read_b128 v[188:191], v171 offset:50176
	ds_read_b128 v[192:195], v171 offset:51200
	ds_read_b128 v[196:199], v171 offset:52224
	ds_read_b128 v[200:203], v171 offset:53248
	ds_read_b128 v[204:207], v171 offset:54272
	ds_read_b128 v[208:211], v171 offset:55296
	ds_read_b128 v[212:215], v171 offset:56320
	global_load_lds_dwordx4 v[216:217], off
	v_lshl_add_u64 v[216:217], v[218:219], 0, s[14:15]
	s_add_i32 m0, s28, 0x2000
	s_add_i32 s28, s61, s37
	global_load_lds_dwordx4 v[216:217], off
	v_lshl_add_u64 v[216:217], v[220:221], 0, s[14:15]
	s_mov_b32 m0, s28
	s_nop 0
	global_load_lds_dwordx4 v[216:217], off
	v_lshl_add_u64 v[216:217], v[222:223], 0, s[14:15]
	s_add_i32 m0, s28, 0x2000
	s_nop 0
	global_load_lds_dwordx4 v[216:217], off
	v_lshl_add_u64 v[216:217], s[26:27], 0, v[146:147]
	s_mov_b32 m0, s46
	s_nop 0
	global_load_lds_dwordx4 v[216:217], off
	v_lshl_add_u64 v[216:217], s[26:27], 0, v[150:151]
	s_mov_b32 m0, s47
	s_nop 0
	global_load_lds_dwordx4 v[216:217], off
	s_waitcnt vmcnt(8)
	s_waitcnt lgkmcnt(0)
	s_setprio 1
	s_waitcnt lgkmcnt(0)
	v_mfma_f32_16x16x32_bf16 v[62:65], v[130:133], v[184:187], v[62:65]
	v_mfma_f32_16x16x32_bf16 v[58:61], v[138:141], v[184:187], v[58:61]
	v_mfma_f32_16x16x32_bf16 v[46:49], v[130:133], v[192:195], v[46:49]
	v_mfma_f32_16x16x32_bf16 v[42:45], v[138:141], v[192:195], v[42:45]
	s_barrier
	v_mfma_f32_16x16x32_bf16 v[30:33], v[130:133], v[200:203], v[30:33]
	v_mfma_f32_16x16x32_bf16 v[26:29], v[138:141], v[200:203], v[26:29]
	v_mfma_f32_16x16x32_bf16 v[14:17], v[130:133], v[208:211], v[14:17]
	v_mfma_f32_16x16x32_bf16 v[10:13], v[138:141], v[208:211], v[10:13]
	v_mfma_f32_16x16x32_bf16 v[62:65], v[134:137], v[188:191], v[62:65]
	v_mfma_f32_16x16x32_bf16 v[58:61], v[142:145], v[188:191], v[58:61]
	v_mfma_f32_16x16x32_bf16 v[46:49], v[134:137], v[196:199], v[46:49]
	v_mfma_f32_16x16x32_bf16 v[42:45], v[142:145], v[196:199], v[42:45]
	v_mfma_f32_16x16x32_bf16 v[30:33], v[134:137], v[204:207], v[30:33]
	v_mfma_f32_16x16x32_bf16 v[26:29], v[142:145], v[204:207], v[26:29]
	v_mfma_f32_16x16x32_bf16 v[14:17], v[134:137], v[212:215], v[14:17]
	v_mfma_f32_16x16x32_bf16 v[10:13], v[142:145], v[212:215], v[10:13]
	s_setprio 0
	s_setprio 1
	v_mfma_f32_16x16x32_bf16 v[54:57], v[162:165], v[184:187], v[54:57]
	v_mfma_f32_16x16x32_bf16 v[50:53], v[176:179], v[184:187], v[50:53]
	v_mfma_f32_16x16x32_bf16 v[38:41], v[162:165], v[192:195], v[38:41]
	v_mfma_f32_16x16x32_bf16 v[34:37], v[176:179], v[192:195], v[34:37]
	v_mfma_f32_16x16x32_bf16 v[22:25], v[162:165], v[200:203], v[22:25]
	v_mfma_f32_16x16x32_bf16 v[18:21], v[176:179], v[200:203], v[18:21]
	v_mfma_f32_16x16x32_bf16 v[6:9], v[162:165], v[208:211], v[6:9]
	v_mfma_f32_16x16x32_bf16 v[2:5], v[176:179], v[208:211], v[2:5]
	v_mfma_f32_16x16x32_bf16 v[54:57], v[172:175], v[188:191], v[54:57]
	v_mfma_f32_16x16x32_bf16 v[50:53], v[180:183], v[188:191], v[50:53]
	v_mfma_f32_16x16x32_bf16 v[38:41], v[172:175], v[196:199], v[38:41]
	v_mfma_f32_16x16x32_bf16 v[34:37], v[180:183], v[196:199], v[34:37]
	v_mfma_f32_16x16x32_bf16 v[22:25], v[172:175], v[204:207], v[22:25]
	v_mfma_f32_16x16x32_bf16 v[18:21], v[180:183], v[204:207], v[18:21]
	v_mfma_f32_16x16x32_bf16 v[6:9], v[172:175], v[212:215], v[6:9]
	v_mfma_f32_16x16x32_bf16 v[2:5], v[180:183], v[212:215], v[2:5]
	s_setprio 0
	s_barrier
	s_add_u32 s57, s57, 0x100
	s_addc_u32 s58, s58, 0
	s_add_u32 s24, s24, 0x10000
	s_addc_u32 s25, s25, 0
	s_cmp_ge_i32 s59, s45
	s_mov_b32 s26, s59
	s_cbranch_scc0 .LBB0_3879
